# k8 plus SB vote flags via LDS ops instead of serialized flat loads, memkv loads fully unrolled, redundant mid-burst setprio 0/1 pairs removed
# speedup vs baseline: 1.0053x; 1.0053x over previous
; #define PG8_STAGE(bufoff, gbase, voff) do { _Pragma("unroll") for (int _i = 0; _i < 2; ++_i) \
;         __builtin_amdgcn_global_load_lds((const unsigned*)((const char*)(gbase) + (voff)[_i]), (PG8_LAS unsigned*)(lds + (bufoff) + ldsw + _i * 8192), 16, 0, 0); } while (0)
; #define PG8_LDA(dst, b, h) do { _Pragma("unroll") for (int m = 0; m < 4; ++m) _Pragma("unroll") for (int k = 0; k < 2; ++k) dst[m][k] = *(const PG8_LAS bf16x8*)(lds + PG8_SA(b, h) + aoff + m * 2048 + k * 1024); } while (0)
; #define PG8_LDB(dst, b, h) do { _Pragma("unroll") for (int n = 0; n < 2; ++n) _Pragma("unroll") for (int k = 0; k < 2; ++k) dst[n][k] = *(const PG8_LAS bf16x8*)(lds + PG8_SB(b, h) + boff + n * 2048 + k * 1024); } while (0)
; #define PG8_MMA(ai, bj, At, Bt) do { __builtin_amdgcn_s_setprio(1); _Pragma("unroll") for (int m = 0; m < 4; ++m) _Pragma("unroll") for (int n = 0; n < 2; ++n) _Pragma("unroll") for (int k = 0; k < 2; ++k) \
;         acc[ai][bj][m][n] = __builtin_amdgcn_mfma_f32_16x16x32_bf16(Bt[n][k], At[m][k], acc[ai][bj][m][n], 0, 0, 0); __builtin_amdgcn_s_setprio(0); } while (0)
; #define PG8_BAR __builtin_amdgcn_s_barrier()
; template <class Epi, class Sched, bool ALIGN_EPI = false, bool SP2 = false>
; __device__ __forceinline__ void gemm_phase(PG8_LAS unsigned char* lds, const Gemm g, const Sched& S, const Epi& E, const int wv0) {
;     ...
;             PG8_LDB(B0, 0, 0); PG8_LDB(B1, 0, 1); PG8_SCHED; PG8_LDA(At, 0, 0); PG8_STAGE(PG8_SA(1, 1), a1 + hstepA, voffA);
;             PG8_WAIT_V(8); PG8_WAIT_L(0); PG8_BAR; PG8_MMA(0, 0, At, B0); PG8_MMA(0, 1, At, B1); PG8_BAR; PG8_SCHED;
;             PG8_LDA(At, 0, 1); PG8_STAGE(PG8_SB(0, 0), b2, voffB); PG8_STAGE(PG8_SB(0, 1), b2 + hstepB, voffB); PG8_STAGE(PG8_SA(0, 0), a2, voffA);
;             PG8_WAIT_V(8); PG8_WAIT_L(0); PG8_BAR; PG8_MMA(1, 0, At, B0); PG8_MMA(1, 1, At, B1); PG8_BAR; PG8_SCHED;
;             PG8_LDB(B0, 1, 0); PG8_LDB(B1, 1, 1); PG8_SCHED; PG8_LDA(At, 1, 0); PG8_STAGE(PG8_SA(0, 1), a2 + hstepA, voffA);
;             PG8_WAIT_V(8); PG8_WAIT_L(0); PG8_BAR; PG8_MMA(0, 0, At, B0); PG8_MMA(0, 1, At, B1); PG8_BAR; PG8_SCHED;
;             PG8_LDA(At, 1, 1); PG8_STAGE(PG8_SB(1, 0), b3, voffB); PG8_STAGE(PG8_SB(1, 1), b3 + hstepB, voffB); PG8_STAGE(PG8_SA(1, 0), a3, voffA);
;             PG8_WAIT_V(8); PG8_WAIT_L(0); PG8_BAR; PG8_MMA(1, 0, At, B0); PG8_MMA(1, 1, At, B1); PG8_BAR; PG8_SCHED;
.LBB0_82:
	ds_read_b128 v[156:159], v152
	ds_read_b128 v[160:163], v152 offset:1024
	ds_read_b128 v[164:167], v152 offset:2048
	ds_read_b128 v[168:171], v152 offset:3072
	ds_read_b128 v[172:175], v153
	ds_read_b128 v[176:179], v153 offset:1024
	ds_read_b128 v[180:183], v153 offset:2048
	ds_read_b128 v[184:187], v153 offset:3072
	s_add_u32 s34, s30, 0xfff80080
	s_addc_u32 s35, s31, -1
	s_cmp_eq_u32 s38, 28
	s_cselect_b32 s37, s25, s35
	s_cselect_b32 s36, s24, s34
	s_cselect_b32 s35, s27, s23
	s_cselect_b32 s34, s26, s21
	v_lshl_add_u64 v[146:147], s[30:31], 0, v[140:141]
	s_add_i32 m0, s29, 0xc000
	ds_read_b128 v[188:191], v154
	ds_read_b128 v[192:195], v154 offset:1024
	ds_read_b128 v[196:199], v154 offset:2048
	ds_read_b128 v[200:203], v154 offset:3072
	ds_read_b128 v[206:209], v154 offset:4096
	ds_read_b128 v[210:213], v154 offset:5120
	ds_read_b128 v[214:217], v154 offset:6144
	ds_read_b128 v[218:221], v154 offset:7168
	global_load_lds_dwordx4 v[146:147], off
	v_lshl_add_u64 v[146:147], s[30:31], 0, v[138:139]
	s_add_i32 m0, s29, 0xe000
	s_nop 0
	global_load_lds_dwordx4 v[146:147], off
	s_waitcnt vmcnt(8)
	s_waitcnt lgkmcnt(0)
	s_barrier
	s_setprio 1
	v_mfma_f32_16x16x32_bf16 v[124:127], v[156:159], v[188:191], v[124:127]
	v_mfma_f32_16x16x32_bf16 v[120:123], v[164:167], v[188:191], v[120:123]
	v_mfma_f32_16x16x32_bf16 v[116:119], v[156:159], v[196:199], v[116:119]
	v_mfma_f32_16x16x32_bf16 v[108:111], v[164:167], v[196:199], v[108:111]
	v_mfma_f32_16x16x32_bf16 v[100:103], v[156:159], v[206:209], v[100:103]
	v_mfma_f32_16x16x32_bf16 v[92:95], v[164:167], v[206:209], v[92:95]
	v_mfma_f32_16x16x32_bf16 v[84:87], v[156:159], v[214:217], v[84:87]
	v_mfma_f32_16x16x32_bf16 v[76:79], v[164:167], v[214:217], v[76:79]
	v_mfma_f32_16x16x32_bf16 v[124:127], v[160:163], v[192:195], v[124:127]
	v_mfma_f32_16x16x32_bf16 v[120:123], v[168:171], v[192:195], v[120:123]
	v_mfma_f32_16x16x32_bf16 v[116:119], v[160:163], v[200:203], v[116:119]
	v_mfma_f32_16x16x32_bf16 v[108:111], v[168:171], v[200:203], v[108:111]
	v_mfma_f32_16x16x32_bf16 v[100:103], v[160:163], v[210:213], v[100:103]
	v_mfma_f32_16x16x32_bf16 v[92:95], v[168:171], v[210:213], v[92:95]
	v_mfma_f32_16x16x32_bf16 v[84:87], v[160:163], v[218:221], v[84:87]
	v_mfma_f32_16x16x32_bf16 v[76:79], v[168:171], v[218:221], v[76:79]
	v_mfma_f32_16x16x32_bf16 v[112:115], v[172:175], v[188:191], v[112:115]
	v_mfma_f32_16x16x32_bf16 v[104:107], v[180:183], v[188:191], v[104:107]
	v_mfma_f32_16x16x32_bf16 v[96:99], v[172:175], v[196:199], v[96:99]
	v_mfma_f32_16x16x32_bf16 v[88:91], v[180:183], v[196:199], v[88:91]
	v_mfma_f32_16x16x32_bf16 v[80:83], v[172:175], v[206:209], v[80:83]
	v_mfma_f32_16x16x32_bf16 v[72:75], v[180:183], v[206:209], v[72:75]
	v_mfma_f32_16x16x32_bf16 v[68:71], v[172:175], v[214:217], v[68:71]
	v_mfma_f32_16x16x32_bf16 v[64:67], v[180:183], v[214:217], v[64:67]
	v_mfma_f32_16x16x32_bf16 v[112:115], v[176:179], v[192:195], v[112:115]
	v_mfma_f32_16x16x32_bf16 v[104:107], v[184:187], v[192:195], v[104:107]
	v_mfma_f32_16x16x32_bf16 v[96:99], v[176:179], v[200:203], v[96:99]
	v_mfma_f32_16x16x32_bf16 v[88:91], v[184:187], v[200:203], v[88:91]
	v_mfma_f32_16x16x32_bf16 v[80:83], v[176:179], v[210:213], v[80:83]
	v_mfma_f32_16x16x32_bf16 v[72:75], v[184:187], v[210:213], v[72:75]
	v_mfma_f32_16x16x32_bf16 v[68:71], v[176:179], v[218:221], v[68:71]
	v_mfma_f32_16x16x32_bf16 v[64:67], v[184:187], v[218:221], v[64:67]
	s_setprio 0
	s_barrier
	s_add_i32 s39, s62, s47
	v_lshl_add_u64 v[146:147], s[34:35], 0, v[132:133]
	s_mov_b32 m0, s39
	ds_read_b128 v[188:191], v154 offset:16384
	ds_read_b128 v[192:195], v154 offset:17408
	ds_read_b128 v[196:199], v154 offset:18432
	ds_read_b128 v[200:203], v154 offset:19456
	ds_read_b128 v[206:209], v154 offset:20480
	ds_read_b128 v[210:213], v154 offset:21504
	ds_read_b128 v[214:217], v154 offset:22528
	ds_read_b128 v[218:221], v154 offset:23552
	global_load_lds_dwordx4 v[146:147], off
	s_add_i32 m0, s39, 0x2000
	s_add_u32 s68, s34, 0x80000
	v_lshl_add_u64 v[222:223], s[34:35], 0, v[128:129]
	s_addc_u32 s69, s35, 0
	s_add_i32 s39, s63, s47
	global_load_lds_dwordx4 v[222:223], off
	v_lshl_add_u64 v[224:225], s[68:69], 0, v[132:133]
	s_mov_b32 m0, s39
	v_lshl_add_u64 v[226:227], s[36:37], 0, v[130:131]
	global_load_lds_dwordx4 v[224:225], off
	v_lshl_add_u64 v[224:225], s[68:69], 0, v[128:129]
	s_add_i32 m0, s39, 0x2000
	s_nop 0
	global_load_lds_dwordx4 v[224:225], off
	v_lshl_add_u64 v[224:225], s[36:37], 0, v[134:135]
	s_mov_b32 m0, s29
	s_nop 0
	global_load_lds_dwordx4 v[224:225], off
	s_mov_b32 m0, s49
	s_nop 0
	global_load_lds_dwordx4 v[226:227], off
	s_waitcnt vmcnt(8)
	s_waitcnt lgkmcnt(0)
	s_barrier
; #define PG8_STAGE(bufoff, gbase, voff) do { _Pragma("unroll") for (int _i = 0; _i < 2; ++_i) \
;         __builtin_amdgcn_global_load_lds((const unsigned*)((const char*)(gbase) + (voff)[_i]), (PG8_LAS unsigned*)(lds + (bufoff) + ldsw + _i * 8192), 16, 0, 0); } while (0)
; #define PG8_LDA(dst, b, h) do { _Pragma("unroll") for (int m = 0; m < 4; ++m) _Pragma("unroll") for (int k = 0; k < 2; ++k) dst[m][k] = *(const PG8_LAS bf16x8*)(lds + PG8_SA(b, h) + aoff + m * 2048 + k * 1024); } while (0)
; #define PG8_LDB(dst, b, h) do { _Pragma("unroll") for (int n = 0; n < 2; ++n) _Pragma("unroll") for (int k = 0; k < 2; ++k) dst[n][k] = *(const PG8_LAS bf16x8*)(lds + PG8_SB(b, h) + boff + n * 2048 + k * 1024); } while (0)
; #define PG8_MMA(ai, bj, At, Bt) do { __builtin_amdgcn_s_setprio(1); _Pragma("unroll") for (int m = 0; m < 4; ++m) _Pragma("unroll") for (int n = 0; n < 2; ++n) _Pragma("unroll") for (int k = 0; k < 2; ++k) \
;         acc[ai][bj][m][n] = __builtin_amdgcn_mfma_f32_16x16x32_bf16(Bt[n][k], At[m][k], acc[ai][bj][m][n], 0, 0, 0); __builtin_amdgcn_s_setprio(0); } while (0)
; #define PG8_BAR __builtin_amdgcn_s_barrier()
; template <class Epi, class Sched, bool ALIGN_EPI = false, bool SP2 = false>
; __device__ __forceinline__ void gemm_phase(PG8_LAS unsigned char* lds, const Gemm g, const Sched& S, const Epi& E, const int wv0) {
;     ...
;             PG8_LDB(B0, 0, 0); PG8_LDB(B1, 0, 1); PG8_SCHED; PG8_LDA(At, 0, 0); PG8_STAGE(PG8_SA(1, 1), a1 + hstepA, voffA);
;             PG8_WAIT_V(8); PG8_WAIT_L(0); PG8_BAR; PG8_MMA(0, 0, At, B0); PG8_MMA(0, 1, At, B1); PG8_BAR; PG8_SCHED;
;             PG8_LDA(At, 0, 1); PG8_STAGE(PG8_SB(0, 0), b2, voffB); PG8_STAGE(PG8_SB(0, 1), b2 + hstepB, voffB); PG8_STAGE(PG8_SA(0, 0), a2, voffA);
;             PG8_WAIT_V(8); PG8_WAIT_L(0); PG8_BAR; PG8_MMA(1, 0, At, B0); PG8_MMA(1, 1, At, B1); PG8_BAR; PG8_SCHED;
;             PG8_LDB(B0, 1, 0); PG8_LDB(B1, 1, 1); PG8_SCHED; PG8_LDA(At, 1, 0); PG8_STAGE(PG8_SA(0, 1), a2 + hstepA, voffA);
;             PG8_WAIT_V(8); PG8_WAIT_L(0); PG8_BAR; PG8_MMA(0, 0, At, B0); PG8_MMA(0, 1, At, B1); PG8_BAR; PG8_SCHED;
;             PG8_LDA(At, 1, 1); PG8_STAGE(PG8_SB(1, 0), b3, voffB); PG8_STAGE(PG8_SB(1, 1), b3 + hstepB, voffB); PG8_STAGE(PG8_SA(1, 0), a3, voffA);
;             PG8_WAIT_V(8); PG8_WAIT_L(0); PG8_BAR; PG8_MMA(1, 0, At, B0); PG8_MMA(1, 1, At, B1); PG8_BAR; PG8_SCHED;
	s_setprio 1
	v_mfma_f32_16x16x32_bf16 v[60:63], v[156:159], v[188:191], v[60:63]
	v_mfma_f32_16x16x32_bf16 v[56:59], v[164:167], v[188:191], v[56:59]
	v_mfma_f32_16x16x32_bf16 v[52:55], v[156:159], v[196:199], v[52:55]
	v_mfma_f32_16x16x32_bf16 v[44:47], v[164:167], v[196:199], v[44:47]
	v_mfma_f32_16x16x32_bf16 v[36:39], v[156:159], v[206:209], v[36:39]
	v_mfma_f32_16x16x32_bf16 v[28:31], v[164:167], v[206:209], v[28:31]
	v_mfma_f32_16x16x32_bf16 v[20:23], v[156:159], v[214:217], v[20:23]
	v_mfma_f32_16x16x32_bf16 v[12:15], v[164:167], v[214:217], v[12:15]
	v_mfma_f32_16x16x32_bf16 v[60:63], v[160:163], v[192:195], v[60:63]
	v_mfma_f32_16x16x32_bf16 v[56:59], v[168:171], v[192:195], v[56:59]
	v_mfma_f32_16x16x32_bf16 v[52:55], v[160:163], v[200:203], v[52:55]
	v_mfma_f32_16x16x32_bf16 v[44:47], v[168:171], v[200:203], v[44:47]
	v_mfma_f32_16x16x32_bf16 v[36:39], v[160:163], v[210:213], v[36:39]
	v_mfma_f32_16x16x32_bf16 v[28:31], v[168:171], v[210:213], v[28:31]
	v_mfma_f32_16x16x32_bf16 v[20:23], v[160:163], v[218:221], v[20:23]
	v_mfma_f32_16x16x32_bf16 v[12:15], v[168:171], v[218:221], v[12:15]
	v_mfma_f32_16x16x32_bf16 v[48:51], v[172:175], v[188:191], v[48:51]
	v_mfma_f32_16x16x32_bf16 v[40:43], v[180:183], v[188:191], v[40:43]
	v_mfma_f32_16x16x32_bf16 v[32:35], v[172:175], v[196:199], v[32:35]
	v_mfma_f32_16x16x32_bf16 v[24:27], v[180:183], v[196:199], v[24:27]
	v_mfma_f32_16x16x32_bf16 v[16:19], v[172:175], v[206:209], v[16:19]
	v_mfma_f32_16x16x32_bf16 v[8:11], v[180:183], v[206:209], v[8:11]
	v_mfma_f32_16x16x32_bf16 v[4:7], v[172:175], v[214:217], v[4:7]
	v_mfma_f32_16x16x32_bf16 v[0:3], v[180:183], v[214:217], v[0:3]
	v_mfma_f32_16x16x32_bf16 v[48:51], v[176:179], v[192:195], v[48:51]
	v_mfma_f32_16x16x32_bf16 v[40:43], v[184:187], v[192:195], v[40:43]
	v_mfma_f32_16x16x32_bf16 v[32:35], v[176:179], v[200:203], v[32:35]
	v_mfma_f32_16x16x32_bf16 v[24:27], v[184:187], v[200:203], v[24:27]
	v_mfma_f32_16x16x32_bf16 v[16:19], v[176:179], v[210:213], v[16:19]
	v_mfma_f32_16x16x32_bf16 v[8:11], v[184:187], v[210:213], v[8:11]
	v_mfma_f32_16x16x32_bf16 v[4:7], v[176:179], v[218:221], v[4:7]
	v_mfma_f32_16x16x32_bf16 v[0:3], v[184:187], v[218:221], v[0:3]
	s_setprio 0
	s_barrier
	s_add_i32 s39, 0, 0x18000
	v_add_u32_e32 v155, s39, v150
	s_add_i32 s68, 0, 0x1c000
	ds_read_b128 v[156:159], v155
	ds_read_b128 v[160:163], v155 offset:1024
	ds_read_b128 v[164:167], v155 offset:2048
	ds_read_b128 v[168:171], v155 offset:3072
	v_add_u32_e32 v155, s68, v150
	ds_read_b128 v[172:175], v155
	ds_read_b128 v[176:179], v155 offset:1024
	ds_read_b128 v[180:183], v155 offset:2048
	ds_read_b128 v[184:187], v155 offset:3072
	s_add_u32 s36, s36, 0x80000
	s_addc_u32 s37, s37, 0
	s_mov_b32 m0, s50
	v_lshl_add_u64 v[228:229], s[36:37], 0, v[134:135]
	ds_read_b128 v[188:191], v154 offset:32768
	ds_read_b128 v[192:195], v154 offset:33792
	ds_read_b128 v[196:199], v154 offset:34816
	ds_read_b128 v[200:203], v154 offset:35840
	ds_read_b128 v[206:209], v154 offset:36864
	ds_read_b128 v[210:213], v154 offset:37888
	ds_read_b128 v[214:217], v154 offset:38912
	ds_read_b128 v[218:221], v154 offset:39936
	global_load_lds_dwordx4 v[228:229], off
	v_lshl_add_u64 v[228:229], s[36:37], 0, v[130:131]
	s_mov_b32 m0, s51
	s_nop 0
	global_load_lds_dwordx4 v[228:229], off
	s_waitcnt vmcnt(8)
	s_waitcnt lgkmcnt(0)
	s_barrier
	s_setprio 1
	v_mfma_f32_16x16x32_bf16 v[124:127], v[156:159], v[188:191], v[124:127]
	v_mfma_f32_16x16x32_bf16 v[120:123], v[164:167], v[188:191], v[120:123]
	v_mfma_f32_16x16x32_bf16 v[116:119], v[156:159], v[196:199], v[116:119]
	v_mfma_f32_16x16x32_bf16 v[108:111], v[164:167], v[196:199], v[108:111]
	v_mfma_f32_16x16x32_bf16 v[100:103], v[156:159], v[206:209], v[100:103]
	v_mfma_f32_16x16x32_bf16 v[92:95], v[164:167], v[206:209], v[92:95]
	v_mfma_f32_16x16x32_bf16 v[84:87], v[156:159], v[214:217], v[84:87]
	v_mfma_f32_16x16x32_bf16 v[76:79], v[164:167], v[214:217], v[76:79]
	v_mfma_f32_16x16x32_bf16 v[124:127], v[160:163], v[192:195], v[124:127]
	v_mfma_f32_16x16x32_bf16 v[120:123], v[168:171], v[192:195], v[120:123]
	v_mfma_f32_16x16x32_bf16 v[116:119], v[160:163], v[200:203], v[116:119]
	v_mfma_f32_16x16x32_bf16 v[108:111], v[168:171], v[200:203], v[108:111]
	v_mfma_f32_16x16x32_bf16 v[100:103], v[160:163], v[210:213], v[100:103]
	v_mfma_f32_16x16x32_bf16 v[92:95], v[168:171], v[210:213], v[92:95]
	v_mfma_f32_16x16x32_bf16 v[84:87], v[160:163], v[218:221], v[84:87]
	v_mfma_f32_16x16x32_bf16 v[76:79], v[168:171], v[218:221], v[76:79]
	v_mfma_f32_16x16x32_bf16 v[112:115], v[172:175], v[188:191], v[112:115]
	v_mfma_f32_16x16x32_bf16 v[104:107], v[180:183], v[188:191], v[104:107]
	v_mfma_f32_16x16x32_bf16 v[96:99], v[172:175], v[196:199], v[96:99]
	v_mfma_f32_16x16x32_bf16 v[88:91], v[180:183], v[196:199], v[88:91]
	v_mfma_f32_16x16x32_bf16 v[80:83], v[172:175], v[206:209], v[80:83]
	v_mfma_f32_16x16x32_bf16 v[72:75], v[180:183], v[206:209], v[72:75]
	v_mfma_f32_16x16x32_bf16 v[68:71], v[172:175], v[214:217], v[68:71]
	v_mfma_f32_16x16x32_bf16 v[64:67], v[180:183], v[214:217], v[64:67]
	v_mfma_f32_16x16x32_bf16 v[112:115], v[176:179], v[192:195], v[112:115]
	v_mfma_f32_16x16x32_bf16 v[104:107], v[184:187], v[192:195], v[104:107]
	v_mfma_f32_16x16x32_bf16 v[96:99], v[176:179], v[200:203], v[96:99]
	v_mfma_f32_16x16x32_bf16 v[88:91], v[184:187], v[200:203], v[88:91]
	v_mfma_f32_16x16x32_bf16 v[80:83], v[176:179], v[210:213], v[80:83]
	v_mfma_f32_16x16x32_bf16 v[72:75], v[184:187], v[210:213], v[72:75]
	v_mfma_f32_16x16x32_bf16 v[68:71], v[176:179], v[218:221], v[68:71]
	v_mfma_f32_16x16x32_bf16 v[64:67], v[184:187], v[218:221], v[64:67]
	s_setprio 0
	s_barrier
; #define PG8_STAGE(bufoff, gbase, voff) do { _Pragma("unroll") for (int _i = 0; _i < 2; ++_i) \
;         __builtin_amdgcn_global_load_lds((const unsigned*)((const char*)(gbase) + (voff)[_i]), (PG8_LAS unsigned*)(lds + (bufoff) + ldsw + _i * 8192), 16, 0, 0); } while (0)
; #define PG8_LDA(dst, b, h) do { _Pragma("unroll") for (int m = 0; m < 4; ++m) _Pragma("unroll") for (int k = 0; k < 2; ++k) dst[m][k] = *(const PG8_LAS bf16x8*)(lds + PG8_SA(b, h) + aoff + m * 2048 + k * 1024); } while (0)
; #define PG8_LDB(dst, b, h) do { _Pragma("unroll") for (int n = 0; n < 2; ++n) _Pragma("unroll") for (int k = 0; k < 2; ++k) dst[n][k] = *(const PG8_LAS bf16x8*)(lds + PG8_SB(b, h) + boff + n * 2048 + k * 1024); } while (0)
; #define PG8_MMA(ai, bj, At, Bt) do { __builtin_amdgcn_s_setprio(1); _Pragma("unroll") for (int m = 0; m < 4; ++m) _Pragma("unroll") for (int n = 0; n < 2; ++n) _Pragma("unroll") for (int k = 0; k < 2; ++k) \
;         acc[ai][bj][m][n] = __builtin_amdgcn_mfma_f32_16x16x32_bf16(Bt[n][k], At[m][k], acc[ai][bj][m][n], 0, 0, 0); __builtin_amdgcn_s_setprio(0); } while (0)
; #define PG8_BAR __builtin_amdgcn_s_barrier()
; template <class Epi, class Sched, bool ALIGN_EPI = false, bool SP2 = false>
; __device__ __forceinline__ void gemm_phase(PG8_LAS unsigned char* lds, const Gemm g, const Sched& S, const Epi& E, const int wv0) {
;     ...
;             PG8_LDB(B0, 0, 0); PG8_LDB(B1, 0, 1); PG8_SCHED; PG8_LDA(At, 0, 0); PG8_STAGE(PG8_SA(1, 1), a1 + hstepA, voffA);
;             PG8_WAIT_V(8); PG8_WAIT_L(0); PG8_BAR; PG8_MMA(0, 0, At, B0); PG8_MMA(0, 1, At, B1); PG8_BAR; PG8_SCHED;
;             PG8_LDA(At, 0, 1); PG8_STAGE(PG8_SB(0, 0), b2, voffB); PG8_STAGE(PG8_SB(0, 1), b2 + hstepB, voffB); PG8_STAGE(PG8_SA(0, 0), a2, voffA);
;             PG8_WAIT_V(8); PG8_WAIT_L(0); PG8_BAR; PG8_MMA(1, 0, At, B0); PG8_MMA(1, 1, At, B1); PG8_BAR; PG8_SCHED;
;             PG8_LDB(B0, 1, 0); PG8_LDB(B1, 1, 1); PG8_SCHED; PG8_LDA(At, 1, 0); PG8_STAGE(PG8_SA(0, 1), a2 + hstepA, voffA);
;             PG8_WAIT_V(8); PG8_WAIT_L(0); PG8_BAR; PG8_MMA(0, 0, At, B0); PG8_MMA(0, 1, At, B1); PG8_BAR; PG8_SCHED;
;             PG8_LDA(At, 1, 1); PG8_STAGE(PG8_SB(1, 0), b3, voffB); PG8_STAGE(PG8_SB(1, 1), b3 + hstepB, voffB); PG8_STAGE(PG8_SA(1, 0), a3, voffA);
;             PG8_WAIT_V(8); PG8_WAIT_L(0); PG8_BAR; PG8_MMA(1, 0, At, B0); PG8_MMA(1, 1, At, B1); PG8_BAR; PG8_SCHED;
	s_add_i32 s36, s39, s47
	v_lshl_add_u64 v[146:147], v[146:147], 0, s[14:15]
	s_mov_b32 m0, s36
	ds_read_b128 v[188:191], v154 offset:49152
	ds_read_b128 v[192:195], v154 offset:50176
	ds_read_b128 v[196:199], v154 offset:51200
	ds_read_b128 v[200:203], v154 offset:52224
	ds_read_b128 v[206:209], v154 offset:53248
	ds_read_b128 v[210:213], v154 offset:54272
	ds_read_b128 v[214:217], v154 offset:55296
	ds_read_b128 v[218:221], v154 offset:56320
	global_load_lds_dwordx4 v[146:147], off
	s_add_i32 m0, s36, 0x2000
	s_add_u32 s34, s34, 0x80080
	v_lshl_add_u64 v[146:147], v[222:223], 0, s[14:15]
	s_addc_u32 s35, s35, 0
	s_add_i32 s36, s68, s47
	global_load_lds_dwordx4 v[146:147], off
	v_lshl_add_u64 v[146:147], s[34:35], 0, v[132:133]
	s_mov_b32 m0, s36
	s_nop 0
	global_load_lds_dwordx4 v[146:147], off
	v_lshl_add_u64 v[146:147], s[34:35], 0, v[128:129]
	s_add_i32 m0, s36, 0x2000
	s_nop 0
	global_load_lds_dwordx4 v[146:147], off
	v_lshl_add_u64 v[146:147], v[224:225], 0, s[14:15]
	s_mov_b32 m0, s58
	s_nop 0
	global_load_lds_dwordx4 v[146:147], off
	v_lshl_add_u64 v[146:147], v[226:227], 0, s[14:15]
	s_mov_b32 m0, s59
	s_nop 0
	global_load_lds_dwordx4 v[146:147], off
	s_waitcnt vmcnt(8)
	s_waitcnt lgkmcnt(0)
	s_barrier
	s_setprio 1
	v_mfma_f32_16x16x32_bf16 v[60:63], v[156:159], v[188:191], v[60:63]
	v_mfma_f32_16x16x32_bf16 v[56:59], v[164:167], v[188:191], v[56:59]
	v_mfma_f32_16x16x32_bf16 v[52:55], v[156:159], v[196:199], v[52:55]
	v_mfma_f32_16x16x32_bf16 v[44:47], v[164:167], v[196:199], v[44:47]
	v_mfma_f32_16x16x32_bf16 v[36:39], v[156:159], v[206:209], v[36:39]
	v_mfma_f32_16x16x32_bf16 v[28:31], v[164:167], v[206:209], v[28:31]
	v_mfma_f32_16x16x32_bf16 v[20:23], v[156:159], v[214:217], v[20:23]
	v_mfma_f32_16x16x32_bf16 v[12:15], v[164:167], v[214:217], v[12:15]
	v_mfma_f32_16x16x32_bf16 v[60:63], v[160:163], v[192:195], v[60:63]
	v_mfma_f32_16x16x32_bf16 v[56:59], v[168:171], v[192:195], v[56:59]
	v_mfma_f32_16x16x32_bf16 v[52:55], v[160:163], v[200:203], v[52:55]
	v_mfma_f32_16x16x32_bf16 v[44:47], v[168:171], v[200:203], v[44:47]
	v_mfma_f32_16x16x32_bf16 v[36:39], v[160:163], v[210:213], v[36:39]
	v_mfma_f32_16x16x32_bf16 v[28:31], v[168:171], v[210:213], v[28:31]
	v_mfma_f32_16x16x32_bf16 v[20:23], v[160:163], v[218:221], v[20:23]
	v_mfma_f32_16x16x32_bf16 v[12:15], v[168:171], v[218:221], v[12:15]
	v_mfma_f32_16x16x32_bf16 v[48:51], v[172:175], v[188:191], v[48:51]
	v_mfma_f32_16x16x32_bf16 v[40:43], v[180:183], v[188:191], v[40:43]
	v_mfma_f32_16x16x32_bf16 v[32:35], v[172:175], v[196:199], v[32:35]
	v_mfma_f32_16x16x32_bf16 v[24:27], v[180:183], v[196:199], v[24:27]
	v_mfma_f32_16x16x32_bf16 v[16:19], v[172:175], v[206:209], v[16:19]
	v_mfma_f32_16x16x32_bf16 v[8:11], v[180:183], v[206:209], v[8:11]
	v_mfma_f32_16x16x32_bf16 v[4:7], v[172:175], v[214:217], v[4:7]
	v_mfma_f32_16x16x32_bf16 v[0:3], v[180:183], v[214:217], v[0:3]
	v_mfma_f32_16x16x32_bf16 v[48:51], v[176:179], v[192:195], v[48:51]
	v_mfma_f32_16x16x32_bf16 v[40:43], v[184:187], v[192:195], v[40:43]
	v_mfma_f32_16x16x32_bf16 v[32:35], v[176:179], v[200:203], v[32:35]
	v_mfma_f32_16x16x32_bf16 v[24:27], v[184:187], v[200:203], v[24:27]
	v_mfma_f32_16x16x32_bf16 v[16:19], v[176:179], v[210:213], v[16:19]
	v_mfma_f32_16x16x32_bf16 v[8:11], v[184:187], v[210:213], v[8:11]
	v_mfma_f32_16x16x32_bf16 v[4:7], v[176:179], v[218:221], v[4:7]
	v_mfma_f32_16x16x32_bf16 v[0:3], v[184:187], v[218:221], v[0:3]
	s_setprio 0
	s_barrier
	s_add_i32 s38, s38, 2
	s_add_u32 s21, s21, 0x100
	s_addc_u32 s23, s23, 0
	s_add_u32 s30, s30, 0x100
	s_addc_u32 s31, s31, 0
	s_cmp_gt_u32 s38, 29
	s_cbranch_scc0 .LBB0_82
	s_and_b64 vcc, exec, s[18:19]
	s_cbranch_vccz .LBB0_85
	s_barrier

; __device__ __forceinline__ int crow(int r, int hi) { return (r & 3) + 8 * (r >> 2) + 4 * hi; }
;     __device__ __forceinline__ unsigned char* ws() const { return (unsigned char*)(__attribute__((address_space(1))) unsigned char*)get(21); }
; __device__ __forceinline__ void memkv_naive(const Ptrs& A, LAS unsigned char* lds, int wave, int lane_, const int wv0) {
;     ...
;         const bf16* hm = (const bf16*)(ws + WS_HM) + ((size_t)l2 * 256 + 32 * mt + r32) * DM + 256 * wave + 8 * hi;
;         const bf16* wk = (const bf16*)(ws + WS_WMK) + ((size_t)l2 * DM + 32 * nt + r32) * DM + 256 * wave + 8 * hi;
;         f32x16 acc = {};
; #pragma unroll 4
;         for (int s = 0; s < 16; ++s) { const bf16x8 a = *(const bf16x8*)(hm + 16 * s), b = *(const bf16x8*)(wk + 16 * s); acc = __builtin_amdgcn_mfma_f32_32x32x16_bf16(a, b, acc, 0, 0, 0); }
; #pragma unroll
;         for (int r = 0; r < 16; ++r) red[(wave * 16 + r) * 64 + lane] = acc[r];
;         __syncthreads();
; #pragma unroll
;         for (int i = 0; i < 2; ++i) { const int e = tid + 512 * i, r = e >> 6, ln = e & 63; float s = 0.f;
; #pragma unroll
;             for (int w = 0; w < 8; ++w) s += red[(w * 16 + r) * 64 + ln];
;             ((float*)(ws + WS_MEMKV))[((size_t)l2 * 256 + 32 * mt + crow(r, ln >> 5)) * DM + 32 * nt + (ln & 31)] = s; }
.LBB0_165:
	global_load_dwordx4 v[62:65], v[30:31], off offset:-64
	global_load_dwordx4 v[66:69], v[32:33], off offset:-64
	global_load_dwordx4 v[70:73], v[30:31], off offset:-32
	global_load_dwordx4 v[74:77], v[32:33], off offset:-32
	global_load_dwordx4 v[78:81], v[30:31], off
	global_load_dwordx4 v[82:85], v[32:33], off
	global_load_dwordx4 v[86:89], v[30:31], off offset:32
	global_load_dwordx4 v[90:93], v[32:33], off offset:32
	global_load_dwordx4 v[94:97], v[30:31], off offset:64
	global_load_dwordx4 v[98:101], v[32:33], off offset:64
	global_load_dwordx4 v[102:105], v[30:31], off offset:96
	global_load_dwordx4 v[106:109], v[32:33], off offset:96
	global_load_dwordx4 v[110:113], v[30:31], off offset:128
	global_load_dwordx4 v[114:117], v[32:33], off offset:128
	global_load_dwordx4 v[118:121], v[30:31], off offset:160
	global_load_dwordx4 v[122:125], v[32:33], off offset:160
	global_load_dwordx4 v[126:129], v[30:31], off offset:192
	global_load_dwordx4 v[130:133], v[32:33], off offset:192
	global_load_dwordx4 v[134:137], v[30:31], off offset:224
	global_load_dwordx4 v[138:141], v[32:33], off offset:224
	global_load_dwordx4 v[142:145], v[30:31], off offset:256
	global_load_dwordx4 v[146:149], v[32:33], off offset:256
	global_load_dwordx4 v[150:153], v[30:31], off offset:288
	global_load_dwordx4 v[154:157], v[32:33], off offset:288
	global_load_dwordx4 v[158:161], v[30:31], off offset:320
	global_load_dwordx4 v[162:165], v[32:33], off offset:320
	global_load_dwordx4 v[166:169], v[30:31], off offset:352
	global_load_dwordx4 v[170:173], v[32:33], off offset:352
	global_load_dwordx4 v[174:177], v[30:31], off offset:384
	global_load_dwordx4 v[178:181], v[32:33], off offset:384
	global_load_dwordx4 v[182:185], v[30:31], off offset:416
	global_load_dwordx4 v[186:189], v[32:33], off offset:416
	s_waitcnt vmcnt(30)
	v_mfma_f32_32x32x16_bf16 v[0:15], v[62:65], v[66:69], v[0:15]
	s_waitcnt vmcnt(28)
	v_mfma_f32_32x32x16_bf16 v[0:15], v[70:73], v[74:77], v[0:15]
	s_waitcnt vmcnt(26)
	v_mfma_f32_32x32x16_bf16 v[0:15], v[78:81], v[82:85], v[0:15]
	s_waitcnt vmcnt(24)
	v_mfma_f32_32x32x16_bf16 v[0:15], v[86:89], v[90:93], v[0:15]
	s_waitcnt vmcnt(22)
	v_mfma_f32_32x32x16_bf16 v[0:15], v[94:97], v[98:101], v[0:15]
	s_waitcnt vmcnt(20)
	v_mfma_f32_32x32x16_bf16 v[0:15], v[102:105], v[106:109], v[0:15]
	s_waitcnt vmcnt(18)
	v_mfma_f32_32x32x16_bf16 v[0:15], v[110:113], v[114:117], v[0:15]
	s_waitcnt vmcnt(16)
	v_mfma_f32_32x32x16_bf16 v[0:15], v[118:121], v[122:125], v[0:15]
	s_waitcnt vmcnt(14)
	v_mfma_f32_32x32x16_bf16 v[0:15], v[126:129], v[130:133], v[0:15]
	s_waitcnt vmcnt(12)
	v_mfma_f32_32x32x16_bf16 v[0:15], v[134:137], v[138:141], v[0:15]
	s_waitcnt vmcnt(10)
	v_mfma_f32_32x32x16_bf16 v[0:15], v[142:145], v[146:149], v[0:15]
	s_waitcnt vmcnt(8)
	v_mfma_f32_32x32x16_bf16 v[0:15], v[150:153], v[154:157], v[0:15]
	s_waitcnt vmcnt(6)
	v_mfma_f32_32x32x16_bf16 v[0:15], v[158:161], v[162:165], v[0:15]
	s_waitcnt vmcnt(4)
	v_mfma_f32_32x32x16_bf16 v[0:15], v[166:169], v[170:173], v[0:15]
	s_waitcnt vmcnt(2)
	v_mfma_f32_32x32x16_bf16 v[0:15], v[174:177], v[178:181], v[0:15]
	s_waitcnt vmcnt(0)
	v_mfma_f32_32x32x16_bf16 v[0:15], v[182:185], v[186:189], v[0:15]
	s_nop 1
	v_add_u32_e32 v18, s7, v34
	s_nop 9
	ds_write2st64_b32 v18, v0, v1 offset1:1
	ds_write2st64_b32 v18, v2, v3 offset0:2 offset1:3
	ds_write2st64_b32 v18, v4, v5 offset0:4 offset1:5
	ds_write2st64_b32 v18, v6, v7 offset0:6 offset1:7
	ds_write2st64_b32 v18, v8, v9 offset0:8 offset1:9
	ds_write2st64_b32 v18, v10, v11 offset0:10 offset1:11
	ds_write2st64_b32 v18, v12, v13 offset0:12 offset1:13
	ds_write2st64_b32 v18, v14, v15 offset0:14 offset1:15
	s_waitcnt lgkmcnt(0)
	s_barrier
	ds_read2st64_b32 v[0:1], v35 offset1:16
	ds_read2st64_b32 v[4:5], v35 offset0:32 offset1:48
	ds_read2st64_b32 v[6:7], v35 offset0:64 offset1:80
	s_or_b32 s2, s2, s0
	s_lshl_b32 s0, s12, 7
	s_waitcnt lgkmcnt(2)
	v_add_f32_e32 v0, 0, v0
	v_add_f32_e32 v8, v0, v1
	ds_read2st64_b32 v[0:1], v35 offset0:96 offset1:112
	s_waitcnt lgkmcnt(2)
	v_add_f32_e32 v4, v8, v4
	v_add_f32_e32 v4, v4, v5
	s_waitcnt lgkmcnt(1)
	v_add_f32_e32 v4, v4, v6
	v_add_f32_e32 v4, v4, v7
	s_waitcnt lgkmcnt(0)
	v_add_f32_e32 v0, v4, v0
	s_and_b32 s0, s0, 0x1f80
	v_add_f32_e32 v6, v0, v1
	v_lshl_add_u64 v[0:1], s[2:3], 0, v[22:23]
	v_lshl_add_u64 v[2:3], v[20:21], 0, s[0:1]
	ds_read2st64_b32 v[4:5], v36 offset1:16
	v_lshlrev_b64 v[0:1], 13, v[0:1]
	v_lshl_add_u64 v[0:1], v[2:3], 0, v[0:1]
	global_store_dword v[0:1], v6, off
	ds_read2st64_b32 v[0:1], v36 offset0:32 offset1:48
	ds_read2st64_b32 v[6:7], v36 offset0:64 offset1:80
	s_waitcnt lgkmcnt(2)
	v_add_f32_e32 v4, 0, v4
	v_add_f32_e32 v8, v4, v5
	ds_read2st64_b32 v[4:5], v36 offset0:96 offset1:112
	s_waitcnt lgkmcnt(2)
	v_add_f32_e32 v0, v8, v0
	v_add_f32_e32 v0, v0, v1
	s_waitcnt lgkmcnt(1)
	v_add_f32_e32 v0, v0, v6
	v_add_f32_e32 v0, v0, v7
	s_waitcnt lgkmcnt(0)
	v_add_f32_e32 v0, v0, v4
	v_add_f32_e32 v4, v0, v5
	v_lshl_add_u64 v[0:1], s[2:3], 0, v[24:25]
	v_lshlrev_b64 v[0:1], 13, v[0:1]
	s_add_i32 s12, s12, s76
	s_add_i32 s10, s10, s11
	v_lshl_add_u64 v[0:1], v[2:3], 0, v[0:1]
	s_cmpk_gt_i32 s12, 0x3ff
	global_store_dword v[0:1], v4, off
	s_barrier
	s_cbranch_scc0 .LBB0_164

; __device__ __forceinline__ int crow(int r, int hi) { return (r & 3) + 8 * (r >> 2) + 4 * hi; }
; __device__ __forceinline__ void qkt(f32x16& p0, f32x16& p1, const char* Ks, const bf16x8* qr, int r32, int hi) {
;     p0 = f32x16{}; p1 = f32x16{};
; #pragma unroll
;     for (int d0 = 0; d0 < 8; ++d0) { const int cb = (d0 * 16 + hi * 8) * 2;
;         const bf16x8 b0 = *reinterpret_cast<const bf16x8*>(Ks + KSWZ(r32, cb));
;         const bf16x8 b1 = *reinterpret_cast<const bf16x8*>(Ks + KSWZ(32 + r32, cb));
;         p0 = __builtin_amdgcn_mfma_f32_32x32x16_bf16(b0, qr[d0], p0, 0, 0, 0);
;         p1 = __builtin_amdgcn_mfma_f32_32x32x16_bf16(b1, qr[d0], p1, 0, 0, 0); }
; __device__ __forceinline__ void sb_half(f32x16& p, float& carry, bool masked, int krow0, int tq, int hi) {
;     float G[4];
; #pragma unroll
;     for (int g = 0; g < 4; ++g) {
;         float q[4];
; #pragma unroll
;         for (int i = 0; i < 4; ++i) { const int r = 4 * g + i; const float e = __builtin_amdgcn_exp2f(p[r]); float qq = __builtin_amdgcn_rcpf(1.0f + e); float b = e * qq;
;             if (masked) { const bool keep = (krow0 + crow(r, hi)) < tq; qq = keep ? qq : 1.0f; b = keep ? b : 0.0f; }
;             q[i] = qq; p[r] = b; }
;         const float s2 = q[3] * q[2], s1 = s2 * q[1]; G[g] = s1 * q[0];
;         p[4 * g + 2] *= q[3]; p[4 * g + 1] *= s2; p[4 * g] *= s1;
;     }
;     float run = carry;
; #pragma unroll
;     for (int g = 3; g >= 0; --g) { const unsigned gu = __builtin_bit_cast(unsigned, G[g]); auto sw = __builtin_amdgcn_permlane32_swap(gu, gu, false, false);
;         const float partner = __builtin_bit_cast(float, hi ? sw[0] : sw[1]);
;         const float base = hi ? run : run * partner;
;         p[4 * g] *= base; p[4 * g + 1] *= base; p[4 * g + 2] *= base; p[4 * g + 3] *= base; run *= G[g] * partner; }
;     carry = run;
.LBB0_287:
	s_add_i32 s72, s41, -1
	ds_read_b128 v[80:83], v201 offset:49152
	ds_read_b128 v[96:99], v201 offset:57344
	ds_read_b128 v[144:147], v202 offset:49152
	ds_read_b128 v[148:151], v202 offset:57344
	v_exp_f32_e32 v64, v64
	s_waitcnt lgkmcnt(3)
	v_mfma_f32_32x32x16_bf16 v[80:95], v[80:83], v[140:143], 0
	v_exp_f32_e32 v65, v65
	v_exp_f32_e32 v66, v66
	v_add_f32_e32 v214, 1.0, v64
	v_rcp_f32_e32 v254, v214
	v_add_u32_e32 v214, s95, v213
	s_cmp_lt_u32 s72, 5
	v_exp_f32_e32 v67, v67
	s_waitcnt lgkmcnt(2)
	v_mfma_f32_32x32x16_bf16 v[96:111], v[96:99], v[140:143], 0
	v_mul_f32_e32 v64, v64, v254
	v_exp_f32_e32 v68, v68
	v_exp_f32_e32 v69, v69
	v_exp_f32_e32 v70, v70
	v_exp_f32_e32 v71, v71
	v_exp_f32_e32 v72, v72
	v_exp_f32_e32 v73, v73
	s_waitcnt lgkmcnt(1)
	v_mfma_f32_32x32x16_bf16 v[80:95], v[144:147], v[136:139], v[80:95]
	v_add_f32_e32 v146, 1.0, v65
	v_add_u32_e32 v144, 0xc0, v214
	v_rcp_f32_e32 v146, v146
	v_cmp_lt_i32_e32 vcc, v144, v164
	v_exp_f32_e32 v74, v74
	v_exp_f32_e32 v75, v75
	v_cndmask_b32_e32 v144, 1.0, v254, vcc
	v_cndmask_b32_e32 v145, 0, v64, vcc
	s_cselect_b64 vcc, -1, 0
	s_waitcnt lgkmcnt(0)
	v_mfma_f32_32x32x16_bf16 v[96:111], v[148:151], v[136:139], v[96:111]
	v_cndmask_b32_e32 v64, v64, v145, vcc
	v_add_u32_e32 v145, 0xc1, v214
	v_add_f32_e32 v148, 1.0, v66
	v_mul_f32_e32 v65, v65, v146
	v_cmp_lt_i32_e64 s[4:5], v145, v164
	v_rcp_f32_e32 v148, v148
	v_cndmask_b32_e32 v144, v254, v144, vcc
	v_cndmask_b32_e64 v145, 1.0, v146, s[4:5]
	v_cndmask_b32_e64 v147, 0, v65, s[4:5]
	v_cndmask_b32_e32 v65, v65, v147, vcc
	v_cndmask_b32_e32 v145, v146, v145, vcc
	v_add_u32_e32 v146, 0xc2, v214
	v_add_f32_e32 v147, 1.0, v67
	v_cmp_lt_i32_e64 s[4:5], v146, v164
	v_rcp_f32_e32 v147, v147
	v_mul_f32_e32 v66, v66, v148
	v_cndmask_b32_e64 v146, 1.0, v148, s[4:5]
	v_cndmask_b32_e32 v146, v148, v146, vcc
	v_add_u32_e32 v148, 0xc3, v214
	v_cndmask_b32_e64 v149, 0, v66, s[4:5]
	v_cmp_lt_i32_e64 s[4:5], v148, v164
	v_mul_f32_e32 v67, v67, v147
	v_cndmask_b32_e32 v66, v66, v149, vcc
	v_cndmask_b32_e64 v148, 1.0, v147, s[4:5]
	v_cndmask_b32_e32 v147, v147, v148, vcc
	v_mul_f32_e32 v146, v147, v146
	v_mul_f32_e32 v145, v145, v146
	v_mul_f32_e32 v65, v65, v146
	v_add_f32_e32 v146, 1.0, v68
	v_rcp_f32_e32 v146, v146
	v_mul_f32_e32 v144, v144, v145
	v_mul_f32_e32 v64, v64, v145
	v_add_u32_e32 v145, 0xc8, v214
	v_add_f32_e32 v148, 1.0, v69
	v_cndmask_b32_e64 v149, 0, v67, s[4:5]
	v_mul_f32_e32 v68, v68, v146
	v_cmp_lt_i32_e64 s[4:5], v145, v164
	v_rcp_f32_e32 v148, v148
	v_mul_f32_e32 v66, v147, v66
	v_cndmask_b32_e64 v145, 1.0, v146, s[4:5]
	v_cndmask_b32_e64 v147, 0, v68, s[4:5]
	v_cndmask_b32_e32 v68, v68, v147, vcc
	v_cndmask_b32_e32 v145, v146, v145, vcc
	v_add_u32_e32 v146, 0xc9, v214
	v_add_f32_e32 v147, 1.0, v70
	v_cmp_lt_i32_e64 s[4:5], v146, v164
	v_rcp_f32_e32 v147, v147
	v_mul_f32_e32 v69, v69, v148
	v_cndmask_b32_e64 v146, 1.0, v148, s[4:5]
	v_cndmask_b32_e32 v146, v148, v146, vcc
	v_add_u32_e32 v148, 0xca, v214
	v_add_f32_e32 v150, 1.0, v71
	v_cndmask_b32_e32 v67, v67, v149, vcc
	v_cndmask_b32_e64 v149, 0, v69, s[4:5]
	v_cmp_lt_i32_e64 s[4:5], v148, v164
	v_rcp_f32_e32 v150, v150
	v_mul_f32_e32 v70, v70, v147
	v_cndmask_b32_e64 v148, 1.0, v147, s[4:5]
	v_cndmask_b32_e32 v147, v147, v148, vcc
	v_add_u32_e32 v148, 0xcb, v214
	v_cndmask_b32_e32 v69, v69, v149, vcc
	v_cndmask_b32_e64 v149, 0, v70, s[4:5]
	v_cmp_lt_i32_e64 s[4:5], v148, v164
	v_cndmask_b32_e32 v70, v70, v149, vcc
	v_mul_f32_e32 v71, v71, v150
	v_cndmask_b32_e64 v148, 1.0, v150, s[4:5]
	v_cndmask_b32_e32 v148, v150, v148, vcc
	v_mul_f32_e32 v147, v148, v147
	v_mul_f32_e32 v146, v146, v147
	v_mul_f32_e32 v69, v69, v147
	v_add_f32_e32 v147, 1.0, v72
	v_rcp_f32_e32 v147, v147
	v_mul_f32_e32 v70, v148, v70
	v_add_f32_e32 v148, 1.0, v73
	v_mul_f32_e32 v145, v145, v146
	v_mul_f32_e32 v68, v68, v146
	v_add_u32_e32 v146, 0xd0, v214
	v_rcp_f32_e32 v148, v148
	v_cndmask_b32_e64 v149, 0, v71, s[4:5]
	v_mul_f32_e32 v72, v72, v147
	v_cmp_lt_i32_e64 s[4:5], v146, v164
	v_cndmask_b32_e32 v71, v71, v149, vcc
	v_mul_f32_e32 v73, v73, v148
	v_cndmask_b32_e64 v146, 1.0, v147, s[4:5]
	v_cndmask_b32_e64 v149, 0, v72, s[4:5]
	v_cndmask_b32_e32 v72, v72, v149, vcc
	v_cndmask_b32_e32 v146, v147, v146, vcc
	v_add_u32_e32 v147, 0xd1, v214
	v_add_f32_e32 v149, 1.0, v74
	v_cmp_lt_i32_e64 s[4:5], v147, v164
	v_rcp_f32_e32 v149, v149
	ds_read_b128 v[152:155], v208 offset:49152
	ds_read_b128 v[156:159], v208 offset:57344
	ds_read_b128 v[216:219], v209 offset:49152
	ds_read_b128 v[220:223], v209 offset:57344
	ds_read_b128 v[224:227], v210 offset:49152
	ds_read_b128 v[228:231], v210 offset:57344
	ds_read_b128 v[232:235], v211 offset:49152
	ds_read_b128 v[236:239], v211 offset:57344
	v_cndmask_b32_e64 v147, 1.0, v148, s[4:5]
	v_cndmask_b32_e64 v150, 0, v73, s[4:5]
	v_cndmask_b32_e32 v73, v73, v150, vcc
	v_cndmask_b32_e32 v147, v148, v147, vcc
	v_add_u32_e32 v148, 0xd2, v214
	v_add_f32_e32 v150, 1.0, v75
	v_cmp_lt_i32_e64 s[4:5], v148, v164
	v_rcp_f32_e32 v150, v150
	s_waitcnt lgkmcnt(7)
	v_mfma_f32_32x32x16_bf16 v[80:95], v[152:155], v[132:135], v[80:95]
	v_cndmask_b32_e64 v148, 1.0, v149, s[4:5]
	v_mul_f32_e32 v74, v74, v149
	v_cndmask_b32_e32 v148, v149, v148, vcc
	v_add_u32_e32 v149, 0xd3, v214
	v_cndmask_b32_e64 v151, 0, v74, s[4:5]
	v_cmp_lt_i32_e64 s[4:5], v149, v164
	v_exp_f32_e32 v76, v76
	s_waitcnt lgkmcnt(6)
	v_mfma_f32_32x32x16_bf16 v[96:111], v[156:159], v[132:135], v[96:111]
	v_cndmask_b32_e64 v149, 1.0, v150, s[4:5]
	v_cndmask_b32_e32 v149, v150, v149, vcc
	v_mul_f32_e32 v148, v149, v148
	v_exp_f32_e32 v77, v77
	v_mul_f32_e32 v147, v147, v148
	v_mul_f32_e32 v73, v73, v148
	v_add_f32_e32 v148, 1.0, v76
	v_rcp_f32_e32 v148, v148
	v_cndmask_b32_e32 v74, v74, v151, vcc
	s_waitcnt lgkmcnt(5)
; __device__ __forceinline__ int crow(int r, int hi) { return (r & 3) + 8 * (r >> 2) + 4 * hi; }
; #define SBAR() __builtin_amdgcn_sched_barrier(0)
; __device__ __forceinline__ void sb_half(f32x16& p, float& carry, bool masked, int krow0, int tq, int hi) {
;     float G[4];
; #pragma unroll
;     for (int g = 0; g < 4; ++g) {
;         float q[4];
; #pragma unroll
;         for (int i = 0; i < 4; ++i) { const int r = 4 * g + i; const float e = __builtin_amdgcn_exp2f(p[r]); float qq = __builtin_amdgcn_rcpf(1.0f + e); float b = e * qq;
;             if (masked) { const bool keep = (krow0 + crow(r, hi)) < tq; qq = keep ? qq : 1.0f; b = keep ? b : 0.0f; }
;             q[i] = qq; p[r] = b; }
;         const float s2 = q[3] * q[2], s1 = s2 * q[1]; G[g] = s1 * q[0];
;         p[4 * g + 2] *= q[3]; p[4 * g + 1] *= s2; p[4 * g] *= s1;
;     }
;     float run = carry;
; #pragma unroll
;     for (int g = 3; g >= 0; --g) { const unsigned gu = __builtin_bit_cast(unsigned, G[g]); auto sw = __builtin_amdgcn_permlane32_swap(gu, gu, false, false);
;         const float partner = __builtin_bit_cast(float, hi ? sw[0] : sw[1]);
;         const float base = hi ? run : run * partner;
;         p[4 * g] *= base; p[4 * g + 1] *= base; p[4 * g + 2] *= base; p[4 * g + 3] *= base; run *= G[g] * partner; }
;     carry = run;
; }
; __device__ __forceinline__ void pack_p(const f32x16& p0, const f32x16& p1, bf16x8& pa0, bf16x8& pa1, bf16x8& pa2, bf16x8& pa3) {
;     ...
;     PK4(p0, 0, pa0); PK4(p0, 8, pa1); PK4(p1, 0, pa2); PK4(p1, 8, pa3);
;     ...
; }
; __device__ __forceinline__ void sb_unit(const bf16* __restrict__ Qb, const bf16* __restrict__ Kh, const bf16* __restrict__ Vh, bf16* __restrict__ Ob, int q0, char* lds, const int wv0) {
;     ...
;         sb_half(pA0, carry, (j - 1) < 4, K0(j - 1), tq, hi); pack_p(pA0, pA1, pa0, pa1, pa2, pa3); SBAR();
;         { const int z = __all(carry == 0.0f); if (lane == 0) votes[wid] = (unsigned)z; }
	v_mfma_f32_32x32x16_bf16 v[80:95], v[216:219], v[128:131], v[80:95]
	v_mul_f32_e32 v74, v149, v74
	v_add_f32_e32 v149, 1.0, v77
	v_exp_f32_e32 v78, v78
	v_mul_f32_e32 v75, v75, v150
	v_mul_f32_e32 v146, v146, v147
	v_mul_f32_e32 v72, v72, v147
	v_add_u32_e32 v147, 0xd8, v214
	s_waitcnt lgkmcnt(4)
	v_mfma_f32_32x32x16_bf16 v[96:111], v[220:223], v[128:131], v[96:111]
	v_rcp_f32_e32 v149, v149
	v_cndmask_b32_e64 v151, 0, v75, s[4:5]
	v_mul_f32_e32 v76, v76, v148
	v_cmp_lt_i32_e64 s[4:5], v147, v164
	v_exp_f32_e32 v79, v79
	v_mul_f32_e32 v77, v77, v149
	v_cndmask_b32_e64 v147, 1.0, v148, s[4:5]
	v_cndmask_b32_e64 v150, 0, v76, s[4:5]
	v_cndmask_b32_e32 v76, v76, v150, vcc
	v_cndmask_b32_e32 v147, v148, v147, vcc
	v_add_u32_e32 v148, 0xd9, v214
	v_add_f32_e32 v150, 1.0, v78
	v_cmp_lt_i32_e64 s[4:5], v148, v164
	v_rcp_f32_e32 v150, v150
	v_cndmask_b32_e32 v75, v75, v151, vcc
	v_cndmask_b32_e64 v148, 1.0, v149, s[4:5]
	v_cndmask_b32_e64 v151, 0, v77, s[4:5]
	v_cndmask_b32_e32 v77, v77, v151, vcc
	v_cndmask_b32_e32 v148, v149, v148, vcc
	v_add_u32_e32 v149, 0xda, v214
	v_add_f32_e32 v151, 1.0, v79
	s_waitcnt lgkmcnt(3)
	v_mfma_f32_32x32x16_bf16 v[80:95], v[224:227], v[124:127], v[80:95]
	v_cmp_lt_i32_e64 s[4:5], v149, v164
	v_rcp_f32_e32 v151, v151
	v_mul_f32_e32 v78, v78, v150
	v_cndmask_b32_e64 v149, 1.0, v150, s[4:5]
	v_cndmask_b32_e32 v149, v150, v149, vcc
	v_add_u32_e32 v150, 0xdb, v214
	v_cndmask_b32_e64 v152, 0, v78, s[4:5]
	s_waitcnt lgkmcnt(2)
	v_mfma_f32_32x32x16_bf16 v[96:111], v[228:231], v[124:127], v[96:111]
	v_cmp_lt_i32_e64 s[4:5], v150, v164
	v_cndmask_b32_e32 v78, v78, v152, vcc
	v_mul_f32_e32 v79, v79, v151
	v_cndmask_b32_e64 v150, 1.0, v151, s[4:5]
	v_cndmask_b32_e32 v150, v151, v150, vcc
	v_mul_f32_e32 v149, v150, v149
	v_mul_f32_e32 v148, v148, v149
	s_waitcnt lgkmcnt(1)
	v_mfma_f32_32x32x16_bf16 v[80:95], v[232:235], v[120:123], v[80:95]
	v_mul_f32_e32 v147, v147, v148
	v_mul_f32_e32 v77, v77, v149
	v_mul_f32_e32 v76, v76, v148
	v_mov_b32_e32 v148, v147
	v_mov_b32_e32 v149, v147
	s_nop 1
	v_permlane32_swap_b32_e32 v148, v149
	s_waitcnt lgkmcnt(0)
	v_mfma_f32_32x32x16_bf16 v[96:111], v[236:239], v[120:123], v[96:111]
	v_cndmask_b32_e64 v148, v148, v149, s[0:1]
	v_mul_f32_e32 v149, v215, v148
	ds_read_b128 v[240:243], v203 offset:49152
	ds_read_b128 v[244:247], v203 offset:57344
	ds_read_b128 v[248:251], v212 offset:49152
	ds_read_b128 v[194:197], v212 offset:57344
	v_cndmask_b32_e64 v152, 0, v79, s[4:5]
	v_mul_f32_e32 v78, v150, v78
	v_cndmask_b32_e64 v149, v215, v149, s[0:1]
	v_cndmask_b32_e32 v79, v79, v152, vcc
	v_mul_f32_e32 v151, v77, v149
	v_mul_f32_e32 v152, v78, v149
	v_mov_b32_e32 v77, v146
	v_mov_b32_e32 v78, v146
	v_mul_f32_e32 v150, v76, v149
	v_mul_f32_e32 v76, v147, v148
	v_permlane32_swap_b32_e32 v77, v78
	s_waitcnt lgkmcnt(3)
	v_mfma_f32_32x32x16_bf16 v[80:95], v[240:243], v[116:119], v[80:95]
	v_mul_f32_e32 v76, v215, v76
	v_cndmask_b32_e64 v77, v77, v78, s[0:1]
	v_mul_f32_e32 v78, v76, v77
	v_cndmask_b32_e64 v78, v76, v78, s[0:1]
	v_mul_f32_e32 v77, v146, v77
	v_mul_f32_e32 v72, v72, v78
	v_mul_f32_e32 v73, v73, v78
	s_waitcnt lgkmcnt(2)
	v_mfma_f32_32x32x16_bf16 v[96:111], v[244:247], v[116:119], v[96:111]
	v_mul_f32_e32 v74, v74, v78
	v_mul_f32_e32 v75, v75, v78
	v_mul_f32_e32 v76, v76, v77
	v_mov_b32_e32 v77, v145
	v_mov_b32_e32 v78, v145
	s_nop 1
	v_permlane32_swap_b32_e32 v77, v78
	v_cndmask_b32_e64 v77, v77, v78, s[0:1]
	v_mul_f32_e32 v78, v76, v77
	v_cndmask_b32_e64 v78, v76, v78, s[0:1]
	v_mul_f32_e32 v77, v145, v77
	s_waitcnt lgkmcnt(1)
	v_mfma_f32_32x32x16_bf16 v[80:95], v[248:251], v[112:115], v[80:95]
	v_mul_f32_e32 v68, v68, v78
	v_mul_f32_e32 v69, v69, v78
	v_mul_f32_e32 v70, v70, v78
	v_mul_f32_e32 v71, v71, v78
	v_mul_f32_e32 v76, v76, v77
	v_mov_b32_e32 v77, v144
	v_mov_b32_e32 v78, v144
	s_waitcnt lgkmcnt(0)
	v_mfma_f32_32x32x16_bf16 v[96:111], v[194:197], v[112:115], v[96:111]
	v_permlane32_swap_b32_e32 v77, v78
	v_cndmask_b32_e64 v77, v77, v78, s[0:1]
	v_mul_f32_e32 v78, v76, v77
	v_cndmask_b32_e64 v78, v76, v78, s[0:1]
	v_mul_f32_e32 v64, v64, v78
	v_mul_f32_e32 v65, v65, v78
	v_mul_f32_e32 v66, v66, v78
	v_mul_f32_e32 v67, v67, v78
	v_mul_f32_e32 v77, v144, v77
	v_mul_f32_e32 v149, v79, v149
	v_mul_f32_e32 v194, v76, v77
	v_cvt_pk_bf16_f32 v76, v64, v65
	v_cvt_pk_bf16_f32 v77, v66, v67
	v_cvt_pk_bf16_f32 v78, v68, v69
	v_cvt_pk_bf16_f32 v79, v70, v71
	v_cvt_pk_bf16_f32 v72, v72, v73
	v_cvt_pk_bf16_f32 v73, v74, v75
	v_cvt_pk_bf16_f32 v74, v150, v151
	v_cvt_pk_bf16_f32 v75, v152, v149
	v_cvt_pk_bf16_f32 v68, v186, v187
	v_cvt_pk_bf16_f32 v69, v178, v179
	v_cvt_pk_bf16_f32 v70, v188, v189
	v_cvt_pk_bf16_f32 v71, v180, v181
	v_cvt_pk_bf16_f32 v64, v190, v191
	v_cvt_pk_bf16_f32 v65, v182, v183
	v_cvt_pk_bf16_f32 v66, v192, v193
	v_cvt_pk_bf16_f32 v67, v184, v185
	s_nop 0
	v_permlane32_swap_b32_e32 v76, v78
	v_permlane32_swap_b32_e32 v77, v79
	v_permlane32_swap_b32_e32 v72, v74
	v_permlane32_swap_b32_e32 v73, v75
	v_permlane32_swap_b32_e32 v68, v70
	v_permlane32_swap_b32_e32 v69, v71
	v_permlane32_swap_b32_e32 v64, v66
	v_permlane32_swap_b32_e32 v65, v67
	s_mov_b64 s[6:7], exec
	v_cmp_eq_f32_e32 vcc, 0, v194
	s_and_saveexec_b64 s[4:5], s[2:3]
	s_cbranch_execz .LBB0_289
	s_cmp_eq_u64 vcc, s[6:7]
	s_cselect_b64 s[6:7], -1, 0
	v_cndmask_b32_e64 v144, 0, 1, s[6:7]
	ds_write_b32 v166, v144
; #define SBAR() __builtin_amdgcn_sched_barrier(0)
; template <int D0> __device__ __forceinline__ void pv_one(f32x16& od, int vb, bf16x8 pa0, bf16x8 pa1, bf16x8 pa2, bf16x8 pa3) {
;     const s16x4 l0 = tr_read<v_rd_off(D0, 0, 0)>(vb), h0 = tr_read<v_rd_off(D0, 0, 1)>(vb), l1 = tr_read<v_rd_off(D0, 1, 0)>(vb), h1 = tr_read<v_rd_off(D0, 1, 1)>(vb);
;     const s16x4 l2 = tr_read<v_rd_off(D0, 2, 0)>(vb), h2 = tr_read<v_rd_off(D0, 2, 1)>(vb), l3 = tr_read<v_rd_off(D0, 3, 0)>(vb), h3 = tr_read<v_rd_off(D0, 3, 1)>(vb);
;     asm volatile("s_waitcnt lgkmcnt(0)" ::: "memory"); SBAR();
;     ...
;     od = __builtin_amdgcn_mfma_f32_32x32x16_bf16(pa0, PK(l0, h0), od, 0, 0, 0);
;     od = __builtin_amdgcn_mfma_f32_32x32x16_bf16(pa1, PK(l1, h1), od, 0, 0, 0);
;     od = __builtin_amdgcn_mfma_f32_32x32x16_bf16(pa2, PK(l2, h2), od, 0, 0, 0);
;     od = __builtin_amdgcn_mfma_f32_32x32x16_bf16(pa3, PK(l3, h3), od, 0, 0, 0);
;     ...
; }
; __device__ __forceinline__ void pv_d0(f32x16* o, int vb, bf16x8 pa0, bf16x8 pa1, bf16x8 pa2, bf16x8 pa3) {
;     pv_one<0>(o[0], vb, pa0, pa1, pa2, pa3); pv_one<1>(o[1], vb, pa0, pa1, pa2, pa3); pv_one<2>(o[2], vb, pa0, pa1, pa2, pa3); pv_one<3>(o[3], vb, pa0, pa1, pa2, pa3);
; }
.LBB0_289:
	s_or_b64 exec, exec, s[4:5]
	v_lshl_add_u64 v[152:153], v[172:173], 0, v[160:161]
	v_add_co_u32_e32 v144, vcc, 0x17a00000, v152
	v_lshl_add_u64 v[156:157], v[170:171], 0, v[160:161]
	s_nop 0
	v_addc_co_u32_e32 v145, vcc, 0, v153, vcc
	v_add_co_u32_e32 v148, vcc, 0x17a00000, v156
	global_load_dwordx4 v[144:147], v[144:145], off
	s_nop 0
	v_addc_co_u32_e32 v149, vcc, 0, v157, vcc
	v_add_co_u32_e32 v152, vcc, 0x15a00000, v152
	global_load_dwordx4 v[148:151], v[148:149], off
	s_nop 0
	v_addc_co_u32_e32 v153, vcc, 0, v153, vcc
	v_add_co_u32_e32 v156, vcc, 0x15a00000, v156
	global_load_dwordx4 v[152:155], v[152:153], off
	s_nop 0
	v_addc_co_u32_e32 v157, vcc, 0, v157, vcc
	global_load_dwordx4 v[156:159], v[156:157], off
	ds_read_b64_tr_b16 v[178:179], v198 offset:0
	ds_read_b64_tr_b16 v[180:181], v198 offset:0x800
	ds_read_b64_tr_b16 v[182:183], v198 offset:0x1000
	ds_read_b64_tr_b16 v[184:185], v198 offset:0x1800
	ds_read_b64_tr_b16 v[186:187], v198 offset:0x2000
	ds_read_b64_tr_b16 v[188:189], v198 offset:0x2800
	ds_read_b64_tr_b16 v[190:191], v198 offset:0x3000
	ds_read_b64_tr_b16 v[192:193], v198 offset:0x3800
	s_waitcnt lgkmcnt(0)
	s_nop 0
	v_mfma_f32_32x32x16_bf16 v[48:63], v[76:79], v[178:181], v[48:63]
	ds_read_b64_tr_b16 v[178:179], v198 offset:0x200
	ds_read_b64_tr_b16 v[180:181], v198 offset:0xa00
	v_mfma_f32_32x32x16_bf16 v[48:63], v[72:75], v[182:185], v[48:63]
	ds_read_b64_tr_b16 v[182:183], v198 offset:0x1200
	ds_read_b64_tr_b16 v[184:185], v198 offset:0x1a00
	v_mfma_f32_32x32x16_bf16 v[48:63], v[68:71], v[186:189], v[48:63]
	ds_read_b64_tr_b16 v[186:187], v198 offset:0x2200
	ds_read_b64_tr_b16 v[188:189], v198 offset:0x2a00
	ds_read_b64_tr_b16 v[216:217], v198 offset:0x3200
	ds_read_b64_tr_b16 v[218:219], v198 offset:0x3a00
	s_waitcnt lgkmcnt(0)
	v_mfma_f32_32x32x16_bf16 v[48:63], v[64:67], v[190:193], v[48:63]
	v_mfma_f32_32x32x16_bf16 v[32:47], v[76:79], v[178:181], v[32:47]
	ds_read_b64_tr_b16 v[178:179], v198 offset:0x400
	ds_read_b64_tr_b16 v[180:181], v198 offset:0xc00
	v_mfma_f32_32x32x16_bf16 v[32:47], v[72:75], v[182:185], v[32:47]
	ds_read_b64_tr_b16 v[182:183], v198 offset:0x1400
	ds_read_b64_tr_b16 v[184:185], v198 offset:0x1c00
	v_mfma_f32_32x32x16_bf16 v[32:47], v[68:71], v[186:189], v[32:47]
	ds_read_b64_tr_b16 v[186:187], v198 offset:0x2400
	ds_read_b64_tr_b16 v[188:189], v198 offset:0x2c00
	ds_read_b64_tr_b16 v[190:191], v198 offset:0x3400
	ds_read_b64_tr_b16 v[192:193], v198 offset:0x3c00
	s_waitcnt lgkmcnt(0)
	v_mfma_f32_32x32x16_bf16 v[32:47], v[64:67], v[216:219], v[32:47]
	v_mfma_f32_32x32x16_bf16 v[16:31], v[76:79], v[178:181], v[16:31]
	ds_read_b64_tr_b16 v[178:179], v198 offset:0x600
	ds_read_b64_tr_b16 v[180:181], v198 offset:0xe00
	ds_read_b64_tr_b16 v[218:219], v198 offset:0x1600
	ds_read_b64_tr_b16 v[220:221], v198 offset:0x1e00
	ds_read_b64_tr_b16 v[222:223], v198 offset:0x2600
	ds_read_b64_tr_b16 v[224:225], v198 offset:0x2e00
	ds_read_b64_tr_b16 v[226:227], v198 offset:0x3600
	v_mfma_f32_32x32x16_bf16 v[16:31], v[72:75], v[182:185], v[16:31]
	ds_read_b64_tr_b16 v[228:229], v198 offset:0x3e00
	s_waitcnt lgkmcnt(0)
	v_mfma_f32_32x32x16_bf16 v[16:31], v[68:71], v[186:189], v[16:31]
	v_mfma_f32_32x32x16_bf16 v[16:31], v[64:67], v[190:193], v[16:31]
	v_mfma_f32_32x32x16_bf16 v[0:15], v[76:79], v[178:181], v[0:15]
	s_cmp_lt_u32 s72, 4
	s_cselect_b64 vcc, -1, 0
	v_exp_f32_e32 v98, v98
	s_cmp_lg_u32 s90, -1
	s_cselect_b32 s20, s90, 0
	v_exp_f32_e32 v195, v97
	s_cselect_b32 s21, s47, 0
	v_mfma_f32_32x32x16_bf16 v[0:15], v[72:75], v[218:221], v[0:15]
	v_exp_f32_e32 v218, v99
	v_exp_f32_e32 v221, v101
	v_exp_f32_e32 v101, v102
	v_exp_f32_e32 v99, v100
	v_add_f32_e32 v73, 1.0, v98
	v_rcp_f32_e32 v188, v73
	v_add_u32_e32 v73, 0xa2, v214
	v_mfma_f32_32x32x16_bf16 v[0:15], v[68:71], v[222:225], v[0:15]
	v_add_f32_e32 v69, 1.0, v218
	v_exp_f32_e32 v223, v103
	v_rcp_f32_e32 v219, v69
	v_add_u32_e32 v69, 0xa3, v214
	v_cmp_lt_i32_e64 s[14:15], v69, v164
	v_exp_f32_e32 v103, v104
	v_cmp_lt_i32_e64 s[6:7], v73, v164
	v_mfma_f32_32x32x16_bf16 v[0:15], v[64:67], v[226:229], v[0:15]
	v_add_f32_e32 v66, 1.0, v101
	v_add_f32_e32 v67, 1.0, v223
	v_cndmask_b32_e64 v64, 1.0, v219, s[14:15]
	v_add_f32_e32 v65, 1.0, v221
	v_rcp_f32_e32 v102, v66
	v_rcp_f32_e32 v224, v67
	v_cndmask_b32_e32 v190, v219, v64, vcc
	v_add_f32_e32 v64, 1.0, v99
	v_rcp_f32_e32 v222, v65
	v_rcp_f32_e32 v100, v64
	v_add_u32_e32 v66, 0xaa, v214
	v_add_u32_e32 v67, 0xab, v214
	v_add_u32_e32 v65, 0xa9, v214
	v_cmp_lt_i32_e64 s[12:13], v66, v164
	v_cmp_lt_i32_e64 s[18:19], v67, v164
	v_add_u32_e32 v64, 0xa8, v214
	v_cmp_lt_i32_e64 s[16:17], v65, v164
	v_cndmask_b32_e64 v66, 1.0, v102, s[12:13]
	v_cndmask_b32_e64 v67, 1.0, v224, s[18:19]
	v_cmp_lt_i32_e64 s[8:9], v64, v164
	v_cndmask_b32_e64 v65, 1.0, v222, s[16:17]
	v_cndmask_b32_e32 v66, v102, v66, vcc
	v_cndmask_b32_e32 v217, v224, v67, vcc
	v_cndmask_b32_e64 v64, 1.0, v100, s[8:9]
	v_cndmask_b32_e32 v65, v222, v65, vcc
	v_mul_f32_e32 v225, v217, v66
	v_cndmask_b32_e32 v64, v100, v64, vcc
	v_mul_f32_e32 v104, v65, v225
	v_mul_f32_e32 v97, v64, v104
	v_mov_b32_e32 v64, s20
	s_add_i32 s20, 0, 0x10004
	s_cmp_lg_u32 s20, -1
	v_mov_b32_e32 v65, s21
	s_cselect_b32 s20, s20, 0
	s_waitcnt lgkmcnt(0)
	s_barrier
; __device__ __forceinline__ int crow(int r, int hi) { return (r & 3) + 8 * (r >> 2) + 4 * hi; }
; __device__ __forceinline__ void sb_half(f32x16& p, float& carry, bool masked, int krow0, int tq, int hi) {
;     float G[4];
; #pragma unroll
;     for (int g = 0; g < 4; ++g) {
;         float q[4];
; #pragma unroll
;         for (int i = 0; i < 4; ++i) { const int r = 4 * g + i; const float e = __builtin_amdgcn_exp2f(p[r]); float qq = __builtin_amdgcn_rcpf(1.0f + e); float b = e * qq;
;             if (masked) { const bool keep = (krow0 + crow(r, hi)) < tq; qq = keep ? qq : 1.0f; b = keep ? b : 0.0f; }
;             q[i] = qq; p[r] = b; }
;         const float s2 = q[3] * q[2], s1 = s2 * q[1]; G[g] = s1 * q[0];
;         p[4 * g + 2] *= q[3]; p[4 * g + 1] *= s2; p[4 * g] *= s1;
;     }
;     float run = carry;
; #pragma unroll
;     for (int g = 3; g >= 0; --g) { const unsigned gu = __builtin_bit_cast(unsigned, G[g]); auto sw = __builtin_amdgcn_permlane32_swap(gu, gu, false, false);
;         const float partner = __builtin_bit_cast(float, hi ? sw[0] : sw[1]);
;         const float base = hi ? run : run * partner;
;         p[4 * g] *= base; p[4 * g + 1] *= base; p[4 * g + 2] *= base; p[4 * g + 3] *= base; run *= G[g] * partner; }
;     carry = run;
; __device__ __forceinline__ void sb_unit(const bf16* __restrict__ Qb, const bf16* __restrict__ Kh, const bf16* __restrict__ Vh, bf16* __restrict__ Ob, int q0, char* lds, const int wv0) {
;     ...
;         { unsigned a = 1u;
; #pragma unroll
;           for (int w = 0; w < 8; ++w) a &= votes[w];
;           if (a) { done = true; break; } }
	ds_read_b32 v67, v64
	s_cselect_b32 s21, s47, 0
	v_mov_b32_e32 v64, s20
	s_add_i32 s20, 0, 0x10008
	v_cndmask_b32_e64 v68, 1.0, v188, s[6:7]
	s_cmp_lg_u32 s20, -1
	v_cndmask_b32_e32 v68, v188, v68, vcc
	v_mov_b32_e32 v65, s21
	s_cselect_b32 s20, s20, 0
	v_mul_f32_e32 v220, v190, v68
	ds_read_b32 v68, v64
	s_cselect_b32 s21, s47, 0
	v_mov_b32_e32 v64, s20
	s_add_i32 s20, 0, 0x1000c
	s_cmp_lg_u32 s20, -1
	v_mov_b32_e32 v65, s21
	s_cselect_b32 s20, s20, 0
	ds_read_b32 v69, v64
	s_cselect_b32 s21, s47, 0
	v_mov_b32_e32 v64, s20
	s_add_i32 s20, 0, 0x10010
	s_cmp_lg_u32 s20, -1
	v_add_f32_e32 v77, 1.0, v195
	v_mov_b32_e32 v65, s21
	s_cselect_b32 s20, s20, 0
	v_rcp_f32_e32 v216, v77
	ds_read_b32 v70, v64
	s_cselect_b32 s21, s47, 0
	v_mov_b32_e32 v64, s20
	s_add_i32 s20, 0, 0x10014
	s_cmp_lg_u32 s20, -1
	v_add_u32_e32 v77, 0xa1, v214
	v_mov_b32_e32 v65, s21
	s_cselect_b32 s20, s20, 0
	v_cmp_lt_i32_e64 s[10:11], v77, v164
	ds_read_b32 v71, v64
	s_cselect_b32 s21, s47, 0
	v_mov_b32_e32 v64, s20
	s_add_i32 s20, 0, 0x10018
	v_cndmask_b32_e64 v72, 1.0, v216, s[10:11]
	s_cmp_lg_u32 s20, -1
	v_cndmask_b32_e32 v72, v216, v72, vcc
	v_mov_b32_e32 v65, s21
	s_cselect_b32 s20, s20, 0
	v_mul_f32_e32 v192, v72, v220
	ds_read_b32 v72, v64
	s_cselect_b32 s21, s47, 0
	v_mov_b32_e32 v64, s20
	s_add_i32 s20, 0, 0x1001c
	s_cmp_lg_u32 s20, -1
	v_mov_b32_e32 v65, s21
	s_cselect_b32 s20, s20, 0
	s_cselect_b32 s21, s47, 0
	ds_read_b32 v73, v64
	v_mov_b32_e32 v64, s20
	v_mov_b32_e32 v65, s21
	ds_read_b32 v64, v64
	v_exp_f32_e32 v229, v105
	v_exp_f32_e32 v105, v106
	v_exp_f32_e32 v232, v107
	v_add_f32_e32 v66, 1.0, v103
	v_rcp_f32_e32 v226, v66
	v_add_f32_e32 v74, 1.0, v105
	v_add_f32_e32 v75, 1.0, v232
	v_add_f32_e32 v66, 1.0, v229
	v_rcp_f32_e32 v227, v74
	v_rcp_f32_e32 v235, v75
	v_rcp_f32_e32 v230, v66
	v_add_u32_e32 v74, 0xb2, v214
	v_add_u32_e32 v75, 0xb3, v214
	v_exp_f32_e32 v233, v109
	v_exp_f32_e32 v109, v110
	v_exp_f32_e32 v237, v111
	v_add_u32_e32 v66, 0xb1, v214
	v_cmp_lt_i32_e64 s[22:23], v74, v164
	v_cmp_lt_i32_e64 s[30:31], v75, v164
	v_add_u32_e32 v65, 0xb0, v214
	v_cmp_lt_i32_e64 s[28:29], v66, v164
	v_cndmask_b32_e64 v74, 1.0, v227, s[22:23]
	v_cndmask_b32_e64 v75, 1.0, v235, s[30:31]
	v_exp_f32_e32 v106, v108
	v_cmp_lt_i32_e64 s[20:21], v65, v164
	v_cndmask_b32_e64 v66, 1.0, v230, s[28:29]
	v_cndmask_b32_e32 v74, v227, v74, vcc
	v_cndmask_b32_e32 v228, v235, v75, vcc
	v_exp_f32_e32 v184, v96
	v_cndmask_b32_e64 v65, 1.0, v226, s[20:21]
	v_cndmask_b32_e32 v66, v230, v66, vcc
	v_mul_f32_e32 v234, v228, v74
	v_add_f32_e32 v74, 1.0, v109
	v_add_f32_e32 v75, 1.0, v237
	v_cndmask_b32_e32 v65, v226, v65, vcc
	v_mul_f32_e32 v108, v66, v234
	v_add_f32_e32 v66, 1.0, v233
	v_rcp_f32_e32 v110, v74
	v_rcp_f32_e32 v239, v75
	v_mul_f32_e32 v180, v65, v108
	v_add_f32_e32 v65, 1.0, v106
	v_rcp_f32_e32 v236, v66
	v_rcp_f32_e32 v107, v65
	v_add_u32_e32 v74, 0xba, v214
	v_add_u32_e32 v75, 0xbb, v214
	v_add_f32_e32 v182, 1.0, v184
	v_add_u32_e32 v66, 0xb9, v214
	v_cmp_lt_i32_e64 s[26:27], v74, v164
	v_cmp_lt_i32_e64 s[36:37], v75, v164
	v_rcp_f32_e32 v186, v182
	v_add_u32_e32 v65, 0xb8, v214
	v_cmp_lt_i32_e64 s[34:35], v66, v164
	v_cndmask_b32_e64 v74, 1.0, v110, s[26:27]
	v_cndmask_b32_e64 v75, 1.0, v239, s[36:37]
	v_cmp_lt_i32_e64 s[24:25], v65, v164
	v_cndmask_b32_e64 v66, 1.0, v236, s[34:35]
	v_cndmask_b32_e32 v74, v110, v74, vcc
	v_cndmask_b32_e32 v231, v239, v75, vcc
	v_add_u32_e32 v96, 0xa0, v214
	v_cndmask_b32_e64 v65, 1.0, v107, s[24:25]
	v_cndmask_b32_e32 v66, v236, v66, vcc
	v_mul_f32_e32 v238, v231, v74
	v_cmp_lt_i32_e64 s[4:5], v96, v164
	v_cndmask_b32_e32 v65, v107, v65, vcc
	v_mul_f32_e32 v111, v66, v238
	v_cndmask_b32_e64 v76, 1.0, v186, s[4:5]
	v_mul_f32_e32 v96, v65, v111
	s_waitcnt lgkmcnt(0)
	v_bitop3_b32 v65, v67, v69, v68 bitop3:0x80
	v_cndmask_b32_e32 v76, v186, v76, vcc
	v_bitop3_b32 v65, v65, v71, v70 bitop3:0x80
	v_mul_f32_e32 v178, v76, v192
	v_mov_b32_e32 v241, v96
	v_mov_b32_e32 v243, v96
	v_mov_b32_e32 v242, v180
	v_mov_b32_e32 v244, v180
	v_mov_b32_e32 v245, v97
	v_bitop3_b32 v65, v65, v73, v72 bitop3:0x80
	v_mov_b32_e32 v246, v97
	v_mov_b32_e32 v182, v178
	v_mov_b32_e32 v240, v178
	v_bitop3_b32 v64, v65, 1, v64 bitop3:0x80
	v_permlane32_swap_b32_e32 v241, v243
	v_permlane32_swap_b32_e32 v242, v244
	v_permlane32_swap_b32_e32 v245, v246
	v_permlane32_swap_b32_e32 v182, v240
	v_cmp_eq_u32_e64 s[38:39], 0, v64
	s_mov_b64 s[70:71], -1
	v_readfirstlane_b32 s96, v0
	s_or_b64 s[66:67], s[66:67], exec
	s_and_saveexec_b64 s[68:69], s[38:39]
	s_cbranch_execz .LBB0_286
; __device__ __forceinline__ int crow(int r, int hi) { return (r & 3) + 8 * (r >> 2) + 4 * hi; }
; #define SBAR() __builtin_amdgcn_sched_barrier(0)
; #define SWRITE(b, i) do { *(bf16x8*)(V_lds + (b) * SHM_V + vst0) = sr_[i].vs0; *(bf16x8*)(V_lds + (b) * SHM_V + vst1) = sr_[i].vs1; const int kc = sc * 2; \
;     *(bf16x8*)(K_lds + (b) * SHM_K + KSWZ(sr, kc)) = sr_[i].ks0; *(bf16x8*)(K_lds + (b) * SHM_K + KSWZ(32 + sr, kc)) = sr_[i].ks1; } while (0)
; #define SWAIT() asm volatile("s_waitcnt vmcnt(0)" ::: "memory")
; __device__ __forceinline__ void sb_half(f32x16& p, float& carry, bool masked, int krow0, int tq, int hi) {
;     float G[4];
; #pragma unroll
;     for (int g = 0; g < 4; ++g) {
;         float q[4];
; #pragma unroll
;         for (int i = 0; i < 4; ++i) { const int r = 4 * g + i; const float e = __builtin_amdgcn_exp2f(p[r]); float qq = __builtin_amdgcn_rcpf(1.0f + e); float b = e * qq;
;             if (masked) { const bool keep = (krow0 + crow(r, hi)) < tq; qq = keep ? qq : 1.0f; b = keep ? b : 0.0f; }
;             q[i] = qq; p[r] = b; }
;         const float s2 = q[3] * q[2], s1 = s2 * q[1]; G[g] = s1 * q[0];
;         p[4 * g + 2] *= q[3]; p[4 * g + 1] *= s2; p[4 * g] *= s1;
;     }
;     float run = carry;
; #pragma unroll
;     for (int g = 3; g >= 0; --g) { const unsigned gu = __builtin_bit_cast(unsigned, G[g]); auto sw = __builtin_amdgcn_permlane32_swap(gu, gu, false, false);
;         const float partner = __builtin_bit_cast(float, hi ? sw[0] : sw[1]);
;         const float base = hi ? run : run * partner;
;         p[4 * g] *= base; p[4 * g + 1] *= base; p[4 * g + 2] *= base; p[4 * g + 3] *= base; run *= G[g] * partner; }
;     carry = run;
; __device__ __forceinline__ void sb_unit(const bf16* __restrict__ Qb, const bf16* __restrict__ Kh, const bf16* __restrict__ Vh, bf16* __restrict__ Ob, int q0, char* lds, const int wv0) {
;     ...
;         SWAIT(); SWRITE(0, SE);
;         __syncthreads();
;         SBAR(); qkt(pA0, pA1, K_lds, qr, r32, hi);
;         sb_half(pB0, carry, j < 4, K0(j), tq, hi); pack_p(pB0, pB1, pa0, pa1, pa2, pa3); SBAR();
	v_cndmask_b32_e64 v68, v241, v243, s[0:1]
	v_mul_f32_e32 v64, v96, v68
	v_cndmask_b32_e64 v69, v242, v244, s[0:1]
	v_mul_f32_e32 v96, v194, v64
	v_mul_f32_e32 v64, v180, v69
	v_cndmask_b32_e64 v65, v245, v246, s[0:1]
	v_pk_mul_f32 v[66:67], v[96:97], v[64:65]
	v_mul_f32_e32 v64, v218, v219
	v_pk_mul_f32 v[180:181], v[66:67], v[66:67] op_sel:[0,1] op_sel_hi:[1,0]
	v_cndmask_b32_e64 v182, v182, v240, s[0:1]
	v_cndmask_b32_e64 v67, 0, v64, s[14:15]
	v_cndmask_b32_e32 v64, v64, v67, vcc
	v_mul_f32_e32 v67, v180, v182
	v_cndmask_b32_e64 v67, v180, v67, s[0:1]
	v_mul_f32_e32 v196, v64, v67
	v_mul_f32_e32 v64, v195, v216
	v_cndmask_b32_e64 v70, 0, v64, s[10:11]
	v_cndmask_b32_e32 v64, v64, v70, vcc
	v_mul_f32_e32 v64, v220, v64
	v_mul_f32_e32 v197, v64, v67
	v_mul_f32_e32 v64, v223, v224
	v_cndmask_b32_e64 v70, 0, v64, s[18:19]
	v_mul_f32_e32 v65, v66, v65
	v_cndmask_b32_e32 v64, v64, v70, vcc
	v_cndmask_b32_e64 v65, v66, v65, s[0:1]
	v_mul_f32_e32 v215, v64, v65
	v_mul_f32_e32 v64, v221, v222
	v_cndmask_b32_e64 v66, 0, v64, s[16:17]
	v_cndmask_b32_e32 v64, v64, v66, vcc
	v_mul_f32_e32 v64, v225, v64
	v_mul_f32_e32 v240, v64, v65
	v_mul_f32_e32 v64, v232, v235
	v_cndmask_b32_e64 v66, 0, v64, s[30:31]
	v_cndmask_b32_e32 v64, v64, v66, vcc
	v_mul_f32_e32 v66, v96, v69
	v_cndmask_b32_e64 v66, v96, v66, s[0:1]
	v_mul_f32_e32 v241, v64, v66
	v_mul_f32_e32 v64, v229, v230
	v_cndmask_b32_e64 v69, 0, v64, s[28:29]
	v_cndmask_b32_e32 v64, v64, v69, vcc
	v_mul_f32_e32 v64, v234, v64
	v_mul_f32_e32 v242, v64, v66
	v_mul_f32_e32 v64, v237, v239
	v_cndmask_b32_e64 v69, 0, v64, s[36:37]
	v_mul_f32_e32 v68, v194, v68
	v_cndmask_b32_e32 v64, v64, v69, vcc
	v_cndmask_b32_e64 v68, v194, v68, s[0:1]
	v_mul_f32_e32 v243, v64, v68
	v_mul_f32_e32 v64, v233, v236
	v_cndmask_b32_e64 v69, 0, v64, s[34:35]
	v_cndmask_b32_e32 v64, v64, v69, vcc
	v_mul_f32_e32 v64, v238, v64
	v_mul_f32_e32 v244, v64, v68
	v_mul_f32_e32 v64, v98, v188
	v_cndmask_b32_e64 v69, 0, v64, s[6:7]
	v_cndmask_b32_e32 v64, v64, v69, vcc
	v_mul_f32_e32 v64, v190, v64
	v_mul_f32_e32 v245, v64, v67
	v_mul_f32_e32 v64, v184, v186
	v_cndmask_b32_e64 v69, 0, v64, s[4:5]
	v_cndmask_b32_e32 v64, v64, v69, vcc
	v_mul_f32_e32 v64, v64, v192
	v_mul_f32_e32 v246, v64, v67
	v_mul_f32_e32 v64, v101, v102
	v_cndmask_b32_e64 v67, 0, v64, s[12:13]
	v_cndmask_b32_e32 v64, v64, v67, vcc
	v_mul_f32_e32 v64, v217, v64
	v_mul_f32_e32 v247, v64, v65
	v_mul_f32_e32 v64, v99, v100
	v_cndmask_b32_e64 v67, 0, v64, s[8:9]
	v_cndmask_b32_e32 v64, v64, v67, vcc
	v_mul_f32_e32 v64, v64, v104
	v_mul_f32_e32 v248, v64, v65
	v_mul_f32_e32 v64, v105, v227
	v_cndmask_b32_e64 v65, 0, v64, s[22:23]
	v_cndmask_b32_e32 v64, v64, v65, vcc
	v_mul_f32_e32 v64, v228, v64
	v_mul_f32_e32 v249, v64, v66
	v_mul_f32_e32 v64, v103, v226
	v_cndmask_b32_e64 v65, 0, v64, s[20:21]
	v_cndmask_b32_e32 v64, v64, v65, vcc
	v_mul_f32_e32 v64, v64, v108
	v_mul_f32_e32 v250, v64, v66
	v_mul_f32_e32 v64, v109, v110
	v_cndmask_b32_e64 v65, 0, v64, s[26:27]
	v_cndmask_b32_e32 v64, v64, v65, vcc
	v_mul_f32_e32 v64, v231, v64
	v_mul_f32_e32 v251, v64, v68
	v_mul_f32_e32 v64, v106, v107
	v_cndmask_b32_e64 v65, 0, v64, s[24:25]
	s_waitcnt vmcnt(0)
	v_cndmask_b32_e32 v64, v64, v65, vcc
	v_mul_f32_e32 v64, v64, v111
	v_add_u32_e32 v179, 0x80, v214
	v_mul_f32_e32 v254, v64, v68
	ds_write_b128 v206, v[144:147]
	ds_write_b128 v207, v[148:151]
	ds_write_b128 v199, v[152:155] offset:32768
	ds_write_b128 v200, v[156:159] offset:32768
	s_waitcnt lgkmcnt(0)
	s_barrier
	ds_read_b128 v[64:67], v201 offset:32768
	ds_read_b128 v[96:99], v201 offset:40960
	v_exp_f32_e32 v80, v80
	v_exp_f32_e32 v81, v81
	ds_read_b128 v[144:147], v202 offset:32768
	ds_read_b128 v[148:151], v202 offset:40960
	ds_read_b128 v[152:155], v208 offset:32768
	ds_read_b128 v[156:159], v208 offset:40960
	ds_read_b128 v[184:187], v209 offset:32768
	ds_read_b128 v[188:191], v209 offset:40960
	ds_read_b128 v[192:195], v210 offset:32768
	ds_read_b128 v[216:219], v210 offset:40960
	s_waitcnt lgkmcnt(9)
	v_mfma_f32_32x32x16_bf16 v[64:79], v[64:67], v[140:143], 0
	v_add_f32_e32 v181, 1.0, v80
	v_exp_f32_e32 v82, v82
	v_rcp_f32_e32 v181, v181
	v_add_f32_e32 v183, 1.0, v81
	v_exp_f32_e32 v83, v83
	v_cmp_lt_i32_e64 s[4:5], v179, v164
	v_mul_f32_e32 v80, v80, v181
	s_waitcnt lgkmcnt(8)
	v_mfma_f32_32x32x16_bf16 v[96:111], v[96:99], v[140:143], 0
	v_cndmask_b32_e64 v179, 1.0, v181, s[4:5]
	v_exp_f32_e32 v84, v84
	ds_read_b128 v[220:223], v211 offset:32768
	ds_read_b128 v[224:227], v211 offset:40960
	ds_read_b128 v[228:231], v203 offset:32768
	ds_read_b128 v[232:235], v203 offset:40960
	s_waitcnt lgkmcnt(11)
	v_mfma_f32_32x32x16_bf16 v[64:79], v[144:147], v[136:139], v[64:79]
	ds_read_b128 v[144:147], v212 offset:32768
	ds_read_b128 v[236:239], v212 offset:40960
	s_waitcnt lgkmcnt(12)
	v_mfma_f32_32x32x16_bf16 v[96:111], v[148:151], v[136:139], v[96:111]
	v_rcp_f32_e32 v148, v183
	v_add_f32_e32 v151, 1.0, v82
	v_add_u32_e32 v150, 0x81, v214
	v_rcp_f32_e32 v151, v151
	v_cndmask_b32_e64 v149, 0, v80, s[4:5]
	v_mul_f32_e32 v81, v81, v148
	v_cmp_lt_i32_e64 s[4:5], v150, v164
	s_waitcnt lgkmcnt(11)
	v_mfma_f32_32x32x16_bf16 v[64:79], v[152:155], v[132:135], v[64:79]
	v_add_f32_e32 v153, 1.0, v83
	v_cndmask_b32_e64 v150, 1.0, v148, s[4:5]
	v_cndmask_b32_e64 v152, 0, v81, s[4:5]
	v_cndmask_b32_e32 v152, v81, v152, vcc
	v_cndmask_b32_e32 v81, v148, v150, vcc
	v_add_u32_e32 v148, 0x82, v214
	v_rcp_f32_e32 v153, v153
	v_mul_f32_e32 v82, v82, v151
	v_cmp_lt_i32_e64 s[4:5], v148, v164
	v_cndmask_b32_e32 v80, v80, v149, vcc
	v_mul_f32_e32 v83, v83, v153
	v_cndmask_b32_e64 v150, 0, v82, s[4:5]
	v_cndmask_b32_e32 v82, v82, v150, vcc
	v_add_u32_e32 v150, 0x83, v214
	v_cndmask_b32_e64 v148, 1.0, v151, s[4:5]
	v_cmp_lt_i32_e64 s[4:5], v150, v164
	v_cndmask_b32_e32 v148, v151, v148, vcc
	v_cndmask_b32_e32 v149, v181, v179, vcc
	v_cndmask_b32_e64 v150, 1.0, v153, s[4:5]
	v_cndmask_b32_e64 v151, 0, v83, s[4:5]
	v_cndmask_b32_e32 v151, v83, v151, vcc
	v_cndmask_b32_e32 v83, v153, v150, vcc
	v_mul_f32_e32 v148, v83, v148
	v_mul_f32_e32 v150, v81, v148
	s_waitcnt lgkmcnt(9)
; __device__ __forceinline__ int crow(int r, int hi) { return (r & 3) + 8 * (r >> 2) + 4 * hi; }
; #define SBAR() __builtin_amdgcn_sched_barrier(0)
; __device__ __forceinline__ void sb_half(f32x16& p, float& carry, bool masked, int krow0, int tq, int hi) {
;     float G[4];
; #pragma unroll
;     for (int g = 0; g < 4; ++g) {
;         float q[4];
; #pragma unroll
;         for (int i = 0; i < 4; ++i) { const int r = 4 * g + i; const float e = __builtin_amdgcn_exp2f(p[r]); float qq = __builtin_amdgcn_rcpf(1.0f + e); float b = e * qq;
;             if (masked) { const bool keep = (krow0 + crow(r, hi)) < tq; qq = keep ? qq : 1.0f; b = keep ? b : 0.0f; }
;             q[i] = qq; p[r] = b; }
;         const float s2 = q[3] * q[2], s1 = s2 * q[1]; G[g] = s1 * q[0];
;         p[4 * g + 2] *= q[3]; p[4 * g + 1] *= s2; p[4 * g] *= s1;
;     }
;     float run = carry;
; #pragma unroll
;     for (int g = 3; g >= 0; --g) { const unsigned gu = __builtin_bit_cast(unsigned, G[g]); auto sw = __builtin_amdgcn_permlane32_swap(gu, gu, false, false);
;         const float partner = __builtin_bit_cast(float, hi ? sw[0] : sw[1]);
;         const float base = hi ? run : run * partner;
;         p[4 * g] *= base; p[4 * g + 1] *= base; p[4 * g + 2] *= base; p[4 * g + 3] *= base; run *= G[g] * partner; }
;     carry = run;
; __device__ __forceinline__ void sb_unit(const bf16* __restrict__ Qb, const bf16* __restrict__ Kh, const bf16* __restrict__ Vh, bf16* __restrict__ Ob, int q0, char* lds, const int wv0) {
;     ...
;         SBAR(); qkt(pA0, pA1, K_lds, qr, r32, hi);
;         sb_half(pB0, carry, j < 4, K0(j), tq, hi); pack_p(pB0, pB1, pa0, pa1, pa2, pa3); SBAR();
	v_mfma_f32_32x32x16_bf16 v[64:79], v[184:187], v[128:131], v[64:79]
	v_mul_f32_e32 v81, v149, v150
	v_mul_f32_e32 v149, v83, v82
	v_add_f32_e32 v82, 1.0, v84
	v_rcp_f32_e32 v82, v82
	v_mul_f32_e32 v150, v80, v150
	v_add_u32_e32 v80, 0x88, v214
	v_cmp_lt_i32_e64 s[4:5], v80, v164
	v_mul_f32_e32 v83, v84, v82
	v_exp_f32_e32 v84, v85
	s_waitcnt lgkmcnt(7)
	v_mfma_f32_32x32x16_bf16 v[64:79], v[192:195], v[124:127], v[64:79]
	v_mul_f32_e32 v148, v148, v152
	v_cndmask_b32_e64 v152, 0, v83, s[4:5]
	v_add_f32_e32 v85, 1.0, v84
	v_rcp_f32_e32 v85, v85
	v_cndmask_b32_e64 v80, 1.0, v82, s[4:5]
	v_cndmask_b32_e32 v152, v83, v152, vcc
	v_add_u32_e32 v83, 0x89, v214
	v_cndmask_b32_e32 v80, v82, v80, vcc
	v_mul_f32_e32 v82, v84, v85
	v_exp_f32_e32 v84, v86
	v_cmp_lt_i32_e64 s[4:5], v83, v164
	s_waitcnt lgkmcnt(5)
	v_mfma_f32_32x32x16_bf16 v[64:79], v[220:223], v[120:123], v[64:79]
	v_add_f32_e32 v153, 1.0, v84
	v_cndmask_b32_e64 v86, 0, v82, s[4:5]
	v_cndmask_b32_e32 v82, v82, v86, vcc
	v_exp_f32_e32 v86, v87
	v_rcp_f32_e32 v153, v153
	v_cndmask_b32_e64 v83, 1.0, v85, s[4:5]
	v_cndmask_b32_e32 v83, v85, v83, vcc
	v_add_f32_e32 v87, 1.0, v86
	v_add_u32_e32 v85, 0x8a, v214
	v_rcp_f32_e32 v87, v87
	v_cmp_lt_i32_e64 s[4:5], v85, v164
	v_mul_f32_e32 v84, v84, v153
	s_waitcnt lgkmcnt(3)
	v_mfma_f32_32x32x16_bf16 v[64:79], v[228:231], v[116:119], v[64:79]
	v_cndmask_b32_e64 v85, 1.0, v153, s[4:5]
	v_cndmask_b32_e32 v85, v153, v85, vcc
	v_add_u32_e32 v153, 0x8b, v214
	v_cndmask_b32_e64 v154, 0, v84, s[4:5]
	v_mul_f32_e32 v86, v86, v87
	v_cmp_lt_i32_e64 s[4:5], v153, v164
	v_cndmask_b32_e32 v84, v84, v154, vcc
	s_waitcnt lgkmcnt(1)
	v_mfma_f32_32x32x16_bf16 v[64:79], v[144:147], v[112:115], v[64:79]
	v_cndmask_b32_e64 v153, 1.0, v87, s[4:5]
	v_cndmask_b32_e64 v154, 0, v86, s[4:5]
	v_cndmask_b32_e32 v154, v86, v154, vcc
	v_cndmask_b32_e32 v86, v87, v153, vcc
	v_mul_f32_e32 v85, v86, v85
	v_mul_f32_e32 v87, v83, v85
	v_mul_f32_e32 v83, v80, v87
	v_exp_f32_e32 v80, v88
	v_mul_f32_e32 v145, v85, v82
	v_exp_f32_e32 v85, v89
	v_mul_f32_e32 v144, v86, v84
	v_add_f32_e32 v82, 1.0, v80
	v_rcp_f32_e32 v82, v82
	v_add_f32_e32 v86, 1.0, v85
	v_rcp_f32_e32 v86, v86
	v_add_u32_e32 v84, 0x90, v214
	v_mul_f32_e32 v80, v80, v82
	v_cmp_lt_i32_e64 s[4:5], v84, v164
	v_mul_f32_e32 v146, v152, v87
	v_mfma_f32_32x32x16_bf16 v[96:111], v[156:159], v[132:135], v[96:111]
	v_cndmask_b32_e64 v84, 1.0, v82, s[4:5]
	v_cndmask_b32_e64 v87, 0, v80, s[4:5]
	v_cndmask_b32_e32 v80, v80, v87, vcc
	v_cndmask_b32_e32 v82, v82, v84, vcc
	v_mul_f32_e32 v84, v85, v86
	v_exp_f32_e32 v85, v90
	v_add_u32_e32 v87, 0x91, v214
	v_cmp_lt_i32_e64 s[4:5], v87, v164
	v_mfma_f32_32x32x16_bf16 v[96:111], v[188:191], v[128:131], v[96:111]
	v_add_f32_e32 v88, 1.0, v85
	v_cndmask_b32_e64 v87, 1.0, v86, s[4:5]
	v_cndmask_b32_e32 v86, v86, v87, vcc
	v_exp_f32_e32 v87, v91
	v_rcp_f32_e32 v88, v88
	v_cndmask_b32_e64 v89, 0, v84, s[4:5]
	v_cndmask_b32_e32 v84, v84, v89, vcc
	v_add_f32_e32 v90, 1.0, v87
	v_add_u32_e32 v89, 0x92, v214
	v_rcp_f32_e32 v90, v90
	v_mul_f32_e32 v85, v85, v88
	v_cmp_lt_i32_e64 s[4:5], v89, v164
	v_mfma_f32_32x32x16_bf16 v[96:111], v[216:219], v[124:127], v[96:111]
	v_mul_f32_e32 v87, v87, v90
	v_cndmask_b32_e64 v89, 1.0, v88, s[4:5]
	v_cndmask_b32_e64 v91, 0, v85, s[4:5]
	v_cndmask_b32_e32 v91, v85, v91, vcc
	v_cndmask_b32_e32 v85, v88, v89, vcc
	v_add_u32_e32 v88, 0x93, v214
	v_cmp_lt_i32_e64 s[4:5], v88, v164
	v_mfma_f32_32x32x16_bf16 v[96:111], v[224:227], v[120:123], v[96:111]
	s_nop 0
	v_cndmask_b32_e64 v89, 0, v87, s[4:5]
	v_cndmask_b32_e32 v147, v87, v89, vcc
	v_exp_f32_e32 v89, v92
	v_cndmask_b32_e64 v88, 1.0, v90, s[4:5]
	v_cndmask_b32_e32 v87, v90, v88, vcc
	v_mul_f32_e32 v88, v87, v85
	v_mul_f32_e32 v86, v86, v88
	v_mul_f32_e32 v90, v88, v84
	v_add_f32_e32 v84, 1.0, v89
	v_mul_f32_e32 v85, v82, v86
	v_mul_f32_e32 v82, v87, v91
	v_rcp_f32_e32 v84, v84
	v_exp_f32_e32 v87, v93
	v_mul_f32_e32 v80, v80, v86
	v_add_u32_e32 v86, 0x98, v214
	v_mul_f32_e32 v88, v89, v84
	v_add_f32_e32 v89, 1.0, v87
	v_rcp_f32_e32 v89, v89
	v_cmp_lt_i32_e64 s[4:5], v86, v164
	v_mfma_f32_32x32x16_bf16 v[96:111], v[232:235], v[116:119], v[96:111]
	s_nop 0
	v_cndmask_b32_e64 v86, 1.0, v84, s[4:5]
	v_cndmask_b32_e32 v179, v84, v86, vcc
	v_mul_f32_e32 v84, v87, v89
	v_exp_f32_e32 v86, v94
	v_add_u32_e32 v87, 0x99, v214
	v_cndmask_b32_e64 v91, 0, v88, s[4:5]
	v_cmp_lt_i32_e64 s[4:5], v87, v164
	v_cndmask_b32_e32 v88, v88, v91, vcc
	v_add_f32_e32 v91, 1.0, v86
	v_cndmask_b32_e64 v87, 1.0, v89, s[4:5]
	v_cndmask_b32_e32 v87, v89, v87, vcc
	v_exp_f32_e32 v89, v95
	v_rcp_f32_e32 v91, v91
	v_cndmask_b32_e64 v92, 0, v84, s[4:5]
	v_cndmask_b32_e32 v84, v84, v92, vcc
	v_add_u32_e32 v92, 0x9a, v214
	v_add_f32_e32 v93, 1.0, v89
	v_cmp_lt_i32_e64 s[4:5], v92, v164
	v_rcp_f32_e32 v93, v93
	v_mul_f32_e32 v86, v86, v91
	v_cndmask_b32_e64 v92, 1.0, v91, s[4:5]
	v_cndmask_b32_e32 v91, v91, v92, vcc
	v_add_u32_e32 v92, 0x9b, v214
	v_cndmask_b32_e64 v94, 0, v86, s[4:5]
	v_cmp_lt_i32_e64 s[4:5], v92, v164
	v_cndmask_b32_e32 v86, v86, v94, vcc
	v_mul_f32_e32 v89, v89, v93
	v_cndmask_b32_e64 v92, 1.0, v93, s[4:5]
	v_cndmask_b32_e32 v92, v93, v92, vcc
	v_mul_f32_e32 v91, v92, v91
	v_mul_f32_e32 v183, v87, v91
	v_mul_f32_e32 v92, v92, v86
	v_pk_mul_f32 v[86:87], v[178:179], v[182:183]
	v_mul_f32_e32 v84, v91, v84
	v_mov_b32_e32 v91, v87
	v_mov_b32_e32 v93, v87
	s_nop 1
	v_permlane32_swap_b32_e32 v91, v93
	v_cndmask_b32_e64 v181, v91, v93, s[0:1]
	v_pk_mul_f32 v[86:87], v[86:87], v[180:181]
	v_cndmask_b32_e64 v94, 0, v89, s[4:5]
	v_mul_f32_e32 v91, v86, v181
	v_mul_f32_e32 v88, v88, v183
	v_cndmask_b32_e64 v91, v86, v91, s[0:1]
	v_cndmask_b32_e32 v89, v89, v94, vcc
	v_mul_f32_e32 v93, v88, v91
	v_mul_f32_e32 v94, v84, v91
	v_mov_b32_e32 v84, v85
	v_mov_b32_e32 v88, v85
	s_nop 1
	v_permlane32_swap_b32_e32 v84, v88
	v_mul_f32_e32 v92, v92, v91
	v_mul_f32_e32 v91, v89, v91
	v_cndmask_b32_e64 v89, v84, v88, s[0:1]
	v_mov_b32_e32 v84, v86
	v_mov_b32_e32 v88, v87
	v_pk_mul_f32 v[84:85], v[84:85], v[88:89]
	s_waitcnt lgkmcnt(0)
; #define SBAR() __builtin_amdgcn_sched_barrier(0)
; #define SLOAD(i, k0) do { sr_[i].vs0 = *reinterpret_cast<const bf16x8*>(&Vh[(size_t)((k0) + sr) * LD + sc]); sr_[i].vs1 = *reinterpret_cast<const bf16x8*>(&Vh[(size_t)((k0) + 32 + sr) * LD + sc]); \
;     sr_[i].ks0 = *reinterpret_cast<const bf16x8*>(&Kh[(size_t)((k0) + sr) * LD + sc]); sr_[i].ks1 = *reinterpret_cast<const bf16x8*>(&Kh[(size_t)((k0) + 32 + sr) * LD + sc]); } while (0)
; __device__ __forceinline__ void pack_p(const f32x16& p0, const f32x16& p1, bf16x8& pa0, bf16x8& pa1, bf16x8& pa2, bf16x8& pa3) {
;     ...
;     PK4(p0, 0, pa0); PK4(p0, 8, pa1); PK4(p1, 0, pa2); PK4(p1, 8, pa3);
;     ...
; }
; __device__ __forceinline__ void sb_unit(const bf16* __restrict__ Qb, const bf16* __restrict__ Kh, const bf16* __restrict__ Vh, bf16* __restrict__ Ob, int q0, char* lds, const int wv0) {
;     ...
;         { const int z = __all(carry == 0.0f); if (lane == 0) votes[8 + wid] = (unsigned)z; }
;         SLOAD(SE, K0(j + 2)); SBAR();
;         pv_d0(o, vb0 + (int)SHM_V, pa0, pa1, pa2, pa3); sb_half(pA1, carry, (j + 1) < 4, K0(j + 1) + 32, tq, hi);
;         __syncthreads();
	v_mfma_f32_32x32x16_bf16 v[96:111], v[236:239], v[112:115], v[96:111]
	v_mul_f32_e32 v86, v84, v89
	v_cndmask_b32_e64 v86, v84, v86, s[0:1]
	v_mul_f32_e32 v88, v80, v86
	v_mul_f32_e32 v89, v90, v86
	v_mul_f32_e32 v90, v82, v86
	v_mov_b32_e32 v80, v83
	v_mov_b32_e32 v82, v83
	s_nop 1
	v_permlane32_swap_b32_e32 v80, v82
	v_mul_f32_e32 v95, v147, v86
	v_cndmask_b32_e64 v87, v80, v82, s[0:1]
	v_mov_b32_e32 v82, v84
	v_mov_b32_e32 v86, v85
	v_pk_mul_f32 v[82:83], v[82:83], v[86:87]
	v_mov_b32_e32 v84, v81
	v_mul_f32_e32 v80, v82, v87
	v_cndmask_b32_e64 v80, v82, v80, s[0:1]
	v_mul_f32_e32 v86, v146, v80
	v_mul_f32_e32 v87, v145, v80
	v_mul_f32_e32 v144, v144, v80
	v_mul_f32_e32 v145, v154, v80
	v_mov_b32_e32 v80, v81
	s_nop 1
	v_permlane32_swap_b32_e32 v80, v84
	v_cndmask_b32_e64 v85, v80, v84, s[0:1]
	v_mov_b32_e32 v80, v82
	v_mov_b32_e32 v84, v83
	v_pk_mul_f32 v[80:81], v[80:81], v[84:85]
	s_nop 0
	v_mul_f32_e32 v82, v80, v85
	v_cndmask_b32_e64 v82, v80, v82, s[0:1]
	v_mul_f32_e32 v83, v150, v82
	v_mul_f32_e32 v84, v148, v82
	v_mul_f32_e32 v85, v149, v82
	v_mul_f32_e32 v82, v151, v82
	v_cvt_pk_bf16_f32 v156, v83, v84
	v_cvt_pk_bf16_f32 v157, v85, v82
	v_cvt_pk_bf16_f32 v158, v86, v87
	v_cvt_pk_bf16_f32 v159, v144, v145
	v_cvt_pk_bf16_f32 v152, v88, v89
	v_cvt_pk_bf16_f32 v153, v90, v95
	v_cvt_pk_bf16_f32 v154, v93, v94
	v_cvt_pk_bf16_f32 v155, v92, v91
	v_cvt_pk_bf16_f32 v148, v246, v197
	v_cvt_pk_bf16_f32 v149, v245, v196
	v_cvt_pk_bf16_f32 v150, v248, v240
	v_cvt_pk_bf16_f32 v151, v247, v215
	v_cvt_pk_bf16_f32 v144, v250, v242
	v_cvt_pk_bf16_f32 v145, v249, v241
	v_cvt_pk_bf16_f32 v146, v254, v244
	v_cvt_pk_bf16_f32 v147, v251, v243
	v_pk_mul_f32 v[194:195], v[80:81], v[80:81] op_sel:[0,1] op_sel_hi:[1,0]
	v_permlane32_swap_b32_e32 v156, v158
	v_permlane32_swap_b32_e32 v157, v159
	v_permlane32_swap_b32_e32 v152, v154
	v_permlane32_swap_b32_e32 v153, v155
	v_permlane32_swap_b32_e32 v148, v150
	v_permlane32_swap_b32_e32 v149, v151
	v_permlane32_swap_b32_e32 v144, v146
	v_permlane32_swap_b32_e32 v145, v147
	s_mov_b64 s[6:7], exec
	v_cmp_eq_f32_e32 vcc, 0, v194
	s_and_saveexec_b64 s[4:5], s[2:3]
	s_cbranch_execz .LBB0_292
	s_cmp_eq_u64 vcc, s[6:7]
	s_cselect_b64 s[6:7], -1, 0
	v_cndmask_b32_e64 v80, 0, 1, s[6:7]
	ds_write_b32 v168, v80
.LBB0_292:
	s_or_b64 exec, exec, s[4:5]
	v_lshl_add_u64 v[88:89], v[176:177], 0, v[160:161]
	v_add_co_u32_e32 v80, vcc, 0x17a00000, v88
	v_lshl_add_u64 v[92:93], v[174:175], 0, v[160:161]
	s_nop 0
	v_addc_co_u32_e32 v81, vcc, 0, v89, vcc
	v_add_co_u32_e32 v84, vcc, 0x17a00000, v92
	global_load_dwordx4 v[80:83], v[80:81], off
	s_nop 0
	v_addc_co_u32_e32 v85, vcc, 0, v93, vcc
	v_add_co_u32_e32 v88, vcc, 0x15a00000, v88
	global_load_dwordx4 v[84:87], v[84:85], off
	s_nop 0
	v_addc_co_u32_e32 v89, vcc, 0, v89, vcc
	v_add_co_u32_e32 v92, vcc, 0x15a00000, v92
	global_load_dwordx4 v[88:91], v[88:89], off
	s_nop 0
	v_addc_co_u32_e32 v93, vcc, 0, v93, vcc
	global_load_dwordx4 v[92:95], v[92:93], off
	ds_read_b64_tr_b16 v[178:179], v165 offset:0
	ds_read_b64_tr_b16 v[180:181], v165 offset:0x800
	ds_read_b64_tr_b16 v[182:183], v165 offset:0x1000
	ds_read_b64_tr_b16 v[184:185], v165 offset:0x1800
	ds_read_b64_tr_b16 v[186:187], v165 offset:0x2000
	ds_read_b64_tr_b16 v[188:189], v165 offset:0x2800
	ds_read_b64_tr_b16 v[190:191], v165 offset:0x3000
	ds_read_b64_tr_b16 v[192:193], v165 offset:0x3800
	s_waitcnt lgkmcnt(0)
	s_nop 0
	v_mfma_f32_32x32x16_bf16 v[48:63], v[156:159], v[178:181], v[48:63]
	ds_read_b64_tr_b16 v[178:179], v165 offset:0x200
	ds_read_b64_tr_b16 v[180:181], v165 offset:0xa00
	v_mfma_f32_32x32x16_bf16 v[48:63], v[152:155], v[182:185], v[48:63]
	ds_read_b64_tr_b16 v[182:183], v165 offset:0x1200
	ds_read_b64_tr_b16 v[184:185], v165 offset:0x1a00
	v_mfma_f32_32x32x16_bf16 v[48:63], v[148:151], v[186:189], v[48:63]
	ds_read_b64_tr_b16 v[186:187], v165 offset:0x2200
	ds_read_b64_tr_b16 v[188:189], v165 offset:0x2a00
	ds_read_b64_tr_b16 v[216:217], v165 offset:0x3200
	ds_read_b64_tr_b16 v[218:219], v165 offset:0x3a00
	s_waitcnt lgkmcnt(0)
	v_mfma_f32_32x32x16_bf16 v[48:63], v[144:147], v[190:193], v[48:63]
	v_mfma_f32_32x32x16_bf16 v[32:47], v[156:159], v[178:181], v[32:47]
	ds_read_b64_tr_b16 v[178:179], v165 offset:0x400
	ds_read_b64_tr_b16 v[180:181], v165 offset:0xc00
	v_mfma_f32_32x32x16_bf16 v[32:47], v[152:155], v[182:185], v[32:47]
	ds_read_b64_tr_b16 v[182:183], v165 offset:0x1400
	ds_read_b64_tr_b16 v[184:185], v165 offset:0x1c00
	v_mfma_f32_32x32x16_bf16 v[32:47], v[148:151], v[186:189], v[32:47]
	ds_read_b64_tr_b16 v[186:187], v165 offset:0x2400
	ds_read_b64_tr_b16 v[188:189], v165 offset:0x2c00
	ds_read_b64_tr_b16 v[190:191], v165 offset:0x3400
	ds_read_b64_tr_b16 v[192:193], v165 offset:0x3c00
	s_waitcnt lgkmcnt(0)
	v_mfma_f32_32x32x16_bf16 v[32:47], v[144:147], v[216:219], v[32:47]
	v_mfma_f32_32x32x16_bf16 v[16:31], v[156:159], v[178:181], v[16:31]
	v_mfma_f32_32x32x16_bf16 v[16:31], v[152:155], v[182:185], v[16:31]
	ds_read_b64_tr_b16 v[184:185], v165 offset:0x600
	v_mfma_f32_32x32x16_bf16 v[16:31], v[148:151], v[186:189], v[16:31]
	ds_read_b64_tr_b16 v[186:187], v165 offset:0xe00
	ds_read_b64_tr_b16 v[216:217], v165 offset:0x1600
	ds_read_b64_tr_b16 v[218:219], v165 offset:0x1e00
	ds_read_b64_tr_b16 v[220:221], v165 offset:0x2600
	ds_read_b64_tr_b16 v[222:223], v165 offset:0x2e00
	ds_read_b64_tr_b16 v[224:225], v165 offset:0x3600
	ds_read_b64_tr_b16 v[226:227], v165 offset:0x3e00
	v_mfma_f32_32x32x16_bf16 v[16:31], v[144:147], v[190:193], v[16:31]
	s_waitcnt lgkmcnt(0)
	v_exp_f32_e32 v180, v96
	s_cmp_lt_u32 s72, 3
	s_cselect_b64 vcc, -1, 0
	s_add_i32 s20, 0, 0x10020
	s_cmp_lg_u32 s20, -1
	v_add_f32_e32 v178, 1.0, v180
	s_cselect_b32 s20, s20, 0
	v_rcp_f32_e32 v182, v178
	s_cselect_b32 s21, s47, 0
	v_mov_b32_e32 v178, s20
	s_add_i32 s20, 0, 0x10024
	s_cmp_lg_u32 s20, -1
	v_mov_b32_e32 v179, s21
	s_cselect_b32 s20, s20, 0
	s_waitcnt lgkmcnt(0)
	s_barrier
; __device__ __forceinline__ int crow(int r, int hi) { return (r & 3) + 8 * (r >> 2) + 4 * hi; }
; __device__ __forceinline__ void sb_half(f32x16& p, float& carry, bool masked, int krow0, int tq, int hi) {
;     float G[4];
; #pragma unroll
;     for (int g = 0; g < 4; ++g) {
;         float q[4];
; #pragma unroll
;         for (int i = 0; i < 4; ++i) { const int r = 4 * g + i; const float e = __builtin_amdgcn_exp2f(p[r]); float qq = __builtin_amdgcn_rcpf(1.0f + e); float b = e * qq;
;             if (masked) { const bool keep = (krow0 + crow(r, hi)) < tq; qq = keep ? qq : 1.0f; b = keep ? b : 0.0f; }
;             q[i] = qq; p[r] = b; }
;         const float s2 = q[3] * q[2], s1 = s2 * q[1]; G[g] = s1 * q[0];
;         p[4 * g + 2] *= q[3]; p[4 * g + 1] *= s2; p[4 * g] *= s1;
;     }
;     float run = carry;
; #pragma unroll
;     for (int g = 3; g >= 0; --g) { const unsigned gu = __builtin_bit_cast(unsigned, G[g]); auto sw = __builtin_amdgcn_permlane32_swap(gu, gu, false, false);
;         const float partner = __builtin_bit_cast(float, hi ? sw[0] : sw[1]);
;         const float base = hi ? run : run * partner;
;         p[4 * g] *= base; p[4 * g + 1] *= base; p[4 * g + 2] *= base; p[4 * g + 3] *= base; run *= G[g] * partner; }
;     carry = run;
; __device__ __forceinline__ void sb_unit(const bf16* __restrict__ Qb, const bf16* __restrict__ Kh, const bf16* __restrict__ Vh, bf16* __restrict__ Ob, int q0, char* lds, const int wv0) {
;     ...
;         pv_d0(o, vb0 + (int)SHM_V, pa0, pa1, pa2, pa3); sb_half(pA1, carry, (j + 1) < 4, K0(j + 1) + 32, tq, hi);
;         __syncthreads();
;         { unsigned a = 1u;
; #pragma unroll
;           for (int w = 0; w < 8; ++w) a &= votes[8 + w];
;           if (a) { done = true; break; } }
	ds_read_b32 v181, v178
	s_cselect_b32 s21, s47, 0
	v_mov_b32_e32 v178, s20
	s_add_i32 s20, 0, 0x10028
	s_cmp_lg_u32 s20, -1
	v_mov_b32_e32 v179, s21
	s_cselect_b32 s20, s20, 0
	ds_read_b32 v183, v178
	s_cselect_b32 s21, s47, 0
	v_mov_b32_e32 v178, s20
	s_add_i32 s20, 0, 0x1002c
	s_cmp_lg_u32 s20, -1
	v_mov_b32_e32 v179, s21
	s_cselect_b32 s20, s20, 0
	v_mfma_f32_32x32x16_bf16 v[0:15], v[156:159], v[184:187], v[0:15]
	ds_read_b32 v185, v178
	s_cselect_b32 s21, s47, 0
	v_mov_b32_e32 v178, s20
	s_add_i32 s20, 0, 0x10030
	s_cmp_lg_u32 s20, -1
	v_mov_b32_e32 v179, s21
	s_cselect_b32 s20, s20, 0
	ds_read_b32 v187, v178
	s_cselect_b32 s21, s47, 0
	v_mov_b32_e32 v178, s20
	s_add_i32 s20, 0, 0x10034
	s_cmp_lg_u32 s20, -1
	v_mov_b32_e32 v179, s21
	s_cselect_b32 s20, s20, 0
	ds_read_b32 v189, v178
	s_cselect_b32 s21, s47, 0
	v_mov_b32_e32 v178, s20
	s_add_i32 s20, 0, 0x10038
	s_cmp_lg_u32 s20, -1
	v_mov_b32_e32 v179, s21
	s_cselect_b32 s20, s20, 0
	ds_read_b32 v191, v178
	s_cselect_b32 s21, s47, 0
	v_mov_b32_e32 v178, s20
	s_add_i32 s20, 0, 0x1003c
	s_cmp_lg_u32 s20, -1
	v_mov_b32_e32 v179, s21
	s_cselect_b32 s20, s20, 0
	s_cselect_b32 s21, s47, 0
	ds_read_b32 v193, v178
	v_mov_b32_e32 v178, s20
	v_mov_b32_e32 v179, s21
	ds_read_b32 v179, v178
	v_mfma_f32_32x32x16_bf16 v[0:15], v[152:155], v[216:219], v[0:15]
	v_exp_f32_e32 v152, v98
	v_exp_f32_e32 v156, v97
	v_exp_f32_e32 v155, v103
	v_exp_f32_e32 v101, v101
	v_add_f32_e32 v98, 1.0, v152
	v_add_f32_e32 v97, 1.0, v156
	v_rcp_f32_e32 v153, v98
	v_mfma_f32_32x32x16_bf16 v[0:15], v[148:151], v[220:223], v[0:15]
	v_exp_f32_e32 v148, v99
	v_rcp_f32_e32 v157, v97
	v_add_u32_e32 v98, 0x62, v214
	v_exp_f32_e32 v151, v102
	v_add_f32_e32 v99, 1.0, v148
	v_rcp_f32_e32 v150, v99
	v_add_u32_e32 v99, 0x63, v214
	v_add_u32_e32 v97, 0x61, v214
	v_cmp_lt_i32_e64 s[10:11], v98, v164
	v_cmp_lt_i32_e64 s[14:15], v99, v164
	v_add_u32_e32 v96, 0x60, v214
	v_cmp_lt_i32_e64 s[6:7], v97, v164
	v_cndmask_b32_e64 v98, 1.0, v153, s[10:11]
	v_cndmask_b32_e64 v99, 1.0, v150, s[14:15]
	v_exp_f32_e32 v100, v100
	v_exp_f32_e32 v192, v106
	v_cmp_lt_i32_e64 s[4:5], v96, v164
	v_cndmask_b32_e64 v97, 1.0, v157, s[6:7]
	v_cndmask_b32_e32 v98, v153, v98, vcc
	v_cndmask_b32_e32 v149, v150, v99, vcc
	v_add_f32_e32 v102, 1.0, v155
	v_cndmask_b32_e64 v96, 1.0, v182, s[4:5]
	v_cndmask_b32_e32 v97, v157, v97, vcc
	v_mfma_f32_32x32x16_bf16 v[0:15], v[144:147], v[224:227], v[0:15]
	v_mul_f32_e32 v147, v149, v98
	v_add_f32_e32 v99, 1.0, v151
	v_rcp_f32_e32 v159, v102
	v_cndmask_b32_e32 v96, v182, v96, vcc
	v_mul_f32_e32 v146, v97, v147
	v_add_f32_e32 v98, 1.0, v101
	v_rcp_f32_e32 v154, v99
	v_exp_f32_e32 v219, v107
	v_mul_f32_e32 v97, v96, v146
	v_add_f32_e32 v96, 1.0, v100
	v_rcp_f32_e32 v145, v98
	v_add_u32_e32 v102, 0x6b, v214
	v_add_f32_e32 v106, 1.0, v192
	v_rcp_f32_e32 v144, v96
	v_add_u32_e32 v99, 0x6a, v214
	v_cmp_lt_i32_e64 s[18:19], v102, v164
	v_rcp_f32_e32 v217, v106
	v_add_u32_e32 v98, 0x69, v214
	v_cmp_lt_i32_e64 s[16:17], v99, v164
	v_cndmask_b32_e64 v102, 1.0, v159, s[18:19]
	v_exp_f32_e32 v105, v105
	v_add_u32_e32 v96, 0x68, v214
	v_cmp_lt_i32_e64 s[12:13], v98, v164
	v_cndmask_b32_e64 v99, 1.0, v154, s[16:17]
	v_cndmask_b32_e32 v158, v159, v102, vcc
	v_exp_f32_e32 v102, v104
	v_add_u32_e32 v106, 0x72, v214
	v_add_f32_e32 v107, 1.0, v219
	v_exp_f32_e32 v110, v110
	v_cmp_lt_i32_e64 s[8:9], v96, v164
	v_cndmask_b32_e64 v98, 1.0, v145, s[12:13]
	v_cndmask_b32_e32 v99, v154, v99, vcc
	v_cmp_lt_i32_e64 s[28:29], v106, v164
	v_rcp_f32_e32 v221, v107
	v_cndmask_b32_e64 v96, 1.0, v144, s[8:9]
	v_cndmask_b32_e32 v98, v145, v98, vcc
	v_mul_f32_e32 v104, v158, v99
	v_cndmask_b32_e64 v106, 1.0, v217, s[28:29]
	v_cndmask_b32_e32 v96, v144, v96, vcc
	v_mul_f32_e32 v103, v98, v104
	v_add_f32_e32 v98, 1.0, v105
	v_cndmask_b32_e32 v107, v217, v106, vcc
	v_add_u32_e32 v106, 0x73, v214
	v_mul_f32_e32 v99, v96, v103
	v_add_f32_e32 v96, 1.0, v102
	v_rcp_f32_e32 v190, v98
	v_cmp_lt_i32_e64 s[30:31], v106, v164
	v_add_f32_e32 v178, 1.0, v110
	v_rcp_f32_e32 v184, v96
	v_cndmask_b32_e64 v106, 1.0, v221, s[30:31]
	v_rcp_f32_e32 v222, v178
	v_exp_f32_e32 v178, v111
	v_add_u32_e32 v98, 0x71, v214
	v_cndmask_b32_e32 v220, v221, v106, vcc
	v_exp_f32_e32 v106, v108
	v_exp_f32_e32 v108, v109
	v_add_u32_e32 v96, 0x70, v214
	v_cmp_lt_i32_e64 s[22:23], v98, v164
	v_cmp_lt_i32_e64 s[20:21], v96, v164
	v_mul_f32_e32 v218, v220, v107
	v_cndmask_b32_e64 v98, 1.0, v190, s[22:23]
	v_cndmask_b32_e64 v96, 1.0, v184, s[20:21]
	v_cndmask_b32_e32 v98, v190, v98, vcc
	v_add_f32_e32 v186, 1.0, v178
	v_cndmask_b32_e32 v96, v184, v96, vcc
	v_mul_f32_e32 v216, v98, v218
	v_add_f32_e32 v98, 1.0, v108
	v_rcp_f32_e32 v186, v186
	v_mul_f32_e32 v195, v96, v216
	v_add_f32_e32 v96, 1.0, v106
	v_rcp_f32_e32 v109, v98
	v_rcp_f32_e32 v107, v96
	v_add_u32_e32 v111, 0x7a, v214
	v_add_u32_e32 v188, 0x7b, v214
	v_add_u32_e32 v98, 0x79, v214
	v_cmp_lt_i32_e64 s[34:35], v111, v164
	v_cmp_lt_i32_e64 s[36:37], v188, v164
	v_add_u32_e32 v96, 0x78, v214
	v_cmp_lt_i32_e64 s[26:27], v98, v164
	v_cndmask_b32_e64 v111, 1.0, v222, s[34:35]
	v_cndmask_b32_e64 v188, 1.0, v186, s[36:37]
	v_cmp_lt_i32_e64 s[24:25], v96, v164
	v_cndmask_b32_e64 v98, 1.0, v109, s[26:27]
	v_cndmask_b32_e32 v111, v222, v111, vcc
	v_cndmask_b32_e32 v223, v186, v188, vcc
	v_cndmask_b32_e64 v96, 1.0, v107, s[24:25]
	v_cndmask_b32_e32 v98, v109, v98, vcc
	v_mul_f32_e32 v214, v223, v111
	s_waitcnt lgkmcnt(0)
	v_bitop3_b32 v181, v181, v185, v183 bitop3:0x80
	v_cndmask_b32_e32 v96, v107, v96, vcc
	v_mul_f32_e32 v111, v98, v214
	v_bitop3_b32 v181, v181, v189, v187 bitop3:0x80
	v_mul_f32_e32 v98, v96, v111
	v_bitop3_b32 v181, v181, v193, v191 bitop3:0x80
	v_mov_b32_e32 v226, v98
	v_mov_b32_e32 v227, v98
	v_mov_b32_e32 v228, v195
	v_mov_b32_e32 v229, v195
	v_mov_b32_e32 v224, v99
	v_mov_b32_e32 v225, v99
	v_mov_b32_e32 v96, v97
	v_mov_b32_e32 v188, v97
	v_bitop3_b32 v179, v181, 1, v179 bitop3:0x80
	v_permlane32_swap_b32_e32 v226, v227
	v_permlane32_swap_b32_e32 v228, v229
	v_permlane32_swap_b32_e32 v224, v225
	v_permlane32_swap_b32_e32 v96, v188
	v_cmp_eq_u32_e64 s[38:39], 0, v179
	s_mov_b64 s[72:73], -1
	v_readfirstlane_b32 s96, v0
	s_mov_b64 s[74:75], -1
	s_and_saveexec_b64 s[70:71], s[38:39]
	s_cbranch_execz .LBB0_285
; #define SWRITE(b, i) do { *(bf16x8*)(V_lds + (b) * SHM_V + vst0) = sr_[i].vs0; *(bf16x8*)(V_lds + (b) * SHM_V + vst1) = sr_[i].vs1; const int kc = sc * 2; \
;     *(bf16x8*)(K_lds + (b) * SHM_K + KSWZ(sr, kc)) = sr_[i].ks0; *(bf16x8*)(K_lds + (b) * SHM_K + KSWZ(32 + sr, kc)) = sr_[i].ks1; } while (0)
; #define SWAIT() asm volatile("s_waitcnt vmcnt(0)" ::: "memory")
; __device__ __forceinline__ void sb_half(f32x16& p, float& carry, bool masked, int krow0, int tq, int hi) {
;     ...
;     float run = carry;
; #pragma unroll
;     for (int g = 3; g >= 0; --g) { const unsigned gu = __builtin_bit_cast(unsigned, G[g]); auto sw = __builtin_amdgcn_permlane32_swap(gu, gu, false, false);
;         const float partner = __builtin_bit_cast(float, hi ? sw[0] : sw[1]);
;         const float base = hi ? run : run * partner;
;         p[4 * g] *= base; p[4 * g + 1] *= base; p[4 * g + 2] *= base; p[4 * g + 3] *= base; run *= G[g] * partner; }
;     carry = run;
; __device__ __forceinline__ void sb_unit(const bf16* __restrict__ Qb, const bf16* __restrict__ Kh, const bf16* __restrict__ Vh, bf16* __restrict__ Ob, int q0, char* lds, const int wv0) {
;     ...
;           for (int w = 0; w < 8; ++w) a &= votes[8 + w];
;           if (a) { done = true; break; } }
;         SWAIT(); SWRITE(1, SO);
;         __syncthreads();
;     }
	v_cndmask_b32_e64 v179, v226, v227, s[0:1]
	v_mul_f32_e32 v196, v98, v179
	v_cndmask_b32_e64 v197, v228, v229, s[0:1]
	v_pk_mul_f32 v[226:227], v[194:195], v[196:197]
	v_cndmask_b32_e64 v225, v224, v225, s[0:1]
	v_mov_b32_e32 v98, v226
	v_mov_b32_e32 v224, v227
	v_pk_mul_f32 v[98:99], v[98:99], v[224:225]
	v_cndmask_b32_e64 v189, v96, v188, s[0:1]
	v_mov_b32_e32 v96, v98
	v_mov_b32_e32 v188, v99
	v_pk_mul_f32 v[96:97], v[96:97], v[188:189]
	s_add_i32 s96, s41, 2
	v_mul_f32_e32 v215, v96, v97
	v_mul_f32_e32 v97, v178, v186
	v_cndmask_b32_e64 v99, 0, v97, s[36:37]
	v_cndmask_b32_e32 v97, v97, v99, vcc
	v_mul_f32_e32 v99, v194, v179
	v_cndmask_b32_e64 v194, v194, v99, s[0:1]
	v_mul_f32_e32 v99, v148, v150
	v_cndmask_b32_e64 v148, 0, v99, s[14:15]
	v_cndmask_b32_e32 v179, v99, v148, vcc
	v_mul_f32_e32 v99, v96, v189
	v_cndmask_b32_e64 v96, v96, v99, s[0:1]
	v_mul_f32_e32 v99, v152, v153
	v_cndmask_b32_e64 v148, 0, v99, s[10:11]
	v_cndmask_b32_e32 v99, v99, v148, vcc
	v_mul_f32_e32 v178, v149, v99
	v_mul_f32_e32 v99, v156, v157
	v_cndmask_b32_e64 v148, 0, v99, s[6:7]
	v_cndmask_b32_e32 v99, v99, v148, vcc
	v_mul_f32_e32 v99, v147, v99
	v_mul_f32_e32 v187, v99, v96
	v_mul_f32_e32 v99, v180, v182
	v_cndmask_b32_e64 v147, 0, v99, s[4:5]
	v_cndmask_b32_e32 v99, v99, v147, vcc
	v_mul_f32_e32 v99, v99, v146
	v_pk_mul_f32 v[178:179], v[178:179], v[96:97] op_sel_hi:[1,0]
	v_mul_f32_e32 v186, v99, v96
	v_mul_f32_e32 v96, v155, v159
	v_cndmask_b32_e64 v99, 0, v96, s[18:19]
	v_cndmask_b32_e32 v99, v96, v99, vcc
	v_mul_f32_e32 v96, v98, v225
	v_cndmask_b32_e64 v96, v98, v96, s[0:1]
	v_mul_f32_e32 v98, v151, v154
	v_cndmask_b32_e64 v146, 0, v98, s[16:17]
	v_cndmask_b32_e32 v98, v98, v146, vcc
	v_mul_f32_e32 v98, v158, v98
	v_pk_mul_f32 v[180:181], v[98:99], v[96:97] op_sel_hi:[1,0]
	v_mul_f32_e32 v98, v101, v145
	v_cndmask_b32_e64 v99, 0, v98, s[12:13]
	v_cndmask_b32_e32 v98, v98, v99, vcc
	v_mul_f32_e32 v98, v104, v98
	v_mul_f32_e32 v189, v98, v96
	v_mul_f32_e32 v98, v100, v144
	v_cndmask_b32_e64 v99, 0, v98, s[8:9]
	v_cndmask_b32_e32 v98, v98, v99, vcc
	v_mul_f32_e32 v98, v98, v103
	v_mul_f32_e32 v188, v98, v96
	v_mul_f32_e32 v96, v219, v221
	v_cndmask_b32_e64 v98, 0, v96, s[30:31]
	v_cndmask_b32_e32 v99, v96, v98, vcc
	v_mul_f32_e32 v98, v192, v217
	v_cndmask_b32_e64 v100, 0, v98, s[28:29]
	v_mul_f32_e32 v96, v226, v197
	v_cndmask_b32_e32 v98, v98, v100, vcc
	v_cndmask_b32_e64 v96, v226, v96, s[0:1]
	v_mul_f32_e32 v98, v220, v98
	v_pk_mul_f32 v[182:183], v[98:99], v[96:97] op_sel_hi:[1,0]
	v_mul_f32_e32 v98, v105, v190
	v_cndmask_b32_e64 v99, 0, v98, s[22:23]
	v_cndmask_b32_e32 v98, v98, v99, vcc
	v_mul_f32_e32 v98, v218, v98
	v_mul_f32_e32 v191, v98, v96
	v_mul_f32_e32 v98, v102, v184
	v_cndmask_b32_e64 v99, 0, v98, s[20:21]
	v_cndmask_b32_e32 v98, v98, v99, vcc
	v_mul_f32_e32 v98, v98, v216
	v_mul_f32_e32 v190, v98, v96
	v_mul_f32_e32 v96, v110, v222
	v_cndmask_b32_e64 v98, 0, v96, s[34:35]
	v_cndmask_b32_e32 v96, v96, v98, vcc
	v_mul_f32_e32 v96, v223, v96
	v_pk_mul_f32 v[184:185], v[96:97], v[194:195] op_sel_hi:[1,0]
	v_mul_f32_e32 v96, v108, v109
	v_cndmask_b32_e64 v97, 0, v96, s[26:27]
	v_cndmask_b32_e32 v96, v96, v97, vcc
	v_mul_f32_e32 v96, v214, v96
	v_mul_f32_e32 v193, v96, v194
	v_mul_f32_e32 v96, v106, v107
	v_cndmask_b32_e64 v97, 0, v96, s[24:25]
	v_cndmask_b32_e32 v96, v96, v97, vcc
	s_waitcnt vmcnt(0)
	s_cmp_ge_u32 s96, s40
	v_mul_f32_e32 v96, v96, v111
	s_cselect_b64 s[4:5], -1, 0
	v_mul_f32_e32 v192, v96, v194
	v_add_u32_e32 v213, 0xffffff80, v213
	v_lshl_add_u64 v[170:171], v[170:171], 0, s[48:49]
	v_lshl_add_u64 v[172:173], v[172:173], 0, s[48:49]
	v_lshl_add_u64 v[174:175], v[174:175], 0, s[48:49]
	v_lshl_add_u64 v[176:177], v[176:177], 0, s[48:49]
	s_xor_b64 s[74:75], exec, -1
	s_orn2_b64 s[72:73], s[4:5], exec
	ds_write_b128 v206, v[80:83] offset:16384
	ds_write_b128 v207, v[84:87] offset:16384
	ds_write_b128 v199, v[88:91] offset:49152
	ds_write_b128 v200, v[92:95] offset:49152
	s_waitcnt lgkmcnt(0)
	s_barrier
	s_branch .LBB0_285

; #define PG8_STAGE(bufoff, gbase, voff) do { _Pragma("unroll") for (int _i = 0; _i < 2; ++_i) \
;         __builtin_amdgcn_global_load_lds((const unsigned*)((const char*)(gbase) + (voff)[_i]), (PG8_LAS unsigned*)(lds + (bufoff) + ldsw + _i * 8192), 16, 0, 0); } while (0)
; #define PG8_LDA(dst, b, h) do { _Pragma("unroll") for (int m = 0; m < 4; ++m) _Pragma("unroll") for (int k = 0; k < 2; ++k) dst[m][k] = *(const PG8_LAS bf16x8*)(lds + PG8_SA(b, h) + aoff + m * 2048 + k * 1024); } while (0)
; #define PG8_LDB(dst, b, h) do { _Pragma("unroll") for (int n = 0; n < 2; ++n) _Pragma("unroll") for (int k = 0; k < 2; ++k) dst[n][k] = *(const PG8_LAS bf16x8*)(lds + PG8_SB(b, h) + boff + n * 2048 + k * 1024); } while (0)
; template <class Epi, class Sched, bool ALIGN_EPI = false, bool SP2 = false>
; __device__ __forceinline__ void gemm_phase(PG8_LAS unsigned char* lds, const Gemm g, const Sched& S, const Epi& E, const int wv0) {
;     ...
;         PG8_STAGE(PG8_SB(0, 0), cB, voffB); PG8_STAGE(PG8_SB(0, 1), cB + hstepB, voffB); PG8_STAGE(PG8_SA(0, 0), cA, voffA); PG8_STAGE(PG8_SA(0, 1), cA + hstepA, voffA);
;         if (wr == 1) PG8_BAR;
;         PG8_WAIT_V(2); PG8_BAR;
;         PG8_STAGE(PG8_SB(1, 0), cB + kstep, voffB); PG8_STAGE(PG8_SA(1, 0), cA + kstep, voffA); PG8_STAGE(PG8_SB(1, 1), cB + hstepB + kstep, voffB);
;         PG8_WAIT_V(6); PG8_BAR;
;     ...
;             PG8_LDB(B0, 0, 0); PG8_LDB(B1, 0, 1); PG8_SCHED; PG8_LDA(At, 0, 0); PG8_STAGE(PG8_SA(1, 1), a1 + hstepA, voffA);
;             PG8_WAIT_V(8); PG8_WAIT_L(0); PG8_BAR; PG8_MMA(0, 0, At, B0); PG8_MMA(0, 1, At, B1); PG8_BAR; PG8_SCHED;
;             PG8_LDA(At, 0, 1); PG8_STAGE(PG8_SB(0, 0), b2, voffB); PG8_STAGE(PG8_SB(0, 1), b2 + hstepB, voffB); PG8_STAGE(PG8_SA(0, 0), a2, voffA);
;             PG8_WAIT_V(8); PG8_WAIT_L(0); PG8_BAR; PG8_MMA(1, 0, At, B0); PG8_MMA(1, 1, At, B1); PG8_BAR; PG8_SCHED;
;             PG8_LDB(B0, 1, 0); PG8_LDB(B1, 1, 1); PG8_SCHED; PG8_LDA(At, 1, 0); PG8_STAGE(PG8_SA(0, 1), a2 + hstepA, voffA);
;             PG8_WAIT_V(8); PG8_WAIT_L(0); PG8_BAR; PG8_MMA(0, 0, At, B0); PG8_MMA(0, 1, At, B1); PG8_BAR; PG8_SCHED;
;             PG8_LDA(At, 1, 1); PG8_STAGE(PG8_SB(1, 0), b3, voffB); PG8_STAGE(PG8_SB(1, 1), b3 + hstepB, voffB); PG8_STAGE(PG8_SA(1, 0), a3, voffA);
;             PG8_WAIT_V(8); PG8_WAIT_L(0); PG8_BAR; PG8_MMA(1, 0, At, B0); PG8_MMA(1, 1, At, B1); PG8_BAR; PG8_SCHED;
.LBB0_358:
	s_add_i32 s53, s36, s66
	s_and_b32 s51, s47, 3
	v_lshl_add_u64 v[2:3], v[26:27], 0, s[8:9]
	s_mov_b32 m0, s53
	s_add_i32 s55, s53, 0x2000
	s_lshl_b32 s63, s50, 13
	s_lshl_b32 s47, s51, 12
	s_waitcnt vmcnt(2)
	s_barrier
	global_load_lds_dwordx4 v[2:3], off
	v_lshl_add_u64 v[4:5], v[28:29], 0, s[8:9]
	s_mov_b32 m0, s55
	s_add_i32 s54, s61, 0x8000
	s_add_i32 s56, s61, 0xa000
	global_load_lds_dwordx4 v[4:5], off
	v_lshl_add_u64 v[0:1], v[20:21], 0, s[8:9]
	s_mov_b32 m0, s54
	s_add_u32 s64, s24, 0x10080
	global_load_lds_dwordx4 v[0:1], off
	v_lshl_add_u64 v[6:7], v[22:23], 0, s[8:9]
	s_mov_b32 m0, s56
	s_addc_u32 s65, s25, 0
	s_add_i32 s58, s37, s66
	global_load_lds_dwordx4 v[6:7], off
	v_lshl_add_u64 v[8:9], s[64:65], 0, v[128:129]
	s_mov_b32 m0, s58
	s_add_i32 s60, s58, 0x2000
	global_load_lds_dwordx4 v[8:9], off
	v_lshl_add_u64 v[10:11], s[64:65], 0, v[32:33]
	s_mov_b32 m0, s60
	v_bfe_u32 v144, v34, 4, 2
	global_load_lds_dwordx4 v[10:11], off
	v_and_b32_e32 v143, 15, v34
	v_lshlrev_b32_e32 v35, 4, v144
	v_lshlrev_b32_e32 v34, 2, v34
	v_lshl_or_b32 v66, v143, 6, v35
	v_and_b32_e32 v67, 32, v34
	v_bitop3_b32 v68, v66, s47, v67 bitop3:0xde
	s_add_i32 s48, 0, 0x10000
	s_add_i32 s47, 0, 0x14000
	v_add_u32_e32 v202, s48, v68
	s_waitcnt vmcnt(6)
	s_barrier
	v_add_u32_e32 v145, s47, v68
	ds_read_b128 v[34:37], v202
	ds_read_b128 v[38:41], v202 offset:1024
	ds_read_b128 v[42:45], v202 offset:2048
	ds_read_b128 v[46:49], v202 offset:3072
	ds_read_b128 v[50:53], v145
	ds_read_b128 v[54:57], v145 offset:1024
	ds_read_b128 v[58:61], v145 offset:2048
	ds_read_b128 v[62:65], v145 offset:3072
	v_bitop3_b32 v66, v66, s63, v67 bitop3:0xde
	v_add_u32_e32 v203, 0, v66
	v_add_u32_e32 v246, s37, v68
	v_add_u32_e32 v247, s36, v68
	s_add_u32 s64, s22, 0x40080
	s_addc_u32 s65, s23, 0
	s_add_i32 s68, s61, 0xc000
	v_lshl_add_u64 v[98:99], s[64:65], 0, v[16:17]
	s_mov_b32 m0, s68
	s_add_i32 s63, s61, 0xe000
	ds_read_b128 v[66:69], v203
	ds_read_b128 v[70:73], v203 offset:1024
	ds_read_b128 v[74:77], v203 offset:2048
	ds_read_b128 v[78:81], v203 offset:3072
	ds_read_b128 v[82:85], v203 offset:4096
	ds_read_b128 v[86:89], v203 offset:5120
	ds_read_b128 v[90:93], v203 offset:6144
	ds_read_b128 v[94:97], v203 offset:7168
	global_load_lds_dwordx4 v[98:99], off
	v_lshl_add_u64 v[98:99], s[64:65], 0, v[30:31]
	s_mov_b32 m0, s63
	s_nop 0
	global_load_lds_dwordx4 v[98:99], off
	s_waitcnt vmcnt(8)
	s_waitcnt lgkmcnt(0)
	s_barrier
	s_setprio 1
	v_mfma_f32_16x16x32_bf16 v[98:101], v[34:37], v[66:69], 0
	v_mfma_f32_16x16x32_bf16 v[102:105], v[42:45], v[66:69], 0
	v_mfma_f32_16x16x32_bf16 v[106:109], v[34:37], v[74:77], 0
	v_mfma_f32_16x16x32_bf16 v[110:113], v[42:45], v[74:77], 0
	v_mfma_f32_16x16x32_bf16 v[114:117], v[34:37], v[82:85], 0
	v_mfma_f32_16x16x32_bf16 v[118:121], v[42:45], v[82:85], 0
	v_mfma_f32_16x16x32_bf16 v[122:125], v[34:37], v[90:93], 0
	v_mfma_f32_16x16x32_bf16 v[98:101], v[38:41], v[70:73], v[98:101]
	v_mfma_f32_16x16x32_bf16 v[102:105], v[46:49], v[70:73], v[102:105]
	v_mfma_f32_16x16x32_bf16 v[106:109], v[38:41], v[78:81], v[106:109]
	v_mfma_f32_16x16x32_bf16 v[110:113], v[46:49], v[78:81], v[110:113]
	v_mfma_f32_16x16x32_bf16 v[114:117], v[38:41], v[86:89], v[114:117]
	v_mfma_f32_16x16x32_bf16 v[118:121], v[46:49], v[86:89], v[118:121]
	v_mfma_f32_16x16x32_bf16 v[122:125], v[38:41], v[94:97], v[122:125]
	v_mfma_f32_16x16x32_bf16 v[130:133], v[42:45], v[90:93], 0
	v_mfma_f32_16x16x32_bf16 v[130:133], v[46:49], v[94:97], v[130:133]
	v_mfma_f32_16x16x32_bf16 v[134:137], v[50:53], v[66:69], 0
	v_mfma_f32_16x16x32_bf16 v[66:69], v[58:61], v[66:69], 0
	v_mfma_f32_16x16x32_bf16 v[134:137], v[54:57], v[70:73], v[134:137]
	v_mfma_f32_16x16x32_bf16 v[66:69], v[62:65], v[70:73], v[66:69]
	v_mfma_f32_16x16x32_bf16 v[70:73], v[50:53], v[74:77], 0
	v_mfma_f32_16x16x32_bf16 v[74:77], v[58:61], v[74:77], 0
	v_mfma_f32_16x16x32_bf16 v[70:73], v[54:57], v[78:81], v[70:73]
	v_mfma_f32_16x16x32_bf16 v[74:77], v[62:65], v[78:81], v[74:77]
	v_mfma_f32_16x16x32_bf16 v[78:81], v[50:53], v[82:85], 0
	v_mfma_f32_16x16x32_bf16 v[82:85], v[58:61], v[82:85], 0
	v_mfma_f32_16x16x32_bf16 v[78:81], v[54:57], v[86:89], v[78:81]
	v_mfma_f32_16x16x32_bf16 v[82:85], v[62:65], v[86:89], v[82:85]
	v_mfma_f32_16x16x32_bf16 v[86:89], v[50:53], v[90:93], 0
	v_mfma_f32_16x16x32_bf16 v[90:93], v[58:61], v[90:93], 0
	v_mfma_f32_16x16x32_bf16 v[86:89], v[54:57], v[94:97], v[86:89]
	v_mfma_f32_16x16x32_bf16 v[90:93], v[62:65], v[94:97], v[90:93]
	s_setprio 0
	s_barrier
	s_add_i32 s64, s48, s66
	s_add_i32 s65, s64, 0x2000
	v_lshl_add_u64 v[126:127], v[26:27], 0, s[10:11]
	s_mov_b32 m0, s64
	s_add_u32 s70, s24, 0x10100
	ds_read_b128 v[94:97], v203 offset:16384
	ds_read_b128 v[138:141], v203 offset:17408
	ds_read_b128 v[146:149], v203 offset:18432
	ds_read_b128 v[150:153], v203 offset:19456
	ds_read_b128 v[154:157], v203 offset:20480
	ds_read_b128 v[158:161], v203 offset:21504
	ds_read_b128 v[162:165], v203 offset:22528
	ds_read_b128 v[166:169], v203 offset:23552
	global_load_lds_dwordx4 v[126:127], off
	v_lshl_add_u64 v[126:127], v[28:29], 0, s[10:11]
	s_mov_b32 m0, s65
	s_addc_u32 s71, s25, 0
	s_add_i32 s66, s47, s66
	global_load_lds_dwordx4 v[126:127], off
	v_lshl_add_u64 v[126:127], s[70:71], 0, v[128:129]
	s_mov_b32 m0, s66
	s_add_i32 s67, s66, 0x2000
	global_load_lds_dwordx4 v[126:127], off
	v_lshl_add_u64 v[126:127], s[70:71], 0, v[32:33]
	s_mov_b32 m0, s67
	s_nop 0
	global_load_lds_dwordx4 v[126:127], off
	v_lshl_add_u64 v[126:127], v[20:21], 0, s[10:11]
	s_mov_b32 m0, s61
	s_nop 0
	global_load_lds_dwordx4 v[126:127], off
	v_lshl_add_u64 v[126:127], v[22:23], 0, s[10:11]
	s_mov_b32 m0, s62
	s_nop 0
	global_load_lds_dwordx4 v[126:127], off
	s_waitcnt vmcnt(8)
	s_waitcnt lgkmcnt(0)
	s_barrier
; #define PG8_STAGE(bufoff, gbase, voff) do { _Pragma("unroll") for (int _i = 0; _i < 2; ++_i) \
;         __builtin_amdgcn_global_load_lds((const unsigned*)((const char*)(gbase) + (voff)[_i]), (PG8_LAS unsigned*)(lds + (bufoff) + ldsw + _i * 8192), 16, 0, 0); } while (0)
; #define PG8_LDA(dst, b, h) do { _Pragma("unroll") for (int m = 0; m < 4; ++m) _Pragma("unroll") for (int k = 0; k < 2; ++k) dst[m][k] = *(const PG8_LAS bf16x8*)(lds + PG8_SA(b, h) + aoff + m * 2048 + k * 1024); } while (0)
; #define PG8_LDB(dst, b, h) do { _Pragma("unroll") for (int n = 0; n < 2; ++n) _Pragma("unroll") for (int k = 0; k < 2; ++k) dst[n][k] = *(const PG8_LAS bf16x8*)(lds + PG8_SB(b, h) + boff + n * 2048 + k * 1024); } while (0)
; #define PG8_MMA(ai, bj, At, Bt) do { __builtin_amdgcn_s_setprio(1); _Pragma("unroll") for (int m = 0; m < 4; ++m) _Pragma("unroll") for (int n = 0; n < 2; ++n) _Pragma("unroll") for (int k = 0; k < 2; ++k) \
;         acc[ai][bj][m][n] = __builtin_amdgcn_mfma_f32_16x16x32_bf16(Bt[n][k], At[m][k], acc[ai][bj][m][n], 0, 0, 0); __builtin_amdgcn_s_setprio(0); } while (0)
; #define PG8_BAR __builtin_amdgcn_s_barrier()
; template <class Epi, class Sched, bool ALIGN_EPI = false, bool SP2 = false>
; __device__ __forceinline__ void gemm_phase(PG8_LAS unsigned char* lds, const Gemm g, const Sched& S, const Epi& E, const int wv0) {
;     ...
;             PG8_LDB(B0, 0, 0); PG8_LDB(B1, 0, 1); PG8_SCHED; PG8_LDA(At, 0, 0); PG8_STAGE(PG8_SA(1, 1), a1 + hstepA, voffA);
;             PG8_WAIT_V(8); PG8_WAIT_L(0); PG8_BAR; PG8_MMA(0, 0, At, B0); PG8_MMA(0, 1, At, B1); PG8_BAR; PG8_SCHED;
;             PG8_LDA(At, 0, 1); PG8_STAGE(PG8_SB(0, 0), b2, voffB); PG8_STAGE(PG8_SB(0, 1), b2 + hstepB, voffB); PG8_STAGE(PG8_SA(0, 0), a2, voffA);
;             PG8_WAIT_V(8); PG8_WAIT_L(0); PG8_BAR; PG8_MMA(1, 0, At, B0); PG8_MMA(1, 1, At, B1); PG8_BAR; PG8_SCHED;
;             PG8_LDB(B0, 1, 0); PG8_LDB(B1, 1, 1); PG8_SCHED; PG8_LDA(At, 1, 0); PG8_STAGE(PG8_SA(0, 1), a2 + hstepA, voffA);
;             PG8_WAIT_V(8); PG8_WAIT_L(0); PG8_BAR; PG8_MMA(0, 0, At, B0); PG8_MMA(0, 1, At, B1); PG8_BAR; PG8_SCHED;
;             PG8_LDA(At, 1, 1); PG8_STAGE(PG8_SB(1, 0), b3, voffB); PG8_STAGE(PG8_SB(1, 1), b3 + hstepB, voffB); PG8_STAGE(PG8_SA(1, 0), a3, voffA);
;             PG8_WAIT_V(8); PG8_WAIT_L(0); PG8_BAR; PG8_MMA(1, 0, At, B0); PG8_MMA(1, 1, At, B1); PG8_BAR; PG8_SCHED;
	s_setprio 1
	v_mfma_f32_16x16x32_bf16 v[170:173], v[34:37], v[94:97], 0
	v_mfma_f32_16x16x32_bf16 v[178:181], v[34:37], v[146:149], 0
	v_mfma_f32_16x16x32_bf16 v[186:189], v[34:37], v[154:157], 0
	v_mfma_f32_16x16x32_bf16 v[34:37], v[34:37], v[162:165], 0
	v_mfma_f32_16x16x32_bf16 v[170:173], v[38:41], v[138:141], v[170:173]
	v_mfma_f32_16x16x32_bf16 v[178:181], v[38:41], v[150:153], v[178:181]
	v_mfma_f32_16x16x32_bf16 v[186:189], v[38:41], v[158:161], v[186:189]
	v_mfma_f32_16x16x32_bf16 v[34:37], v[38:41], v[166:169], v[34:37]
	v_mfma_f32_16x16x32_bf16 v[38:41], v[42:45], v[162:165], 0
	v_mfma_f32_16x16x32_bf16 v[174:177], v[42:45], v[94:97], 0
	v_mfma_f32_16x16x32_bf16 v[182:185], v[42:45], v[146:149], 0
	v_mfma_f32_16x16x32_bf16 v[190:193], v[42:45], v[154:157], 0
	v_mfma_f32_16x16x32_bf16 v[38:41], v[46:49], v[166:169], v[38:41]
	v_mfma_f32_16x16x32_bf16 v[174:177], v[46:49], v[138:141], v[174:177]
	v_mfma_f32_16x16x32_bf16 v[182:185], v[46:49], v[150:153], v[182:185]
	v_mfma_f32_16x16x32_bf16 v[190:193], v[46:49], v[158:161], v[190:193]
	v_mfma_f32_16x16x32_bf16 v[42:45], v[50:53], v[94:97], 0
	v_mfma_f32_16x16x32_bf16 v[46:49], v[58:61], v[94:97], 0
	v_mfma_f32_16x16x32_bf16 v[42:45], v[54:57], v[138:141], v[42:45]
	v_mfma_f32_16x16x32_bf16 v[46:49], v[62:65], v[138:141], v[46:49]
	v_mfma_f32_16x16x32_bf16 v[94:97], v[50:53], v[146:149], 0
	v_mfma_f32_16x16x32_bf16 v[138:141], v[58:61], v[146:149], 0
	v_mfma_f32_16x16x32_bf16 v[146:149], v[50:53], v[154:157], 0
	v_mfma_f32_16x16x32_bf16 v[50:53], v[50:53], v[162:165], 0
	v_mfma_f32_16x16x32_bf16 v[94:97], v[54:57], v[150:153], v[94:97]
	v_mfma_f32_16x16x32_bf16 v[146:149], v[54:57], v[158:161], v[146:149]
	v_mfma_f32_16x16x32_bf16 v[50:53], v[54:57], v[166:169], v[50:53]
	v_mfma_f32_16x16x32_bf16 v[54:57], v[58:61], v[162:165], 0
	v_mfma_f32_16x16x32_bf16 v[138:141], v[62:65], v[150:153], v[138:141]
	v_mfma_f32_16x16x32_bf16 v[150:153], v[58:61], v[154:157], 0
	v_mfma_f32_16x16x32_bf16 v[54:57], v[62:65], v[166:169], v[54:57]
	v_mfma_f32_16x16x32_bf16 v[150:153], v[62:65], v[158:161], v[150:153]
	s_setprio 0
	s_barrier
	ds_read_b128 v[58:61], v247
	ds_read_b128 v[62:65], v247 offset:1024
	ds_read_b128 v[154:157], v247 offset:2048
	ds_read_b128 v[158:161], v247 offset:3072
	ds_read_b128 v[162:165], v246
	ds_read_b128 v[166:169], v246 offset:1024
	ds_read_b128 v[194:197], v246 offset:2048
	ds_read_b128 v[198:201], v246 offset:3072
	s_add_u32 s70, s22, 0x40100
	s_addc_u32 s71, s23, 0
	s_mov_b32 m0, s57
	v_lshl_add_u64 v[126:127], s[70:71], 0, v[16:17]
	ds_read_b128 v[206:209], v203 offset:32768
	ds_read_b128 v[210:213], v203 offset:33792
	ds_read_b128 v[214:217], v203 offset:34816
	ds_read_b128 v[218:221], v203 offset:35840
	ds_read_b128 v[222:225], v203 offset:36864
	ds_read_b128 v[226:229], v203 offset:37888
	ds_read_b128 v[230:233], v203 offset:38912
	ds_read_b128 v[234:237], v203 offset:39936
	global_load_lds_dwordx4 v[126:127], off
	v_lshl_add_u64 v[126:127], s[70:71], 0, v[30:31]
	s_mov_b32 m0, s59
	s_nop 0
	global_load_lds_dwordx4 v[126:127], off
	s_waitcnt vmcnt(8)
	s_waitcnt lgkmcnt(0)
	s_barrier
	s_setprio 1
	v_mfma_f32_16x16x32_bf16 v[98:101], v[58:61], v[206:209], v[98:101]
	v_mfma_f32_16x16x32_bf16 v[102:105], v[154:157], v[206:209], v[102:105]
	v_mfma_f32_16x16x32_bf16 v[106:109], v[58:61], v[214:217], v[106:109]
	v_mfma_f32_16x16x32_bf16 v[110:113], v[154:157], v[214:217], v[110:113]
	v_mfma_f32_16x16x32_bf16 v[114:117], v[58:61], v[222:225], v[114:117]
	v_mfma_f32_16x16x32_bf16 v[118:121], v[154:157], v[222:225], v[118:121]
	v_mfma_f32_16x16x32_bf16 v[122:125], v[58:61], v[230:233], v[122:125]
	v_mfma_f32_16x16x32_bf16 v[98:101], v[62:65], v[210:213], v[98:101]
	v_mfma_f32_16x16x32_bf16 v[102:105], v[158:161], v[210:213], v[102:105]
	v_mfma_f32_16x16x32_bf16 v[106:109], v[62:65], v[218:221], v[106:109]
	v_mfma_f32_16x16x32_bf16 v[110:113], v[158:161], v[218:221], v[110:113]
	v_mfma_f32_16x16x32_bf16 v[114:117], v[62:65], v[226:229], v[114:117]
	v_mfma_f32_16x16x32_bf16 v[118:121], v[158:161], v[226:229], v[118:121]
	v_mfma_f32_16x16x32_bf16 v[122:125], v[62:65], v[234:237], v[122:125]
	v_mfma_f32_16x16x32_bf16 v[130:133], v[154:157], v[230:233], v[130:133]
	v_mfma_f32_16x16x32_bf16 v[130:133], v[158:161], v[234:237], v[130:133]
	v_mfma_f32_16x16x32_bf16 v[66:69], v[194:197], v[206:209], v[66:69]
	v_mfma_f32_16x16x32_bf16 v[70:73], v[162:165], v[214:217], v[70:73]
	v_mfma_f32_16x16x32_bf16 v[74:77], v[194:197], v[214:217], v[74:77]
	v_mfma_f32_16x16x32_bf16 v[78:81], v[162:165], v[222:225], v[78:81]
	v_mfma_f32_16x16x32_bf16 v[82:85], v[194:197], v[222:225], v[82:85]
	v_mfma_f32_16x16x32_bf16 v[86:89], v[162:165], v[230:233], v[86:89]
	v_mfma_f32_16x16x32_bf16 v[90:93], v[194:197], v[230:233], v[90:93]
	v_mfma_f32_16x16x32_bf16 v[134:137], v[162:165], v[206:209], v[134:137]
	v_mfma_f32_16x16x32_bf16 v[66:69], v[198:201], v[210:213], v[66:69]
	v_mfma_f32_16x16x32_bf16 v[70:73], v[166:169], v[218:221], v[70:73]
	v_mfma_f32_16x16x32_bf16 v[74:77], v[198:201], v[218:221], v[74:77]
	v_mfma_f32_16x16x32_bf16 v[78:81], v[166:169], v[226:229], v[78:81]
	v_mfma_f32_16x16x32_bf16 v[82:85], v[198:201], v[226:229], v[82:85]
	v_mfma_f32_16x16x32_bf16 v[86:89], v[166:169], v[234:237], v[86:89]
	v_mfma_f32_16x16x32_bf16 v[90:93], v[198:201], v[234:237], v[90:93]
	v_mfma_f32_16x16x32_bf16 v[134:137], v[166:169], v[210:213], v[134:137]
	s_setprio 0
	s_barrier
; #define PG8_STAGE(bufoff, gbase, voff) do { _Pragma("unroll") for (int _i = 0; _i < 2; ++_i) \
;         __builtin_amdgcn_global_load_lds((const unsigned*)((const char*)(gbase) + (voff)[_i]), (PG8_LAS unsigned*)(lds + (bufoff) + ldsw + _i * 8192), 16, 0, 0); } while (0)
; #define PG8_LDA(dst, b, h) do { _Pragma("unroll") for (int m = 0; m < 4; ++m) _Pragma("unroll") for (int k = 0; k < 2; ++k) dst[m][k] = *(const PG8_LAS bf16x8*)(lds + PG8_SA(b, h) + aoff + m * 2048 + k * 1024); } while (0)
; #define PG8_LDB(dst, b, h) do { _Pragma("unroll") for (int n = 0; n < 2; ++n) _Pragma("unroll") for (int k = 0; k < 2; ++k) dst[n][k] = *(const PG8_LAS bf16x8*)(lds + PG8_SB(b, h) + boff + n * 2048 + k * 1024); } while (0)
; #define PG8_MMA(ai, bj, At, Bt) do { __builtin_amdgcn_s_setprio(1); _Pragma("unroll") for (int m = 0; m < 4; ++m) _Pragma("unroll") for (int n = 0; n < 2; ++n) _Pragma("unroll") for (int k = 0; k < 2; ++k) \
;         acc[ai][bj][m][n] = __builtin_amdgcn_mfma_f32_16x16x32_bf16(Bt[n][k], At[m][k], acc[ai][bj][m][n], 0, 0, 0); __builtin_amdgcn_s_setprio(0); } while (0)
; #define PG8_BAR __builtin_amdgcn_s_barrier()
; template <class Epi, class Sched, bool ALIGN_EPI = false, bool SP2 = false>
; __device__ __forceinline__ void gemm_phase(PG8_LAS unsigned char* lds, const Gemm g, const Sched& S, const Epi& E, const int wv0) {
;     ...
;             PG8_LDB(B0, 0, 0); PG8_LDB(B1, 0, 1); PG8_SCHED; PG8_LDA(At, 0, 0); PG8_STAGE(PG8_SA(1, 1), a1 + hstepA, voffA);
;             PG8_WAIT_V(8); PG8_WAIT_L(0); PG8_BAR; PG8_MMA(0, 0, At, B0); PG8_MMA(0, 1, At, B1); PG8_BAR; PG8_SCHED;
;             PG8_LDA(At, 0, 1); PG8_STAGE(PG8_SB(0, 0), b2, voffB); PG8_STAGE(PG8_SB(0, 1), b2 + hstepB, voffB); PG8_STAGE(PG8_SA(0, 0), a2, voffA);
;             PG8_WAIT_V(8); PG8_WAIT_L(0); PG8_BAR; PG8_MMA(1, 0, At, B0); PG8_MMA(1, 1, At, B1); PG8_BAR; PG8_SCHED;
;             PG8_LDB(B0, 1, 0); PG8_LDB(B1, 1, 1); PG8_SCHED; PG8_LDA(At, 1, 0); PG8_STAGE(PG8_SA(0, 1), a2 + hstepA, voffA);
;             PG8_WAIT_V(8); PG8_WAIT_L(0); PG8_BAR; PG8_MMA(0, 0, At, B0); PG8_MMA(0, 1, At, B1); PG8_BAR; PG8_SCHED;
;             PG8_LDA(At, 1, 1); PG8_STAGE(PG8_SB(1, 0), b3, voffB); PG8_STAGE(PG8_SB(1, 1), b3 + hstepB, voffB); PG8_STAGE(PG8_SA(1, 0), a3, voffA);
;             PG8_WAIT_V(8); PG8_WAIT_L(0); PG8_BAR; PG8_MMA(1, 0, At, B0); PG8_MMA(1, 1, At, B1); PG8_BAR; PG8_SCHED;
	s_mov_b32 m0, s53
	v_lshl_add_u64 v[126:127], v[26:27], 0, s[12:13]
	s_add_u32 s24, s24, 0x10180
	ds_read_b128 v[206:209], v203 offset:49152
	ds_read_b128 v[210:213], v203 offset:50176
	ds_read_b128 v[214:217], v203 offset:51200
	ds_read_b128 v[218:221], v203 offset:52224
	ds_read_b128 v[222:225], v203 offset:53248
	ds_read_b128 v[226:229], v203 offset:54272
	ds_read_b128 v[230:233], v203 offset:55296
	ds_read_b128 v[234:237], v203 offset:56320
	global_load_lds_dwordx4 v[126:127], off
	v_lshl_add_u64 v[126:127], v[28:29], 0, s[12:13]
	s_mov_b32 m0, s55
	s_addc_u32 s25, s25, 0
	global_load_lds_dwordx4 v[126:127], off
	v_lshl_add_u64 v[126:127], s[24:25], 0, v[128:129]
	s_mov_b32 m0, s58
	v_lshl_add_u64 v[32:33], s[24:25], 0, v[32:33]
	global_load_lds_dwordx4 v[126:127], off
	s_mov_b32 m0, s60
	s_nop 0
	global_load_lds_dwordx4 v[32:33], off
	v_lshl_add_u64 v[32:33], v[20:21], 0, s[12:13]
	s_mov_b32 m0, s54
	s_nop 0
	global_load_lds_dwordx4 v[32:33], off
	v_lshl_add_u64 v[32:33], v[22:23], 0, s[12:13]
	s_mov_b32 m0, s56
	s_nop 0
	global_load_lds_dwordx4 v[32:33], off
	s_waitcnt vmcnt(8)
	s_waitcnt lgkmcnt(0)
	s_barrier
	s_setprio 1
	v_mfma_f32_16x16x32_bf16 v[32:35], v[58:61], v[230:233], v[34:37]
	v_mfma_f32_16x16x32_bf16 v[36:39], v[154:157], v[230:233], v[38:41]
	v_mfma_f32_16x16x32_bf16 v[170:173], v[58:61], v[206:209], v[170:173]
	v_mfma_f32_16x16x32_bf16 v[174:177], v[154:157], v[206:209], v[174:177]
	v_mfma_f32_16x16x32_bf16 v[178:181], v[58:61], v[214:217], v[178:181]
	v_mfma_f32_16x16x32_bf16 v[182:185], v[154:157], v[214:217], v[182:185]
	v_mfma_f32_16x16x32_bf16 v[186:189], v[58:61], v[222:225], v[186:189]
	v_mfma_f32_16x16x32_bf16 v[190:193], v[154:157], v[222:225], v[190:193]
	v_mfma_f32_16x16x32_bf16 v[32:35], v[62:65], v[234:237], v[32:35]
	v_mfma_f32_16x16x32_bf16 v[36:39], v[158:161], v[234:237], v[36:39]
	v_mfma_f32_16x16x32_bf16 v[170:173], v[62:65], v[210:213], v[170:173]
	v_mfma_f32_16x16x32_bf16 v[174:177], v[158:161], v[210:213], v[174:177]
	v_mfma_f32_16x16x32_bf16 v[178:181], v[62:65], v[218:221], v[178:181]
	v_mfma_f32_16x16x32_bf16 v[182:185], v[158:161], v[218:221], v[182:185]
	v_mfma_f32_16x16x32_bf16 v[186:189], v[62:65], v[226:229], v[186:189]
	v_mfma_f32_16x16x32_bf16 v[190:193], v[158:161], v[226:229], v[190:193]
	v_mfma_f32_16x16x32_bf16 v[40:43], v[162:165], v[206:209], v[42:45]
	v_mfma_f32_16x16x32_bf16 v[44:47], v[194:197], v[206:209], v[46:49]
	v_mfma_f32_16x16x32_bf16 v[58:61], v[162:165], v[214:217], v[94:97]
	v_mfma_f32_16x16x32_bf16 v[62:65], v[194:197], v[214:217], v[138:141]
	v_mfma_f32_16x16x32_bf16 v[94:97], v[162:165], v[222:225], v[146:149]
	v_mfma_f32_16x16x32_bf16 v[48:51], v[162:165], v[230:233], v[50:53]
	v_mfma_f32_16x16x32_bf16 v[52:55], v[194:197], v[230:233], v[54:57]
	v_mfma_f32_16x16x32_bf16 v[40:43], v[166:169], v[210:213], v[40:43]
	v_mfma_f32_16x16x32_bf16 v[44:47], v[198:201], v[210:213], v[44:47]
	v_mfma_f32_16x16x32_bf16 v[58:61], v[166:169], v[218:221], v[58:61]
	v_mfma_f32_16x16x32_bf16 v[62:65], v[198:201], v[218:221], v[62:65]
	v_mfma_f32_16x16x32_bf16 v[94:97], v[166:169], v[226:229], v[94:97]
	v_mfma_f32_16x16x32_bf16 v[138:141], v[194:197], v[222:225], v[150:153]
	v_mfma_f32_16x16x32_bf16 v[48:51], v[166:169], v[234:237], v[48:51]
	v_mfma_f32_16x16x32_bf16 v[52:55], v[198:201], v[234:237], v[52:55]
	v_mfma_f32_16x16x32_bf16 v[138:141], v[198:201], v[226:229], v[138:141]
	s_setprio 0
	s_barrier
	ds_read_b128 v[146:149], v202
	ds_read_b128 v[150:153], v202 offset:1024
	ds_read_b128 v[154:157], v202 offset:2048
	ds_read_b128 v[158:161], v202 offset:3072
	ds_read_b128 v[162:165], v145
	ds_read_b128 v[166:169], v145 offset:1024
	ds_read_b128 v[194:197], v145 offset:2048
	ds_read_b128 v[198:201], v145 offset:3072
	s_add_u32 s22, s22, 0x40180
	s_addc_u32 s23, s23, 0
	s_mov_b32 m0, s68
	v_lshl_add_u64 v[16:17], s[22:23], 0, v[16:17]
	ds_read_b128 v[206:209], v203
	ds_read_b128 v[210:213], v203 offset:1024
	ds_read_b128 v[214:217], v203 offset:2048
	ds_read_b128 v[218:221], v203 offset:3072
	ds_read_b128 v[222:225], v203 offset:4096
	ds_read_b128 v[226:229], v203 offset:5120
	ds_read_b128 v[230:233], v203 offset:6144
	ds_read_b128 v[234:237], v203 offset:7168
	global_load_lds_dwordx4 v[16:17], off
	v_lshl_add_u64 v[16:17], s[22:23], 0, v[30:31]
	s_mov_b32 m0, s63
	s_nop 0
	global_load_lds_dwordx4 v[16:17], off
	s_waitcnt vmcnt(8)
	s_waitcnt lgkmcnt(0)
	s_barrier
	s_setprio 1
	v_mfma_f32_16x16x32_bf16 v[114:117], v[146:149], v[222:225], v[114:117]
	v_mfma_f32_16x16x32_bf16 v[238:241], v[150:153], v[226:229], v[114:117]
	v_mfma_f32_16x16x32_bf16 v[114:117], v[154:157], v[222:225], v[118:121]
	v_mfma_f32_16x16x32_bf16 v[98:101], v[146:149], v[206:209], v[98:101]
	v_mfma_f32_16x16x32_bf16 v[102:105], v[154:157], v[206:209], v[102:105]
	v_mfma_f32_16x16x32_bf16 v[106:109], v[146:149], v[214:217], v[106:109]
	v_mfma_f32_16x16x32_bf16 v[110:113], v[154:157], v[214:217], v[110:113]
	v_mfma_f32_16x16x32_bf16 v[242:245], v[158:161], v[226:229], v[114:117]
	v_mfma_f32_16x16x32_bf16 v[114:117], v[146:149], v[230:233], v[122:125]
	v_mfma_f32_16x16x32_bf16 v[98:101], v[150:153], v[210:213], v[98:101]
	v_mfma_f32_16x16x32_bf16 v[102:105], v[158:161], v[210:213], v[102:105]
	v_mfma_f32_16x16x32_bf16 v[106:109], v[150:153], v[218:221], v[106:109]
	v_mfma_f32_16x16x32_bf16 v[110:113], v[158:161], v[218:221], v[110:113]
	v_mfma_f32_16x16x32_bf16 v[124:127], v[150:153], v[234:237], v[114:117]
	v_mfma_f32_16x16x32_bf16 v[114:117], v[154:157], v[230:233], v[130:133]
	v_mfma_f32_16x16x32_bf16 v[130:133], v[158:161], v[234:237], v[114:117]
	v_mfma_f32_16x16x32_bf16 v[66:69], v[194:197], v[206:209], v[66:69]
	v_mfma_f32_16x16x32_bf16 v[114:117], v[162:165], v[206:209], v[134:137]
	v_mfma_f32_16x16x32_bf16 v[206:209], v[198:201], v[210:213], v[66:69]
	v_mfma_f32_16x16x32_bf16 v[66:69], v[162:165], v[214:217], v[70:73]
	v_mfma_f32_16x16x32_bf16 v[134:137], v[166:169], v[210:213], v[114:117]
	v_mfma_f32_16x16x32_bf16 v[210:213], v[166:169], v[218:221], v[66:69]
	v_mfma_f32_16x16x32_bf16 v[66:69], v[194:197], v[214:217], v[74:77]
	v_mfma_f32_16x16x32_bf16 v[214:217], v[198:201], v[218:221], v[66:69]
	v_mfma_f32_16x16x32_bf16 v[66:69], v[162:165], v[222:225], v[78:81]
	v_mfma_f32_16x16x32_bf16 v[76:79], v[166:169], v[226:229], v[66:69]
	v_mfma_f32_16x16x32_bf16 v[66:69], v[194:197], v[222:225], v[82:85]
	v_mfma_f32_16x16x32_bf16 v[80:83], v[198:201], v[226:229], v[66:69]
	v_mfma_f32_16x16x32_bf16 v[66:69], v[162:165], v[230:233], v[86:89]
	v_mfma_f32_16x16x32_bf16 v[218:221], v[166:169], v[234:237], v[66:69]
	v_mfma_f32_16x16x32_bf16 v[66:69], v[194:197], v[230:233], v[90:93]
	v_mfma_f32_16x16x32_bf16 v[222:225], v[198:201], v[234:237], v[66:69]
	s_setprio 0
	s_barrier
; #define PG8_STAGE(bufoff, gbase, voff) do { _Pragma("unroll") for (int _i = 0; _i < 2; ++_i) \
;         __builtin_amdgcn_global_load_lds((const unsigned*)((const char*)(gbase) + (voff)[_i]), (PG8_LAS unsigned*)(lds + (bufoff) + ldsw + _i * 8192), 16, 0, 0); } while (0)
; #define PG8_LDA(dst, b, h) do { _Pragma("unroll") for (int m = 0; m < 4; ++m) _Pragma("unroll") for (int k = 0; k < 2; ++k) dst[m][k] = *(const PG8_LAS bf16x8*)(lds + PG8_SA(b, h) + aoff + m * 2048 + k * 1024); } while (0)
; #define PG8_LDB(dst, b, h) do { _Pragma("unroll") for (int n = 0; n < 2; ++n) _Pragma("unroll") for (int k = 0; k < 2; ++k) dst[n][k] = *(const PG8_LAS bf16x8*)(lds + PG8_SB(b, h) + boff + n * 2048 + k * 1024); } while (0)
; #define PG8_MMA(ai, bj, At, Bt) do { __builtin_amdgcn_s_setprio(1); _Pragma("unroll") for (int m = 0; m < 4; ++m) _Pragma("unroll") for (int n = 0; n < 2; ++n) _Pragma("unroll") for (int k = 0; k < 2; ++k) \
;         acc[ai][bj][m][n] = __builtin_amdgcn_mfma_f32_16x16x32_bf16(Bt[n][k], At[m][k], acc[ai][bj][m][n], 0, 0, 0); __builtin_amdgcn_s_setprio(0); } while (0)
; #define PG8_BAR __builtin_amdgcn_s_barrier()
; template <class Epi, class Sched, bool ALIGN_EPI = false, bool SP2 = false>
; __device__ __forceinline__ void gemm_phase(PG8_LAS unsigned char* lds, const Gemm g, const Sched& S, const Epi& E, const int wv0) {
;     ...
;             PG8_LDB(B0, 0, 0); PG8_LDB(B1, 0, 1); PG8_SCHED; PG8_LDA(At, 0, 0); PG8_STAGE(PG8_SA(1, 1), a1 + hstepA, voffA);
;             PG8_WAIT_V(8); PG8_WAIT_L(0); PG8_BAR; PG8_MMA(0, 0, At, B0); PG8_MMA(0, 1, At, B1); PG8_BAR; PG8_SCHED;
;             PG8_LDA(At, 0, 1); PG8_STAGE(PG8_SB(0, 0), b2, voffB); PG8_STAGE(PG8_SB(0, 1), b2 + hstepB, voffB); PG8_STAGE(PG8_SA(0, 0), a2, voffA);
;             PG8_WAIT_V(8); PG8_WAIT_L(0); PG8_BAR; PG8_MMA(1, 0, At, B0); PG8_MMA(1, 1, At, B1); PG8_BAR; PG8_SCHED;
;             PG8_LDB(B0, 1, 0); PG8_LDB(B1, 1, 1); PG8_SCHED; PG8_LDA(At, 1, 0); PG8_STAGE(PG8_SA(0, 1), a2 + hstepA, voffA);
;             PG8_WAIT_V(8); PG8_WAIT_L(0); PG8_BAR; PG8_MMA(0, 0, At, B0); PG8_MMA(0, 1, At, B1); PG8_BAR; PG8_SCHED;
;             PG8_LDA(At, 1, 1); PG8_STAGE(PG8_SB(1, 0), b3, voffB); PG8_STAGE(PG8_SB(1, 1), b3 + hstepB, voffB); PG8_STAGE(PG8_SA(1, 0), a3, voffA);
;             PG8_WAIT_V(8); PG8_WAIT_L(0); PG8_BAR; PG8_MMA(1, 0, At, B0); PG8_MMA(1, 1, At, B1); PG8_BAR; PG8_SCHED;
	s_mov_b32 m0, s64
	s_nop 3
	ds_read_b128 v[66:69], v203 offset:16384
	ds_read_b128 v[70:73], v203 offset:17408
	ds_read_b128 v[84:87], v203 offset:18432
	ds_read_b128 v[88:91], v203 offset:19456
	ds_read_b128 v[114:117], v203 offset:20480
	ds_read_b128 v[118:121], v203 offset:21504
	ds_read_b128 v[226:229], v203 offset:22528
	ds_read_b128 v[230:233], v203 offset:23552
	global_load_lds_dwordx4 v[26:27], off
	s_mov_b32 m0, s65
	s_nop 0
	global_load_lds_dwordx4 v[28:29], off
	s_mov_b32 m0, s66
	s_nop 0
	global_load_lds_dwordx4 v[24:25], off
	s_mov_b32 m0, s67
	s_nop 0
	global_load_lds_dwordx4 v[18:19], off
	s_mov_b32 m0, s61
	s_nop 0
	global_load_lds_dwordx4 v[20:21], off
	s_mov_b32 m0, s62
	s_nop 0
	global_load_lds_dwordx4 v[22:23], off
	s_waitcnt vmcnt(8)
	s_waitcnt lgkmcnt(0)
	s_barrier
	s_setprio 1
	v_mfma_f32_16x16x32_bf16 v[16:19], v[146:149], v[66:69], v[170:173]
	v_mfma_f32_16x16x32_bf16 v[20:23], v[154:157], v[66:69], v[174:177]
	v_mfma_f32_16x16x32_bf16 v[24:27], v[146:149], v[84:87], v[178:181]
	v_mfma_f32_16x16x32_bf16 v[28:31], v[154:157], v[84:87], v[182:185]
	v_mfma_f32_16x16x32_bf16 v[32:35], v[146:149], v[226:229], v[32:35]
	v_mfma_f32_16x16x32_bf16 v[16:19], v[150:153], v[70:73], v[16:19]
	v_mfma_f32_16x16x32_bf16 v[20:23], v[158:161], v[70:73], v[20:23]
	v_mfma_f32_16x16x32_bf16 v[24:27], v[150:153], v[88:91], v[24:27]
	v_mfma_f32_16x16x32_bf16 v[28:31], v[158:161], v[88:91], v[28:31]
	v_mfma_f32_16x16x32_bf16 v[170:173], v[146:149], v[114:117], v[186:189]
	v_mfma_f32_16x16x32_bf16 v[174:177], v[154:157], v[114:117], v[190:193]
	v_mfma_f32_16x16x32_bf16 v[32:35], v[150:153], v[230:233], v[32:35]
	v_mfma_f32_16x16x32_bf16 v[36:39], v[154:157], v[226:229], v[36:39]
	v_mfma_f32_16x16x32_bf16 v[170:173], v[150:153], v[118:121], v[170:173]
	v_mfma_f32_16x16x32_bf16 v[174:177], v[158:161], v[118:121], v[174:177]
	v_mfma_f32_16x16x32_bf16 v[146:149], v[158:161], v[230:233], v[36:39]
	v_mfma_f32_16x16x32_bf16 v[36:39], v[162:165], v[66:69], v[40:43]
	v_mfma_f32_16x16x32_bf16 v[150:153], v[166:169], v[70:73], v[36:39]
	v_mfma_f32_16x16x32_bf16 v[36:39], v[194:197], v[66:69], v[44:47]
	v_mfma_f32_16x16x32_bf16 v[44:47], v[198:201], v[70:73], v[36:39]
	v_mfma_f32_16x16x32_bf16 v[36:39], v[162:165], v[84:87], v[58:61]
	v_mfma_f32_16x16x32_bf16 v[154:157], v[166:169], v[88:91], v[36:39]
	v_mfma_f32_16x16x32_bf16 v[36:39], v[194:197], v[84:87], v[62:65]
	v_mfma_f32_16x16x32_bf16 v[158:161], v[198:201], v[88:91], v[36:39]
	v_mfma_f32_16x16x32_bf16 v[36:39], v[162:165], v[114:117], v[94:97]
	v_mfma_f32_16x16x32_bf16 v[178:181], v[166:169], v[118:121], v[36:39]
	v_mfma_f32_16x16x32_bf16 v[36:39], v[194:197], v[114:117], v[138:141]
	v_mfma_f32_16x16x32_bf16 v[138:141], v[198:201], v[118:121], v[36:39]
	v_mfma_f32_16x16x32_bf16 v[36:39], v[162:165], v[226:229], v[48:51]
	v_mfma_f32_16x16x32_bf16 v[162:165], v[166:169], v[230:233], v[36:39]
	v_mfma_f32_16x16x32_bf16 v[36:39], v[194:197], v[226:229], v[52:55]
	v_mfma_f32_16x16x32_bf16 v[166:169], v[198:201], v[230:233], v[36:39]
	s_setprio 0
	s_barrier
	ds_read_b128 v[48:51], v247
	ds_read_b128 v[64:67], v247 offset:1024
	ds_read_b128 v[182:185], v247 offset:2048
	ds_read_b128 v[186:189], v247 offset:3072
	ds_read_b128 v[190:193], v246
	ds_read_b128 v[194:197], v246 offset:1024
	ds_read_b128 v[198:201], v246 offset:2048
	ds_read_b128 v[226:229], v246 offset:3072
	s_mov_b32 m0, s57
	ds_read_b128 v[36:39], v203 offset:32768
	ds_read_b128 v[40:43], v203 offset:33792
	ds_read_b128 v[52:55], v203 offset:34816
	ds_read_b128 v[56:59], v203 offset:35840
	ds_read_b128 v[60:63], v203 offset:36864
	ds_read_b128 v[230:233], v203 offset:37888
	ds_read_b128 v[234:237], v203 offset:38912
	ds_read_b128 v[246:249], v203 offset:39936
	global_load_lds_dwordx4 v[12:13], off
	s_mov_b32 m0, s59
	s_nop 0
	global_load_lds_dwordx4 v[14:15], off
	s_waitcnt vmcnt(8)
	s_waitcnt lgkmcnt(0)
	s_barrier
; #define PG8_STAGE(bufoff, gbase, voff) do { _Pragma("unroll") for (int _i = 0; _i < 2; ++_i) \
;         __builtin_amdgcn_global_load_lds((const unsigned*)((const char*)(gbase) + (voff)[_i]), (PG8_LAS unsigned*)(lds + (bufoff) + ldsw + _i * 8192), 16, 0, 0); } while (0)
; #define PG8_LDA(dst, b, h) do { _Pragma("unroll") for (int m = 0; m < 4; ++m) _Pragma("unroll") for (int k = 0; k < 2; ++k) dst[m][k] = *(const PG8_LAS bf16x8*)(lds + PG8_SA(b, h) + aoff + m * 2048 + k * 1024); } while (0)
; #define PG8_LDB(dst, b, h) do { _Pragma("unroll") for (int n = 0; n < 2; ++n) _Pragma("unroll") for (int k = 0; k < 2; ++k) dst[n][k] = *(const PG8_LAS bf16x8*)(lds + PG8_SB(b, h) + boff + n * 2048 + k * 1024); } while (0)
; #define PG8_MMA(ai, bj, At, Bt) do { __builtin_amdgcn_s_setprio(1); _Pragma("unroll") for (int m = 0; m < 4; ++m) _Pragma("unroll") for (int n = 0; n < 2; ++n) _Pragma("unroll") for (int k = 0; k < 2; ++k) \
;         acc[ai][bj][m][n] = __builtin_amdgcn_mfma_f32_16x16x32_bf16(Bt[n][k], At[m][k], acc[ai][bj][m][n], 0, 0, 0); __builtin_amdgcn_s_setprio(0); } while (0)
; #define PG8_BAR __builtin_amdgcn_s_barrier()
; template <class Epi, class Sched, bool ALIGN_EPI = false, bool SP2 = false>
; __device__ __forceinline__ void gemm_phase(PG8_LAS unsigned char* lds, const Gemm g, const Sched& S, const Epi& E, const int wv0) {
;     ...
;             PG8_LDB(B0, 0, 0); PG8_LDB(B1, 0, 1); PG8_SCHED; PG8_LDA(At, 0, 0); PG8_STAGE(PG8_SA(1, 1), a1 + hstepA, voffA);
;             PG8_WAIT_V(8); PG8_WAIT_L(0); PG8_BAR; PG8_MMA(0, 0, At, B0); PG8_MMA(0, 1, At, B1); PG8_BAR; PG8_SCHED;
;             PG8_LDA(At, 0, 1); PG8_STAGE(PG8_SB(0, 0), b2, voffB); PG8_STAGE(PG8_SB(0, 1), b2 + hstepB, voffB); PG8_STAGE(PG8_SA(0, 0), a2, voffA);
;             PG8_WAIT_V(8); PG8_WAIT_L(0); PG8_BAR; PG8_MMA(1, 0, At, B0); PG8_MMA(1, 1, At, B1); PG8_BAR; PG8_SCHED;
;             PG8_LDB(B0, 1, 0); PG8_LDB(B1, 1, 1); PG8_SCHED; PG8_LDA(At, 1, 0); PG8_STAGE(PG8_SA(0, 1), a2 + hstepA, voffA);
;             PG8_WAIT_V(8); PG8_WAIT_L(0); PG8_BAR; PG8_MMA(0, 0, At, B0); PG8_MMA(0, 1, At, B1); PG8_BAR; PG8_SCHED;
;             PG8_LDA(At, 1, 1); PG8_STAGE(PG8_SB(1, 0), b3, voffB); PG8_STAGE(PG8_SB(1, 1), b3 + hstepB, voffB); PG8_STAGE(PG8_SA(1, 0), a3, voffA);
;             PG8_WAIT_V(8); PG8_WAIT_L(0); PG8_BAR; PG8_MMA(1, 0, At, B0); PG8_MMA(1, 1, At, B1); PG8_BAR; PG8_SCHED;
	s_setprio 1
	v_mfma_f32_16x16x32_bf16 v[12:15], v[48:51], v[36:39], v[98:101]
	v_mfma_f32_16x16x32_bf16 v[120:123], v[64:67], v[40:43], v[12:15]
	v_mfma_f32_16x16x32_bf16 v[12:15], v[182:185], v[36:39], v[102:105]
	v_mfma_f32_16x16x32_bf16 v[116:119], v[186:189], v[40:43], v[12:15]
	v_mfma_f32_16x16x32_bf16 v[12:15], v[48:51], v[52:55], v[106:109]
	v_mfma_f32_16x16x32_bf16 v[104:107], v[64:67], v[56:59], v[12:15]
	v_mfma_f32_16x16x32_bf16 v[12:15], v[182:185], v[52:55], v[110:113]
	v_mfma_f32_16x16x32_bf16 v[100:103], v[186:189], v[56:59], v[12:15]
	v_mfma_f32_16x16x32_bf16 v[12:15], v[48:51], v[60:63], v[238:241]
	v_mfma_f32_16x16x32_bf16 v[88:91], v[64:67], v[230:233], v[12:15]
	v_mfma_f32_16x16x32_bf16 v[12:15], v[182:185], v[60:63], v[242:245]
	v_mfma_f32_16x16x32_bf16 v[84:87], v[186:189], v[230:233], v[12:15]
	v_mfma_f32_16x16x32_bf16 v[12:15], v[48:51], v[234:237], v[124:127]
	v_mfma_f32_16x16x32_bf16 v[72:75], v[64:67], v[246:249], v[12:15]
	v_mfma_f32_16x16x32_bf16 v[12:15], v[182:185], v[234:237], v[130:133]
	v_mfma_f32_16x16x32_bf16 v[68:71], v[186:189], v[246:249], v[12:15]
	v_mfma_f32_16x16x32_bf16 v[12:15], v[190:193], v[36:39], v[134:137]
	v_mfma_f32_16x16x32_bf16 v[124:127], v[194:197], v[40:43], v[12:15]
	v_mfma_f32_16x16x32_bf16 v[12:15], v[198:201], v[36:39], v[206:209]
	v_mfma_f32_16x16x32_bf16 v[112:115], v[226:229], v[40:43], v[12:15]
	v_mfma_f32_16x16x32_bf16 v[12:15], v[190:193], v[52:55], v[210:213]
	v_mfma_f32_16x16x32_bf16 v[108:111], v[194:197], v[56:59], v[12:15]
	v_mfma_f32_16x16x32_bf16 v[12:15], v[198:201], v[52:55], v[214:217]
	v_mfma_f32_16x16x32_bf16 v[96:99], v[226:229], v[56:59], v[12:15]
	v_mfma_f32_16x16x32_bf16 v[12:15], v[190:193], v[60:63], v[76:79]
	v_mfma_f32_16x16x32_bf16 v[92:95], v[194:197], v[230:233], v[12:15]
	v_mfma_f32_16x16x32_bf16 v[12:15], v[198:201], v[60:63], v[80:83]
	v_mfma_f32_16x16x32_bf16 v[80:83], v[226:229], v[230:233], v[12:15]
	v_mfma_f32_16x16x32_bf16 v[12:15], v[190:193], v[234:237], v[218:221]
	v_mfma_f32_16x16x32_bf16 v[76:79], v[194:197], v[246:249], v[12:15]
	v_mfma_f32_16x16x32_bf16 v[12:15], v[198:201], v[234:237], v[222:225]
	v_mfma_f32_16x16x32_bf16 v[56:59], v[226:229], v[246:249], v[12:15]
	s_setprio 0
	s_barrier
	s_mov_b32 m0, s53
	s_nop 3
	ds_read_b128 v[12:15], v203 offset:49152
	ds_read_b128 v[130:133], v203 offset:50176
	ds_read_b128 v[134:137], v203 offset:51200
	ds_read_b128 v[206:209], v203 offset:52224
	ds_read_b128 v[210:213], v203 offset:53248
	ds_read_b128 v[214:217], v203 offset:54272
	ds_read_b128 v[218:221], v203 offset:55296
	ds_read_b128 v[222:225], v203 offset:56320
	global_load_lds_dwordx4 v[2:3], off
	s_mov_b32 m0, s55
	s_nop 0
	global_load_lds_dwordx4 v[4:5], off
	s_mov_b32 m0, s58
	s_nop 0
	global_load_lds_dwordx4 v[8:9], off
	s_mov_b32 m0, s60
	s_nop 0
	global_load_lds_dwordx4 v[10:11], off
	s_mov_b32 m0, s54
	s_nop 0
	global_load_lds_dwordx4 v[0:1], off
	s_mov_b32 m0, s56
	s_nop 0
	global_load_lds_dwordx4 v[6:7], off
	s_waitcnt vmcnt(8)
	s_waitcnt lgkmcnt(0)
	s_barrier
	s_setprio 1
	v_mfma_f32_16x16x32_bf16 v[0:3], v[48:51], v[12:15], v[16:19]
	v_mfma_f32_16x16x32_bf16 v[60:63], v[64:67], v[130:133], v[0:3]
	v_mfma_f32_16x16x32_bf16 v[0:3], v[182:185], v[12:15], v[20:23]
	v_mfma_f32_16x16x32_bf16 v[52:55], v[186:189], v[130:133], v[0:3]
	v_mfma_f32_16x16x32_bf16 v[0:3], v[48:51], v[134:137], v[24:27]
	v_mfma_f32_16x16x32_bf16 v[40:43], v[64:67], v[206:209], v[0:3]
	v_mfma_f32_16x16x32_bf16 v[0:3], v[182:185], v[134:137], v[28:31]
	v_mfma_f32_16x16x32_bf16 v[36:39], v[186:189], v[206:209], v[0:3]
	v_mfma_f32_16x16x32_bf16 v[0:3], v[48:51], v[210:213], v[170:173]
	v_mfma_f32_16x16x32_bf16 v[24:27], v[64:67], v[214:217], v[0:3]
	v_mfma_f32_16x16x32_bf16 v[0:3], v[182:185], v[210:213], v[174:177]
	v_mfma_f32_16x16x32_bf16 v[20:23], v[186:189], v[214:217], v[0:3]
	v_mfma_f32_16x16x32_bf16 v[0:3], v[48:51], v[218:221], v[32:35]
	v_mfma_f32_16x16x32_bf16 v[8:11], v[64:67], v[222:225], v[0:3]
	v_mfma_f32_16x16x32_bf16 v[0:3], v[182:185], v[218:221], v[146:149]
	v_mfma_f32_16x16x32_bf16 v[4:7], v[186:189], v[222:225], v[0:3]
	v_mfma_f32_16x16x32_bf16 v[0:3], v[190:193], v[12:15], v[150:153]
	v_mfma_f32_16x16x32_bf16 v[64:67], v[194:197], v[130:133], v[0:3]
	v_mfma_f32_16x16x32_bf16 v[0:3], v[198:201], v[12:15], v[44:47]
	v_mfma_f32_16x16x32_bf16 v[48:51], v[226:229], v[130:133], v[0:3]
	v_mfma_f32_16x16x32_bf16 v[0:3], v[190:193], v[134:137], v[154:157]
	v_mfma_f32_16x16x32_bf16 v[44:47], v[194:197], v[206:209], v[0:3]
	v_mfma_f32_16x16x32_bf16 v[0:3], v[198:201], v[134:137], v[158:161]
	v_mfma_f32_16x16x32_bf16 v[32:35], v[226:229], v[206:209], v[0:3]
	v_mfma_f32_16x16x32_bf16 v[0:3], v[190:193], v[210:213], v[178:181]
	v_mfma_f32_16x16x32_bf16 v[28:31], v[194:197], v[214:217], v[0:3]
	v_mfma_f32_16x16x32_bf16 v[0:3], v[198:201], v[210:213], v[138:141]
	v_mfma_f32_16x16x32_bf16 v[16:19], v[226:229], v[214:217], v[0:3]
	v_mfma_f32_16x16x32_bf16 v[0:3], v[190:193], v[218:221], v[162:165]
	v_mfma_f32_16x16x32_bf16 v[12:15], v[194:197], v[222:225], v[0:3]
	v_mfma_f32_16x16x32_bf16 v[0:3], v[198:201], v[218:221], v[166:169]
	v_mfma_f32_16x16x32_bf16 v[0:3], v[226:229], v[222:225], v[0:3]
	s_setprio 0
	s_barrier
	s_waitcnt vmcnt(0)
	s_cmpk_gt_u32 s52, 0xff
	s_cbranch_scc1 .LBB0_360
	s_barrier

; #define PG8_STAGE(bufoff, gbase, voff) do { _Pragma("unroll") for (int _i = 0; _i < 2; ++_i) \
;         __builtin_amdgcn_global_load_lds((const unsigned*)((const char*)(gbase) + (voff)[_i]), (PG8_LAS unsigned*)(lds + (bufoff) + ldsw + _i * 8192), 16, 0, 0); } while (0)
; #define PG8_LDA(dst, b, h) do { _Pragma("unroll") for (int m = 0; m < 4; ++m) _Pragma("unroll") for (int k = 0; k < 2; ++k) dst[m][k] = *(const PG8_LAS bf16x8*)(lds + PG8_SA(b, h) + aoff + m * 2048 + k * 1024); } while (0)
; #define PG8_LDB(dst, b, h) do { _Pragma("unroll") for (int n = 0; n < 2; ++n) _Pragma("unroll") for (int k = 0; k < 2; ++k) dst[n][k] = *(const PG8_LAS bf16x8*)(lds + PG8_SB(b, h) + boff + n * 2048 + k * 1024); } while (0)
; template <class Epi, class Sched, bool ALIGN_EPI = false, bool SP2 = false>
; __device__ __forceinline__ void gemm_phase(PG8_LAS unsigned char* lds, const Gemm g, const Sched& S, const Epi& E, const int wv0) {
;     ...
;         PG8_STAGE(PG8_SB(0, 0), cB, voffB); PG8_STAGE(PG8_SB(0, 1), cB + hstepB, voffB); PG8_STAGE(PG8_SA(0, 0), cA, voffA); PG8_STAGE(PG8_SA(0, 1), cA + hstepA, voffA);
;         if (wr == 1) PG8_BAR;
;         PG8_WAIT_V(2); PG8_BAR;
;         PG8_STAGE(PG8_SB(1, 0), cB + kstep, voffB); PG8_STAGE(PG8_SA(1, 0), cA + kstep, voffA); PG8_STAGE(PG8_SB(1, 1), cB + hstepB + kstep, voffB);
;         PG8_WAIT_V(6); PG8_BAR;
;     ...
;             PG8_LDB(B0, 0, 0); PG8_LDB(B1, 0, 1); PG8_SCHED; PG8_LDA(At, 0, 0); PG8_STAGE(PG8_SA(1, 1), a1 + hstepA, voffA);
;             PG8_WAIT_V(8); PG8_WAIT_L(0); PG8_BAR; PG8_MMA(0, 0, At, B0); PG8_MMA(0, 1, At, B1); PG8_BAR; PG8_SCHED;
;             PG8_LDA(At, 0, 1); PG8_STAGE(PG8_SB(0, 0), b2, voffB); PG8_STAGE(PG8_SB(0, 1), b2 + hstepB, voffB); PG8_STAGE(PG8_SA(0, 0), a2, voffA);
;             PG8_WAIT_V(8); PG8_WAIT_L(0); PG8_BAR; PG8_MMA(1, 0, At, B0); PG8_MMA(1, 1, At, B1); PG8_BAR; PG8_SCHED;
;             PG8_LDB(B0, 1, 0); PG8_LDB(B1, 1, 1); PG8_SCHED; PG8_LDA(At, 1, 0); PG8_STAGE(PG8_SA(0, 1), a2 + hstepA, voffA);
;             PG8_WAIT_V(8); PG8_WAIT_L(0); PG8_BAR; PG8_MMA(0, 0, At, B0); PG8_MMA(0, 1, At, B1); PG8_BAR; PG8_SCHED;
;             PG8_LDA(At, 1, 1); PG8_STAGE(PG8_SB(1, 0), b3, voffB); PG8_STAGE(PG8_SB(1, 1), b3 + hstepB, voffB); PG8_STAGE(PG8_SA(1, 0), a3, voffA);
;             PG8_WAIT_V(8); PG8_WAIT_L(0); PG8_BAR; PG8_MMA(1, 0, At, B0); PG8_MMA(1, 1, At, B1); PG8_BAR; PG8_SCHED;
.LBB0_378:
	s_lshl_b32 s50, s50, 5
	s_add_i32 s51, s36, s63
	s_and_b32 s50, s50, 0x60
	v_lshl_add_u64 v[2:3], v[26:27], 0, s[8:9]
	s_mov_b32 m0, s51
	s_add_i32 s53, s51, 0x2000
	s_lshl_b32 s62, s61, 13
	s_lshl_b32 s66, s50, 7
	s_waitcnt vmcnt(2)
	s_barrier
	global_load_lds_dwordx4 v[2:3], off
	v_lshl_add_u64 v[4:5], v[28:29], 0, s[8:9]
	s_mov_b32 m0, s53
	s_add_i32 s52, s59, 0x8000
	s_add_i32 s54, s59, 0xa000
	global_load_lds_dwordx4 v[4:5], off
	v_lshl_add_u64 v[0:1], v[20:21], 0, s[8:9]
	s_mov_b32 m0, s52
	s_add_u32 s64, s22, 0x10080
	global_load_lds_dwordx4 v[0:1], off
	v_lshl_add_u64 v[6:7], v[22:23], 0, s[8:9]
	s_mov_b32 m0, s54
	s_addc_u32 s65, s23, 0
	s_add_i32 s57, s37, s63
	global_load_lds_dwordx4 v[6:7], off
	v_lshl_add_u64 v[8:9], s[64:65], 0, v[128:129]
	s_mov_b32 m0, s57
	s_add_i32 s58, s57, 0x2000
	global_load_lds_dwordx4 v[8:9], off
	v_lshl_add_u64 v[10:11], s[64:65], 0, v[32:33]
	s_mov_b32 m0, s58
	v_lshrrev_b32_e32 v37, 1, v34
	global_load_lds_dwordx4 v[10:11], off
	v_and_b32_e32 v37, 24, v37
	v_and_b32_e32 v35, 15, v34
	v_lshlrev_b32_e32 v38, 1, v37
	v_lshlrev_b32_e32 v34, 2, v34
	v_lshl_or_b32 v36, s61, 6, v35
	v_lshl_or_b32 v35, v35, 6, v38
	v_and_b32_e32 v34, 32, v34
	v_bitop3_b32 v70, v35, s66, v34 bitop3:0xde
	v_add_u32_e32 v127, s48, v70
	s_waitcnt vmcnt(6)
	s_barrier
	v_add_u32_e32 v126, s47, v70
	ds_read_b128 v[38:41], v127
	ds_read_b128 v[42:45], v127 offset:1024
	ds_read_b128 v[46:49], v127 offset:2048
	ds_read_b128 v[50:53], v127 offset:3072
	ds_read_b128 v[54:57], v126
	ds_read_b128 v[58:61], v126 offset:1024
	ds_read_b128 v[62:65], v126 offset:2048
	ds_read_b128 v[66:69], v126 offset:3072
	v_bitop3_b32 v34, v35, s62, v34 bitop3:0xde
	v_add_u32_e32 v143, 0, v34
	v_add_u32_e32 v238, s37, v70
	v_add_u32_e32 v239, s36, v70
	s_add_u32 s66, s20, 0x40080
	s_addc_u32 s67, s21, 0
	s_add_i32 s64, s59, 0xc000
	v_lshl_add_u64 v[34:35], s[66:67], 0, v[16:17]
	s_mov_b32 m0, s64
	s_add_i32 s61, s59, 0xe000
	ds_read_b128 v[70:73], v143
	ds_read_b128 v[74:77], v143 offset:1024
	ds_read_b128 v[78:81], v143 offset:2048
	ds_read_b128 v[82:85], v143 offset:3072
	ds_read_b128 v[86:89], v143 offset:4096
	ds_read_b128 v[90:93], v143 offset:5120
	ds_read_b128 v[94:97], v143 offset:6144
	ds_read_b128 v[98:101], v143 offset:7168
	global_load_lds_dwordx4 v[34:35], off
	v_lshl_add_u64 v[34:35], s[66:67], 0, v[30:31]
	s_mov_b32 m0, s61
	s_nop 0
	global_load_lds_dwordx4 v[34:35], off
	s_waitcnt vmcnt(8)
	s_waitcnt lgkmcnt(0)
	s_barrier
	s_setprio 1
	v_mfma_f32_16x16x32_bf16 v[102:105], v[38:41], v[70:73], 0
	v_mfma_f32_16x16x32_bf16 v[106:109], v[46:49], v[70:73], 0
	v_mfma_f32_16x16x32_bf16 v[110:113], v[38:41], v[78:81], 0
	v_mfma_f32_16x16x32_bf16 v[114:117], v[46:49], v[78:81], 0
	v_mfma_f32_16x16x32_bf16 v[118:121], v[38:41], v[86:89], 0
	v_mfma_f32_16x16x32_bf16 v[122:125], v[46:49], v[86:89], 0
	v_mfma_f32_16x16x32_bf16 v[130:133], v[38:41], v[94:97], 0
	v_mfma_f32_16x16x32_bf16 v[134:137], v[46:49], v[94:97], 0
	v_mfma_f32_16x16x32_bf16 v[102:105], v[42:45], v[74:77], v[102:105]
	v_mfma_f32_16x16x32_bf16 v[106:109], v[50:53], v[74:77], v[106:109]
	v_mfma_f32_16x16x32_bf16 v[110:113], v[42:45], v[82:85], v[110:113]
	v_mfma_f32_16x16x32_bf16 v[114:117], v[50:53], v[82:85], v[114:117]
	v_mfma_f32_16x16x32_bf16 v[118:121], v[42:45], v[90:93], v[118:121]
	v_mfma_f32_16x16x32_bf16 v[122:125], v[50:53], v[90:93], v[122:125]
	v_mfma_f32_16x16x32_bf16 v[130:133], v[42:45], v[98:101], v[130:133]
	v_mfma_f32_16x16x32_bf16 v[134:137], v[50:53], v[98:101], v[134:137]
	v_mfma_f32_16x16x32_bf16 v[138:141], v[54:57], v[70:73], 0
	v_mfma_f32_16x16x32_bf16 v[70:73], v[62:65], v[70:73], 0
	v_mfma_f32_16x16x32_bf16 v[138:141], v[58:61], v[74:77], v[138:141]
	v_mfma_f32_16x16x32_bf16 v[70:73], v[66:69], v[74:77], v[70:73]
	v_mfma_f32_16x16x32_bf16 v[74:77], v[54:57], v[78:81], 0
	v_mfma_f32_16x16x32_bf16 v[78:81], v[62:65], v[78:81], 0
	v_mfma_f32_16x16x32_bf16 v[74:77], v[58:61], v[82:85], v[74:77]
	v_mfma_f32_16x16x32_bf16 v[78:81], v[66:69], v[82:85], v[78:81]
	v_mfma_f32_16x16x32_bf16 v[82:85], v[54:57], v[86:89], 0
	v_mfma_f32_16x16x32_bf16 v[86:89], v[62:65], v[86:89], 0
	v_mfma_f32_16x16x32_bf16 v[82:85], v[58:61], v[90:93], v[82:85]
	v_mfma_f32_16x16x32_bf16 v[86:89], v[66:69], v[90:93], v[86:89]
	v_mfma_f32_16x16x32_bf16 v[90:93], v[54:57], v[94:97], 0
	v_mfma_f32_16x16x32_bf16 v[94:97], v[62:65], v[94:97], 0
	v_mfma_f32_16x16x32_bf16 v[90:93], v[58:61], v[98:101], v[90:93]
	v_mfma_f32_16x16x32_bf16 v[94:97], v[66:69], v[98:101], v[94:97]
	s_setprio 0
	s_barrier
	s_add_i32 s48, s48, s63
	s_add_i32 s62, s48, 0x2000
	v_lshl_add_u64 v[34:35], v[26:27], 0, s[10:11]
	s_mov_b32 m0, s48
	s_add_u32 s66, s22, 0x10100
	ds_read_b128 v[98:101], v143 offset:16384
	ds_read_b128 v[144:147], v143 offset:17408
	ds_read_b128 v[148:151], v143 offset:18432
	ds_read_b128 v[152:155], v143 offset:19456
	ds_read_b128 v[156:159], v143 offset:20480
	ds_read_b128 v[160:163], v143 offset:21504
	ds_read_b128 v[164:167], v143 offset:22528
	ds_read_b128 v[168:171], v143 offset:23552
	global_load_lds_dwordx4 v[34:35], off
	v_lshl_add_u64 v[34:35], v[28:29], 0, s[10:11]
	s_mov_b32 m0, s62
	s_addc_u32 s67, s23, 0
	s_add_i32 s47, s47, s63
	global_load_lds_dwordx4 v[34:35], off
	v_lshl_add_u64 v[34:35], s[66:67], 0, v[128:129]
	s_mov_b32 m0, s47
	s_add_i32 s63, s47, 0x2000
	global_load_lds_dwordx4 v[34:35], off
	v_lshl_add_u64 v[34:35], s[66:67], 0, v[32:33]
	s_mov_b32 m0, s63
	s_nop 0
	global_load_lds_dwordx4 v[34:35], off
	v_lshl_add_u64 v[34:35], v[20:21], 0, s[10:11]
	s_mov_b32 m0, s59
	s_nop 0
	global_load_lds_dwordx4 v[34:35], off
	v_lshl_add_u64 v[34:35], v[22:23], 0, s[10:11]
	s_mov_b32 m0, s60
	s_nop 0
	global_load_lds_dwordx4 v[34:35], off
	s_waitcnt vmcnt(8)
	s_waitcnt lgkmcnt(0)
	s_barrier
; #define PG8_STAGE(bufoff, gbase, voff) do { _Pragma("unroll") for (int _i = 0; _i < 2; ++_i) \
;         __builtin_amdgcn_global_load_lds((const unsigned*)((const char*)(gbase) + (voff)[_i]), (PG8_LAS unsigned*)(lds + (bufoff) + ldsw + _i * 8192), 16, 0, 0); } while (0)
; #define PG8_LDA(dst, b, h) do { _Pragma("unroll") for (int m = 0; m < 4; ++m) _Pragma("unroll") for (int k = 0; k < 2; ++k) dst[m][k] = *(const PG8_LAS bf16x8*)(lds + PG8_SA(b, h) + aoff + m * 2048 + k * 1024); } while (0)
; #define PG8_LDB(dst, b, h) do { _Pragma("unroll") for (int n = 0; n < 2; ++n) _Pragma("unroll") for (int k = 0; k < 2; ++k) dst[n][k] = *(const PG8_LAS bf16x8*)(lds + PG8_SB(b, h) + boff + n * 2048 + k * 1024); } while (0)
; template <class Epi, class Sched, bool ALIGN_EPI = false, bool SP2 = false>
; __device__ __forceinline__ void gemm_phase(PG8_LAS unsigned char* lds, const Gemm g, const Sched& S, const Epi& E, const int wv0) {
;     ...
;         for (int t = 0; t < nt; t += 2) {
;             const bool last = (t == nt - 2);
;             const char* a1 = cA + (size_t)(t + 1) * kstep;
;             const char* a2 = last ? nA : cA + (size_t)(t + 2) * kstep; const char* b2 = last ? nB : cB + (size_t)(t + 2) * kstep;
;             const char* a3 = a2 + kstep; const char* b3 = b2 + kstep;
;             if constexpr (SP2) {
;             PG8_LDB(B0, 0, 0); PG8_LDB(B1, 0, 1); PG8_SCHED; PG8_LDA(At, 0, 0); PG8_STAGE(PG8_SA(1, 1), a1 + hstepA, voffA);
;             PG8_WAIT_V(8); PG8_WAIT_L(0); PG8_BAR; PG8_MMA(0, 0, At, B0); PG8_MMA(0, 1, At, B1); PG8_BAR; PG8_SCHED;
;             PG8_LDA(At, 0, 1); PG8_STAGE(PG8_SB(0, 0), b2, voffB); PG8_STAGE(PG8_SB(0, 1), b2 + hstepB, voffB); PG8_STAGE(PG8_SA(0, 0), a2, voffA);
;             PG8_WAIT_V(8); PG8_WAIT_L(0); PG8_BAR; PG8_MMA(1, 0, At, B0); PG8_MMA(1, 1, At, B1); PG8_BAR; PG8_SCHED;
;             PG8_LDB(B0, 1, 0); PG8_LDB(B1, 1, 1); PG8_SCHED; PG8_LDA(At, 1, 0); PG8_STAGE(PG8_SA(0, 1), a2 + hstepA, voffA);
;             PG8_WAIT_V(8); PG8_WAIT_L(0); PG8_BAR; PG8_MMA(0, 0, At, B0); PG8_MMA(0, 1, At, B1); PG8_BAR; PG8_SCHED;
;             PG8_LDA(At, 1, 1); PG8_STAGE(PG8_SB(1, 0), b3, voffB); PG8_STAGE(PG8_SB(1, 1), b3 + hstepB, voffB); PG8_STAGE(PG8_SA(1, 0), a3, voffA);
;             PG8_WAIT_V(8); PG8_WAIT_L(0); PG8_BAR; PG8_MMA(1, 0, At, B0); PG8_MMA(1, 1, At, B1); PG8_BAR; PG8_SCHED;
	s_setprio 1
	v_mfma_f32_16x16x32_bf16 v[172:175], v[38:41], v[98:101], 0
	v_mfma_f32_16x16x32_bf16 v[180:183], v[38:41], v[148:151], 0
	v_mfma_f32_16x16x32_bf16 v[188:191], v[38:41], v[156:159], 0
	v_mfma_f32_16x16x32_bf16 v[38:41], v[38:41], v[164:167], 0
	v_mfma_f32_16x16x32_bf16 v[172:175], v[42:45], v[144:147], v[172:175]
	v_mfma_f32_16x16x32_bf16 v[176:179], v[46:49], v[98:101], 0
	v_mfma_f32_16x16x32_bf16 v[180:183], v[42:45], v[152:155], v[180:183]
	v_mfma_f32_16x16x32_bf16 v[184:187], v[46:49], v[148:151], 0
	v_mfma_f32_16x16x32_bf16 v[188:191], v[42:45], v[160:163], v[188:191]
	v_mfma_f32_16x16x32_bf16 v[192:195], v[46:49], v[156:159], 0
	v_mfma_f32_16x16x32_bf16 v[38:41], v[42:45], v[168:171], v[38:41]
	v_mfma_f32_16x16x32_bf16 v[42:45], v[46:49], v[164:167], 0
	v_mfma_f32_16x16x32_bf16 v[176:179], v[50:53], v[144:147], v[176:179]
	v_mfma_f32_16x16x32_bf16 v[184:187], v[50:53], v[152:155], v[184:187]
	v_mfma_f32_16x16x32_bf16 v[192:195], v[50:53], v[160:163], v[192:195]
	v_mfma_f32_16x16x32_bf16 v[42:45], v[50:53], v[168:171], v[42:45]
	v_mfma_f32_16x16x32_bf16 v[46:49], v[54:57], v[98:101], 0
	v_mfma_f32_16x16x32_bf16 v[50:53], v[62:65], v[98:101], 0
	v_mfma_f32_16x16x32_bf16 v[46:49], v[58:61], v[144:147], v[46:49]
	v_mfma_f32_16x16x32_bf16 v[50:53], v[66:69], v[144:147], v[50:53]
	v_mfma_f32_16x16x32_bf16 v[98:101], v[54:57], v[148:151], 0
	v_mfma_f32_16x16x32_bf16 v[144:147], v[62:65], v[148:151], 0
	v_mfma_f32_16x16x32_bf16 v[148:151], v[54:57], v[156:159], 0
	v_mfma_f32_16x16x32_bf16 v[54:57], v[54:57], v[164:167], 0
	v_mfma_f32_16x16x32_bf16 v[98:101], v[58:61], v[152:155], v[98:101]
	v_mfma_f32_16x16x32_bf16 v[144:147], v[66:69], v[152:155], v[144:147]
	v_mfma_f32_16x16x32_bf16 v[148:151], v[58:61], v[160:163], v[148:151]
	v_mfma_f32_16x16x32_bf16 v[152:155], v[62:65], v[156:159], 0
	v_mfma_f32_16x16x32_bf16 v[54:57], v[58:61], v[168:171], v[54:57]
	v_mfma_f32_16x16x32_bf16 v[58:61], v[62:65], v[164:167], 0
	v_mfma_f32_16x16x32_bf16 v[152:155], v[66:69], v[160:163], v[152:155]
	v_mfma_f32_16x16x32_bf16 v[58:61], v[66:69], v[168:171], v[58:61]
	s_setprio 0
	s_barrier
	ds_read_b128 v[62:65], v239
	ds_read_b128 v[66:69], v239 offset:1024
	ds_read_b128 v[156:159], v239 offset:2048
	ds_read_b128 v[160:163], v239 offset:3072
	ds_read_b128 v[164:167], v238
	ds_read_b128 v[168:171], v238 offset:1024
	ds_read_b128 v[196:199], v238 offset:2048
	ds_read_b128 v[200:203], v238 offset:3072
	s_add_u32 s66, s20, 0x40100
	s_addc_u32 s67, s21, 0
	s_mov_b32 m0, s55
	v_lshl_add_u64 v[34:35], s[66:67], 0, v[16:17]
	ds_read_b128 v[206:209], v143 offset:32768
	ds_read_b128 v[210:213], v143 offset:33792
	ds_read_b128 v[214:217], v143 offset:34816
	ds_read_b128 v[218:221], v143 offset:35840
	ds_read_b128 v[222:225], v143 offset:36864
	ds_read_b128 v[226:229], v143 offset:37888
	ds_read_b128 v[230:233], v143 offset:38912
	ds_read_b128 v[234:237], v143 offset:39936
	global_load_lds_dwordx4 v[34:35], off
	v_lshl_add_u64 v[34:35], s[66:67], 0, v[30:31]
	s_mov_b32 m0, s56
	s_nop 0
	global_load_lds_dwordx4 v[34:35], off
	s_waitcnt vmcnt(8)
	s_waitcnt lgkmcnt(0)
	s_barrier
	s_setprio 1
	v_mfma_f32_16x16x32_bf16 v[102:105], v[62:65], v[206:209], v[102:105]
	v_mfma_f32_16x16x32_bf16 v[106:109], v[156:159], v[206:209], v[106:109]
	v_mfma_f32_16x16x32_bf16 v[110:113], v[62:65], v[214:217], v[110:113]
	v_mfma_f32_16x16x32_bf16 v[114:117], v[156:159], v[214:217], v[114:117]
	v_mfma_f32_16x16x32_bf16 v[118:121], v[62:65], v[222:225], v[118:121]
	v_mfma_f32_16x16x32_bf16 v[122:125], v[156:159], v[222:225], v[122:125]
	v_mfma_f32_16x16x32_bf16 v[130:133], v[62:65], v[230:233], v[130:133]
	v_mfma_f32_16x16x32_bf16 v[134:137], v[156:159], v[230:233], v[134:137]
	v_mfma_f32_16x16x32_bf16 v[102:105], v[66:69], v[210:213], v[102:105]
	v_mfma_f32_16x16x32_bf16 v[106:109], v[160:163], v[210:213], v[106:109]
	v_mfma_f32_16x16x32_bf16 v[110:113], v[66:69], v[218:221], v[110:113]
	v_mfma_f32_16x16x32_bf16 v[114:117], v[160:163], v[218:221], v[114:117]
	v_mfma_f32_16x16x32_bf16 v[118:121], v[66:69], v[226:229], v[118:121]
	v_mfma_f32_16x16x32_bf16 v[122:125], v[160:163], v[226:229], v[122:125]
	v_mfma_f32_16x16x32_bf16 v[130:133], v[66:69], v[234:237], v[130:133]
	v_mfma_f32_16x16x32_bf16 v[134:137], v[160:163], v[234:237], v[134:137]
	v_mfma_f32_16x16x32_bf16 v[138:141], v[164:167], v[206:209], v[138:141]
	v_mfma_f32_16x16x32_bf16 v[70:73], v[196:199], v[206:209], v[70:73]
	v_mfma_f32_16x16x32_bf16 v[74:77], v[164:167], v[214:217], v[74:77]
	v_mfma_f32_16x16x32_bf16 v[78:81], v[196:199], v[214:217], v[78:81]
	v_mfma_f32_16x16x32_bf16 v[82:85], v[164:167], v[222:225], v[82:85]
	v_mfma_f32_16x16x32_bf16 v[86:89], v[196:199], v[222:225], v[86:89]
	v_mfma_f32_16x16x32_bf16 v[90:93], v[164:167], v[230:233], v[90:93]
	v_mfma_f32_16x16x32_bf16 v[94:97], v[196:199], v[230:233], v[94:97]
	v_mfma_f32_16x16x32_bf16 v[138:141], v[168:171], v[210:213], v[138:141]
	v_mfma_f32_16x16x32_bf16 v[70:73], v[200:203], v[210:213], v[70:73]
	v_mfma_f32_16x16x32_bf16 v[74:77], v[168:171], v[218:221], v[74:77]
	v_mfma_f32_16x16x32_bf16 v[78:81], v[200:203], v[218:221], v[78:81]
	v_mfma_f32_16x16x32_bf16 v[82:85], v[168:171], v[226:229], v[82:85]
	v_mfma_f32_16x16x32_bf16 v[86:89], v[200:203], v[226:229], v[86:89]
	v_mfma_f32_16x16x32_bf16 v[90:93], v[168:171], v[234:237], v[90:93]
	v_mfma_f32_16x16x32_bf16 v[94:97], v[200:203], v[234:237], v[94:97]
	s_setprio 0
	s_barrier
; #define PG8_STAGE(bufoff, gbase, voff) do { _Pragma("unroll") for (int _i = 0; _i < 2; ++_i) \
;         __builtin_amdgcn_global_load_lds((const unsigned*)((const char*)(gbase) + (voff)[_i]), (PG8_LAS unsigned*)(lds + (bufoff) + ldsw + _i * 8192), 16, 0, 0); } while (0)
; #define PG8_LDA(dst, b, h) do { _Pragma("unroll") for (int m = 0; m < 4; ++m) _Pragma("unroll") for (int k = 0; k < 2; ++k) dst[m][k] = *(const PG8_LAS bf16x8*)(lds + PG8_SA(b, h) + aoff + m * 2048 + k * 1024); } while (0)
; #define PG8_LDB(dst, b, h) do { _Pragma("unroll") for (int n = 0; n < 2; ++n) _Pragma("unroll") for (int k = 0; k < 2; ++k) dst[n][k] = *(const PG8_LAS bf16x8*)(lds + PG8_SB(b, h) + boff + n * 2048 + k * 1024); } while (0)
; template <class Epi, class Sched, bool ALIGN_EPI = false, bool SP2 = false>
; __device__ __forceinline__ void gemm_phase(PG8_LAS unsigned char* lds, const Gemm g, const Sched& S, const Epi& E, const int wv0) {
;     ...
;         for (int t = 0; t < nt; t += 2) {
;             const bool last = (t == nt - 2);
;             const char* a1 = cA + (size_t)(t + 1) * kstep;
;             const char* a2 = last ? nA : cA + (size_t)(t + 2) * kstep; const char* b2 = last ? nB : cB + (size_t)(t + 2) * kstep;
;             const char* a3 = a2 + kstep; const char* b3 = b2 + kstep;
;             if constexpr (SP2) {
;             PG8_LDB(B0, 0, 0); PG8_LDB(B1, 0, 1); PG8_SCHED; PG8_LDA(At, 0, 0); PG8_STAGE(PG8_SA(1, 1), a1 + hstepA, voffA);
;             PG8_WAIT_V(8); PG8_WAIT_L(0); PG8_BAR; PG8_MMA(0, 0, At, B0); PG8_MMA(0, 1, At, B1); PG8_BAR; PG8_SCHED;
;             PG8_LDA(At, 0, 1); PG8_STAGE(PG8_SB(0, 0), b2, voffB); PG8_STAGE(PG8_SB(0, 1), b2 + hstepB, voffB); PG8_STAGE(PG8_SA(0, 0), a2, voffA);
;             PG8_WAIT_V(8); PG8_WAIT_L(0); PG8_BAR; PG8_MMA(1, 0, At, B0); PG8_MMA(1, 1, At, B1); PG8_BAR; PG8_SCHED;
;             PG8_LDB(B0, 1, 0); PG8_LDB(B1, 1, 1); PG8_SCHED; PG8_LDA(At, 1, 0); PG8_STAGE(PG8_SA(0, 1), a2 + hstepA, voffA);
;             PG8_WAIT_V(8); PG8_WAIT_L(0); PG8_BAR; PG8_MMA(0, 0, At, B0); PG8_MMA(0, 1, At, B1); PG8_BAR; PG8_SCHED;
;             PG8_LDA(At, 1, 1); PG8_STAGE(PG8_SB(1, 0), b3, voffB); PG8_STAGE(PG8_SB(1, 1), b3 + hstepB, voffB); PG8_STAGE(PG8_SA(1, 0), a3, voffA);
;             PG8_WAIT_V(8); PG8_WAIT_L(0); PG8_BAR; PG8_MMA(1, 0, At, B0); PG8_MMA(1, 1, At, B1); PG8_BAR; PG8_SCHED;
	s_mov_b32 m0, s51
	v_lshl_add_u64 v[34:35], v[26:27], 0, s[12:13]
	s_add_u32 s22, s22, 0x10180
	ds_read_b128 v[206:209], v143 offset:49152
	ds_read_b128 v[210:213], v143 offset:50176
	ds_read_b128 v[214:217], v143 offset:51200
	ds_read_b128 v[218:221], v143 offset:52224
	ds_read_b128 v[222:225], v143 offset:53248
	ds_read_b128 v[226:229], v143 offset:54272
	ds_read_b128 v[230:233], v143 offset:55296
	ds_read_b128 v[234:237], v143 offset:56320
	global_load_lds_dwordx4 v[34:35], off
	v_lshl_add_u64 v[34:35], v[28:29], 0, s[12:13]
	s_mov_b32 m0, s53
	s_addc_u32 s23, s23, 0
	global_load_lds_dwordx4 v[34:35], off
	v_lshl_add_u64 v[34:35], s[22:23], 0, v[128:129]
	s_mov_b32 m0, s57
	v_lshl_add_u64 v[32:33], s[22:23], 0, v[32:33]
	global_load_lds_dwordx4 v[34:35], off
	s_mov_b32 m0, s58
	s_nop 0
	global_load_lds_dwordx4 v[32:33], off
	v_lshl_add_u64 v[32:33], v[20:21], 0, s[12:13]
	s_mov_b32 m0, s52
	s_nop 0
	global_load_lds_dwordx4 v[32:33], off
	v_lshl_add_u64 v[32:33], v[22:23], 0, s[12:13]
	s_mov_b32 m0, s54
	s_nop 0
	global_load_lds_dwordx4 v[32:33], off
	s_waitcnt vmcnt(8)
	s_waitcnt lgkmcnt(0)
	s_barrier
	s_setprio 1
	v_mfma_f32_16x16x32_bf16 v[32:35], v[62:65], v[206:209], v[172:175]
	v_mfma_f32_16x16x32_bf16 v[172:175], v[156:159], v[206:209], v[176:179]
	v_mfma_f32_16x16x32_bf16 v[176:179], v[62:65], v[214:217], v[180:183]
	v_mfma_f32_16x16x32_bf16 v[180:183], v[156:159], v[214:217], v[184:187]
	v_mfma_f32_16x16x32_bf16 v[184:187], v[62:65], v[222:225], v[188:191]
	v_mfma_f32_16x16x32_bf16 v[188:191], v[156:159], v[222:225], v[192:195]
	v_mfma_f32_16x16x32_bf16 v[38:41], v[62:65], v[230:233], v[38:41]
	v_mfma_f32_16x16x32_bf16 v[42:45], v[156:159], v[230:233], v[42:45]
	v_mfma_f32_16x16x32_bf16 v[32:35], v[66:69], v[210:213], v[32:35]
	v_mfma_f32_16x16x32_bf16 v[172:175], v[160:163], v[210:213], v[172:175]
	v_mfma_f32_16x16x32_bf16 v[176:179], v[66:69], v[218:221], v[176:179]
	v_mfma_f32_16x16x32_bf16 v[180:183], v[160:163], v[218:221], v[180:183]
	v_mfma_f32_16x16x32_bf16 v[184:187], v[66:69], v[226:229], v[184:187]
	v_mfma_f32_16x16x32_bf16 v[188:191], v[160:163], v[226:229], v[188:191]
	v_mfma_f32_16x16x32_bf16 v[38:41], v[66:69], v[234:237], v[38:41]
	v_mfma_f32_16x16x32_bf16 v[42:45], v[160:163], v[234:237], v[42:45]
	v_mfma_f32_16x16x32_bf16 v[46:49], v[164:167], v[206:209], v[46:49]
	v_mfma_f32_16x16x32_bf16 v[50:53], v[196:199], v[206:209], v[50:53]
	v_mfma_f32_16x16x32_bf16 v[62:65], v[164:167], v[214:217], v[98:101]
	v_mfma_f32_16x16x32_bf16 v[66:69], v[196:199], v[214:217], v[144:147]
	v_mfma_f32_16x16x32_bf16 v[98:101], v[164:167], v[222:225], v[148:151]
	v_mfma_f32_16x16x32_bf16 v[144:147], v[196:199], v[222:225], v[152:155]
	v_mfma_f32_16x16x32_bf16 v[54:57], v[164:167], v[230:233], v[54:57]
	v_mfma_f32_16x16x32_bf16 v[58:61], v[196:199], v[230:233], v[58:61]
	v_mfma_f32_16x16x32_bf16 v[46:49], v[168:171], v[210:213], v[46:49]
	v_mfma_f32_16x16x32_bf16 v[50:53], v[200:203], v[210:213], v[50:53]
	v_mfma_f32_16x16x32_bf16 v[62:65], v[168:171], v[218:221], v[62:65]
	v_mfma_f32_16x16x32_bf16 v[66:69], v[200:203], v[218:221], v[66:69]
	v_mfma_f32_16x16x32_bf16 v[98:101], v[168:171], v[226:229], v[98:101]
	v_mfma_f32_16x16x32_bf16 v[144:147], v[200:203], v[226:229], v[144:147]
	v_mfma_f32_16x16x32_bf16 v[54:57], v[168:171], v[234:237], v[54:57]
	v_mfma_f32_16x16x32_bf16 v[58:61], v[200:203], v[234:237], v[58:61]
	s_setprio 0
	s_barrier
	ds_read_b128 v[148:151], v127
	ds_read_b128 v[152:155], v127 offset:1024
	ds_read_b128 v[156:159], v127 offset:2048
	ds_read_b128 v[160:163], v127 offset:3072
	ds_read_b128 v[164:167], v126
	ds_read_b128 v[168:171], v126 offset:1024
	ds_read_b128 v[192:195], v126 offset:2048
	ds_read_b128 v[196:199], v126 offset:3072
	s_add_u32 s20, s20, 0x40180
	s_addc_u32 s21, s21, 0
	s_mov_b32 m0, s64
	v_lshl_add_u64 v[16:17], s[20:21], 0, v[16:17]
	ds_read_b128 v[200:203], v143
	ds_read_b128 v[206:209], v143 offset:1024
	ds_read_b128 v[210:213], v143 offset:2048
	ds_read_b128 v[214:217], v143 offset:3072
	ds_read_b128 v[218:221], v143 offset:4096
	ds_read_b128 v[222:225], v143 offset:5120
	ds_read_b128 v[226:229], v143 offset:6144
	ds_read_b128 v[230:233], v143 offset:7168
	global_load_lds_dwordx4 v[16:17], off
	v_lshl_add_u64 v[16:17], s[20:21], 0, v[30:31]
	s_mov_b32 m0, s61
	s_nop 0
	global_load_lds_dwordx4 v[16:17], off
	s_waitcnt vmcnt(8)
	s_waitcnt lgkmcnt(0)
	s_barrier
	s_setprio 1
	v_mfma_f32_16x16x32_bf16 v[102:105], v[148:151], v[200:203], v[102:105]
	v_mfma_f32_16x16x32_bf16 v[106:109], v[156:159], v[200:203], v[106:109]
	v_mfma_f32_16x16x32_bf16 v[110:113], v[148:151], v[210:213], v[110:113]
	v_mfma_f32_16x16x32_bf16 v[114:117], v[156:159], v[210:213], v[114:117]
	v_mfma_f32_16x16x32_bf16 v[118:121], v[148:151], v[218:221], v[118:121]
	v_mfma_f32_16x16x32_bf16 v[122:125], v[156:159], v[218:221], v[122:125]
	v_mfma_f32_16x16x32_bf16 v[130:133], v[148:151], v[226:229], v[130:133]
	v_mfma_f32_16x16x32_bf16 v[134:137], v[156:159], v[226:229], v[134:137]
	v_mfma_f32_16x16x32_bf16 v[102:105], v[152:155], v[206:209], v[102:105]
	v_mfma_f32_16x16x32_bf16 v[106:109], v[160:163], v[206:209], v[106:109]
	v_mfma_f32_16x16x32_bf16 v[110:113], v[152:155], v[214:217], v[110:113]
	v_mfma_f32_16x16x32_bf16 v[114:117], v[160:163], v[214:217], v[114:117]
	v_mfma_f32_16x16x32_bf16 v[118:121], v[152:155], v[222:225], v[118:121]
	v_mfma_f32_16x16x32_bf16 v[122:125], v[160:163], v[222:225], v[122:125]
	v_mfma_f32_16x16x32_bf16 v[130:133], v[152:155], v[230:233], v[130:133]
	v_mfma_f32_16x16x32_bf16 v[134:137], v[160:163], v[230:233], v[134:137]
	v_mfma_f32_16x16x32_bf16 v[138:141], v[164:167], v[200:203], v[138:141]
	v_mfma_f32_16x16x32_bf16 v[70:73], v[192:195], v[200:203], v[70:73]
	v_mfma_f32_16x16x32_bf16 v[74:77], v[164:167], v[210:213], v[74:77]
	v_mfma_f32_16x16x32_bf16 v[78:81], v[192:195], v[210:213], v[78:81]
	v_mfma_f32_16x16x32_bf16 v[82:85], v[164:167], v[218:221], v[82:85]
	v_mfma_f32_16x16x32_bf16 v[86:89], v[192:195], v[218:221], v[86:89]
	v_mfma_f32_16x16x32_bf16 v[90:93], v[164:167], v[226:229], v[90:93]
	v_mfma_f32_16x16x32_bf16 v[94:97], v[192:195], v[226:229], v[94:97]
	v_mfma_f32_16x16x32_bf16 v[138:141], v[168:171], v[206:209], v[138:141]
	v_mfma_f32_16x16x32_bf16 v[70:73], v[196:199], v[206:209], v[70:73]
	v_mfma_f32_16x16x32_bf16 v[74:77], v[168:171], v[214:217], v[74:77]
	v_mfma_f32_16x16x32_bf16 v[78:81], v[196:199], v[214:217], v[78:81]
	v_mfma_f32_16x16x32_bf16 v[82:85], v[168:171], v[222:225], v[82:85]
	v_mfma_f32_16x16x32_bf16 v[86:89], v[196:199], v[222:225], v[86:89]
	v_mfma_f32_16x16x32_bf16 v[90:93], v[168:171], v[230:233], v[90:93]
	v_mfma_f32_16x16x32_bf16 v[94:97], v[196:199], v[230:233], v[94:97]
	s_setprio 0
	s_barrier
; #define PG8_STAGE(bufoff, gbase, voff) do { _Pragma("unroll") for (int _i = 0; _i < 2; ++_i) \
;         __builtin_amdgcn_global_load_lds((const unsigned*)((const char*)(gbase) + (voff)[_i]), (PG8_LAS unsigned*)(lds + (bufoff) + ldsw + _i * 8192), 16, 0, 0); } while (0)
; #define PG8_LDA(dst, b, h) do { _Pragma("unroll") for (int m = 0; m < 4; ++m) _Pragma("unroll") for (int k = 0; k < 2; ++k) dst[m][k] = *(const PG8_LAS bf16x8*)(lds + PG8_SA(b, h) + aoff + m * 2048 + k * 1024); } while (0)
; #define PG8_LDB(dst, b, h) do { _Pragma("unroll") for (int n = 0; n < 2; ++n) _Pragma("unroll") for (int k = 0; k < 2; ++k) dst[n][k] = *(const PG8_LAS bf16x8*)(lds + PG8_SB(b, h) + boff + n * 2048 + k * 1024); } while (0)
; template <class Epi, class Sched, bool ALIGN_EPI = false, bool SP2 = false>
; __device__ __forceinline__ void gemm_phase(PG8_LAS unsigned char* lds, const Gemm g, const Sched& S, const Epi& E, const int wv0) {
;     ...
;         for (int t = 0; t < nt; t += 2) {
;             const bool last = (t == nt - 2);
;             const char* a1 = cA + (size_t)(t + 1) * kstep;
;             const char* a2 = last ? nA : cA + (size_t)(t + 2) * kstep; const char* b2 = last ? nB : cB + (size_t)(t + 2) * kstep;
;             const char* a3 = a2 + kstep; const char* b3 = b2 + kstep;
;             if constexpr (SP2) {
;             PG8_LDB(B0, 0, 0); PG8_LDB(B1, 0, 1); PG8_SCHED; PG8_LDA(At, 0, 0); PG8_STAGE(PG8_SA(1, 1), a1 + hstepA, voffA);
;             PG8_WAIT_V(8); PG8_WAIT_L(0); PG8_BAR; PG8_MMA(0, 0, At, B0); PG8_MMA(0, 1, At, B1); PG8_BAR; PG8_SCHED;
;             PG8_LDA(At, 0, 1); PG8_STAGE(PG8_SB(0, 0), b2, voffB); PG8_STAGE(PG8_SB(0, 1), b2 + hstepB, voffB); PG8_STAGE(PG8_SA(0, 0), a2, voffA);
;             PG8_WAIT_V(8); PG8_WAIT_L(0); PG8_BAR; PG8_MMA(1, 0, At, B0); PG8_MMA(1, 1, At, B1); PG8_BAR; PG8_SCHED;
;             PG8_LDB(B0, 1, 0); PG8_LDB(B1, 1, 1); PG8_SCHED; PG8_LDA(At, 1, 0); PG8_STAGE(PG8_SA(0, 1), a2 + hstepA, voffA);
;             PG8_WAIT_V(8); PG8_WAIT_L(0); PG8_BAR; PG8_MMA(0, 0, At, B0); PG8_MMA(0, 1, At, B1); PG8_BAR; PG8_SCHED;
;             PG8_LDA(At, 1, 1); PG8_STAGE(PG8_SB(1, 0), b3, voffB); PG8_STAGE(PG8_SB(1, 1), b3 + hstepB, voffB); PG8_STAGE(PG8_SA(1, 0), a3, voffA);
;             PG8_WAIT_V(8); PG8_WAIT_L(0); PG8_BAR; PG8_MMA(1, 0, At, B0); PG8_MMA(1, 1, At, B1); PG8_BAR; PG8_SCHED;
	s_mov_b32 m0, s48
	ds_read_b128 v[200:203], v143 offset:16384
	ds_read_b128 v[206:209], v143 offset:17408
	ds_read_b128 v[210:213], v143 offset:18432
	ds_read_b128 v[214:217], v143 offset:19456
	ds_read_b128 v[218:221], v143 offset:20480
	ds_read_b128 v[222:225], v143 offset:21504
	ds_read_b128 v[226:229], v143 offset:22528
	ds_read_b128 v[230:233], v143 offset:23552
	global_load_lds_dwordx4 v[26:27], off
	s_mov_b32 m0, s62
	s_nop 0
	global_load_lds_dwordx4 v[28:29], off
	s_mov_b32 m0, s47
	s_nop 0
	global_load_lds_dwordx4 v[24:25], off
	s_mov_b32 m0, s63
	s_nop 0
	global_load_lds_dwordx4 v[18:19], off
	s_mov_b32 m0, s59
	s_nop 0
	global_load_lds_dwordx4 v[20:21], off
	s_mov_b32 m0, s60
	s_nop 0
	global_load_lds_dwordx4 v[22:23], off
	s_waitcnt vmcnt(8)
	s_waitcnt lgkmcnt(0)
	s_barrier
	s_setprio 1
	v_mfma_f32_16x16x32_bf16 v[16:19], v[148:151], v[200:203], v[32:35]
	v_mfma_f32_16x16x32_bf16 v[20:23], v[156:159], v[200:203], v[172:175]
	v_mfma_f32_16x16x32_bf16 v[24:27], v[148:151], v[210:213], v[176:179]
	v_mfma_f32_16x16x32_bf16 v[28:31], v[156:159], v[210:213], v[180:183]
	v_mfma_f32_16x16x32_bf16 v[32:35], v[148:151], v[218:221], v[184:187]
	v_mfma_f32_16x16x32_bf16 v[172:175], v[156:159], v[218:221], v[188:191]
	v_mfma_f32_16x16x32_bf16 v[38:41], v[148:151], v[226:229], v[38:41]
	v_mfma_f32_16x16x32_bf16 v[42:45], v[156:159], v[226:229], v[42:45]
	v_mfma_f32_16x16x32_bf16 v[16:19], v[152:155], v[206:209], v[16:19]
	v_mfma_f32_16x16x32_bf16 v[20:23], v[160:163], v[206:209], v[20:23]
	v_mfma_f32_16x16x32_bf16 v[24:27], v[152:155], v[214:217], v[24:27]
	v_mfma_f32_16x16x32_bf16 v[28:31], v[160:163], v[214:217], v[28:31]
	v_mfma_f32_16x16x32_bf16 v[32:35], v[152:155], v[222:225], v[32:35]
	v_mfma_f32_16x16x32_bf16 v[172:175], v[160:163], v[222:225], v[172:175]
	v_mfma_f32_16x16x32_bf16 v[38:41], v[152:155], v[230:233], v[38:41]
	v_mfma_f32_16x16x32_bf16 v[42:45], v[160:163], v[230:233], v[42:45]
	v_mfma_f32_16x16x32_bf16 v[46:49], v[164:167], v[200:203], v[46:49]
	v_mfma_f32_16x16x32_bf16 v[50:53], v[192:195], v[200:203], v[50:53]
	v_mfma_f32_16x16x32_bf16 v[62:65], v[164:167], v[210:213], v[62:65]
	v_mfma_f32_16x16x32_bf16 v[66:69], v[192:195], v[210:213], v[66:69]
	v_mfma_f32_16x16x32_bf16 v[98:101], v[164:167], v[218:221], v[98:101]
	v_mfma_f32_16x16x32_bf16 v[144:147], v[192:195], v[218:221], v[144:147]
	v_mfma_f32_16x16x32_bf16 v[54:57], v[164:167], v[226:229], v[54:57]
	v_mfma_f32_16x16x32_bf16 v[58:61], v[192:195], v[226:229], v[58:61]
	v_mfma_f32_16x16x32_bf16 v[46:49], v[168:171], v[206:209], v[46:49]
	v_mfma_f32_16x16x32_bf16 v[50:53], v[196:199], v[206:209], v[50:53]
	v_mfma_f32_16x16x32_bf16 v[62:65], v[168:171], v[214:217], v[62:65]
	v_mfma_f32_16x16x32_bf16 v[66:69], v[196:199], v[214:217], v[66:69]
	v_mfma_f32_16x16x32_bf16 v[98:101], v[168:171], v[222:225], v[98:101]
	v_mfma_f32_16x16x32_bf16 v[144:147], v[196:199], v[222:225], v[144:147]
	v_mfma_f32_16x16x32_bf16 v[54:57], v[168:171], v[230:233], v[54:57]
	v_mfma_f32_16x16x32_bf16 v[58:61], v[196:199], v[230:233], v[58:61]
	s_setprio 0
	s_barrier
	ds_read_b128 v[148:151], v239
	ds_read_b128 v[152:155], v239 offset:1024
	ds_read_b128 v[156:159], v239 offset:2048
	ds_read_b128 v[160:163], v239 offset:3072
	ds_read_b128 v[164:167], v238
	ds_read_b128 v[168:171], v238 offset:1024
	ds_read_b128 v[176:179], v238 offset:2048
	ds_read_b128 v[180:183], v238 offset:3072
	s_mov_b32 m0, s55
	ds_read_b128 v[184:187], v143 offset:32768
	ds_read_b128 v[188:191], v143 offset:33792
	ds_read_b128 v[192:195], v143 offset:34816
	ds_read_b128 v[196:199], v143 offset:35840
	ds_read_b128 v[200:203], v143 offset:36864
	ds_read_b128 v[206:209], v143 offset:37888
	ds_read_b128 v[210:213], v143 offset:38912
	ds_read_b128 v[214:217], v143 offset:39936
	global_load_lds_dwordx4 v[12:13], off
	s_mov_b32 m0, s56
	s_nop 0
	global_load_lds_dwordx4 v[14:15], off
	s_waitcnt vmcnt(8)
	s_waitcnt lgkmcnt(0)
	s_barrier
	s_setprio 1
	v_mfma_f32_16x16x32_bf16 v[12:15], v[148:151], v[184:187], v[102:105]
	v_mfma_f32_16x16x32_bf16 v[102:105], v[152:155], v[188:191], v[12:15]
	v_mfma_f32_16x16x32_bf16 v[12:15], v[156:159], v[184:187], v[106:109]
	v_mfma_f32_16x16x32_bf16 v[106:109], v[160:163], v[188:191], v[12:15]
	v_mfma_f32_16x16x32_bf16 v[12:15], v[148:151], v[192:195], v[110:113]
	v_mfma_f32_16x16x32_bf16 v[110:113], v[152:155], v[196:199], v[12:15]
	v_mfma_f32_16x16x32_bf16 v[12:15], v[156:159], v[192:195], v[114:117]
	v_mfma_f32_16x16x32_bf16 v[114:117], v[160:163], v[196:199], v[12:15]
	v_mfma_f32_16x16x32_bf16 v[12:15], v[148:151], v[200:203], v[118:121]
	v_mfma_f32_16x16x32_bf16 v[118:121], v[152:155], v[206:209], v[12:15]
	v_mfma_f32_16x16x32_bf16 v[12:15], v[156:159], v[200:203], v[122:125]
	v_mfma_f32_16x16x32_bf16 v[122:125], v[160:163], v[206:209], v[12:15]
	v_mfma_f32_16x16x32_bf16 v[12:15], v[148:151], v[210:213], v[130:133]
	v_mfma_f32_16x16x32_bf16 v[130:133], v[152:155], v[214:217], v[12:15]
	v_mfma_f32_16x16x32_bf16 v[12:15], v[156:159], v[210:213], v[134:137]
	v_mfma_f32_16x16x32_bf16 v[134:137], v[160:163], v[214:217], v[12:15]
	v_mfma_f32_16x16x32_bf16 v[12:15], v[164:167], v[184:187], v[138:141]
	v_mfma_f32_16x16x32_bf16 v[138:141], v[168:171], v[188:191], v[12:15]
	v_mfma_f32_16x16x32_bf16 v[12:15], v[176:179], v[184:187], v[70:73]
	v_mfma_f32_16x16x32_bf16 v[70:73], v[180:183], v[188:191], v[12:15]
	v_mfma_f32_16x16x32_bf16 v[12:15], v[164:167], v[192:195], v[74:77]
	v_mfma_f32_16x16x32_bf16 v[74:77], v[168:171], v[196:199], v[12:15]
	v_mfma_f32_16x16x32_bf16 v[12:15], v[176:179], v[192:195], v[78:81]
	v_mfma_f32_16x16x32_bf16 v[78:81], v[180:183], v[196:199], v[12:15]
	v_mfma_f32_16x16x32_bf16 v[12:15], v[164:167], v[200:203], v[82:85]
	v_mfma_f32_16x16x32_bf16 v[82:85], v[168:171], v[206:209], v[12:15]
	v_mfma_f32_16x16x32_bf16 v[12:15], v[176:179], v[200:203], v[86:89]
	v_mfma_f32_16x16x32_bf16 v[86:89], v[180:183], v[206:209], v[12:15]
	v_mfma_f32_16x16x32_bf16 v[12:15], v[164:167], v[210:213], v[90:93]
	v_mfma_f32_16x16x32_bf16 v[90:93], v[168:171], v[214:217], v[12:15]
	v_mfma_f32_16x16x32_bf16 v[12:15], v[176:179], v[210:213], v[94:97]
	v_mfma_f32_16x16x32_bf16 v[94:97], v[180:183], v[214:217], v[12:15]
	s_setprio 0
	s_barrier
; #define PG8_STAGE(bufoff, gbase, voff) do { _Pragma("unroll") for (int _i = 0; _i < 2; ++_i) \
;         __builtin_amdgcn_global_load_lds((const unsigned*)((const char*)(gbase) + (voff)[_i]), (PG8_LAS unsigned*)(lds + (bufoff) + ldsw + _i * 8192), 16, 0, 0); } while (0)
; #define PG8_LDA(dst, b, h) do { _Pragma("unroll") for (int m = 0; m < 4; ++m) _Pragma("unroll") for (int k = 0; k < 2; ++k) dst[m][k] = *(const PG8_LAS bf16x8*)(lds + PG8_SA(b, h) + aoff + m * 2048 + k * 1024); } while (0)
; #define PG8_LDB(dst, b, h) do { _Pragma("unroll") for (int n = 0; n < 2; ++n) _Pragma("unroll") for (int k = 0; k < 2; ++k) dst[n][k] = *(const PG8_LAS bf16x8*)(lds + PG8_SB(b, h) + boff + n * 2048 + k * 1024); } while (0)
; template <class Epi, class Sched, bool ALIGN_EPI = false, bool SP2 = false>
; __device__ __forceinline__ void gemm_phase(PG8_LAS unsigned char* lds, const Gemm g, const Sched& S, const Epi& E, const int wv0) {
;     ...
;         for (int t = 0; t < nt; t += 2) {
;             const bool last = (t == nt - 2);
;             const char* a1 = cA + (size_t)(t + 1) * kstep;
;             const char* a2 = last ? nA : cA + (size_t)(t + 2) * kstep; const char* b2 = last ? nB : cB + (size_t)(t + 2) * kstep;
;             const char* a3 = a2 + kstep; const char* b3 = b2 + kstep;
;             if constexpr (SP2) {
;             PG8_LDB(B0, 0, 0); PG8_LDB(B1, 0, 1); PG8_SCHED; PG8_LDA(At, 0, 0); PG8_STAGE(PG8_SA(1, 1), a1 + hstepA, voffA);
;             PG8_WAIT_V(8); PG8_WAIT_L(0); PG8_BAR; PG8_MMA(0, 0, At, B0); PG8_MMA(0, 1, At, B1); PG8_BAR; PG8_SCHED;
;             PG8_LDA(At, 0, 1); PG8_STAGE(PG8_SB(0, 0), b2, voffB); PG8_STAGE(PG8_SB(0, 1), b2 + hstepB, voffB); PG8_STAGE(PG8_SA(0, 0), a2, voffA);
;             PG8_WAIT_V(8); PG8_WAIT_L(0); PG8_BAR; PG8_MMA(1, 0, At, B0); PG8_MMA(1, 1, At, B1); PG8_BAR; PG8_SCHED;
;             PG8_LDB(B0, 1, 0); PG8_LDB(B1, 1, 1); PG8_SCHED; PG8_LDA(At, 1, 0); PG8_STAGE(PG8_SA(0, 1), a2 + hstepA, voffA);
;             PG8_WAIT_V(8); PG8_WAIT_L(0); PG8_BAR; PG8_MMA(0, 0, At, B0); PG8_MMA(0, 1, At, B1); PG8_BAR; PG8_SCHED;
;             PG8_LDA(At, 1, 1); PG8_STAGE(PG8_SB(1, 0), b3, voffB); PG8_STAGE(PG8_SB(1, 1), b3 + hstepB, voffB); PG8_STAGE(PG8_SA(1, 0), a3, voffA);
;             PG8_WAIT_V(8); PG8_WAIT_L(0); PG8_BAR; PG8_MMA(1, 0, At, B0); PG8_MMA(1, 1, At, B1); PG8_BAR; PG8_SCHED;
	s_mov_b32 m0, s51
	ds_read_b128 v[184:187], v143 offset:49152
	ds_read_b128 v[188:191], v143 offset:50176
	ds_read_b128 v[192:195], v143 offset:51200
	ds_read_b128 v[196:199], v143 offset:52224
	ds_read_b128 v[200:203], v143 offset:53248
	ds_read_b128 v[206:209], v143 offset:54272
	ds_read_b128 v[210:213], v143 offset:55296
	ds_read_b128 v[214:217], v143 offset:56320
	global_load_lds_dwordx4 v[2:3], off
	s_mov_b32 m0, s53
	s_nop 0
	global_load_lds_dwordx4 v[4:5], off
	s_mov_b32 m0, s57
	s_nop 0
	global_load_lds_dwordx4 v[8:9], off
	s_mov_b32 m0, s58
	s_nop 0
	global_load_lds_dwordx4 v[10:11], off
	s_mov_b32 m0, s52
	s_nop 0
	global_load_lds_dwordx4 v[0:1], off
	s_mov_b32 m0, s54
	s_nop 0
	global_load_lds_dwordx4 v[6:7], off
	s_waitcnt vmcnt(8)
	s_waitcnt lgkmcnt(0)
	s_barrier
	s_setprio 1
	v_mfma_f32_16x16x32_bf16 v[0:3], v[148:151], v[184:187], v[16:19]
	v_mfma_f32_16x16x32_bf16 v[218:221], v[152:155], v[188:191], v[0:3]
	v_mfma_f32_16x16x32_bf16 v[0:3], v[156:159], v[184:187], v[20:23]
	v_mfma_f32_16x16x32_bf16 v[222:225], v[160:163], v[188:191], v[0:3]
	v_mfma_f32_16x16x32_bf16 v[0:3], v[148:151], v[192:195], v[24:27]
	v_mfma_f32_16x16x32_bf16 v[226:229], v[152:155], v[196:199], v[0:3]
	v_mfma_f32_16x16x32_bf16 v[0:3], v[156:159], v[192:195], v[28:31]
	v_mfma_f32_16x16x32_bf16 v[230:233], v[160:163], v[196:199], v[0:3]
	v_mfma_f32_16x16x32_bf16 v[0:3], v[148:151], v[200:203], v[32:35]
	v_mfma_f32_16x16x32_bf16 v[28:31], v[152:155], v[206:209], v[0:3]
	v_mfma_f32_16x16x32_bf16 v[0:3], v[156:159], v[200:203], v[172:175]
	v_mfma_f32_16x16x32_bf16 v[20:23], v[160:163], v[206:209], v[0:3]
	v_mfma_f32_16x16x32_bf16 v[0:3], v[148:151], v[210:213], v[38:41]
	v_mfma_f32_16x16x32_bf16 v[12:15], v[152:155], v[214:217], v[0:3]
	v_mfma_f32_16x16x32_bf16 v[0:3], v[156:159], v[210:213], v[42:45]
	v_mfma_f32_16x16x32_bf16 v[4:7], v[160:163], v[214:217], v[0:3]
	v_mfma_f32_16x16x32_bf16 v[0:3], v[164:167], v[184:187], v[46:49]
	v_mfma_f32_16x16x32_bf16 v[38:41], v[168:171], v[188:191], v[0:3]
	v_mfma_f32_16x16x32_bf16 v[0:3], v[176:179], v[184:187], v[50:53]
	v_mfma_f32_16x16x32_bf16 v[42:45], v[180:183], v[188:191], v[0:3]
	v_mfma_f32_16x16x32_bf16 v[0:3], v[164:167], v[192:195], v[62:65]
	v_mfma_f32_16x16x32_bf16 v[46:49], v[168:171], v[196:199], v[0:3]
	v_mfma_f32_16x16x32_bf16 v[0:3], v[176:179], v[192:195], v[66:69]
	v_mfma_f32_16x16x32_bf16 v[32:35], v[180:183], v[196:199], v[0:3]
	v_mfma_f32_16x16x32_bf16 v[0:3], v[164:167], v[200:203], v[98:101]
	v_mfma_f32_16x16x32_bf16 v[24:27], v[168:171], v[206:209], v[0:3]
	v_mfma_f32_16x16x32_bf16 v[0:3], v[176:179], v[200:203], v[144:147]
	v_mfma_f32_16x16x32_bf16 v[16:19], v[180:183], v[206:209], v[0:3]
	v_mfma_f32_16x16x32_bf16 v[0:3], v[164:167], v[210:213], v[54:57]
	v_mfma_f32_16x16x32_bf16 v[8:11], v[168:171], v[214:217], v[0:3]
	v_mfma_f32_16x16x32_bf16 v[0:3], v[176:179], v[210:213], v[58:61]
	v_mfma_f32_16x16x32_bf16 v[0:3], v[180:183], v[214:217], v[0:3]
	s_setprio 0
	s_barrier
; __device__ __forceinline__ unsigned cvtpk(float lo, float hi) { unsigned r; asm volatile("v_cvt_pk_bf16_f32 %0, %1, %2" : "=v"(r) : "v"(lo), "v"(hi)); return r; }
;     __device__ __forceinline__ void operator()(const f32x4 (&acc)[2][2][4][2], const Unit& u, int wr, int wc, int fr, int fq) const {
;         const int row0 = u.pm * BM + wr * 64 + fr; const int col0 = u.pn * BM + wc * 32 + 8 * fq;
; #pragma unroll
;         for (int ai = 0; ai < 2; ++ai)
; #pragma unroll
;             for (int m = 0; m < 4; ++m) { bf16* rowp = O + (size_t)(row0 + ai * HALF + m * 16) * ldc + col0;
; #pragma unroll
;                 for (int bj = 0; bj < 2; ++bj) { const f32x4 v0 = acc[ai][bj][m][0], v1 = acc[ai][bj][m][1];
;                     u32x4 w; w.x = cvtpk(v0[0], v0[1]); w.y = cvtpk(v0[2], v0[3]); w.z = cvtpk(v1[0], v1[1]); w.w = cvtpk(v1[2], v1[3]);
;                     *(u32x4*)(rowp + bj * HALF) = w; } }
;     }
	v_add_u32_e32 v54, s24, v36
	v_or_b32_e32 v36, s49, v37
	v_ashrrev_i32_e32 v55, 31, v54
	v_or_b32_e32 v50, s50, v36
	v_lshlrev_b64 v[36:37], 11, v[54:55]
	v_lshl_add_u64 v[36:37], s[4:5], 0, v[36:37]
	v_lshlrev_b32_e32 v128, 1, v50
	v_lshl_add_u64 v[36:37], v[36:37], 0, v[128:129]
	v_cvt_pk_bf16_f32 v50, v102, v103
	v_cvt_pk_bf16_f32 v51, v104, v105
	v_cvt_pk_bf16_f32 v52, v106, v107
	v_cvt_pk_bf16_f32 v53, v108, v109
	global_store_dwordx4 v[36:37], v[50:53], off
	s_cmpk_gt_u32 s25, 0xff
	s_nop 0
	v_cvt_pk_bf16_f32 v50, v138, v139
	v_cvt_pk_bf16_f32 v51, v140, v141
	v_cvt_pk_bf16_f32 v52, v70, v71
	v_cvt_pk_bf16_f32 v53, v72, v73
	global_store_dwordx4 v[36:37], v[50:53], off offset:256
	s_nop 1
	v_or_b32_e32 v50, 16, v54
	v_ashrrev_i32_e32 v51, 31, v50
	v_lshlrev_b64 v[50:51], 11, v[50:51]
	v_lshl_add_u64 v[50:51], s[4:5], 0, v[50:51]
	v_lshl_add_u64 v[56:57], v[50:51], 0, v[128:129]
	v_cvt_pk_bf16_f32 v50, v110, v111
	v_cvt_pk_bf16_f32 v51, v112, v113
	v_cvt_pk_bf16_f32 v52, v114, v115
	v_cvt_pk_bf16_f32 v53, v116, v117
	global_store_dwordx4 v[56:57], v[50:53], off
	s_nop 1
	v_cvt_pk_bf16_f32 v50, v74, v75
	v_cvt_pk_bf16_f32 v51, v76, v77
	v_cvt_pk_bf16_f32 v52, v78, v79
	v_cvt_pk_bf16_f32 v53, v80, v81
	global_store_dwordx4 v[56:57], v[50:53], off offset:256
	s_nop 1
	v_or_b32_e32 v50, 32, v54
	v_ashrrev_i32_e32 v51, 31, v50
	v_lshlrev_b64 v[50:51], 11, v[50:51]
	v_lshl_add_u64 v[50:51], s[4:5], 0, v[50:51]
	v_lshl_add_u64 v[56:57], v[50:51], 0, v[128:129]
	v_cvt_pk_bf16_f32 v50, v118, v119
	v_cvt_pk_bf16_f32 v51, v120, v121
	v_cvt_pk_bf16_f32 v52, v122, v123
	v_cvt_pk_bf16_f32 v53, v124, v125
	global_store_dwordx4 v[56:57], v[50:53], off
	s_nop 1
	v_cvt_pk_bf16_f32 v50, v82, v83
	v_cvt_pk_bf16_f32 v51, v84, v85
	v_cvt_pk_bf16_f32 v52, v86, v87
	v_cvt_pk_bf16_f32 v53, v88, v89
	global_store_dwordx4 v[56:57], v[50:53], off offset:256
	v_add_co_u32_e32 v56, vcc, s39, v36
	s_nop 0
	v_or_b32_e32 v50, 48, v54
	v_ashrrev_i32_e32 v51, 31, v50
	v_lshlrev_b64 v[50:51], 11, v[50:51]
	v_lshl_add_u64 v[50:51], s[4:5], 0, v[50:51]
	v_lshl_add_u64 v[54:55], v[50:51], 0, v[128:129]
	v_cvt_pk_bf16_f32 v50, v130, v131
	v_cvt_pk_bf16_f32 v51, v132, v133
	v_cvt_pk_bf16_f32 v52, v134, v135
	v_cvt_pk_bf16_f32 v53, v136, v137
	global_store_dwordx4 v[54:55], v[50:53], off
	v_addc_co_u32_e32 v57, vcc, 0, v37, vcc
	s_nop 0
	v_cvt_pk_bf16_f32 v50, v90, v91
	v_cvt_pk_bf16_f32 v51, v92, v93
	v_cvt_pk_bf16_f32 v52, v94, v95
	v_cvt_pk_bf16_f32 v53, v96, v97
	global_store_dwordx4 v[54:55], v[50:53], off offset:256
	v_lshl_add_u64 v[54:55], v[36:37], 0, s[6:7]
	s_nop 0
	v_cvt_pk_bf16_f32 v50, v218, v219
	v_cvt_pk_bf16_f32 v51, v220, v221
	v_cvt_pk_bf16_f32 v52, v222, v223
	v_cvt_pk_bf16_f32 v53, v224, v225
	global_store_dwordx4 v[56:57], v[50:53], off
	v_cvt_pk_bf16_f32 v38, v38, v39
	v_cvt_pk_bf16_f32 v39, v40, v41
	v_cvt_pk_bf16_f32 v40, v42, v43
	v_cvt_pk_bf16_f32 v41, v44, v45
	v_add_co_u32_e32 v44, vcc, s40, v36
	global_store_dwordx4 v[54:55], v[38:41], off offset:256
	v_lshl_add_u64 v[42:43], v[36:37], 0, s[14:15]
	v_addc_co_u32_e32 v45, vcc, 0, v37, vcc
	v_cvt_pk_bf16_f32 v38, v226, v227
	v_cvt_pk_bf16_f32 v39, v228, v229
	v_cvt_pk_bf16_f32 v40, v230, v231
	v_cvt_pk_bf16_f32 v41, v232, v233
	global_store_dwordx4 v[44:45], v[38:41], off
	s_nop 1
	v_cvt_pk_bf16_f32 v38, v46, v47
	v_cvt_pk_bf16_f32 v39, v48, v49
	v_cvt_pk_bf16_f32 v40, v32, v33
	v_cvt_pk_bf16_f32 v41, v34, v35
	global_store_dwordx4 v[42:43], v[38:41], off offset:256
	v_cvt_pk_bf16_f32 v28, v28, v29
	v_cvt_pk_bf16_f32 v29, v30, v31
	v_cvt_pk_bf16_f32 v30, v20, v21
	v_add_co_u32_e32 v20, vcc, s41, v36
	v_lshl_add_u64 v[32:33], v[36:37], 0, s[16:17]
	s_nop 0
	v_addc_co_u32_e32 v21, vcc, 0, v37, vcc
	v_cvt_pk_bf16_f32 v31, v22, v23
	global_store_dwordx4 v[20:21], v[28:31], off
	v_cvt_pk_bf16_f32 v20, v24, v25
	v_cvt_pk_bf16_f32 v21, v26, v27
	v_cvt_pk_bf16_f32 v22, v16, v17
	v_cvt_pk_bf16_f32 v23, v18, v19
	global_store_dwordx4 v[32:33], v[20:23], off offset:256
	v_cvt_pk_bf16_f32 v12, v12, v13
	v_cvt_pk_bf16_f32 v13, v14, v15
	v_cvt_pk_bf16_f32 v14, v4, v5
	v_add_co_u32_e32 v4, vcc, s45, v36
	v_lshl_add_u64 v[16:17], v[36:37], 0, s[18:19]
	s_nop 0
	v_addc_co_u32_e32 v5, vcc, 0, v37, vcc
	v_cvt_pk_bf16_f32 v15, v6, v7
	global_store_dwordx4 v[4:5], v[12:15], off
	v_cvt_pk_bf16_f32 v4, v8, v9
	v_cvt_pk_bf16_f32 v5, v10, v11
	v_cvt_pk_bf16_f32 v6, v0, v1
	v_cvt_pk_bf16_f32 v7, v2, v3
	global_store_dwordx4 v[16:17], v[4:7], off offset:256
	s_waitcnt vmcnt(0)
	s_cbranch_scc1 .LBB0_355
	s_barrier
	s_branch .LBB0_355

; #define PG8_STAGE(bufoff, gbase, voff) do { _Pragma("unroll") for (int _i = 0; _i < 2; ++_i) \
;         __builtin_amdgcn_global_load_lds((const unsigned*)((const char*)(gbase) + (voff)[_i]), (PG8_LAS unsigned*)(lds + (bufoff) + ldsw + _i * 8192), 16, 0, 0); } while (0)
; #define PG8_LDA(dst, b, h) do { _Pragma("unroll") for (int m = 0; m < 4; ++m) _Pragma("unroll") for (int k = 0; k < 2; ++k) dst[m][k] = *(const PG8_LAS bf16x8*)(lds + PG8_SA(b, h) + aoff + m * 2048 + k * 1024); } while (0)
; #define PG8_LDB(dst, b, h) do { _Pragma("unroll") for (int n = 0; n < 2; ++n) _Pragma("unroll") for (int k = 0; k < 2; ++k) dst[n][k] = *(const PG8_LAS bf16x8*)(lds + PG8_SB(b, h) + boff + n * 2048 + k * 1024); } while (0)
; template <class Epi, class Sched, bool ALIGN_EPI = false, bool SP2 = false>
; __device__ __forceinline__ void gemm_phase(PG8_LAS unsigned char* lds, const Gemm g, const Sched& S, const Epi& E, const int wv0) {
;     ...
;         for (int t = 0; t < nt; t += 2) {
;             const bool last = (t == nt - 2);
;             const char* a1 = cA + (size_t)(t + 1) * kstep;
;             const char* a2 = last ? nA : cA + (size_t)(t + 2) * kstep; const char* b2 = last ? nB : cB + (size_t)(t + 2) * kstep;
;             const char* a3 = a2 + kstep; const char* b3 = b2 + kstep;
;             if constexpr (SP2) {
;             PG8_LDB(B0, 0, 0); PG8_LDB(B1, 0, 1); PG8_SCHED; PG8_LDA(At, 0, 0); PG8_STAGE(PG8_SA(1, 1), a1 + hstepA, voffA);
;             PG8_WAIT_V(8); PG8_WAIT_L(0); PG8_BAR; PG8_MMA(0, 0, At, B0); PG8_MMA(0, 1, At, B1); PG8_BAR; PG8_SCHED;
;             PG8_LDA(At, 0, 1); PG8_STAGE(PG8_SB(0, 0), b2, voffB); PG8_STAGE(PG8_SB(0, 1), b2 + hstepB, voffB); PG8_STAGE(PG8_SA(0, 0), a2, voffA);
;             PG8_WAIT_V(8); PG8_WAIT_L(0); PG8_BAR; PG8_MMA(1, 0, At, B0); PG8_MMA(1, 1, At, B1); PG8_BAR; PG8_SCHED;
;             PG8_LDB(B0, 1, 0); PG8_LDB(B1, 1, 1); PG8_SCHED; PG8_LDA(At, 1, 0); PG8_STAGE(PG8_SA(0, 1), a2 + hstepA, voffA);
;             PG8_WAIT_V(8); PG8_WAIT_L(0); PG8_BAR; PG8_MMA(0, 0, At, B0); PG8_MMA(0, 1, At, B1); PG8_BAR; PG8_SCHED;
;             PG8_LDA(At, 1, 1); PG8_STAGE(PG8_SB(1, 0), b3, voffB); PG8_STAGE(PG8_SB(1, 1), b3 + hstepB, voffB); PG8_STAGE(PG8_SA(1, 0), a3, voffA);
;             PG8_WAIT_V(8); PG8_WAIT_L(0); PG8_BAR; PG8_MMA(1, 0, At, B0); PG8_MMA(1, 1, At, B1); PG8_BAR; PG8_SCHED;
.LBB0_494:
	v_add_u32_e32 v158, s61, v207
	v_add_u32_e32 v174, s62, v207
	ds_read_b128 v[146:149], v158
	ds_read_b128 v[150:153], v158 offset:1024
	ds_read_b128 v[154:157], v158 offset:2048
	ds_read_b128 v[158:161], v158 offset:3072
	ds_read_b128 v[162:165], v174
	ds_read_b128 v[166:169], v174 offset:1024
	ds_read_b128 v[170:173], v174 offset:2048
	ds_read_b128 v[174:177], v174 offset:3072
	s_add_u32 s41, s38, 0xfffc0080
	s_addc_u32 s44, s39, -1
	s_cmp_eq_u32 s29, 12
	s_cselect_b32 s47, s5, s44
	s_cselect_b32 s46, s4, s41
	s_cselect_b32 s45, s37, s27
	s_cselect_b32 s44, s36, s25
	v_lshl_add_u64 v[202:203], s[38:39], 0, v[140:141]
	s_add_i32 m0, s55, 0xc000
	ds_read_b128 v[178:181], v209
	ds_read_b128 v[182:185], v209 offset:1024
	ds_read_b128 v[186:189], v209 offset:2048
	ds_read_b128 v[190:193], v209 offset:3072
	ds_read_b128 v[194:197], v209 offset:4096
	ds_read_b128 v[198:201], v209 offset:5120
	ds_read_b128 v[210:213], v209 offset:6144
	ds_read_b128 v[214:217], v209 offset:7168
	global_load_lds_dwordx4 v[202:203], off
	v_lshl_add_u64 v[202:203], s[38:39], 0, v[138:139]
	s_add_i32 m0, s55, 0xe000
	s_nop 0
	global_load_lds_dwordx4 v[202:203], off
	s_waitcnt vmcnt(8)
	s_waitcnt lgkmcnt(0)
	s_barrier
	s_setprio 1
	v_mfma_f32_16x16x32_bf16 v[124:127], v[146:149], v[178:181], v[124:127]
	v_mfma_f32_16x16x32_bf16 v[120:123], v[154:157], v[178:181], v[120:123]
	v_mfma_f32_16x16x32_bf16 v[108:111], v[146:149], v[186:189], v[108:111]
	v_mfma_f32_16x16x32_bf16 v[104:107], v[154:157], v[186:189], v[104:107]
	v_mfma_f32_16x16x32_bf16 v[92:95], v[146:149], v[194:197], v[92:95]
	v_mfma_f32_16x16x32_bf16 v[88:91], v[154:157], v[194:197], v[88:91]
	v_mfma_f32_16x16x32_bf16 v[76:79], v[146:149], v[210:213], v[76:79]
	v_mfma_f32_16x16x32_bf16 v[72:75], v[154:157], v[210:213], v[72:75]
	v_mfma_f32_16x16x32_bf16 v[124:127], v[150:153], v[182:185], v[124:127]
	v_mfma_f32_16x16x32_bf16 v[120:123], v[158:161], v[182:185], v[120:123]
	v_mfma_f32_16x16x32_bf16 v[108:111], v[150:153], v[190:193], v[108:111]
	v_mfma_f32_16x16x32_bf16 v[104:107], v[158:161], v[190:193], v[104:107]
	v_mfma_f32_16x16x32_bf16 v[92:95], v[150:153], v[198:201], v[92:95]
	v_mfma_f32_16x16x32_bf16 v[88:91], v[158:161], v[198:201], v[88:91]
	v_mfma_f32_16x16x32_bf16 v[76:79], v[150:153], v[214:217], v[76:79]
	v_mfma_f32_16x16x32_bf16 v[72:75], v[158:161], v[214:217], v[72:75]
	v_mfma_f32_16x16x32_bf16 v[116:119], v[162:165], v[178:181], v[116:119]
	v_mfma_f32_16x16x32_bf16 v[112:115], v[170:173], v[178:181], v[112:115]
	v_mfma_f32_16x16x32_bf16 v[100:103], v[162:165], v[186:189], v[100:103]
	v_mfma_f32_16x16x32_bf16 v[96:99], v[170:173], v[186:189], v[96:99]
	v_mfma_f32_16x16x32_bf16 v[84:87], v[162:165], v[194:197], v[84:87]
	v_mfma_f32_16x16x32_bf16 v[80:83], v[170:173], v[194:197], v[80:83]
	v_mfma_f32_16x16x32_bf16 v[68:71], v[162:165], v[210:213], v[68:71]
	v_mfma_f32_16x16x32_bf16 v[64:67], v[170:173], v[210:213], v[64:67]
	v_mfma_f32_16x16x32_bf16 v[116:119], v[166:169], v[182:185], v[116:119]
	v_mfma_f32_16x16x32_bf16 v[112:115], v[174:177], v[182:185], v[112:115]
	v_mfma_f32_16x16x32_bf16 v[100:103], v[166:169], v[190:193], v[100:103]
	v_mfma_f32_16x16x32_bf16 v[96:99], v[174:177], v[190:193], v[96:99]
	v_mfma_f32_16x16x32_bf16 v[84:87], v[166:169], v[198:201], v[84:87]
	v_mfma_f32_16x16x32_bf16 v[80:83], v[174:177], v[198:201], v[80:83]
	v_mfma_f32_16x16x32_bf16 v[68:71], v[166:169], v[214:217], v[68:71]
	v_mfma_f32_16x16x32_bf16 v[64:67], v[174:177], v[214:217], v[64:67]
	s_setprio 0
	s_barrier
	s_add_i32 s41, s61, s54
	v_lshl_add_u64 v[202:203], s[44:45], 0, v[130:131]
	s_mov_b32 m0, s41
	ds_read_b128 v[178:181], v209 offset:16384
	ds_read_b128 v[182:185], v209 offset:17408
	ds_read_b128 v[186:189], v209 offset:18432
	ds_read_b128 v[190:193], v209 offset:19456
	ds_read_b128 v[194:197], v209 offset:20480
	ds_read_b128 v[198:201], v209 offset:21504
	ds_read_b128 v[210:213], v209 offset:22528
	ds_read_b128 v[214:217], v209 offset:23552
	global_load_lds_dwordx4 v[202:203], off
	s_add_i32 m0, s41, 0x2000
	s_add_u32 s64, s44, 0x40000
	v_lshl_add_u64 v[218:219], s[44:45], 0, v[134:135]
	s_addc_u32 s65, s45, 0
	s_add_i32 s41, s62, s54
	global_load_lds_dwordx4 v[218:219], off
	v_lshl_add_u64 v[220:221], s[64:65], 0, v[130:131]
	s_mov_b32 m0, s41
	v_lshl_add_u64 v[222:223], s[46:47], 0, v[132:133]
	global_load_lds_dwordx4 v[220:221], off
	v_lshl_add_u64 v[220:221], s[64:65], 0, v[134:135]
	s_add_i32 m0, s41, 0x2000
	s_nop 0
	global_load_lds_dwordx4 v[220:221], off
	v_lshl_add_u64 v[220:221], s[46:47], 0, v[128:129]
	s_mov_b32 m0, s55
	s_nop 0
	global_load_lds_dwordx4 v[220:221], off
	s_mov_b32 m0, s56
	s_nop 0
	global_load_lds_dwordx4 v[222:223], off
	s_waitcnt vmcnt(8)
	s_waitcnt lgkmcnt(0)
	s_barrier
; #define PG8_STAGE(bufoff, gbase, voff) do { _Pragma("unroll") for (int _i = 0; _i < 2; ++_i) \
;         __builtin_amdgcn_global_load_lds((const unsigned*)((const char*)(gbase) + (voff)[_i]), (PG8_LAS unsigned*)(lds + (bufoff) + ldsw + _i * 8192), 16, 0, 0); } while (0)
; #define PG8_LDA(dst, b, h) do { _Pragma("unroll") for (int m = 0; m < 4; ++m) _Pragma("unroll") for (int k = 0; k < 2; ++k) dst[m][k] = *(const PG8_LAS bf16x8*)(lds + PG8_SA(b, h) + aoff + m * 2048 + k * 1024); } while (0)
; #define PG8_LDB(dst, b, h) do { _Pragma("unroll") for (int n = 0; n < 2; ++n) _Pragma("unroll") for (int k = 0; k < 2; ++k) dst[n][k] = *(const PG8_LAS bf16x8*)(lds + PG8_SB(b, h) + boff + n * 2048 + k * 1024); } while (0)
; template <class Epi, class Sched, bool ALIGN_EPI = false, bool SP2 = false>
; __device__ __forceinline__ void gemm_phase(PG8_LAS unsigned char* lds, const Gemm g, const Sched& S, const Epi& E, const int wv0) {
;     ...
;         for (int t = 0; t < nt; t += 2) {
;             const bool last = (t == nt - 2);
;             const char* a1 = cA + (size_t)(t + 1) * kstep;
;             const char* a2 = last ? nA : cA + (size_t)(t + 2) * kstep; const char* b2 = last ? nB : cB + (size_t)(t + 2) * kstep;
;             const char* a3 = a2 + kstep; const char* b3 = b2 + kstep;
;             if constexpr (SP2) {
;             PG8_LDB(B0, 0, 0); PG8_LDB(B1, 0, 1); PG8_SCHED; PG8_LDA(At, 0, 0); PG8_STAGE(PG8_SA(1, 1), a1 + hstepA, voffA);
;             PG8_WAIT_V(8); PG8_WAIT_L(0); PG8_BAR; PG8_MMA(0, 0, At, B0); PG8_MMA(0, 1, At, B1); PG8_BAR; PG8_SCHED;
;             PG8_LDA(At, 0, 1); PG8_STAGE(PG8_SB(0, 0), b2, voffB); PG8_STAGE(PG8_SB(0, 1), b2 + hstepB, voffB); PG8_STAGE(PG8_SA(0, 0), a2, voffA);
;             PG8_WAIT_V(8); PG8_WAIT_L(0); PG8_BAR; PG8_MMA(1, 0, At, B0); PG8_MMA(1, 1, At, B1); PG8_BAR; PG8_SCHED;
;             PG8_LDB(B0, 1, 0); PG8_LDB(B1, 1, 1); PG8_SCHED; PG8_LDA(At, 1, 0); PG8_STAGE(PG8_SA(0, 1), a2 + hstepA, voffA);
;             PG8_WAIT_V(8); PG8_WAIT_L(0); PG8_BAR; PG8_MMA(0, 0, At, B0); PG8_MMA(0, 1, At, B1); PG8_BAR; PG8_SCHED;
;             PG8_LDA(At, 1, 1); PG8_STAGE(PG8_SB(1, 0), b3, voffB); PG8_STAGE(PG8_SB(1, 1), b3 + hstepB, voffB); PG8_STAGE(PG8_SA(1, 0), a3, voffA);
;             PG8_WAIT_V(8); PG8_WAIT_L(0); PG8_BAR; PG8_MMA(1, 0, At, B0); PG8_MMA(1, 1, At, B1); PG8_BAR; PG8_SCHED;
	s_setprio 1
	v_mfma_f32_16x16x32_bf16 v[60:63], v[146:149], v[178:181], v[60:63]
	v_mfma_f32_16x16x32_bf16 v[56:59], v[154:157], v[178:181], v[56:59]
	v_mfma_f32_16x16x32_bf16 v[44:47], v[146:149], v[186:189], v[44:47]
	v_mfma_f32_16x16x32_bf16 v[40:43], v[154:157], v[186:189], v[40:43]
	v_mfma_f32_16x16x32_bf16 v[28:31], v[146:149], v[194:197], v[28:31]
	v_mfma_f32_16x16x32_bf16 v[24:27], v[154:157], v[194:197], v[24:27]
	v_mfma_f32_16x16x32_bf16 v[12:15], v[146:149], v[210:213], v[12:15]
	v_mfma_f32_16x16x32_bf16 v[8:11], v[154:157], v[210:213], v[8:11]
	v_mfma_f32_16x16x32_bf16 v[60:63], v[150:153], v[182:185], v[60:63]
	v_mfma_f32_16x16x32_bf16 v[56:59], v[158:161], v[182:185], v[56:59]
	v_mfma_f32_16x16x32_bf16 v[44:47], v[150:153], v[190:193], v[44:47]
	v_mfma_f32_16x16x32_bf16 v[40:43], v[158:161], v[190:193], v[40:43]
	v_mfma_f32_16x16x32_bf16 v[28:31], v[150:153], v[198:201], v[28:31]
	v_mfma_f32_16x16x32_bf16 v[24:27], v[158:161], v[198:201], v[24:27]
	v_mfma_f32_16x16x32_bf16 v[12:15], v[150:153], v[214:217], v[12:15]
	v_mfma_f32_16x16x32_bf16 v[8:11], v[158:161], v[214:217], v[8:11]
	v_mfma_f32_16x16x32_bf16 v[52:55], v[162:165], v[178:181], v[52:55]
	v_mfma_f32_16x16x32_bf16 v[48:51], v[170:173], v[178:181], v[48:51]
	v_mfma_f32_16x16x32_bf16 v[36:39], v[162:165], v[186:189], v[36:39]
	v_mfma_f32_16x16x32_bf16 v[32:35], v[170:173], v[186:189], v[32:35]
	v_mfma_f32_16x16x32_bf16 v[20:23], v[162:165], v[194:197], v[20:23]
	v_mfma_f32_16x16x32_bf16 v[16:19], v[170:173], v[194:197], v[16:19]
	v_mfma_f32_16x16x32_bf16 v[4:7], v[162:165], v[210:213], v[4:7]
	v_mfma_f32_16x16x32_bf16 v[0:3], v[170:173], v[210:213], v[0:3]
	v_mfma_f32_16x16x32_bf16 v[52:55], v[166:169], v[182:185], v[52:55]
	v_mfma_f32_16x16x32_bf16 v[48:51], v[174:177], v[182:185], v[48:51]
	v_mfma_f32_16x16x32_bf16 v[36:39], v[166:169], v[190:193], v[36:39]
	v_mfma_f32_16x16x32_bf16 v[32:35], v[174:177], v[190:193], v[32:35]
	v_mfma_f32_16x16x32_bf16 v[20:23], v[166:169], v[198:201], v[20:23]
	v_mfma_f32_16x16x32_bf16 v[16:19], v[174:177], v[198:201], v[16:19]
	v_mfma_f32_16x16x32_bf16 v[4:7], v[166:169], v[214:217], v[4:7]
	v_mfma_f32_16x16x32_bf16 v[0:3], v[174:177], v[214:217], v[0:3]
	s_setprio 0
	s_barrier
	s_add_i32 s41, 0, 0x18000
	s_add_i32 s64, 0, 0x1c000
	v_add_u32_e32 v158, s41, v207
	v_add_u32_e32 v174, s64, v207
	ds_read_b128 v[146:149], v158
	ds_read_b128 v[150:153], v158 offset:1024
	ds_read_b128 v[154:157], v158 offset:2048
	ds_read_b128 v[158:161], v158 offset:3072
	ds_read_b128 v[162:165], v174
	ds_read_b128 v[166:169], v174 offset:1024
	ds_read_b128 v[170:173], v174 offset:2048
	ds_read_b128 v[174:177], v174 offset:3072
	s_add_u32 s46, s46, 0x40000
	s_addc_u32 s47, s47, 0
	s_mov_b32 m0, s57
	v_lshl_add_u64 v[224:225], s[46:47], 0, v[128:129]
	ds_read_b128 v[178:181], v209 offset:32768
	ds_read_b128 v[182:185], v209 offset:33792
	ds_read_b128 v[186:189], v209 offset:34816
	ds_read_b128 v[190:193], v209 offset:35840
	ds_read_b128 v[194:197], v209 offset:36864
	ds_read_b128 v[198:201], v209 offset:37888
	ds_read_b128 v[210:213], v209 offset:38912
	ds_read_b128 v[214:217], v209 offset:39936
	global_load_lds_dwordx4 v[224:225], off
	v_lshl_add_u64 v[224:225], s[46:47], 0, v[132:133]
	s_mov_b32 m0, s58
	s_nop 0
	global_load_lds_dwordx4 v[224:225], off
	s_waitcnt vmcnt(8)
	s_waitcnt lgkmcnt(0)
	s_barrier
	s_setprio 1
	v_mfma_f32_16x16x32_bf16 v[124:127], v[146:149], v[178:181], v[124:127]
	v_mfma_f32_16x16x32_bf16 v[120:123], v[154:157], v[178:181], v[120:123]
	v_mfma_f32_16x16x32_bf16 v[108:111], v[146:149], v[186:189], v[108:111]
	v_mfma_f32_16x16x32_bf16 v[104:107], v[154:157], v[186:189], v[104:107]
	v_mfma_f32_16x16x32_bf16 v[92:95], v[146:149], v[194:197], v[92:95]
	v_mfma_f32_16x16x32_bf16 v[88:91], v[154:157], v[194:197], v[88:91]
	v_mfma_f32_16x16x32_bf16 v[76:79], v[146:149], v[210:213], v[76:79]
	v_mfma_f32_16x16x32_bf16 v[72:75], v[154:157], v[210:213], v[72:75]
	v_mfma_f32_16x16x32_bf16 v[124:127], v[150:153], v[182:185], v[124:127]
	v_mfma_f32_16x16x32_bf16 v[120:123], v[158:161], v[182:185], v[120:123]
	v_mfma_f32_16x16x32_bf16 v[108:111], v[150:153], v[190:193], v[108:111]
	v_mfma_f32_16x16x32_bf16 v[104:107], v[158:161], v[190:193], v[104:107]
	v_mfma_f32_16x16x32_bf16 v[92:95], v[150:153], v[198:201], v[92:95]
	v_mfma_f32_16x16x32_bf16 v[88:91], v[158:161], v[198:201], v[88:91]
	v_mfma_f32_16x16x32_bf16 v[76:79], v[150:153], v[214:217], v[76:79]
	v_mfma_f32_16x16x32_bf16 v[72:75], v[158:161], v[214:217], v[72:75]
	v_mfma_f32_16x16x32_bf16 v[116:119], v[162:165], v[178:181], v[116:119]
	v_mfma_f32_16x16x32_bf16 v[112:115], v[170:173], v[178:181], v[112:115]
	v_mfma_f32_16x16x32_bf16 v[100:103], v[162:165], v[186:189], v[100:103]
	v_mfma_f32_16x16x32_bf16 v[96:99], v[170:173], v[186:189], v[96:99]
	v_mfma_f32_16x16x32_bf16 v[84:87], v[162:165], v[194:197], v[84:87]
	v_mfma_f32_16x16x32_bf16 v[80:83], v[170:173], v[194:197], v[80:83]
	v_mfma_f32_16x16x32_bf16 v[68:71], v[162:165], v[210:213], v[68:71]
	v_mfma_f32_16x16x32_bf16 v[64:67], v[170:173], v[210:213], v[64:67]
	v_mfma_f32_16x16x32_bf16 v[116:119], v[166:169], v[182:185], v[116:119]
	v_mfma_f32_16x16x32_bf16 v[112:115], v[174:177], v[182:185], v[112:115]
	v_mfma_f32_16x16x32_bf16 v[100:103], v[166:169], v[190:193], v[100:103]
	v_mfma_f32_16x16x32_bf16 v[96:99], v[174:177], v[190:193], v[96:99]
	v_mfma_f32_16x16x32_bf16 v[84:87], v[166:169], v[198:201], v[84:87]
	v_mfma_f32_16x16x32_bf16 v[80:83], v[174:177], v[198:201], v[80:83]
	v_mfma_f32_16x16x32_bf16 v[68:71], v[166:169], v[214:217], v[68:71]
	v_mfma_f32_16x16x32_bf16 v[64:67], v[174:177], v[214:217], v[64:67]
	s_setprio 0
	s_barrier
; #define PG8_STAGE(bufoff, gbase, voff) do { _Pragma("unroll") for (int _i = 0; _i < 2; ++_i) \
;         __builtin_amdgcn_global_load_lds((const unsigned*)((const char*)(gbase) + (voff)[_i]), (PG8_LAS unsigned*)(lds + (bufoff) + ldsw + _i * 8192), 16, 0, 0); } while (0)
; #define PG8_LDA(dst, b, h) do { _Pragma("unroll") for (int m = 0; m < 4; ++m) _Pragma("unroll") for (int k = 0; k < 2; ++k) dst[m][k] = *(const PG8_LAS bf16x8*)(lds + PG8_SA(b, h) + aoff + m * 2048 + k * 1024); } while (0)
; #define PG8_LDB(dst, b, h) do { _Pragma("unroll") for (int n = 0; n < 2; ++n) _Pragma("unroll") for (int k = 0; k < 2; ++k) dst[n][k] = *(const PG8_LAS bf16x8*)(lds + PG8_SB(b, h) + boff + n * 2048 + k * 1024); } while (0)
; template <class Epi, class Sched, bool ALIGN_EPI = false, bool SP2 = false>
; __device__ __forceinline__ void gemm_phase(PG8_LAS unsigned char* lds, const Gemm g, const Sched& S, const Epi& E, const int wv0) {
;     ...
;         for (int t = 0; t < nt; t += 2) {
;             const bool last = (t == nt - 2);
;             const char* a1 = cA + (size_t)(t + 1) * kstep;
;             const char* a2 = last ? nA : cA + (size_t)(t + 2) * kstep; const char* b2 = last ? nB : cB + (size_t)(t + 2) * kstep;
;             const char* a3 = a2 + kstep; const char* b3 = b2 + kstep;
;             if constexpr (SP2) {
;             PG8_LDB(B0, 0, 0); PG8_LDB(B1, 0, 1); PG8_SCHED; PG8_LDA(At, 0, 0); PG8_STAGE(PG8_SA(1, 1), a1 + hstepA, voffA);
;             PG8_WAIT_V(8); PG8_WAIT_L(0); PG8_BAR; PG8_MMA(0, 0, At, B0); PG8_MMA(0, 1, At, B1); PG8_BAR; PG8_SCHED;
;             PG8_LDA(At, 0, 1); PG8_STAGE(PG8_SB(0, 0), b2, voffB); PG8_STAGE(PG8_SB(0, 1), b2 + hstepB, voffB); PG8_STAGE(PG8_SA(0, 0), a2, voffA);
;             PG8_WAIT_V(8); PG8_WAIT_L(0); PG8_BAR; PG8_MMA(1, 0, At, B0); PG8_MMA(1, 1, At, B1); PG8_BAR; PG8_SCHED;
;             PG8_LDB(B0, 1, 0); PG8_LDB(B1, 1, 1); PG8_SCHED; PG8_LDA(At, 1, 0); PG8_STAGE(PG8_SA(0, 1), a2 + hstepA, voffA);
;             PG8_WAIT_V(8); PG8_WAIT_L(0); PG8_BAR; PG8_MMA(0, 0, At, B0); PG8_MMA(0, 1, At, B1); PG8_BAR; PG8_SCHED;
;             PG8_LDA(At, 1, 1); PG8_STAGE(PG8_SB(1, 0), b3, voffB); PG8_STAGE(PG8_SB(1, 1), b3 + hstepB, voffB); PG8_STAGE(PG8_SA(1, 0), a3, voffA);
;             PG8_WAIT_V(8); PG8_WAIT_L(0); PG8_BAR; PG8_MMA(1, 0, At, B0); PG8_MMA(1, 1, At, B1); PG8_BAR; PG8_SCHED;
	s_add_i32 s41, s41, s54
	v_lshl_add_u64 v[202:203], v[202:203], 0, s[10:11]
	s_mov_b32 m0, s41
	ds_read_b128 v[178:181], v209 offset:49152
	ds_read_b128 v[182:185], v209 offset:50176
	ds_read_b128 v[186:189], v209 offset:51200
	ds_read_b128 v[190:193], v209 offset:52224
	ds_read_b128 v[194:197], v209 offset:53248
	ds_read_b128 v[198:201], v209 offset:54272
	ds_read_b128 v[210:213], v209 offset:55296
	ds_read_b128 v[214:217], v209 offset:56320
	global_load_lds_dwordx4 v[202:203], off
	s_add_i32 m0, s41, 0x2000
	s_add_u32 s44, s44, 0x40080
	v_lshl_add_u64 v[202:203], v[218:219], 0, s[10:11]
	s_addc_u32 s45, s45, 0
	s_add_i32 s41, s64, s54
	global_load_lds_dwordx4 v[202:203], off
	v_lshl_add_u64 v[202:203], s[44:45], 0, v[130:131]
	s_mov_b32 m0, s41
	s_nop 0
	global_load_lds_dwordx4 v[202:203], off
	v_lshl_add_u64 v[202:203], s[44:45], 0, v[134:135]
	s_add_i32 m0, s41, 0x2000
	s_nop 0
	global_load_lds_dwordx4 v[202:203], off
	v_lshl_add_u64 v[202:203], v[220:221], 0, s[10:11]
	s_mov_b32 m0, s59
	s_nop 0
	global_load_lds_dwordx4 v[202:203], off
	v_lshl_add_u64 v[202:203], v[222:223], 0, s[10:11]
	s_mov_b32 m0, s60
	s_nop 0
	global_load_lds_dwordx4 v[202:203], off
	s_waitcnt vmcnt(8)
	s_waitcnt lgkmcnt(0)
	s_barrier
	s_setprio 1
	v_mfma_f32_16x16x32_bf16 v[60:63], v[146:149], v[178:181], v[60:63]
	v_mfma_f32_16x16x32_bf16 v[56:59], v[154:157], v[178:181], v[56:59]
	v_mfma_f32_16x16x32_bf16 v[44:47], v[146:149], v[186:189], v[44:47]
	v_mfma_f32_16x16x32_bf16 v[40:43], v[154:157], v[186:189], v[40:43]
	v_mfma_f32_16x16x32_bf16 v[28:31], v[146:149], v[194:197], v[28:31]
	v_mfma_f32_16x16x32_bf16 v[24:27], v[154:157], v[194:197], v[24:27]
	v_mfma_f32_16x16x32_bf16 v[12:15], v[146:149], v[210:213], v[12:15]
	v_mfma_f32_16x16x32_bf16 v[8:11], v[154:157], v[210:213], v[8:11]
	v_mfma_f32_16x16x32_bf16 v[60:63], v[150:153], v[182:185], v[60:63]
	v_mfma_f32_16x16x32_bf16 v[56:59], v[158:161], v[182:185], v[56:59]
	v_mfma_f32_16x16x32_bf16 v[44:47], v[150:153], v[190:193], v[44:47]
	v_mfma_f32_16x16x32_bf16 v[40:43], v[158:161], v[190:193], v[40:43]
	v_mfma_f32_16x16x32_bf16 v[28:31], v[150:153], v[198:201], v[28:31]
	v_mfma_f32_16x16x32_bf16 v[24:27], v[158:161], v[198:201], v[24:27]
	v_mfma_f32_16x16x32_bf16 v[12:15], v[150:153], v[214:217], v[12:15]
	v_mfma_f32_16x16x32_bf16 v[8:11], v[158:161], v[214:217], v[8:11]
	v_mfma_f32_16x16x32_bf16 v[52:55], v[162:165], v[178:181], v[52:55]
	v_mfma_f32_16x16x32_bf16 v[48:51], v[170:173], v[178:181], v[48:51]
	v_mfma_f32_16x16x32_bf16 v[36:39], v[162:165], v[186:189], v[36:39]
	v_mfma_f32_16x16x32_bf16 v[32:35], v[170:173], v[186:189], v[32:35]
	v_mfma_f32_16x16x32_bf16 v[20:23], v[162:165], v[194:197], v[20:23]
	v_mfma_f32_16x16x32_bf16 v[16:19], v[170:173], v[194:197], v[16:19]
	v_mfma_f32_16x16x32_bf16 v[4:7], v[162:165], v[210:213], v[4:7]
	v_mfma_f32_16x16x32_bf16 v[0:3], v[170:173], v[210:213], v[0:3]
	v_mfma_f32_16x16x32_bf16 v[52:55], v[166:169], v[182:185], v[52:55]
	v_mfma_f32_16x16x32_bf16 v[48:51], v[174:177], v[182:185], v[48:51]
	v_mfma_f32_16x16x32_bf16 v[36:39], v[166:169], v[190:193], v[36:39]
	v_mfma_f32_16x16x32_bf16 v[32:35], v[174:177], v[190:193], v[32:35]
	v_mfma_f32_16x16x32_bf16 v[20:23], v[166:169], v[198:201], v[20:23]
	v_mfma_f32_16x16x32_bf16 v[16:19], v[174:177], v[198:201], v[16:19]
	v_mfma_f32_16x16x32_bf16 v[4:7], v[166:169], v[214:217], v[4:7]
	v_mfma_f32_16x16x32_bf16 v[0:3], v[174:177], v[214:217], v[0:3]
	s_setprio 0
	s_barrier
	s_add_i32 s29, s29, 2
	s_add_u32 s25, s25, 0x100
	s_addc_u32 s27, s27, 0
	s_add_u32 s38, s38, 0x100
	s_addc_u32 s39, s39, 0
	s_cmp_gt_u32 s29, 13
	s_cbranch_scc0 .LBB0_494
	s_and_b64 vcc, exec, s[12:13]
	s_cbranch_vccz .LBB0_497
	s_barrier

; #define PG8_STAGE(bufoff, gbase, voff) do { _Pragma("unroll") for (int _i = 0; _i < 2; ++_i) \
;         __builtin_amdgcn_global_load_lds((const unsigned*)((const char*)(gbase) + (voff)[_i]), (PG8_LAS unsigned*)(lds + (bufoff) + ldsw + _i * 8192), 16, 0, 0); } while (0)
; #define PG8_LDA(dst, b, h) do { _Pragma("unroll") for (int m = 0; m < 4; ++m) _Pragma("unroll") for (int k = 0; k < 2; ++k) dst[m][k] = *(const PG8_LAS bf16x8*)(lds + PG8_SA(b, h) + aoff + m * 2048 + k * 1024); } while (0)
; #define PG8_LDB(dst, b, h) do { _Pragma("unroll") for (int n = 0; n < 2; ++n) _Pragma("unroll") for (int k = 0; k < 2; ++k) dst[n][k] = *(const PG8_LAS bf16x8*)(lds + PG8_SB(b, h) + boff + n * 2048 + k * 1024); } while (0)
; template <class Epi, class Sched, bool ALIGN_EPI = false, bool SP2 = false>
; __device__ __forceinline__ void gemm_phase(PG8_LAS unsigned char* lds, const Gemm g, const Sched& S, const Epi& E, const int wv0) {
;     ...
;         for (int t = 0; t < nt; t += 2) {
;             const bool last = (t == nt - 2);
;             const char* a1 = cA + (size_t)(t + 1) * kstep;
;             const char* a2 = last ? nA : cA + (size_t)(t + 2) * kstep; const char* b2 = last ? nB : cB + (size_t)(t + 2) * kstep;
;             const char* a3 = a2 + kstep; const char* b3 = b2 + kstep;
;             if constexpr (SP2) {
;             PG8_LDB(B0, 0, 0); PG8_LDB(B1, 0, 1); PG8_SCHED; PG8_LDA(At, 0, 0); PG8_STAGE(PG8_SA(1, 1), a1 + hstepA, voffA);
;             PG8_WAIT_V(8); PG8_WAIT_L(0); PG8_BAR; PG8_MMA(0, 0, At, B0); PG8_MMA(0, 1, At, B1); PG8_BAR; PG8_SCHED;
;             PG8_LDA(At, 0, 1); PG8_STAGE(PG8_SB(0, 0), b2, voffB); PG8_STAGE(PG8_SB(0, 1), b2 + hstepB, voffB); PG8_STAGE(PG8_SA(0, 0), a2, voffA);
;             PG8_WAIT_V(8); PG8_WAIT_L(0); PG8_BAR; PG8_MMA(1, 0, At, B0); PG8_MMA(1, 1, At, B1); PG8_BAR; PG8_SCHED;
;             PG8_LDB(B0, 1, 0); PG8_LDB(B1, 1, 1); PG8_SCHED; PG8_LDA(At, 1, 0); PG8_STAGE(PG8_SA(0, 1), a2 + hstepA, voffA);
;             PG8_WAIT_V(8); PG8_WAIT_L(0); PG8_BAR; PG8_MMA(0, 0, At, B0); PG8_MMA(0, 1, At, B1); PG8_BAR; PG8_SCHED;
;             PG8_LDA(At, 1, 1); PG8_STAGE(PG8_SB(1, 0), b3, voffB); PG8_STAGE(PG8_SB(1, 1), b3 + hstepB, voffB); PG8_STAGE(PG8_SA(1, 0), a3, voffA);
;             PG8_WAIT_V(8); PG8_WAIT_L(0); PG8_BAR; PG8_MMA(1, 0, At, B0); PG8_MMA(1, 1, At, B1); PG8_BAR; PG8_SCHED;
.LBB0_667:
	ds_read_b128 v[144:147], v153
	ds_read_b128 v[156:159], v153 offset:1024
	ds_read_b128 v[160:163], v153 offset:2048
	ds_read_b128 v[164:167], v153 offset:3072
	ds_read_b128 v[168:171], v154
	ds_read_b128 v[172:175], v154 offset:1024
	ds_read_b128 v[176:179], v154 offset:2048
	ds_read_b128 v[180:183], v154 offset:3072
	s_add_u32 s24, s22, 0xfff80080
	s_addc_u32 s25, s23, -1
	s_cmp_eq_u32 s50, 28
	s_cselect_b32 s27, s17, s25
	s_cselect_b32 s26, s16, s24
	s_cselect_b32 s25, s19, s15
	s_cselect_b32 s24, s18, s13
	v_lshl_add_u64 v[148:149], s[22:23], 0, v[138:139]
	s_add_i32 m0, s21, 0xc000
	ds_read_b128 v[184:187], v155
	ds_read_b128 v[188:191], v155 offset:1024
	ds_read_b128 v[192:195], v155 offset:2048
	ds_read_b128 v[196:199], v155 offset:3072
	ds_read_b128 v[200:203], v155 offset:4096
	ds_read_b128 v[206:209], v155 offset:5120
	ds_read_b128 v[210:213], v155 offset:6144
	ds_read_b128 v[214:217], v155 offset:7168
	global_load_lds_dwordx4 v[148:149], off
	v_lshl_add_u64 v[148:149], s[22:23], 0, v[136:137]
	s_add_i32 m0, s21, 0xe000
	s_nop 0
	global_load_lds_dwordx4 v[148:149], off
	s_waitcnt vmcnt(8)
	s_waitcnt lgkmcnt(0)
	s_barrier
	s_setprio 1
	v_mfma_f32_16x16x32_bf16 v[124:127], v[144:147], v[184:187], v[124:127]
	v_mfma_f32_16x16x32_bf16 v[120:123], v[160:163], v[184:187], v[120:123]
	v_mfma_f32_16x16x32_bf16 v[116:119], v[144:147], v[192:195], v[116:119]
	v_mfma_f32_16x16x32_bf16 v[112:115], v[160:163], v[192:195], v[112:115]
	v_mfma_f32_16x16x32_bf16 v[92:95], v[144:147], v[200:203], v[92:95]
	v_mfma_f32_16x16x32_bf16 v[88:91], v[160:163], v[200:203], v[88:91]
	v_mfma_f32_16x16x32_bf16 v[84:87], v[144:147], v[210:213], v[84:87]
	v_mfma_f32_16x16x32_bf16 v[80:83], v[160:163], v[210:213], v[80:83]
	v_mfma_f32_16x16x32_bf16 v[124:127], v[156:159], v[188:191], v[124:127]
	v_mfma_f32_16x16x32_bf16 v[120:123], v[164:167], v[188:191], v[120:123]
	v_mfma_f32_16x16x32_bf16 v[116:119], v[156:159], v[196:199], v[116:119]
	v_mfma_f32_16x16x32_bf16 v[112:115], v[164:167], v[196:199], v[112:115]
	v_mfma_f32_16x16x32_bf16 v[92:95], v[156:159], v[206:209], v[92:95]
	v_mfma_f32_16x16x32_bf16 v[88:91], v[164:167], v[206:209], v[88:91]
	v_mfma_f32_16x16x32_bf16 v[84:87], v[156:159], v[214:217], v[84:87]
	v_mfma_f32_16x16x32_bf16 v[80:83], v[164:167], v[214:217], v[80:83]
	v_mfma_f32_16x16x32_bf16 v[108:111], v[168:171], v[184:187], v[108:111]
	v_mfma_f32_16x16x32_bf16 v[104:107], v[176:179], v[184:187], v[104:107]
	v_mfma_f32_16x16x32_bf16 v[100:103], v[168:171], v[192:195], v[100:103]
	v_mfma_f32_16x16x32_bf16 v[96:99], v[176:179], v[192:195], v[96:99]
	v_mfma_f32_16x16x32_bf16 v[76:79], v[168:171], v[200:203], v[76:79]
	v_mfma_f32_16x16x32_bf16 v[72:75], v[176:179], v[200:203], v[72:75]
	v_mfma_f32_16x16x32_bf16 v[68:71], v[168:171], v[210:213], v[68:71]
	v_mfma_f32_16x16x32_bf16 v[64:67], v[176:179], v[210:213], v[64:67]
	v_mfma_f32_16x16x32_bf16 v[108:111], v[172:175], v[188:191], v[108:111]
	v_mfma_f32_16x16x32_bf16 v[104:107], v[180:183], v[188:191], v[104:107]
	v_mfma_f32_16x16x32_bf16 v[100:103], v[172:175], v[196:199], v[100:103]
	v_mfma_f32_16x16x32_bf16 v[96:99], v[180:183], v[196:199], v[96:99]
	v_mfma_f32_16x16x32_bf16 v[76:79], v[172:175], v[206:209], v[76:79]
	v_mfma_f32_16x16x32_bf16 v[72:75], v[180:183], v[206:209], v[72:75]
	v_mfma_f32_16x16x32_bf16 v[68:71], v[172:175], v[214:217], v[68:71]
	v_mfma_f32_16x16x32_bf16 v[64:67], v[180:183], v[214:217], v[64:67]
	s_setprio 0
	s_barrier
	s_add_i32 s51, s47, s37
	v_lshl_add_u64 v[148:149], s[24:25], 0, v[130:131]
	s_mov_b32 m0, s51
	ds_read_b128 v[184:187], v155 offset:16384
	ds_read_b128 v[188:191], v155 offset:17408
	ds_read_b128 v[192:195], v155 offset:18432
	ds_read_b128 v[196:199], v155 offset:19456
	ds_read_b128 v[200:203], v155 offset:20480
	ds_read_b128 v[206:209], v155 offset:21504
	ds_read_b128 v[210:213], v155 offset:22528
	ds_read_b128 v[214:217], v155 offset:23552
	global_load_lds_dwordx4 v[148:149], off
	s_add_i32 m0, s51, 0x2000
	s_add_u32 s52, s24, 0x80000
	v_lshl_add_u64 v[218:219], s[24:25], 0, v[134:135]
	s_addc_u32 s53, s25, 0
	s_add_i32 s51, s48, s37
	global_load_lds_dwordx4 v[218:219], off
	v_lshl_add_u64 v[220:221], s[52:53], 0, v[130:131]
	s_mov_b32 m0, s51
	v_lshl_add_u64 v[222:223], s[26:27], 0, v[132:133]
	global_load_lds_dwordx4 v[220:221], off
	v_lshl_add_u64 v[220:221], s[52:53], 0, v[134:135]
	s_add_i32 m0, s51, 0x2000
	s_nop 0
	global_load_lds_dwordx4 v[220:221], off
	v_lshl_add_u64 v[220:221], s[26:27], 0, v[128:129]
	s_mov_b32 m0, s21
	s_nop 0
	global_load_lds_dwordx4 v[220:221], off
	s_mov_b32 m0, s38
	s_nop 0
	global_load_lds_dwordx4 v[222:223], off
	s_waitcnt vmcnt(8)
	s_waitcnt lgkmcnt(0)
	s_barrier
; #define PG8_STAGE(bufoff, gbase, voff) do { _Pragma("unroll") for (int _i = 0; _i < 2; ++_i) \
;         __builtin_amdgcn_global_load_lds((const unsigned*)((const char*)(gbase) + (voff)[_i]), (PG8_LAS unsigned*)(lds + (bufoff) + ldsw + _i * 8192), 16, 0, 0); } while (0)
; #define PG8_LDA(dst, b, h) do { _Pragma("unroll") for (int m = 0; m < 4; ++m) _Pragma("unroll") for (int k = 0; k < 2; ++k) dst[m][k] = *(const PG8_LAS bf16x8*)(lds + PG8_SA(b, h) + aoff + m * 2048 + k * 1024); } while (0)
; #define PG8_LDB(dst, b, h) do { _Pragma("unroll") for (int n = 0; n < 2; ++n) _Pragma("unroll") for (int k = 0; k < 2; ++k) dst[n][k] = *(const PG8_LAS bf16x8*)(lds + PG8_SB(b, h) + boff + n * 2048 + k * 1024); } while (0)
; template <class Epi, class Sched, bool ALIGN_EPI = false, bool SP2 = false>
; __device__ __forceinline__ void gemm_phase(PG8_LAS unsigned char* lds, const Gemm g, const Sched& S, const Epi& E, const int wv0) {
;     ...
;         for (int t = 0; t < nt; t += 2) {
;             const bool last = (t == nt - 2);
;             const char* a1 = cA + (size_t)(t + 1) * kstep;
;             const char* a2 = last ? nA : cA + (size_t)(t + 2) * kstep; const char* b2 = last ? nB : cB + (size_t)(t + 2) * kstep;
;             const char* a3 = a2 + kstep; const char* b3 = b2 + kstep;
;             if constexpr (SP2) {
;             PG8_LDB(B0, 0, 0); PG8_LDB(B1, 0, 1); PG8_SCHED; PG8_LDA(At, 0, 0); PG8_STAGE(PG8_SA(1, 1), a1 + hstepA, voffA);
;             PG8_WAIT_V(8); PG8_WAIT_L(0); PG8_BAR; PG8_MMA(0, 0, At, B0); PG8_MMA(0, 1, At, B1); PG8_BAR; PG8_SCHED;
;             PG8_LDA(At, 0, 1); PG8_STAGE(PG8_SB(0, 0), b2, voffB); PG8_STAGE(PG8_SB(0, 1), b2 + hstepB, voffB); PG8_STAGE(PG8_SA(0, 0), a2, voffA);
;             PG8_WAIT_V(8); PG8_WAIT_L(0); PG8_BAR; PG8_MMA(1, 0, At, B0); PG8_MMA(1, 1, At, B1); PG8_BAR; PG8_SCHED;
;             PG8_LDB(B0, 1, 0); PG8_LDB(B1, 1, 1); PG8_SCHED; PG8_LDA(At, 1, 0); PG8_STAGE(PG8_SA(0, 1), a2 + hstepA, voffA);
;             PG8_WAIT_V(8); PG8_WAIT_L(0); PG8_BAR; PG8_MMA(0, 0, At, B0); PG8_MMA(0, 1, At, B1); PG8_BAR; PG8_SCHED;
;             PG8_LDA(At, 1, 1); PG8_STAGE(PG8_SB(1, 0), b3, voffB); PG8_STAGE(PG8_SB(1, 1), b3 + hstepB, voffB); PG8_STAGE(PG8_SA(1, 0), a3, voffA);
;             PG8_WAIT_V(8); PG8_WAIT_L(0); PG8_BAR; PG8_MMA(1, 0, At, B0); PG8_MMA(1, 1, At, B1); PG8_BAR; PG8_SCHED;
	s_setprio 1
	v_mfma_f32_16x16x32_bf16 v[60:63], v[144:147], v[184:187], v[60:63]
	v_mfma_f32_16x16x32_bf16 v[56:59], v[160:163], v[184:187], v[56:59]
	v_mfma_f32_16x16x32_bf16 v[52:55], v[144:147], v[192:195], v[52:55]
	v_mfma_f32_16x16x32_bf16 v[48:51], v[160:163], v[192:195], v[48:51]
	v_mfma_f32_16x16x32_bf16 v[28:31], v[144:147], v[200:203], v[28:31]
	v_mfma_f32_16x16x32_bf16 v[24:27], v[160:163], v[200:203], v[24:27]
	v_mfma_f32_16x16x32_bf16 v[20:23], v[144:147], v[210:213], v[20:23]
	v_mfma_f32_16x16x32_bf16 v[16:19], v[160:163], v[210:213], v[16:19]
	v_mfma_f32_16x16x32_bf16 v[60:63], v[156:159], v[188:191], v[60:63]
	v_mfma_f32_16x16x32_bf16 v[56:59], v[164:167], v[188:191], v[56:59]
	v_mfma_f32_16x16x32_bf16 v[52:55], v[156:159], v[196:199], v[52:55]
	v_mfma_f32_16x16x32_bf16 v[48:51], v[164:167], v[196:199], v[48:51]
	v_mfma_f32_16x16x32_bf16 v[28:31], v[156:159], v[206:209], v[28:31]
	v_mfma_f32_16x16x32_bf16 v[24:27], v[164:167], v[206:209], v[24:27]
	v_mfma_f32_16x16x32_bf16 v[20:23], v[156:159], v[214:217], v[20:23]
	v_mfma_f32_16x16x32_bf16 v[16:19], v[164:167], v[214:217], v[16:19]
	v_mfma_f32_16x16x32_bf16 v[44:47], v[168:171], v[184:187], v[44:47]
	v_mfma_f32_16x16x32_bf16 v[40:43], v[176:179], v[184:187], v[40:43]
	v_mfma_f32_16x16x32_bf16 v[36:39], v[168:171], v[192:195], v[36:39]
	v_mfma_f32_16x16x32_bf16 v[32:35], v[176:179], v[192:195], v[32:35]
	v_mfma_f32_16x16x32_bf16 v[12:15], v[168:171], v[200:203], v[12:15]
	v_mfma_f32_16x16x32_bf16 v[8:11], v[176:179], v[200:203], v[8:11]
	v_mfma_f32_16x16x32_bf16 v[4:7], v[168:171], v[210:213], v[4:7]
	v_mfma_f32_16x16x32_bf16 v[0:3], v[176:179], v[210:213], v[0:3]
	v_mfma_f32_16x16x32_bf16 v[44:47], v[172:175], v[188:191], v[44:47]
	v_mfma_f32_16x16x32_bf16 v[40:43], v[180:183], v[188:191], v[40:43]
	v_mfma_f32_16x16x32_bf16 v[36:39], v[172:175], v[196:199], v[36:39]
	v_mfma_f32_16x16x32_bf16 v[32:35], v[180:183], v[196:199], v[32:35]
	v_mfma_f32_16x16x32_bf16 v[12:15], v[172:175], v[206:209], v[12:15]
	v_mfma_f32_16x16x32_bf16 v[8:11], v[180:183], v[206:209], v[8:11]
	v_mfma_f32_16x16x32_bf16 v[4:7], v[172:175], v[214:217], v[4:7]
	v_mfma_f32_16x16x32_bf16 v[0:3], v[180:183], v[214:217], v[0:3]
	s_setprio 0
	s_barrier
	s_add_i32 s51, 0, 0x18000
	s_add_i32 s52, 0, 0x1c000
	v_add_u32_e32 v164, s51, v151
	v_add_u32_e32 v180, s52, v151
	ds_read_b128 v[144:147], v164
	ds_read_b128 v[156:159], v164 offset:1024
	ds_read_b128 v[160:163], v164 offset:2048
	ds_read_b128 v[164:167], v164 offset:3072
	ds_read_b128 v[168:171], v180
	ds_read_b128 v[172:175], v180 offset:1024
	ds_read_b128 v[176:179], v180 offset:2048
	ds_read_b128 v[180:183], v180 offset:3072
	s_add_u32 s26, s26, 0x80000
	s_addc_u32 s27, s27, 0
	s_mov_b32 m0, s39
	v_lshl_add_u64 v[224:225], s[26:27], 0, v[128:129]
	ds_read_b128 v[184:187], v155 offset:32768
	ds_read_b128 v[188:191], v155 offset:33792
	ds_read_b128 v[192:195], v155 offset:34816
	ds_read_b128 v[196:199], v155 offset:35840
	ds_read_b128 v[200:203], v155 offset:36864
	ds_read_b128 v[206:209], v155 offset:37888
	ds_read_b128 v[210:213], v155 offset:38912
	ds_read_b128 v[214:217], v155 offset:39936
	global_load_lds_dwordx4 v[224:225], off
	v_lshl_add_u64 v[224:225], s[26:27], 0, v[132:133]
	s_mov_b32 m0, s40
	s_nop 0
	global_load_lds_dwordx4 v[224:225], off
	s_waitcnt vmcnt(8)
	s_waitcnt lgkmcnt(0)
	s_barrier
	s_setprio 1
	v_mfma_f32_16x16x32_bf16 v[124:127], v[144:147], v[184:187], v[124:127]
	v_mfma_f32_16x16x32_bf16 v[120:123], v[160:163], v[184:187], v[120:123]
	v_mfma_f32_16x16x32_bf16 v[116:119], v[144:147], v[192:195], v[116:119]
	v_mfma_f32_16x16x32_bf16 v[112:115], v[160:163], v[192:195], v[112:115]
	v_mfma_f32_16x16x32_bf16 v[92:95], v[144:147], v[200:203], v[92:95]
	v_mfma_f32_16x16x32_bf16 v[88:91], v[160:163], v[200:203], v[88:91]
	v_mfma_f32_16x16x32_bf16 v[84:87], v[144:147], v[210:213], v[84:87]
	v_mfma_f32_16x16x32_bf16 v[80:83], v[160:163], v[210:213], v[80:83]
	v_mfma_f32_16x16x32_bf16 v[124:127], v[156:159], v[188:191], v[124:127]
	v_mfma_f32_16x16x32_bf16 v[120:123], v[164:167], v[188:191], v[120:123]
	v_mfma_f32_16x16x32_bf16 v[116:119], v[156:159], v[196:199], v[116:119]
	v_mfma_f32_16x16x32_bf16 v[112:115], v[164:167], v[196:199], v[112:115]
	v_mfma_f32_16x16x32_bf16 v[92:95], v[156:159], v[206:209], v[92:95]
	v_mfma_f32_16x16x32_bf16 v[88:91], v[164:167], v[206:209], v[88:91]
	v_mfma_f32_16x16x32_bf16 v[84:87], v[156:159], v[214:217], v[84:87]
	v_mfma_f32_16x16x32_bf16 v[80:83], v[164:167], v[214:217], v[80:83]
	v_mfma_f32_16x16x32_bf16 v[108:111], v[168:171], v[184:187], v[108:111]
	v_mfma_f32_16x16x32_bf16 v[104:107], v[176:179], v[184:187], v[104:107]
	v_mfma_f32_16x16x32_bf16 v[100:103], v[168:171], v[192:195], v[100:103]
	v_mfma_f32_16x16x32_bf16 v[96:99], v[176:179], v[192:195], v[96:99]
	v_mfma_f32_16x16x32_bf16 v[76:79], v[168:171], v[200:203], v[76:79]
	v_mfma_f32_16x16x32_bf16 v[72:75], v[176:179], v[200:203], v[72:75]
	v_mfma_f32_16x16x32_bf16 v[68:71], v[168:171], v[210:213], v[68:71]
	v_mfma_f32_16x16x32_bf16 v[64:67], v[176:179], v[210:213], v[64:67]
	v_mfma_f32_16x16x32_bf16 v[108:111], v[172:175], v[188:191], v[108:111]
	v_mfma_f32_16x16x32_bf16 v[104:107], v[180:183], v[188:191], v[104:107]
	v_mfma_f32_16x16x32_bf16 v[100:103], v[172:175], v[196:199], v[100:103]
	v_mfma_f32_16x16x32_bf16 v[96:99], v[180:183], v[196:199], v[96:99]
	v_mfma_f32_16x16x32_bf16 v[76:79], v[172:175], v[206:209], v[76:79]
	v_mfma_f32_16x16x32_bf16 v[72:75], v[180:183], v[206:209], v[72:75]
	v_mfma_f32_16x16x32_bf16 v[68:71], v[172:175], v[214:217], v[68:71]
	v_mfma_f32_16x16x32_bf16 v[64:67], v[180:183], v[214:217], v[64:67]
	s_setprio 0
	s_barrier
; #define PG8_STAGE(bufoff, gbase, voff) do { _Pragma("unroll") for (int _i = 0; _i < 2; ++_i) \
;         __builtin_amdgcn_global_load_lds((const unsigned*)((const char*)(gbase) + (voff)[_i]), (PG8_LAS unsigned*)(lds + (bufoff) + ldsw + _i * 8192), 16, 0, 0); } while (0)
; #define PG8_LDA(dst, b, h) do { _Pragma("unroll") for (int m = 0; m < 4; ++m) _Pragma("unroll") for (int k = 0; k < 2; ++k) dst[m][k] = *(const PG8_LAS bf16x8*)(lds + PG8_SA(b, h) + aoff + m * 2048 + k * 1024); } while (0)
; #define PG8_LDB(dst, b, h) do { _Pragma("unroll") for (int n = 0; n < 2; ++n) _Pragma("unroll") for (int k = 0; k < 2; ++k) dst[n][k] = *(const PG8_LAS bf16x8*)(lds + PG8_SB(b, h) + boff + n * 2048 + k * 1024); } while (0)
; template <class Epi, class Sched, bool ALIGN_EPI = false, bool SP2 = false>
; __device__ __forceinline__ void gemm_phase(PG8_LAS unsigned char* lds, const Gemm g, const Sched& S, const Epi& E, const int wv0) {
;     ...
;         for (int t = 0; t < nt; t += 2) {
;             const bool last = (t == nt - 2);
;             const char* a1 = cA + (size_t)(t + 1) * kstep;
;             const char* a2 = last ? nA : cA + (size_t)(t + 2) * kstep; const char* b2 = last ? nB : cB + (size_t)(t + 2) * kstep;
;             const char* a3 = a2 + kstep; const char* b3 = b2 + kstep;
;             if constexpr (SP2) {
;             PG8_LDB(B0, 0, 0); PG8_LDB(B1, 0, 1); PG8_SCHED; PG8_LDA(At, 0, 0); PG8_STAGE(PG8_SA(1, 1), a1 + hstepA, voffA);
;             PG8_WAIT_V(8); PG8_WAIT_L(0); PG8_BAR; PG8_MMA(0, 0, At, B0); PG8_MMA(0, 1, At, B1); PG8_BAR; PG8_SCHED;
;             PG8_LDA(At, 0, 1); PG8_STAGE(PG8_SB(0, 0), b2, voffB); PG8_STAGE(PG8_SB(0, 1), b2 + hstepB, voffB); PG8_STAGE(PG8_SA(0, 0), a2, voffA);
;             PG8_WAIT_V(8); PG8_WAIT_L(0); PG8_BAR; PG8_MMA(1, 0, At, B0); PG8_MMA(1, 1, At, B1); PG8_BAR; PG8_SCHED;
;             PG8_LDB(B0, 1, 0); PG8_LDB(B1, 1, 1); PG8_SCHED; PG8_LDA(At, 1, 0); PG8_STAGE(PG8_SA(0, 1), a2 + hstepA, voffA);
;             PG8_WAIT_V(8); PG8_WAIT_L(0); PG8_BAR; PG8_MMA(0, 0, At, B0); PG8_MMA(0, 1, At, B1); PG8_BAR; PG8_SCHED;
;             PG8_LDA(At, 1, 1); PG8_STAGE(PG8_SB(1, 0), b3, voffB); PG8_STAGE(PG8_SB(1, 1), b3 + hstepB, voffB); PG8_STAGE(PG8_SA(1, 0), a3, voffA);
;             PG8_WAIT_V(8); PG8_WAIT_L(0); PG8_BAR; PG8_MMA(1, 0, At, B0); PG8_MMA(1, 1, At, B1); PG8_BAR; PG8_SCHED;
	s_add_i32 s26, s51, s37
	v_lshl_add_u64 v[148:149], v[148:149], 0, s[8:9]
	s_mov_b32 m0, s26
	ds_read_b128 v[184:187], v155 offset:49152
	ds_read_b128 v[188:191], v155 offset:50176
	ds_read_b128 v[192:195], v155 offset:51200
	ds_read_b128 v[196:199], v155 offset:52224
	ds_read_b128 v[200:203], v155 offset:53248
	ds_read_b128 v[206:209], v155 offset:54272
	ds_read_b128 v[210:213], v155 offset:55296
	ds_read_b128 v[214:217], v155 offset:56320
	global_load_lds_dwordx4 v[148:149], off
	s_add_i32 m0, s26, 0x2000
	s_add_u32 s24, s24, 0x80080
	v_lshl_add_u64 v[148:149], v[218:219], 0, s[8:9]
	s_addc_u32 s25, s25, 0
	s_add_i32 s26, s52, s37
	global_load_lds_dwordx4 v[148:149], off
	v_lshl_add_u64 v[148:149], s[24:25], 0, v[130:131]
	s_mov_b32 m0, s26
	s_nop 0
	global_load_lds_dwordx4 v[148:149], off
	v_lshl_add_u64 v[148:149], s[24:25], 0, v[134:135]
	s_add_i32 m0, s26, 0x2000
	s_nop 0
	global_load_lds_dwordx4 v[148:149], off
	v_lshl_add_u64 v[148:149], v[220:221], 0, s[8:9]
	s_mov_b32 m0, s44
	s_nop 0
	global_load_lds_dwordx4 v[148:149], off
	v_lshl_add_u64 v[148:149], v[222:223], 0, s[8:9]
	s_mov_b32 m0, s45
	s_nop 0
	global_load_lds_dwordx4 v[148:149], off
	s_waitcnt vmcnt(8)
	s_waitcnt lgkmcnt(0)
	s_barrier
	s_setprio 1
	v_mfma_f32_16x16x32_bf16 v[60:63], v[144:147], v[184:187], v[60:63]
	v_mfma_f32_16x16x32_bf16 v[56:59], v[160:163], v[184:187], v[56:59]
	v_mfma_f32_16x16x32_bf16 v[52:55], v[144:147], v[192:195], v[52:55]
	v_mfma_f32_16x16x32_bf16 v[48:51], v[160:163], v[192:195], v[48:51]
	v_mfma_f32_16x16x32_bf16 v[28:31], v[144:147], v[200:203], v[28:31]
	v_mfma_f32_16x16x32_bf16 v[24:27], v[160:163], v[200:203], v[24:27]
	v_mfma_f32_16x16x32_bf16 v[20:23], v[144:147], v[210:213], v[20:23]
	v_mfma_f32_16x16x32_bf16 v[16:19], v[160:163], v[210:213], v[16:19]
	v_mfma_f32_16x16x32_bf16 v[60:63], v[156:159], v[188:191], v[60:63]
	v_mfma_f32_16x16x32_bf16 v[56:59], v[164:167], v[188:191], v[56:59]
	v_mfma_f32_16x16x32_bf16 v[52:55], v[156:159], v[196:199], v[52:55]
	v_mfma_f32_16x16x32_bf16 v[48:51], v[164:167], v[196:199], v[48:51]
	v_mfma_f32_16x16x32_bf16 v[28:31], v[156:159], v[206:209], v[28:31]
	v_mfma_f32_16x16x32_bf16 v[24:27], v[164:167], v[206:209], v[24:27]
	v_mfma_f32_16x16x32_bf16 v[20:23], v[156:159], v[214:217], v[20:23]
	v_mfma_f32_16x16x32_bf16 v[16:19], v[164:167], v[214:217], v[16:19]
	v_mfma_f32_16x16x32_bf16 v[44:47], v[168:171], v[184:187], v[44:47]
	v_mfma_f32_16x16x32_bf16 v[40:43], v[176:179], v[184:187], v[40:43]
	v_mfma_f32_16x16x32_bf16 v[36:39], v[168:171], v[192:195], v[36:39]
	v_mfma_f32_16x16x32_bf16 v[32:35], v[176:179], v[192:195], v[32:35]
	v_mfma_f32_16x16x32_bf16 v[12:15], v[168:171], v[200:203], v[12:15]
	v_mfma_f32_16x16x32_bf16 v[8:11], v[176:179], v[200:203], v[8:11]
	v_mfma_f32_16x16x32_bf16 v[4:7], v[168:171], v[210:213], v[4:7]
	v_mfma_f32_16x16x32_bf16 v[0:3], v[176:179], v[210:213], v[0:3]
	v_mfma_f32_16x16x32_bf16 v[44:47], v[172:175], v[188:191], v[44:47]
	v_mfma_f32_16x16x32_bf16 v[40:43], v[180:183], v[188:191], v[40:43]
	v_mfma_f32_16x16x32_bf16 v[36:39], v[172:175], v[196:199], v[36:39]
	v_mfma_f32_16x16x32_bf16 v[32:35], v[180:183], v[196:199], v[32:35]
	v_mfma_f32_16x16x32_bf16 v[12:15], v[172:175], v[206:209], v[12:15]
	v_mfma_f32_16x16x32_bf16 v[8:11], v[180:183], v[206:209], v[8:11]
	v_mfma_f32_16x16x32_bf16 v[4:7], v[172:175], v[214:217], v[4:7]
	v_mfma_f32_16x16x32_bf16 v[0:3], v[180:183], v[214:217], v[0:3]
	s_setprio 0
	s_barrier
	s_add_i32 s50, s50, 2
	s_add_u32 s13, s13, 0x100
	s_addc_u32 s15, s15, 0
	s_add_u32 s22, s22, 0x100
	s_addc_u32 s23, s23, 0
	s_cmp_gt_u32 s50, 29
	s_cbranch_scc0 .LBB0_667
	s_and_b64 vcc, exec, s[10:11]
	s_cbranch_vccz .LBB0_670
	s_barrier

; #define PG8_STAGE(bufoff, gbase, voff) do { _Pragma("unroll") for (int _i = 0; _i < 2; ++_i) \
;         __builtin_amdgcn_global_load_lds((const unsigned*)((const char*)(gbase) + (voff)[_i]), (PG8_LAS unsigned*)(lds + (bufoff) + ldsw + _i * 8192), 16, 0, 0); } while (0)
; #define PG8_LDA(dst, b, h) do { _Pragma("unroll") for (int m = 0; m < 4; ++m) _Pragma("unroll") for (int k = 0; k < 2; ++k) dst[m][k] = *(const PG8_LAS bf16x8*)(lds + PG8_SA(b, h) + aoff + m * 2048 + k * 1024); } while (0)
; #define PG8_LDB(dst, b, h) do { _Pragma("unroll") for (int n = 0; n < 2; ++n) _Pragma("unroll") for (int k = 0; k < 2; ++k) dst[n][k] = *(const PG8_LAS bf16x8*)(lds + PG8_SB(b, h) + boff + n * 2048 + k * 1024); } while (0)
; template <class Epi, class Sched, bool ALIGN_EPI = false, bool SP2 = false>
; __device__ __forceinline__ void gemm_phase(PG8_LAS unsigned char* lds, const Gemm g, const Sched& S, const Epi& E, const int wv0) {
;     ...
;         for (int t = 0; t < nt; t += 2) {
;             const bool last = (t == nt - 2);
;             const char* a1 = cA + (size_t)(t + 1) * kstep;
;             const char* a2 = last ? nA : cA + (size_t)(t + 2) * kstep; const char* b2 = last ? nB : cB + (size_t)(t + 2) * kstep;
;             const char* a3 = a2 + kstep; const char* b3 = b2 + kstep;
;             if constexpr (SP2) {
;             PG8_LDB(B0, 0, 0); PG8_LDB(B1, 0, 1); PG8_SCHED; PG8_LDA(At, 0, 0); PG8_STAGE(PG8_SA(1, 1), a1 + hstepA, voffA);
;             PG8_WAIT_V(8); PG8_WAIT_L(0); PG8_BAR; PG8_MMA(0, 0, At, B0); PG8_MMA(0, 1, At, B1); PG8_BAR; PG8_SCHED;
;             PG8_LDA(At, 0, 1); PG8_STAGE(PG8_SB(0, 0), b2, voffB); PG8_STAGE(PG8_SB(0, 1), b2 + hstepB, voffB); PG8_STAGE(PG8_SA(0, 0), a2, voffA);
;             PG8_WAIT_V(8); PG8_WAIT_L(0); PG8_BAR; PG8_MMA(1, 0, At, B0); PG8_MMA(1, 1, At, B1); PG8_BAR; PG8_SCHED;
;             PG8_LDB(B0, 1, 0); PG8_LDB(B1, 1, 1); PG8_SCHED; PG8_LDA(At, 1, 0); PG8_STAGE(PG8_SA(0, 1), a2 + hstepA, voffA);
;             PG8_WAIT_V(8); PG8_WAIT_L(0); PG8_BAR; PG8_MMA(0, 0, At, B0); PG8_MMA(0, 1, At, B1); PG8_BAR; PG8_SCHED;
;             PG8_LDA(At, 1, 1); PG8_STAGE(PG8_SB(1, 0), b3, voffB); PG8_STAGE(PG8_SB(1, 1), b3 + hstepB, voffB); PG8_STAGE(PG8_SA(1, 0), a3, voffA);
;             PG8_WAIT_V(8); PG8_WAIT_L(0); PG8_BAR; PG8_MMA(1, 0, At, B0); PG8_MMA(1, 1, At, B1); PG8_BAR; PG8_SCHED;
.LBB0_790:
	ds_read_b128 v[152:155], v149
	ds_read_b128 v[156:159], v149 offset:1024
	ds_read_b128 v[160:163], v149 offset:2048
	ds_read_b128 v[164:167], v149 offset:3072
	ds_read_b128 v[168:171], v150
	ds_read_b128 v[172:175], v150 offset:1024
	ds_read_b128 v[176:179], v150 offset:2048
	ds_read_b128 v[180:183], v150 offset:3072
	s_add_u32 s22, s20, 0xfff80080
	s_addc_u32 s23, s21, -1
	s_cmp_eq_u32 s50, 28
	s_cselect_b32 s25, s15, s23
	s_cselect_b32 s24, s14, s22
	s_cselect_b32 s23, s17, s13
	s_cselect_b32 s22, s16, s11
	v_lshl_add_u64 v[144:145], s[20:21], 0, v[138:139]
	s_add_i32 m0, s19, 0xc000
	ds_read_b128 v[184:187], v151
	ds_read_b128 v[188:191], v151 offset:1024
	ds_read_b128 v[192:195], v151 offset:2048
	ds_read_b128 v[196:199], v151 offset:3072
	ds_read_b128 v[200:203], v151 offset:4096
	ds_read_b128 v[206:209], v151 offset:5120
	ds_read_b128 v[210:213], v151 offset:6144
	ds_read_b128 v[214:217], v151 offset:7168
	global_load_lds_dwordx4 v[144:145], off
	v_lshl_add_u64 v[144:145], s[20:21], 0, v[136:137]
	s_add_i32 m0, s19, 0xe000
	s_nop 0
	global_load_lds_dwordx4 v[144:145], off
	s_waitcnt vmcnt(8)
	s_waitcnt lgkmcnt(0)
	s_barrier
	s_setprio 1
	v_mfma_f32_16x16x32_bf16 v[124:127], v[152:155], v[184:187], v[124:127]
	v_mfma_f32_16x16x32_bf16 v[120:123], v[160:163], v[184:187], v[120:123]
	v_mfma_f32_16x16x32_bf16 v[108:111], v[152:155], v[192:195], v[108:111]
	v_mfma_f32_16x16x32_bf16 v[104:107], v[160:163], v[192:195], v[104:107]
	v_mfma_f32_16x16x32_bf16 v[92:95], v[152:155], v[200:203], v[92:95]
	v_mfma_f32_16x16x32_bf16 v[88:91], v[160:163], v[200:203], v[88:91]
	v_mfma_f32_16x16x32_bf16 v[76:79], v[152:155], v[210:213], v[76:79]
	v_mfma_f32_16x16x32_bf16 v[72:75], v[160:163], v[210:213], v[72:75]
	v_mfma_f32_16x16x32_bf16 v[124:127], v[156:159], v[188:191], v[124:127]
	v_mfma_f32_16x16x32_bf16 v[120:123], v[164:167], v[188:191], v[120:123]
	v_mfma_f32_16x16x32_bf16 v[108:111], v[156:159], v[196:199], v[108:111]
	v_mfma_f32_16x16x32_bf16 v[104:107], v[164:167], v[196:199], v[104:107]
	v_mfma_f32_16x16x32_bf16 v[92:95], v[156:159], v[206:209], v[92:95]
	v_mfma_f32_16x16x32_bf16 v[88:91], v[164:167], v[206:209], v[88:91]
	v_mfma_f32_16x16x32_bf16 v[76:79], v[156:159], v[214:217], v[76:79]
	v_mfma_f32_16x16x32_bf16 v[72:75], v[164:167], v[214:217], v[72:75]
	v_mfma_f32_16x16x32_bf16 v[116:119], v[168:171], v[184:187], v[116:119]
	v_mfma_f32_16x16x32_bf16 v[112:115], v[176:179], v[184:187], v[112:115]
	v_mfma_f32_16x16x32_bf16 v[100:103], v[168:171], v[192:195], v[100:103]
	v_mfma_f32_16x16x32_bf16 v[96:99], v[176:179], v[192:195], v[96:99]
	v_mfma_f32_16x16x32_bf16 v[84:87], v[168:171], v[200:203], v[84:87]
	v_mfma_f32_16x16x32_bf16 v[80:83], v[176:179], v[200:203], v[80:83]
	v_mfma_f32_16x16x32_bf16 v[68:71], v[168:171], v[210:213], v[68:71]
	v_mfma_f32_16x16x32_bf16 v[64:67], v[176:179], v[210:213], v[64:67]
	v_mfma_f32_16x16x32_bf16 v[116:119], v[172:175], v[188:191], v[116:119]
	v_mfma_f32_16x16x32_bf16 v[112:115], v[180:183], v[188:191], v[112:115]
	v_mfma_f32_16x16x32_bf16 v[100:103], v[172:175], v[196:199], v[100:103]
	v_mfma_f32_16x16x32_bf16 v[96:99], v[180:183], v[196:199], v[96:99]
	v_mfma_f32_16x16x32_bf16 v[84:87], v[172:175], v[206:209], v[84:87]
	v_mfma_f32_16x16x32_bf16 v[80:83], v[180:183], v[206:209], v[80:83]
	v_mfma_f32_16x16x32_bf16 v[68:71], v[172:175], v[214:217], v[68:71]
	v_mfma_f32_16x16x32_bf16 v[64:67], v[180:183], v[214:217], v[64:67]
	s_setprio 0
	s_barrier
	s_add_i32 s51, s46, s35
	v_lshl_add_u64 v[144:145], s[22:23], 0, v[132:133]
	s_mov_b32 m0, s51
	ds_read_b128 v[184:187], v151 offset:16384
	ds_read_b128 v[188:191], v151 offset:17408
	ds_read_b128 v[192:195], v151 offset:18432
	ds_read_b128 v[196:199], v151 offset:19456
	ds_read_b128 v[200:203], v151 offset:20480
	ds_read_b128 v[206:209], v151 offset:21504
	ds_read_b128 v[210:213], v151 offset:22528
	ds_read_b128 v[214:217], v151 offset:23552
	global_load_lds_dwordx4 v[144:145], off
	s_add_i32 m0, s51, 0x2000
	s_add_u32 s52, s22, 0x80000
	v_lshl_add_u64 v[218:219], s[22:23], 0, v[128:129]
	s_addc_u32 s53, s23, 0
	s_add_i32 s51, s47, s35
	global_load_lds_dwordx4 v[218:219], off
	v_lshl_add_u64 v[220:221], s[52:53], 0, v[132:133]
	s_mov_b32 m0, s51
	v_lshl_add_u64 v[222:223], s[24:25], 0, v[130:131]
	global_load_lds_dwordx4 v[220:221], off
	v_lshl_add_u64 v[220:221], s[52:53], 0, v[128:129]
	s_add_i32 m0, s51, 0x2000
	s_nop 0
	global_load_lds_dwordx4 v[220:221], off
	v_lshl_add_u64 v[220:221], s[24:25], 0, v[134:135]
	s_mov_b32 m0, s19
	s_nop 0
	global_load_lds_dwordx4 v[220:221], off
	s_mov_b32 m0, s37
	s_nop 0
	global_load_lds_dwordx4 v[222:223], off
	s_waitcnt vmcnt(8)
	s_waitcnt lgkmcnt(0)
	s_barrier
; #define PG8_STAGE(bufoff, gbase, voff) do { _Pragma("unroll") for (int _i = 0; _i < 2; ++_i) \
;         __builtin_amdgcn_global_load_lds((const unsigned*)((const char*)(gbase) + (voff)[_i]), (PG8_LAS unsigned*)(lds + (bufoff) + ldsw + _i * 8192), 16, 0, 0); } while (0)
; #define PG8_LDA(dst, b, h) do { _Pragma("unroll") for (int m = 0; m < 4; ++m) _Pragma("unroll") for (int k = 0; k < 2; ++k) dst[m][k] = *(const PG8_LAS bf16x8*)(lds + PG8_SA(b, h) + aoff + m * 2048 + k * 1024); } while (0)
; #define PG8_LDB(dst, b, h) do { _Pragma("unroll") for (int n = 0; n < 2; ++n) _Pragma("unroll") for (int k = 0; k < 2; ++k) dst[n][k] = *(const PG8_LAS bf16x8*)(lds + PG8_SB(b, h) + boff + n * 2048 + k * 1024); } while (0)
; template <class Epi, class Sched, bool ALIGN_EPI = false, bool SP2 = false>
; __device__ __forceinline__ void gemm_phase(PG8_LAS unsigned char* lds, const Gemm g, const Sched& S, const Epi& E, const int wv0) {
;     ...
;         for (int t = 0; t < nt; t += 2) {
;             const bool last = (t == nt - 2);
;             const char* a1 = cA + (size_t)(t + 1) * kstep;
;             const char* a2 = last ? nA : cA + (size_t)(t + 2) * kstep; const char* b2 = last ? nB : cB + (size_t)(t + 2) * kstep;
;             const char* a3 = a2 + kstep; const char* b3 = b2 + kstep;
;             if constexpr (SP2) {
;             PG8_LDB(B0, 0, 0); PG8_LDB(B1, 0, 1); PG8_SCHED; PG8_LDA(At, 0, 0); PG8_STAGE(PG8_SA(1, 1), a1 + hstepA, voffA);
;             PG8_WAIT_V(8); PG8_WAIT_L(0); PG8_BAR; PG8_MMA(0, 0, At, B0); PG8_MMA(0, 1, At, B1); PG8_BAR; PG8_SCHED;
;             PG8_LDA(At, 0, 1); PG8_STAGE(PG8_SB(0, 0), b2, voffB); PG8_STAGE(PG8_SB(0, 1), b2 + hstepB, voffB); PG8_STAGE(PG8_SA(0, 0), a2, voffA);
;             PG8_WAIT_V(8); PG8_WAIT_L(0); PG8_BAR; PG8_MMA(1, 0, At, B0); PG8_MMA(1, 1, At, B1); PG8_BAR; PG8_SCHED;
;             PG8_LDB(B0, 1, 0); PG8_LDB(B1, 1, 1); PG8_SCHED; PG8_LDA(At, 1, 0); PG8_STAGE(PG8_SA(0, 1), a2 + hstepA, voffA);
;             PG8_WAIT_V(8); PG8_WAIT_L(0); PG8_BAR; PG8_MMA(0, 0, At, B0); PG8_MMA(0, 1, At, B1); PG8_BAR; PG8_SCHED;
;             PG8_LDA(At, 1, 1); PG8_STAGE(PG8_SB(1, 0), b3, voffB); PG8_STAGE(PG8_SB(1, 1), b3 + hstepB, voffB); PG8_STAGE(PG8_SA(1, 0), a3, voffA);
;             PG8_WAIT_V(8); PG8_WAIT_L(0); PG8_BAR; PG8_MMA(1, 0, At, B0); PG8_MMA(1, 1, At, B1); PG8_BAR; PG8_SCHED;
	s_setprio 1
	v_mfma_f32_16x16x32_bf16 v[60:63], v[152:155], v[184:187], v[60:63]
	v_mfma_f32_16x16x32_bf16 v[56:59], v[160:163], v[184:187], v[56:59]
	v_mfma_f32_16x16x32_bf16 v[44:47], v[152:155], v[192:195], v[44:47]
	v_mfma_f32_16x16x32_bf16 v[40:43], v[160:163], v[192:195], v[40:43]
	v_mfma_f32_16x16x32_bf16 v[28:31], v[152:155], v[200:203], v[28:31]
	v_mfma_f32_16x16x32_bf16 v[24:27], v[160:163], v[200:203], v[24:27]
	v_mfma_f32_16x16x32_bf16 v[12:15], v[152:155], v[210:213], v[12:15]
	v_mfma_f32_16x16x32_bf16 v[8:11], v[160:163], v[210:213], v[8:11]
	v_mfma_f32_16x16x32_bf16 v[60:63], v[156:159], v[188:191], v[60:63]
	v_mfma_f32_16x16x32_bf16 v[56:59], v[164:167], v[188:191], v[56:59]
	v_mfma_f32_16x16x32_bf16 v[44:47], v[156:159], v[196:199], v[44:47]
	v_mfma_f32_16x16x32_bf16 v[40:43], v[164:167], v[196:199], v[40:43]
	v_mfma_f32_16x16x32_bf16 v[28:31], v[156:159], v[206:209], v[28:31]
	v_mfma_f32_16x16x32_bf16 v[24:27], v[164:167], v[206:209], v[24:27]
	v_mfma_f32_16x16x32_bf16 v[12:15], v[156:159], v[214:217], v[12:15]
	v_mfma_f32_16x16x32_bf16 v[8:11], v[164:167], v[214:217], v[8:11]
	v_mfma_f32_16x16x32_bf16 v[52:55], v[168:171], v[184:187], v[52:55]
	v_mfma_f32_16x16x32_bf16 v[48:51], v[176:179], v[184:187], v[48:51]
	v_mfma_f32_16x16x32_bf16 v[36:39], v[168:171], v[192:195], v[36:39]
	v_mfma_f32_16x16x32_bf16 v[32:35], v[176:179], v[192:195], v[32:35]
	v_mfma_f32_16x16x32_bf16 v[20:23], v[168:171], v[200:203], v[20:23]
	v_mfma_f32_16x16x32_bf16 v[16:19], v[176:179], v[200:203], v[16:19]
	v_mfma_f32_16x16x32_bf16 v[4:7], v[168:171], v[210:213], v[4:7]
	v_mfma_f32_16x16x32_bf16 v[0:3], v[176:179], v[210:213], v[0:3]
	v_mfma_f32_16x16x32_bf16 v[52:55], v[172:175], v[188:191], v[52:55]
	v_mfma_f32_16x16x32_bf16 v[48:51], v[180:183], v[188:191], v[48:51]
	v_mfma_f32_16x16x32_bf16 v[36:39], v[172:175], v[196:199], v[36:39]
	v_mfma_f32_16x16x32_bf16 v[32:35], v[180:183], v[196:199], v[32:35]
	v_mfma_f32_16x16x32_bf16 v[20:23], v[172:175], v[206:209], v[20:23]
	v_mfma_f32_16x16x32_bf16 v[16:19], v[180:183], v[206:209], v[16:19]
	v_mfma_f32_16x16x32_bf16 v[4:7], v[172:175], v[214:217], v[4:7]
	v_mfma_f32_16x16x32_bf16 v[0:3], v[180:183], v[214:217], v[0:3]
	s_setprio 0
	s_barrier
	s_add_i32 s51, 0, 0x18000
	s_add_i32 s52, 0, 0x1c000
	v_add_u32_e32 v164, s51, v147
	v_add_u32_e32 v180, s52, v147
	ds_read_b128 v[152:155], v164
	ds_read_b128 v[156:159], v164 offset:1024
	ds_read_b128 v[160:163], v164 offset:2048
	ds_read_b128 v[164:167], v164 offset:3072
	ds_read_b128 v[168:171], v180
	ds_read_b128 v[172:175], v180 offset:1024
	ds_read_b128 v[176:179], v180 offset:2048
	ds_read_b128 v[180:183], v180 offset:3072
	s_add_u32 s24, s24, 0x80000
	s_addc_u32 s25, s25, 0
	s_mov_b32 m0, s38
	v_lshl_add_u64 v[224:225], s[24:25], 0, v[134:135]
	ds_read_b128 v[184:187], v151 offset:32768
	ds_read_b128 v[188:191], v151 offset:33792
	ds_read_b128 v[192:195], v151 offset:34816
	ds_read_b128 v[196:199], v151 offset:35840
	ds_read_b128 v[200:203], v151 offset:36864
	ds_read_b128 v[206:209], v151 offset:37888
	ds_read_b128 v[210:213], v151 offset:38912
	ds_read_b128 v[214:217], v151 offset:39936
	global_load_lds_dwordx4 v[224:225], off
	v_lshl_add_u64 v[224:225], s[24:25], 0, v[130:131]
	s_mov_b32 m0, s39
	s_nop 0
	global_load_lds_dwordx4 v[224:225], off
	s_waitcnt vmcnt(8)
	s_waitcnt lgkmcnt(0)
	s_barrier
	s_setprio 1
	v_mfma_f32_16x16x32_bf16 v[124:127], v[152:155], v[184:187], v[124:127]
	v_mfma_f32_16x16x32_bf16 v[120:123], v[160:163], v[184:187], v[120:123]
	v_mfma_f32_16x16x32_bf16 v[108:111], v[152:155], v[192:195], v[108:111]
	v_mfma_f32_16x16x32_bf16 v[104:107], v[160:163], v[192:195], v[104:107]
	v_mfma_f32_16x16x32_bf16 v[92:95], v[152:155], v[200:203], v[92:95]
	v_mfma_f32_16x16x32_bf16 v[88:91], v[160:163], v[200:203], v[88:91]
	v_mfma_f32_16x16x32_bf16 v[76:79], v[152:155], v[210:213], v[76:79]
	v_mfma_f32_16x16x32_bf16 v[72:75], v[160:163], v[210:213], v[72:75]
	v_mfma_f32_16x16x32_bf16 v[124:127], v[156:159], v[188:191], v[124:127]
	v_mfma_f32_16x16x32_bf16 v[120:123], v[164:167], v[188:191], v[120:123]
	v_mfma_f32_16x16x32_bf16 v[108:111], v[156:159], v[196:199], v[108:111]
	v_mfma_f32_16x16x32_bf16 v[104:107], v[164:167], v[196:199], v[104:107]
	v_mfma_f32_16x16x32_bf16 v[92:95], v[156:159], v[206:209], v[92:95]
	v_mfma_f32_16x16x32_bf16 v[88:91], v[164:167], v[206:209], v[88:91]
	v_mfma_f32_16x16x32_bf16 v[76:79], v[156:159], v[214:217], v[76:79]
	v_mfma_f32_16x16x32_bf16 v[72:75], v[164:167], v[214:217], v[72:75]
	v_mfma_f32_16x16x32_bf16 v[116:119], v[168:171], v[184:187], v[116:119]
	v_mfma_f32_16x16x32_bf16 v[112:115], v[176:179], v[184:187], v[112:115]
	v_mfma_f32_16x16x32_bf16 v[100:103], v[168:171], v[192:195], v[100:103]
	v_mfma_f32_16x16x32_bf16 v[96:99], v[176:179], v[192:195], v[96:99]
	v_mfma_f32_16x16x32_bf16 v[84:87], v[168:171], v[200:203], v[84:87]
	v_mfma_f32_16x16x32_bf16 v[80:83], v[176:179], v[200:203], v[80:83]
	v_mfma_f32_16x16x32_bf16 v[68:71], v[168:171], v[210:213], v[68:71]
	v_mfma_f32_16x16x32_bf16 v[64:67], v[176:179], v[210:213], v[64:67]
	v_mfma_f32_16x16x32_bf16 v[116:119], v[172:175], v[188:191], v[116:119]
	v_mfma_f32_16x16x32_bf16 v[112:115], v[180:183], v[188:191], v[112:115]
	v_mfma_f32_16x16x32_bf16 v[100:103], v[172:175], v[196:199], v[100:103]
	v_mfma_f32_16x16x32_bf16 v[96:99], v[180:183], v[196:199], v[96:99]
	v_mfma_f32_16x16x32_bf16 v[84:87], v[172:175], v[206:209], v[84:87]
	v_mfma_f32_16x16x32_bf16 v[80:83], v[180:183], v[206:209], v[80:83]
	v_mfma_f32_16x16x32_bf16 v[68:71], v[172:175], v[214:217], v[68:71]
	v_mfma_f32_16x16x32_bf16 v[64:67], v[180:183], v[214:217], v[64:67]
	s_setprio 0
	s_barrier
; #define PG8_STAGE(bufoff, gbase, voff) do { _Pragma("unroll") for (int _i = 0; _i < 2; ++_i) \
;         __builtin_amdgcn_global_load_lds((const unsigned*)((const char*)(gbase) + (voff)[_i]), (PG8_LAS unsigned*)(lds + (bufoff) + ldsw + _i * 8192), 16, 0, 0); } while (0)
; #define PG8_LDA(dst, b, h) do { _Pragma("unroll") for (int m = 0; m < 4; ++m) _Pragma("unroll") for (int k = 0; k < 2; ++k) dst[m][k] = *(const PG8_LAS bf16x8*)(lds + PG8_SA(b, h) + aoff + m * 2048 + k * 1024); } while (0)
; #define PG8_LDB(dst, b, h) do { _Pragma("unroll") for (int n = 0; n < 2; ++n) _Pragma("unroll") for (int k = 0; k < 2; ++k) dst[n][k] = *(const PG8_LAS bf16x8*)(lds + PG8_SB(b, h) + boff + n * 2048 + k * 1024); } while (0)
; template <class Epi, class Sched, bool ALIGN_EPI = false, bool SP2 = false>
; __device__ __forceinline__ void gemm_phase(PG8_LAS unsigned char* lds, const Gemm g, const Sched& S, const Epi& E, const int wv0) {
;     ...
;         for (int t = 0; t < nt; t += 2) {
;             const bool last = (t == nt - 2);
;             const char* a1 = cA + (size_t)(t + 1) * kstep;
;             const char* a2 = last ? nA : cA + (size_t)(t + 2) * kstep; const char* b2 = last ? nB : cB + (size_t)(t + 2) * kstep;
;             const char* a3 = a2 + kstep; const char* b3 = b2 + kstep;
;             if constexpr (SP2) {
;             PG8_LDB(B0, 0, 0); PG8_LDB(B1, 0, 1); PG8_SCHED; PG8_LDA(At, 0, 0); PG8_STAGE(PG8_SA(1, 1), a1 + hstepA, voffA);
;             PG8_WAIT_V(8); PG8_WAIT_L(0); PG8_BAR; PG8_MMA(0, 0, At, B0); PG8_MMA(0, 1, At, B1); PG8_BAR; PG8_SCHED;
;             PG8_LDA(At, 0, 1); PG8_STAGE(PG8_SB(0, 0), b2, voffB); PG8_STAGE(PG8_SB(0, 1), b2 + hstepB, voffB); PG8_STAGE(PG8_SA(0, 0), a2, voffA);
;             PG8_WAIT_V(8); PG8_WAIT_L(0); PG8_BAR; PG8_MMA(1, 0, At, B0); PG8_MMA(1, 1, At, B1); PG8_BAR; PG8_SCHED;
;             PG8_LDB(B0, 1, 0); PG8_LDB(B1, 1, 1); PG8_SCHED; PG8_LDA(At, 1, 0); PG8_STAGE(PG8_SA(0, 1), a2 + hstepA, voffA);
;             PG8_WAIT_V(8); PG8_WAIT_L(0); PG8_BAR; PG8_MMA(0, 0, At, B0); PG8_MMA(0, 1, At, B1); PG8_BAR; PG8_SCHED;
;             PG8_LDA(At, 1, 1); PG8_STAGE(PG8_SB(1, 0), b3, voffB); PG8_STAGE(PG8_SB(1, 1), b3 + hstepB, voffB); PG8_STAGE(PG8_SA(1, 0), a3, voffA);
;             PG8_WAIT_V(8); PG8_WAIT_L(0); PG8_BAR; PG8_MMA(1, 0, At, B0); PG8_MMA(1, 1, At, B1); PG8_BAR; PG8_SCHED;
	s_add_i32 s24, s51, s35
	v_lshl_add_u64 v[144:145], v[144:145], 0, s[6:7]
	s_mov_b32 m0, s24
	ds_read_b128 v[184:187], v151 offset:49152
	ds_read_b128 v[188:191], v151 offset:50176
	ds_read_b128 v[192:195], v151 offset:51200
	ds_read_b128 v[196:199], v151 offset:52224
	ds_read_b128 v[200:203], v151 offset:53248
	ds_read_b128 v[206:209], v151 offset:54272
	ds_read_b128 v[210:213], v151 offset:55296
	ds_read_b128 v[214:217], v151 offset:56320
	global_load_lds_dwordx4 v[144:145], off
	s_add_i32 m0, s24, 0x2000
	s_add_u32 s22, s22, 0x80080
	v_lshl_add_u64 v[144:145], v[218:219], 0, s[6:7]
	s_addc_u32 s23, s23, 0
	s_add_i32 s24, s52, s35
	global_load_lds_dwordx4 v[144:145], off
	v_lshl_add_u64 v[144:145], s[22:23], 0, v[132:133]
	s_mov_b32 m0, s24
	s_nop 0
	global_load_lds_dwordx4 v[144:145], off
	v_lshl_add_u64 v[144:145], s[22:23], 0, v[128:129]
	s_add_i32 m0, s24, 0x2000
	s_nop 0
	global_load_lds_dwordx4 v[144:145], off
	v_lshl_add_u64 v[144:145], v[220:221], 0, s[6:7]
	s_mov_b32 m0, s41
	s_nop 0
	global_load_lds_dwordx4 v[144:145], off
	v_lshl_add_u64 v[144:145], v[222:223], 0, s[6:7]
	s_mov_b32 m0, s44
	s_nop 0
	global_load_lds_dwordx4 v[144:145], off
	s_waitcnt vmcnt(8)
	s_waitcnt lgkmcnt(0)
	s_barrier
	s_setprio 1
	v_mfma_f32_16x16x32_bf16 v[60:63], v[152:155], v[184:187], v[60:63]
	v_mfma_f32_16x16x32_bf16 v[56:59], v[160:163], v[184:187], v[56:59]
	v_mfma_f32_16x16x32_bf16 v[44:47], v[152:155], v[192:195], v[44:47]
	v_mfma_f32_16x16x32_bf16 v[40:43], v[160:163], v[192:195], v[40:43]
	v_mfma_f32_16x16x32_bf16 v[28:31], v[152:155], v[200:203], v[28:31]
	v_mfma_f32_16x16x32_bf16 v[24:27], v[160:163], v[200:203], v[24:27]
	v_mfma_f32_16x16x32_bf16 v[12:15], v[152:155], v[210:213], v[12:15]
	v_mfma_f32_16x16x32_bf16 v[8:11], v[160:163], v[210:213], v[8:11]
	v_mfma_f32_16x16x32_bf16 v[60:63], v[156:159], v[188:191], v[60:63]
	v_mfma_f32_16x16x32_bf16 v[56:59], v[164:167], v[188:191], v[56:59]
	v_mfma_f32_16x16x32_bf16 v[44:47], v[156:159], v[196:199], v[44:47]
	v_mfma_f32_16x16x32_bf16 v[40:43], v[164:167], v[196:199], v[40:43]
	v_mfma_f32_16x16x32_bf16 v[28:31], v[156:159], v[206:209], v[28:31]
	v_mfma_f32_16x16x32_bf16 v[24:27], v[164:167], v[206:209], v[24:27]
	v_mfma_f32_16x16x32_bf16 v[12:15], v[156:159], v[214:217], v[12:15]
	v_mfma_f32_16x16x32_bf16 v[8:11], v[164:167], v[214:217], v[8:11]
	v_mfma_f32_16x16x32_bf16 v[52:55], v[168:171], v[184:187], v[52:55]
	v_mfma_f32_16x16x32_bf16 v[48:51], v[176:179], v[184:187], v[48:51]
	v_mfma_f32_16x16x32_bf16 v[36:39], v[168:171], v[192:195], v[36:39]
	v_mfma_f32_16x16x32_bf16 v[32:35], v[176:179], v[192:195], v[32:35]
	v_mfma_f32_16x16x32_bf16 v[20:23], v[168:171], v[200:203], v[20:23]
	v_mfma_f32_16x16x32_bf16 v[16:19], v[176:179], v[200:203], v[16:19]
	v_mfma_f32_16x16x32_bf16 v[4:7], v[168:171], v[210:213], v[4:7]
	v_mfma_f32_16x16x32_bf16 v[0:3], v[176:179], v[210:213], v[0:3]
	v_mfma_f32_16x16x32_bf16 v[52:55], v[172:175], v[188:191], v[52:55]
	v_mfma_f32_16x16x32_bf16 v[48:51], v[180:183], v[188:191], v[48:51]
	v_mfma_f32_16x16x32_bf16 v[36:39], v[172:175], v[196:199], v[36:39]
	v_mfma_f32_16x16x32_bf16 v[32:35], v[180:183], v[196:199], v[32:35]
	v_mfma_f32_16x16x32_bf16 v[20:23], v[172:175], v[206:209], v[20:23]
	v_mfma_f32_16x16x32_bf16 v[16:19], v[180:183], v[206:209], v[16:19]
	v_mfma_f32_16x16x32_bf16 v[4:7], v[172:175], v[214:217], v[4:7]
	v_mfma_f32_16x16x32_bf16 v[0:3], v[180:183], v[214:217], v[0:3]
	s_setprio 0
	s_barrier
	s_add_i32 s50, s50, 2
	s_add_u32 s11, s11, 0x100
	s_addc_u32 s13, s13, 0
	s_add_u32 s20, s20, 0x100
	s_addc_u32 s21, s21, 0
	s_cmp_gt_u32 s50, 29
	s_cbranch_scc0 .LBB0_790
	s_and_b64 vcc, exec, s[8:9]
	s_cbranch_vccz .LBB0_793
	s_barrier

; #define PG8_STAGE(bufoff, gbase, voff) do { _Pragma("unroll") for (int _i = 0; _i < 2; ++_i) \
;         __builtin_amdgcn_global_load_lds((const unsigned*)((const char*)(gbase) + (voff)[_i]), (PG8_LAS unsigned*)(lds + (bufoff) + ldsw + _i * 8192), 16, 0, 0); } while (0)
; #define PG8_LDA(dst, b, h) do { _Pragma("unroll") for (int m = 0; m < 4; ++m) _Pragma("unroll") for (int k = 0; k < 2; ++k) dst[m][k] = *(const PG8_LAS bf16x8*)(lds + PG8_SA(b, h) + aoff + m * 2048 + k * 1024); } while (0)
; #define PG8_LDB(dst, b, h) do { _Pragma("unroll") for (int n = 0; n < 2; ++n) _Pragma("unroll") for (int k = 0; k < 2; ++k) dst[n][k] = *(const PG8_LAS bf16x8*)(lds + PG8_SB(b, h) + boff + n * 2048 + k * 1024); } while (0)
; template <class Epi, class Sched, bool ALIGN_EPI = false, bool SP2 = false>
; __device__ __forceinline__ void gemm_phase(PG8_LAS unsigned char* lds, const Gemm g, const Sched& S, const Epi& E, const int wv0) {
;     ...
;         for (int t = 0; t < nt; t += 2) {
;             const bool last = (t == nt - 2);
;             const char* a1 = cA + (size_t)(t + 1) * kstep;
;             const char* a2 = last ? nA : cA + (size_t)(t + 2) * kstep; const char* b2 = last ? nB : cB + (size_t)(t + 2) * kstep;
;             const char* a3 = a2 + kstep; const char* b3 = b2 + kstep;
;             if constexpr (SP2) {
;             PG8_LDB(B0, 0, 0); PG8_LDB(B1, 0, 1); PG8_SCHED; PG8_LDA(At, 0, 0); PG8_STAGE(PG8_SA(1, 1), a1 + hstepA, voffA);
;             PG8_WAIT_V(8); PG8_WAIT_L(0); PG8_BAR; PG8_MMA(0, 0, At, B0); PG8_MMA(0, 1, At, B1); PG8_BAR; PG8_SCHED;
;             PG8_LDA(At, 0, 1); PG8_STAGE(PG8_SB(0, 0), b2, voffB); PG8_STAGE(PG8_SB(0, 1), b2 + hstepB, voffB); PG8_STAGE(PG8_SA(0, 0), a2, voffA);
;             PG8_WAIT_V(8); PG8_WAIT_L(0); PG8_BAR; PG8_MMA(1, 0, At, B0); PG8_MMA(1, 1, At, B1); PG8_BAR; PG8_SCHED;
;             PG8_LDB(B0, 1, 0); PG8_LDB(B1, 1, 1); PG8_SCHED; PG8_LDA(At, 1, 0); PG8_STAGE(PG8_SA(0, 1), a2 + hstepA, voffA);
;             PG8_WAIT_V(8); PG8_WAIT_L(0); PG8_BAR; PG8_MMA(0, 0, At, B0); PG8_MMA(0, 1, At, B1); PG8_BAR; PG8_SCHED;
;             PG8_LDA(At, 1, 1); PG8_STAGE(PG8_SB(1, 0), b3, voffB); PG8_STAGE(PG8_SB(1, 1), b3 + hstepB, voffB); PG8_STAGE(PG8_SA(1, 0), a3, voffA);
;             PG8_WAIT_V(8); PG8_WAIT_L(0); PG8_BAR; PG8_MMA(1, 0, At, B0); PG8_MMA(1, 1, At, B1); PG8_BAR; PG8_SCHED;
.LBB0_867:
	ds_read_b128 v[144:147], v155
	ds_read_b128 v[148:151], v155 offset:1024
	ds_read_b128 v[158:161], v155 offset:2048
	ds_read_b128 v[162:165], v155 offset:3072
	ds_read_b128 v[166:169], v156
	ds_read_b128 v[170:173], v156 offset:1024
	ds_read_b128 v[174:177], v156 offset:2048
	ds_read_b128 v[178:181], v156 offset:3072
	s_add_u32 s24, s22, 0x100
	s_addc_u32 s25, s23, 0
	s_cmpk_eq_i32 s58, 0x54
	s_cselect_b32 s29, s19, s25
	s_cselect_b32 s28, s18, s24
	s_cselect_b32 s27, s21, s57
	s_cselect_b32 s26, s20, s56
	v_lshl_add_u64 v[202:203], s[22:23], 0, v[138:139]
	s_add_i32 m0, s40, 0xc000
	ds_read_b128 v[182:185], v157
	ds_read_b128 v[186:189], v157 offset:1024
	ds_read_b128 v[190:193], v157 offset:2048
	ds_read_b128 v[194:197], v157 offset:3072
	ds_read_b128 v[198:201], v157 offset:4096
	ds_read_b128 v[206:209], v157 offset:5120
	ds_read_b128 v[210:213], v157 offset:6144
	ds_read_b128 v[214:217], v157 offset:7168
	global_load_lds_dwordx4 v[202:203], off
	v_lshl_add_u64 v[202:203], s[22:23], 0, v[136:137]
	s_add_i32 m0, s40, 0xe000
	s_nop 0
	global_load_lds_dwordx4 v[202:203], off
	s_waitcnt vmcnt(8)
	s_waitcnt lgkmcnt(0)
	s_barrier
	s_setprio 1
	v_mfma_f32_16x16x32_bf16 v[124:127], v[144:147], v[182:185], v[124:127]
	v_mfma_f32_16x16x32_bf16 v[120:123], v[158:161], v[182:185], v[120:123]
	v_mfma_f32_16x16x32_bf16 v[116:119], v[144:147], v[190:193], v[116:119]
	v_mfma_f32_16x16x32_bf16 v[112:115], v[158:161], v[190:193], v[112:115]
	v_mfma_f32_16x16x32_bf16 v[92:95], v[144:147], v[198:201], v[92:95]
	v_mfma_f32_16x16x32_bf16 v[88:91], v[158:161], v[198:201], v[88:91]
	v_mfma_f32_16x16x32_bf16 v[84:87], v[144:147], v[210:213], v[84:87]
	v_mfma_f32_16x16x32_bf16 v[80:83], v[158:161], v[210:213], v[80:83]
	v_mfma_f32_16x16x32_bf16 v[124:127], v[148:151], v[186:189], v[124:127]
	v_mfma_f32_16x16x32_bf16 v[120:123], v[162:165], v[186:189], v[120:123]
	v_mfma_f32_16x16x32_bf16 v[116:119], v[148:151], v[194:197], v[116:119]
	v_mfma_f32_16x16x32_bf16 v[112:115], v[162:165], v[194:197], v[112:115]
	v_mfma_f32_16x16x32_bf16 v[92:95], v[148:151], v[206:209], v[92:95]
	v_mfma_f32_16x16x32_bf16 v[88:91], v[162:165], v[206:209], v[88:91]
	v_mfma_f32_16x16x32_bf16 v[84:87], v[148:151], v[214:217], v[84:87]
	v_mfma_f32_16x16x32_bf16 v[80:83], v[162:165], v[214:217], v[80:83]
	v_mfma_f32_16x16x32_bf16 v[108:111], v[166:169], v[182:185], v[108:111]
	v_mfma_f32_16x16x32_bf16 v[104:107], v[174:177], v[182:185], v[104:107]
	v_mfma_f32_16x16x32_bf16 v[100:103], v[166:169], v[190:193], v[100:103]
	v_mfma_f32_16x16x32_bf16 v[96:99], v[174:177], v[190:193], v[96:99]
	v_mfma_f32_16x16x32_bf16 v[76:79], v[166:169], v[198:201], v[76:79]
	v_mfma_f32_16x16x32_bf16 v[72:75], v[174:177], v[198:201], v[72:75]
	v_mfma_f32_16x16x32_bf16 v[68:71], v[166:169], v[210:213], v[68:71]
	v_mfma_f32_16x16x32_bf16 v[64:67], v[174:177], v[210:213], v[64:67]
	v_mfma_f32_16x16x32_bf16 v[108:111], v[170:173], v[186:189], v[108:111]
	v_mfma_f32_16x16x32_bf16 v[104:107], v[178:181], v[186:189], v[104:107]
	v_mfma_f32_16x16x32_bf16 v[100:103], v[170:173], v[194:197], v[100:103]
	v_mfma_f32_16x16x32_bf16 v[96:99], v[178:181], v[194:197], v[96:99]
	v_mfma_f32_16x16x32_bf16 v[76:79], v[170:173], v[206:209], v[76:79]
	v_mfma_f32_16x16x32_bf16 v[72:75], v[178:181], v[206:209], v[72:75]
	v_mfma_f32_16x16x32_bf16 v[68:71], v[170:173], v[214:217], v[68:71]
	v_mfma_f32_16x16x32_bf16 v[64:67], v[178:181], v[214:217], v[64:67]
	s_setprio 0
	s_barrier
	s_add_i32 s22, s50, s39
	v_lshl_add_u64 v[202:203], s[26:27], 0, v[130:131]
	s_mov_b32 m0, s22
	ds_read_b128 v[182:185], v157 offset:16384
	ds_read_b128 v[186:189], v157 offset:17408
	ds_read_b128 v[190:193], v157 offset:18432
	ds_read_b128 v[194:197], v157 offset:19456
	ds_read_b128 v[198:201], v157 offset:20480
	ds_read_b128 v[206:209], v157 offset:21504
	ds_read_b128 v[210:213], v157 offset:22528
	ds_read_b128 v[214:217], v157 offset:23552
	global_load_lds_dwordx4 v[202:203], off
	s_add_i32 m0, s22, 0x2000
	s_add_u32 s22, s26, 0x160000
	v_lshl_add_u64 v[218:219], s[26:27], 0, v[134:135]
	s_addc_u32 s23, s27, 0
	s_add_i32 s59, s51, s39
	global_load_lds_dwordx4 v[218:219], off
	v_lshl_add_u64 v[220:221], s[22:23], 0, v[130:131]
	s_mov_b32 m0, s59
	v_lshl_add_u64 v[222:223], s[28:29], 0, v[132:133]
	global_load_lds_dwordx4 v[220:221], off
	v_lshl_add_u64 v[220:221], s[22:23], 0, v[134:135]
	s_add_i32 m0, s59, 0x2000
	s_nop 0
	global_load_lds_dwordx4 v[220:221], off
	v_lshl_add_u64 v[220:221], s[28:29], 0, v[128:129]
	s_mov_b32 m0, s40
	s_nop 0
	global_load_lds_dwordx4 v[220:221], off
	s_mov_b32 m0, s41
	s_nop 0
	global_load_lds_dwordx4 v[222:223], off
	s_waitcnt vmcnt(8)
	s_waitcnt lgkmcnt(0)
	s_barrier
; #define PG8_STAGE(bufoff, gbase, voff) do { _Pragma("unroll") for (int _i = 0; _i < 2; ++_i) \
;         __builtin_amdgcn_global_load_lds((const unsigned*)((const char*)(gbase) + (voff)[_i]), (PG8_LAS unsigned*)(lds + (bufoff) + ldsw + _i * 8192), 16, 0, 0); } while (0)
; #define PG8_LDA(dst, b, h) do { _Pragma("unroll") for (int m = 0; m < 4; ++m) _Pragma("unroll") for (int k = 0; k < 2; ++k) dst[m][k] = *(const PG8_LAS bf16x8*)(lds + PG8_SA(b, h) + aoff + m * 2048 + k * 1024); } while (0)
; #define PG8_LDB(dst, b, h) do { _Pragma("unroll") for (int n = 0; n < 2; ++n) _Pragma("unroll") for (int k = 0; k < 2; ++k) dst[n][k] = *(const PG8_LAS bf16x8*)(lds + PG8_SB(b, h) + boff + n * 2048 + k * 1024); } while (0)
; template <class Epi, class Sched, bool ALIGN_EPI = false, bool SP2 = false>
; __device__ __forceinline__ void gemm_phase(PG8_LAS unsigned char* lds, const Gemm g, const Sched& S, const Epi& E, const int wv0) {
;     ...
;         for (int t = 0; t < nt; t += 2) {
;             const bool last = (t == nt - 2);
;             const char* a1 = cA + (size_t)(t + 1) * kstep;
;             const char* a2 = last ? nA : cA + (size_t)(t + 2) * kstep; const char* b2 = last ? nB : cB + (size_t)(t + 2) * kstep;
;             const char* a3 = a2 + kstep; const char* b3 = b2 + kstep;
;             if constexpr (SP2) {
;             PG8_LDB(B0, 0, 0); PG8_LDB(B1, 0, 1); PG8_SCHED; PG8_LDA(At, 0, 0); PG8_STAGE(PG8_SA(1, 1), a1 + hstepA, voffA);
;             PG8_WAIT_V(8); PG8_WAIT_L(0); PG8_BAR; PG8_MMA(0, 0, At, B0); PG8_MMA(0, 1, At, B1); PG8_BAR; PG8_SCHED;
;             PG8_LDA(At, 0, 1); PG8_STAGE(PG8_SB(0, 0), b2, voffB); PG8_STAGE(PG8_SB(0, 1), b2 + hstepB, voffB); PG8_STAGE(PG8_SA(0, 0), a2, voffA);
;             PG8_WAIT_V(8); PG8_WAIT_L(0); PG8_BAR; PG8_MMA(1, 0, At, B0); PG8_MMA(1, 1, At, B1); PG8_BAR; PG8_SCHED;
;             PG8_LDB(B0, 1, 0); PG8_LDB(B1, 1, 1); PG8_SCHED; PG8_LDA(At, 1, 0); PG8_STAGE(PG8_SA(0, 1), a2 + hstepA, voffA);
;             PG8_WAIT_V(8); PG8_WAIT_L(0); PG8_BAR; PG8_MMA(0, 0, At, B0); PG8_MMA(0, 1, At, B1); PG8_BAR; PG8_SCHED;
;             PG8_LDA(At, 1, 1); PG8_STAGE(PG8_SB(1, 0), b3, voffB); PG8_STAGE(PG8_SB(1, 1), b3 + hstepB, voffB); PG8_STAGE(PG8_SA(1, 0), a3, voffA);
;             PG8_WAIT_V(8); PG8_WAIT_L(0); PG8_BAR; PG8_MMA(1, 0, At, B0); PG8_MMA(1, 1, At, B1); PG8_BAR; PG8_SCHED;
	s_setprio 1
	v_mfma_f32_16x16x32_bf16 v[60:63], v[144:147], v[182:185], v[60:63]
	v_mfma_f32_16x16x32_bf16 v[56:59], v[158:161], v[182:185], v[56:59]
	v_mfma_f32_16x16x32_bf16 v[52:55], v[144:147], v[190:193], v[52:55]
	v_mfma_f32_16x16x32_bf16 v[48:51], v[158:161], v[190:193], v[48:51]
	v_mfma_f32_16x16x32_bf16 v[28:31], v[144:147], v[198:201], v[28:31]
	v_mfma_f32_16x16x32_bf16 v[24:27], v[158:161], v[198:201], v[24:27]
	v_mfma_f32_16x16x32_bf16 v[20:23], v[144:147], v[210:213], v[20:23]
	v_mfma_f32_16x16x32_bf16 v[16:19], v[158:161], v[210:213], v[16:19]
	v_mfma_f32_16x16x32_bf16 v[60:63], v[148:151], v[186:189], v[60:63]
	v_mfma_f32_16x16x32_bf16 v[56:59], v[162:165], v[186:189], v[56:59]
	v_mfma_f32_16x16x32_bf16 v[52:55], v[148:151], v[194:197], v[52:55]
	v_mfma_f32_16x16x32_bf16 v[48:51], v[162:165], v[194:197], v[48:51]
	v_mfma_f32_16x16x32_bf16 v[28:31], v[148:151], v[206:209], v[28:31]
	v_mfma_f32_16x16x32_bf16 v[24:27], v[162:165], v[206:209], v[24:27]
	v_mfma_f32_16x16x32_bf16 v[20:23], v[148:151], v[214:217], v[20:23]
	v_mfma_f32_16x16x32_bf16 v[16:19], v[162:165], v[214:217], v[16:19]
	v_mfma_f32_16x16x32_bf16 v[44:47], v[166:169], v[182:185], v[44:47]
	v_mfma_f32_16x16x32_bf16 v[40:43], v[174:177], v[182:185], v[40:43]
	v_mfma_f32_16x16x32_bf16 v[36:39], v[166:169], v[190:193], v[36:39]
	v_mfma_f32_16x16x32_bf16 v[32:35], v[174:177], v[190:193], v[32:35]
	v_mfma_f32_16x16x32_bf16 v[12:15], v[166:169], v[198:201], v[12:15]
	v_mfma_f32_16x16x32_bf16 v[8:11], v[174:177], v[198:201], v[8:11]
	v_mfma_f32_16x16x32_bf16 v[4:7], v[166:169], v[210:213], v[4:7]
	v_mfma_f32_16x16x32_bf16 v[0:3], v[174:177], v[210:213], v[0:3]
	v_mfma_f32_16x16x32_bf16 v[44:47], v[170:173], v[186:189], v[44:47]
	v_mfma_f32_16x16x32_bf16 v[40:43], v[178:181], v[186:189], v[40:43]
	v_mfma_f32_16x16x32_bf16 v[36:39], v[170:173], v[194:197], v[36:39]
	v_mfma_f32_16x16x32_bf16 v[32:35], v[178:181], v[194:197], v[32:35]
	v_mfma_f32_16x16x32_bf16 v[12:15], v[170:173], v[206:209], v[12:15]
	v_mfma_f32_16x16x32_bf16 v[8:11], v[178:181], v[206:209], v[8:11]
	v_mfma_f32_16x16x32_bf16 v[4:7], v[170:173], v[214:217], v[4:7]
	v_mfma_f32_16x16x32_bf16 v[0:3], v[178:181], v[214:217], v[0:3]
	s_setprio 0
	s_barrier
	s_add_i32 s59, 0, 0x18000
	s_add_i32 s60, 0, 0x1c000
	v_add_u32_e32 v162, s59, v153
	v_add_u32_e32 v178, s60, v153
	ds_read_b128 v[144:147], v162
	ds_read_b128 v[148:151], v162 offset:1024
	ds_read_b128 v[158:161], v162 offset:2048
	ds_read_b128 v[162:165], v162 offset:3072
	ds_read_b128 v[166:169], v178
	ds_read_b128 v[170:173], v178 offset:1024
	ds_read_b128 v[174:177], v178 offset:2048
	ds_read_b128 v[178:181], v178 offset:3072
	s_add_u32 s22, s28, 0x160000
	s_addc_u32 s23, s29, 0
	s_mov_b32 m0, s44
	v_lshl_add_u64 v[224:225], s[22:23], 0, v[128:129]
	ds_read_b128 v[182:185], v157 offset:32768
	ds_read_b128 v[186:189], v157 offset:33792
	ds_read_b128 v[190:193], v157 offset:34816
	ds_read_b128 v[194:197], v157 offset:35840
	ds_read_b128 v[198:201], v157 offset:36864
	ds_read_b128 v[206:209], v157 offset:37888
	ds_read_b128 v[210:213], v157 offset:38912
	ds_read_b128 v[214:217], v157 offset:39936
	global_load_lds_dwordx4 v[224:225], off
	v_lshl_add_u64 v[224:225], s[22:23], 0, v[132:133]
	s_mov_b32 m0, s45
	s_nop 0
	global_load_lds_dwordx4 v[224:225], off
	s_waitcnt vmcnt(8)
	s_waitcnt lgkmcnt(0)
	s_barrier
	s_setprio 1
	v_mfma_f32_16x16x32_bf16 v[124:127], v[144:147], v[182:185], v[124:127]
	v_mfma_f32_16x16x32_bf16 v[120:123], v[158:161], v[182:185], v[120:123]
	v_mfma_f32_16x16x32_bf16 v[116:119], v[144:147], v[190:193], v[116:119]
	v_mfma_f32_16x16x32_bf16 v[112:115], v[158:161], v[190:193], v[112:115]
	v_mfma_f32_16x16x32_bf16 v[92:95], v[144:147], v[198:201], v[92:95]
	v_mfma_f32_16x16x32_bf16 v[88:91], v[158:161], v[198:201], v[88:91]
	v_mfma_f32_16x16x32_bf16 v[84:87], v[144:147], v[210:213], v[84:87]
	v_mfma_f32_16x16x32_bf16 v[80:83], v[158:161], v[210:213], v[80:83]
	v_mfma_f32_16x16x32_bf16 v[124:127], v[148:151], v[186:189], v[124:127]
	v_mfma_f32_16x16x32_bf16 v[120:123], v[162:165], v[186:189], v[120:123]
	v_mfma_f32_16x16x32_bf16 v[116:119], v[148:151], v[194:197], v[116:119]
	v_mfma_f32_16x16x32_bf16 v[112:115], v[162:165], v[194:197], v[112:115]
	v_mfma_f32_16x16x32_bf16 v[92:95], v[148:151], v[206:209], v[92:95]
	v_mfma_f32_16x16x32_bf16 v[88:91], v[162:165], v[206:209], v[88:91]
	v_mfma_f32_16x16x32_bf16 v[84:87], v[148:151], v[214:217], v[84:87]
	v_mfma_f32_16x16x32_bf16 v[80:83], v[162:165], v[214:217], v[80:83]
	v_mfma_f32_16x16x32_bf16 v[108:111], v[166:169], v[182:185], v[108:111]
	v_mfma_f32_16x16x32_bf16 v[104:107], v[174:177], v[182:185], v[104:107]
	v_mfma_f32_16x16x32_bf16 v[100:103], v[166:169], v[190:193], v[100:103]
	v_mfma_f32_16x16x32_bf16 v[96:99], v[174:177], v[190:193], v[96:99]
	v_mfma_f32_16x16x32_bf16 v[76:79], v[166:169], v[198:201], v[76:79]
	v_mfma_f32_16x16x32_bf16 v[72:75], v[174:177], v[198:201], v[72:75]
	v_mfma_f32_16x16x32_bf16 v[68:71], v[166:169], v[210:213], v[68:71]
	v_mfma_f32_16x16x32_bf16 v[64:67], v[174:177], v[210:213], v[64:67]
	v_mfma_f32_16x16x32_bf16 v[108:111], v[170:173], v[186:189], v[108:111]
	v_mfma_f32_16x16x32_bf16 v[104:107], v[178:181], v[186:189], v[104:107]
	v_mfma_f32_16x16x32_bf16 v[100:103], v[170:173], v[194:197], v[100:103]
	v_mfma_f32_16x16x32_bf16 v[96:99], v[178:181], v[194:197], v[96:99]
	v_mfma_f32_16x16x32_bf16 v[76:79], v[170:173], v[206:209], v[76:79]
	v_mfma_f32_16x16x32_bf16 v[72:75], v[178:181], v[206:209], v[72:75]
	v_mfma_f32_16x16x32_bf16 v[68:71], v[170:173], v[214:217], v[68:71]
	v_mfma_f32_16x16x32_bf16 v[64:67], v[178:181], v[214:217], v[64:67]
	s_setprio 0
	s_barrier
; #define PG8_STAGE(bufoff, gbase, voff) do { _Pragma("unroll") for (int _i = 0; _i < 2; ++_i) \
;         __builtin_amdgcn_global_load_lds((const unsigned*)((const char*)(gbase) + (voff)[_i]), (PG8_LAS unsigned*)(lds + (bufoff) + ldsw + _i * 8192), 16, 0, 0); } while (0)
; #define PG8_LDA(dst, b, h) do { _Pragma("unroll") for (int m = 0; m < 4; ++m) _Pragma("unroll") for (int k = 0; k < 2; ++k) dst[m][k] = *(const PG8_LAS bf16x8*)(lds + PG8_SA(b, h) + aoff + m * 2048 + k * 1024); } while (0)
; #define PG8_LDB(dst, b, h) do { _Pragma("unroll") for (int n = 0; n < 2; ++n) _Pragma("unroll") for (int k = 0; k < 2; ++k) dst[n][k] = *(const PG8_LAS bf16x8*)(lds + PG8_SB(b, h) + boff + n * 2048 + k * 1024); } while (0)
; template <class Epi, class Sched, bool ALIGN_EPI = false, bool SP2 = false>
; __device__ __forceinline__ void gemm_phase(PG8_LAS unsigned char* lds, const Gemm g, const Sched& S, const Epi& E, const int wv0) {
;     ...
;         for (int t = 0; t < nt; t += 2) {
;             const bool last = (t == nt - 2);
;             const char* a1 = cA + (size_t)(t + 1) * kstep;
;             const char* a2 = last ? nA : cA + (size_t)(t + 2) * kstep; const char* b2 = last ? nB : cB + (size_t)(t + 2) * kstep;
;             const char* a3 = a2 + kstep; const char* b3 = b2 + kstep;
;             if constexpr (SP2) {
;             PG8_LDB(B0, 0, 0); PG8_LDB(B1, 0, 1); PG8_SCHED; PG8_LDA(At, 0, 0); PG8_STAGE(PG8_SA(1, 1), a1 + hstepA, voffA);
;             PG8_WAIT_V(8); PG8_WAIT_L(0); PG8_BAR; PG8_MMA(0, 0, At, B0); PG8_MMA(0, 1, At, B1); PG8_BAR; PG8_SCHED;
;             PG8_LDA(At, 0, 1); PG8_STAGE(PG8_SB(0, 0), b2, voffB); PG8_STAGE(PG8_SB(0, 1), b2 + hstepB, voffB); PG8_STAGE(PG8_SA(0, 0), a2, voffA);
;             PG8_WAIT_V(8); PG8_WAIT_L(0); PG8_BAR; PG8_MMA(1, 0, At, B0); PG8_MMA(1, 1, At, B1); PG8_BAR; PG8_SCHED;
;             PG8_LDB(B0, 1, 0); PG8_LDB(B1, 1, 1); PG8_SCHED; PG8_LDA(At, 1, 0); PG8_STAGE(PG8_SA(0, 1), a2 + hstepA, voffA);
;             PG8_WAIT_V(8); PG8_WAIT_L(0); PG8_BAR; PG8_MMA(0, 0, At, B0); PG8_MMA(0, 1, At, B1); PG8_BAR; PG8_SCHED;
;             PG8_LDA(At, 1, 1); PG8_STAGE(PG8_SB(1, 0), b3, voffB); PG8_STAGE(PG8_SB(1, 1), b3 + hstepB, voffB); PG8_STAGE(PG8_SA(1, 0), a3, voffA);
;             PG8_WAIT_V(8); PG8_WAIT_L(0); PG8_BAR; PG8_MMA(1, 0, At, B0); PG8_MMA(1, 1, At, B1); PG8_BAR; PG8_SCHED;
	s_add_i32 s22, s59, s39
	v_lshl_add_u64 v[202:203], v[202:203], 0, s[6:7]
	s_mov_b32 m0, s22
	ds_read_b128 v[182:185], v157 offset:49152
	ds_read_b128 v[186:189], v157 offset:50176
	ds_read_b128 v[190:193], v157 offset:51200
	ds_read_b128 v[194:197], v157 offset:52224
	ds_read_b128 v[198:201], v157 offset:53248
	ds_read_b128 v[206:209], v157 offset:54272
	ds_read_b128 v[210:213], v157 offset:55296
	ds_read_b128 v[214:217], v157 offset:56320
	global_load_lds_dwordx4 v[202:203], off
	s_add_i32 m0, s22, 0x2000
	s_add_u32 s22, s26, 0x160080
	v_lshl_add_u64 v[202:203], v[218:219], 0, s[6:7]
	s_addc_u32 s23, s27, 0
	s_add_i32 s26, s60, s39
	global_load_lds_dwordx4 v[202:203], off
	v_lshl_add_u64 v[202:203], s[22:23], 0, v[130:131]
	s_mov_b32 m0, s26
	s_nop 0
	global_load_lds_dwordx4 v[202:203], off
	v_lshl_add_u64 v[202:203], s[22:23], 0, v[134:135]
	s_add_i32 m0, s26, 0x2000
	s_nop 0
	global_load_lds_dwordx4 v[202:203], off
	v_lshl_add_u64 v[202:203], v[220:221], 0, s[6:7]
	s_mov_b32 m0, s47
	s_nop 0
	global_load_lds_dwordx4 v[202:203], off
	v_lshl_add_u64 v[202:203], v[222:223], 0, s[6:7]
	s_mov_b32 m0, s48
	s_nop 0
	global_load_lds_dwordx4 v[202:203], off
	s_waitcnt vmcnt(8)
	s_waitcnt lgkmcnt(0)
	s_barrier
	s_setprio 1
	v_mfma_f32_16x16x32_bf16 v[60:63], v[144:147], v[182:185], v[60:63]
	v_mfma_f32_16x16x32_bf16 v[56:59], v[158:161], v[182:185], v[56:59]
	v_mfma_f32_16x16x32_bf16 v[52:55], v[144:147], v[190:193], v[52:55]
	v_mfma_f32_16x16x32_bf16 v[48:51], v[158:161], v[190:193], v[48:51]
	v_mfma_f32_16x16x32_bf16 v[28:31], v[144:147], v[198:201], v[28:31]
	v_mfma_f32_16x16x32_bf16 v[24:27], v[158:161], v[198:201], v[24:27]
	v_mfma_f32_16x16x32_bf16 v[20:23], v[144:147], v[210:213], v[20:23]
	v_mfma_f32_16x16x32_bf16 v[16:19], v[158:161], v[210:213], v[16:19]
	v_mfma_f32_16x16x32_bf16 v[60:63], v[148:151], v[186:189], v[60:63]
	v_mfma_f32_16x16x32_bf16 v[56:59], v[162:165], v[186:189], v[56:59]
	v_mfma_f32_16x16x32_bf16 v[52:55], v[148:151], v[194:197], v[52:55]
	v_mfma_f32_16x16x32_bf16 v[48:51], v[162:165], v[194:197], v[48:51]
	v_mfma_f32_16x16x32_bf16 v[28:31], v[148:151], v[206:209], v[28:31]
	v_mfma_f32_16x16x32_bf16 v[24:27], v[162:165], v[206:209], v[24:27]
	v_mfma_f32_16x16x32_bf16 v[20:23], v[148:151], v[214:217], v[20:23]
	v_mfma_f32_16x16x32_bf16 v[16:19], v[162:165], v[214:217], v[16:19]
	v_mfma_f32_16x16x32_bf16 v[44:47], v[166:169], v[182:185], v[44:47]
	v_mfma_f32_16x16x32_bf16 v[40:43], v[174:177], v[182:185], v[40:43]
	v_mfma_f32_16x16x32_bf16 v[36:39], v[166:169], v[190:193], v[36:39]
	v_mfma_f32_16x16x32_bf16 v[32:35], v[174:177], v[190:193], v[32:35]
	v_mfma_f32_16x16x32_bf16 v[12:15], v[166:169], v[198:201], v[12:15]
	v_mfma_f32_16x16x32_bf16 v[8:11], v[174:177], v[198:201], v[8:11]
	v_mfma_f32_16x16x32_bf16 v[4:7], v[166:169], v[210:213], v[4:7]
	v_mfma_f32_16x16x32_bf16 v[0:3], v[174:177], v[210:213], v[0:3]
	v_mfma_f32_16x16x32_bf16 v[44:47], v[170:173], v[186:189], v[44:47]
	v_mfma_f32_16x16x32_bf16 v[40:43], v[178:181], v[186:189], v[40:43]
	v_mfma_f32_16x16x32_bf16 v[36:39], v[170:173], v[194:197], v[36:39]
	v_mfma_f32_16x16x32_bf16 v[32:35], v[178:181], v[194:197], v[32:35]
	v_mfma_f32_16x16x32_bf16 v[12:15], v[170:173], v[206:209], v[12:15]
	v_mfma_f32_16x16x32_bf16 v[8:11], v[178:181], v[206:209], v[8:11]
	v_mfma_f32_16x16x32_bf16 v[4:7], v[170:173], v[214:217], v[4:7]
	v_mfma_f32_16x16x32_bf16 v[0:3], v[178:181], v[214:217], v[0:3]
	s_setprio 0
	s_barrier
	s_add_i32 s58, s58, 2
	s_add_u32 s56, s56, 0x100
	s_addc_u32 s57, s57, 0
	s_cmpk_gt_u32 s58, 0x55
	s_mov_b64 s[22:23], s[24:25]
	s_cbranch_scc0 .LBB0_867
	s_and_b64 vcc, exec, s[8:9]
	s_cbranch_vccz .LBB0_870
	s_barrier

; __device__ __forceinline__ int crow(int r, int hi) { return (r & 3) + 8 * (r >> 2) + 4 * hi; }
; __device__ __forceinline__ void qkt(f32x16& p0, f32x16& p1, const char* Ks, const bf16x8* qr, int r32, int hi) {
;     p0 = f32x16{}; p1 = f32x16{};
; #pragma unroll
;     for (int d0 = 0; d0 < 8; ++d0) { const int cb = (d0 * 16 + hi * 8) * 2;
;         const bf16x8 b0 = *reinterpret_cast<const bf16x8*>(Ks + KSWZ(r32, cb));
;         const bf16x8 b1 = *reinterpret_cast<const bf16x8*>(Ks + KSWZ(32 + r32, cb));
;         p0 = __builtin_amdgcn_mfma_f32_32x32x16_bf16(b0, qr[d0], p0, 0, 0, 0);
;         p1 = __builtin_amdgcn_mfma_f32_32x32x16_bf16(b1, qr[d0], p1, 0, 0, 0); }
; }
; __device__ __forceinline__ void sb_half(f32x16& p, float& carry, bool masked, int krow0, int tq, int hi) {
;     float G[4];
; #pragma unroll
;     for (int g = 0; g < 4; ++g) {
;         float q[4];
; #pragma unroll
;         for (int i = 0; i < 4; ++i) { const int r = 4 * g + i; const float e = __builtin_amdgcn_exp2f(p[r]); float qq = __builtin_amdgcn_rcpf(1.0f + e); float b = e * qq;
;             if (masked) { const bool keep = (krow0 + crow(r, hi)) < tq; qq = keep ? qq : 1.0f; b = keep ? b : 0.0f; }
;             q[i] = qq; p[r] = b; }
;         const float s2 = q[3] * q[2], s1 = s2 * q[1]; G[g] = s1 * q[0];
;         p[4 * g + 2] *= q[3]; p[4 * g + 1] *= s2; p[4 * g] *= s1;
;     }
;     float run = carry;
; #pragma unroll
;     for (int g = 3; g >= 0; --g) { const unsigned gu = __builtin_bit_cast(unsigned, G[g]); auto sw = __builtin_amdgcn_permlane32_swap(gu, gu, false, false);
;         const float partner = __builtin_bit_cast(float, hi ? sw[0] : sw[1]);
;         const float base = hi ? run : run * partner;
;         p[4 * g] *= base; p[4 * g + 1] *= base; p[4 * g + 2] *= base; p[4 * g + 3] *= base; run *= G[g] * partner; }
;     carry = run;
; }
.LBB0_1228:
	s_add_i32 s72, s79, -1
	ds_read_b128 v[80:83], v201 offset:49152
	ds_read_b128 v[96:99], v201 offset:57344
	ds_read_b128 v[144:147], v202 offset:49152
	ds_read_b128 v[148:151], v202 offset:57344
	v_exp_f32_e32 v64, v64
	s_waitcnt lgkmcnt(3)
	v_mfma_f32_32x32x16_bf16 v[80:95], v[80:83], v[140:143], 0
	v_exp_f32_e32 v65, v65
	v_exp_f32_e32 v66, v66
	v_add_f32_e32 v214, 1.0, v64
	v_rcp_f32_e32 v254, v214
	v_add_u32_e32 v214, s94, v213
	s_cmp_lt_u32 s72, 5
	v_exp_f32_e32 v67, v67
	s_waitcnt lgkmcnt(2)
	v_mfma_f32_32x32x16_bf16 v[96:111], v[96:99], v[140:143], 0
	v_mul_f32_e32 v64, v64, v254
	v_exp_f32_e32 v68, v68
	v_exp_f32_e32 v69, v69
	v_exp_f32_e32 v70, v70
	v_exp_f32_e32 v71, v71
	v_exp_f32_e32 v72, v72
	v_exp_f32_e32 v73, v73
	s_waitcnt lgkmcnt(1)
	v_mfma_f32_32x32x16_bf16 v[80:95], v[144:147], v[136:139], v[80:95]
	v_add_f32_e32 v146, 1.0, v65
	v_add_u32_e32 v144, 0xc0, v214
	v_rcp_f32_e32 v146, v146
	v_cmp_lt_i32_e32 vcc, v144, v164
	v_exp_f32_e32 v74, v74
	v_exp_f32_e32 v75, v75
	v_cndmask_b32_e32 v144, 1.0, v254, vcc
	v_cndmask_b32_e32 v145, 0, v64, vcc
	s_cselect_b64 vcc, -1, 0
	s_waitcnt lgkmcnt(0)
	v_mfma_f32_32x32x16_bf16 v[96:111], v[148:151], v[136:139], v[96:111]
	v_cndmask_b32_e32 v64, v64, v145, vcc
	v_add_u32_e32 v145, 0xc1, v214
	v_add_f32_e32 v148, 1.0, v66
	v_mul_f32_e32 v65, v65, v146
	v_cmp_lt_i32_e64 s[4:5], v145, v164
	v_rcp_f32_e32 v148, v148
	v_cndmask_b32_e32 v144, v254, v144, vcc
	v_cndmask_b32_e64 v145, 1.0, v146, s[4:5]
	v_cndmask_b32_e64 v147, 0, v65, s[4:5]
	v_cndmask_b32_e32 v65, v65, v147, vcc
	v_cndmask_b32_e32 v145, v146, v145, vcc
	v_add_u32_e32 v146, 0xc2, v214
	v_add_f32_e32 v147, 1.0, v67
	v_cmp_lt_i32_e64 s[4:5], v146, v164
	v_rcp_f32_e32 v147, v147
	v_mul_f32_e32 v66, v66, v148
	v_cndmask_b32_e64 v146, 1.0, v148, s[4:5]
	v_cndmask_b32_e32 v146, v148, v146, vcc
	v_add_u32_e32 v148, 0xc3, v214
	v_cndmask_b32_e64 v149, 0, v66, s[4:5]
	v_cmp_lt_i32_e64 s[4:5], v148, v164
	v_mul_f32_e32 v67, v67, v147
	v_cndmask_b32_e32 v66, v66, v149, vcc
	v_cndmask_b32_e64 v148, 1.0, v147, s[4:5]
	v_cndmask_b32_e32 v147, v147, v148, vcc
	v_mul_f32_e32 v146, v147, v146
	v_mul_f32_e32 v145, v145, v146
	v_mul_f32_e32 v65, v65, v146
	v_add_f32_e32 v146, 1.0, v68
	v_rcp_f32_e32 v146, v146
	v_mul_f32_e32 v144, v144, v145
	v_mul_f32_e32 v64, v64, v145
	v_add_u32_e32 v145, 0xc8, v214
	v_add_f32_e32 v148, 1.0, v69
	v_cndmask_b32_e64 v149, 0, v67, s[4:5]
	v_mul_f32_e32 v68, v68, v146
	v_cmp_lt_i32_e64 s[4:5], v145, v164
	v_rcp_f32_e32 v148, v148
	v_mul_f32_e32 v66, v147, v66
	v_cndmask_b32_e64 v145, 1.0, v146, s[4:5]
	v_cndmask_b32_e64 v147, 0, v68, s[4:5]
	v_cndmask_b32_e32 v68, v68, v147, vcc
	v_cndmask_b32_e32 v145, v146, v145, vcc
	v_add_u32_e32 v146, 0xc9, v214
	v_add_f32_e32 v147, 1.0, v70
	v_cmp_lt_i32_e64 s[4:5], v146, v164
	v_rcp_f32_e32 v147, v147
	v_mul_f32_e32 v69, v69, v148
	v_cndmask_b32_e64 v146, 1.0, v148, s[4:5]
	v_cndmask_b32_e32 v146, v148, v146, vcc
	v_add_u32_e32 v148, 0xca, v214
	v_add_f32_e32 v150, 1.0, v71
	v_cndmask_b32_e32 v67, v67, v149, vcc
	v_cndmask_b32_e64 v149, 0, v69, s[4:5]
	v_cmp_lt_i32_e64 s[4:5], v148, v164
	v_rcp_f32_e32 v150, v150
	v_mul_f32_e32 v70, v70, v147
	v_cndmask_b32_e64 v148, 1.0, v147, s[4:5]
	v_cndmask_b32_e32 v147, v147, v148, vcc
	v_add_u32_e32 v148, 0xcb, v214
	v_cndmask_b32_e32 v69, v69, v149, vcc
	v_cndmask_b32_e64 v149, 0, v70, s[4:5]
	v_cmp_lt_i32_e64 s[4:5], v148, v164
	v_cndmask_b32_e32 v70, v70, v149, vcc
	v_mul_f32_e32 v71, v71, v150
	v_cndmask_b32_e64 v148, 1.0, v150, s[4:5]
	v_cndmask_b32_e32 v148, v150, v148, vcc
	v_mul_f32_e32 v147, v148, v147
	v_mul_f32_e32 v146, v146, v147
	v_mul_f32_e32 v69, v69, v147
	v_add_f32_e32 v147, 1.0, v72
	v_rcp_f32_e32 v147, v147
	v_mul_f32_e32 v70, v148, v70
	v_add_f32_e32 v148, 1.0, v73
	v_mul_f32_e32 v145, v145, v146
	v_mul_f32_e32 v68, v68, v146
	v_add_u32_e32 v146, 0xd0, v214
	v_rcp_f32_e32 v148, v148
	v_cndmask_b32_e64 v149, 0, v71, s[4:5]
	v_mul_f32_e32 v72, v72, v147
	v_cmp_lt_i32_e64 s[4:5], v146, v164
	v_cndmask_b32_e32 v71, v71, v149, vcc
	v_mul_f32_e32 v73, v73, v148
	v_cndmask_b32_e64 v146, 1.0, v147, s[4:5]
	v_cndmask_b32_e64 v149, 0, v72, s[4:5]
	v_cndmask_b32_e32 v72, v72, v149, vcc
	v_cndmask_b32_e32 v146, v147, v146, vcc
	v_add_u32_e32 v147, 0xd1, v214
	v_add_f32_e32 v149, 1.0, v74
	v_cmp_lt_i32_e64 s[4:5], v147, v164
	v_rcp_f32_e32 v149, v149
	ds_read_b128 v[152:155], v208 offset:49152
	ds_read_b128 v[156:159], v208 offset:57344
	ds_read_b128 v[216:219], v209 offset:49152
	ds_read_b128 v[220:223], v209 offset:57344
	ds_read_b128 v[224:227], v210 offset:49152
	ds_read_b128 v[228:231], v210 offset:57344
	ds_read_b128 v[232:235], v211 offset:49152
	ds_read_b128 v[236:239], v211 offset:57344
	v_cndmask_b32_e64 v147, 1.0, v148, s[4:5]
	v_cndmask_b32_e64 v150, 0, v73, s[4:5]
	v_cndmask_b32_e32 v73, v73, v150, vcc
	v_cndmask_b32_e32 v147, v148, v147, vcc
	v_add_u32_e32 v148, 0xd2, v214
	v_add_f32_e32 v150, 1.0, v75
	v_cmp_lt_i32_e64 s[4:5], v148, v164
	v_rcp_f32_e32 v150, v150
	s_waitcnt lgkmcnt(7)
	v_mfma_f32_32x32x16_bf16 v[80:95], v[152:155], v[132:135], v[80:95]
	v_cndmask_b32_e64 v148, 1.0, v149, s[4:5]
	v_mul_f32_e32 v74, v74, v149
	v_cndmask_b32_e32 v148, v149, v148, vcc
	v_add_u32_e32 v149, 0xd3, v214
	v_cndmask_b32_e64 v151, 0, v74, s[4:5]
	v_cmp_lt_i32_e64 s[4:5], v149, v164
	v_exp_f32_e32 v76, v76
	s_waitcnt lgkmcnt(6)
	v_mfma_f32_32x32x16_bf16 v[96:111], v[156:159], v[132:135], v[96:111]
	v_cndmask_b32_e64 v149, 1.0, v150, s[4:5]
	v_cndmask_b32_e32 v149, v150, v149, vcc
	v_mul_f32_e32 v148, v149, v148
	v_exp_f32_e32 v77, v77
	v_mul_f32_e32 v147, v147, v148
	v_mul_f32_e32 v73, v73, v148
	v_add_f32_e32 v148, 1.0, v76
	v_rcp_f32_e32 v148, v148
	v_cndmask_b32_e32 v74, v74, v151, vcc
	s_waitcnt lgkmcnt(5)
; __device__ __forceinline__ void sb_half(f32x16& p, float& carry, bool masked, int krow0, int tq, int hi) {
;     ...
;     float run = carry;
; #pragma unroll
;     for (int g = 3; g >= 0; --g) { const unsigned gu = __builtin_bit_cast(unsigned, G[g]); auto sw = __builtin_amdgcn_permlane32_swap(gu, gu, false, false);
;         const float partner = __builtin_bit_cast(float, hi ? sw[0] : sw[1]);
;         const float base = hi ? run : run * partner;
;         p[4 * g] *= base; p[4 * g + 1] *= base; p[4 * g + 2] *= base; p[4 * g + 3] *= base; run *= G[g] * partner; }
;     carry = run;
; }
; __device__ __forceinline__ void pack_p(const f32x16& p0, const f32x16& p1, bf16x8& pa0, bf16x8& pa1, bf16x8& pa2, bf16x8& pa3) {
;     ...
;     PK4(p0, 0, pa0); PK4(p0, 8, pa1); PK4(p1, 0, pa2); PK4(p1, 8, pa3);
;     ...
; }
; __device__ __forceinline__ void sb_unit(const bf16* __restrict__ Qb, const bf16* __restrict__ Kh, const bf16* __restrict__ Vh, bf16* __restrict__ Ob, int q0, char* lds, const int wv0) {
;     ...
;         { const int z = __all(carry == 0.0f); if (lane == 0) votes[wid] = (unsigned)z; }
	v_mfma_f32_32x32x16_bf16 v[80:95], v[216:219], v[128:131], v[80:95]
	v_mul_f32_e32 v74, v149, v74
	v_add_f32_e32 v149, 1.0, v77
	v_exp_f32_e32 v78, v78
	v_mul_f32_e32 v75, v75, v150
	v_mul_f32_e32 v146, v146, v147
	v_mul_f32_e32 v72, v72, v147
	v_add_u32_e32 v147, 0xd8, v214
	s_waitcnt lgkmcnt(4)
	v_mfma_f32_32x32x16_bf16 v[96:111], v[220:223], v[128:131], v[96:111]
	v_rcp_f32_e32 v149, v149
	v_cndmask_b32_e64 v151, 0, v75, s[4:5]
	v_mul_f32_e32 v76, v76, v148
	v_cmp_lt_i32_e64 s[4:5], v147, v164
	v_exp_f32_e32 v79, v79
	v_mul_f32_e32 v77, v77, v149
	v_cndmask_b32_e64 v147, 1.0, v148, s[4:5]
	v_cndmask_b32_e64 v150, 0, v76, s[4:5]
	v_cndmask_b32_e32 v76, v76, v150, vcc
	v_cndmask_b32_e32 v147, v148, v147, vcc
	v_add_u32_e32 v148, 0xd9, v214
	v_add_f32_e32 v150, 1.0, v78
	v_cmp_lt_i32_e64 s[4:5], v148, v164
	v_rcp_f32_e32 v150, v150
	v_cndmask_b32_e32 v75, v75, v151, vcc
	v_cndmask_b32_e64 v148, 1.0, v149, s[4:5]
	v_cndmask_b32_e64 v151, 0, v77, s[4:5]
	v_cndmask_b32_e32 v77, v77, v151, vcc
	v_cndmask_b32_e32 v148, v149, v148, vcc
	v_add_u32_e32 v149, 0xda, v214
	v_add_f32_e32 v151, 1.0, v79
	s_waitcnt lgkmcnt(3)
	v_mfma_f32_32x32x16_bf16 v[80:95], v[224:227], v[124:127], v[80:95]
	v_cmp_lt_i32_e64 s[4:5], v149, v164
	v_rcp_f32_e32 v151, v151
	v_mul_f32_e32 v78, v78, v150
	v_cndmask_b32_e64 v149, 1.0, v150, s[4:5]
	v_cndmask_b32_e32 v149, v150, v149, vcc
	v_add_u32_e32 v150, 0xdb, v214
	v_cndmask_b32_e64 v152, 0, v78, s[4:5]
	s_waitcnt lgkmcnt(2)
	v_mfma_f32_32x32x16_bf16 v[96:111], v[228:231], v[124:127], v[96:111]
	v_cmp_lt_i32_e64 s[4:5], v150, v164
	v_cndmask_b32_e32 v78, v78, v152, vcc
	v_mul_f32_e32 v79, v79, v151
	v_cndmask_b32_e64 v150, 1.0, v151, s[4:5]
	v_cndmask_b32_e32 v150, v151, v150, vcc
	v_mul_f32_e32 v149, v150, v149
	v_mul_f32_e32 v148, v148, v149
	s_waitcnt lgkmcnt(1)
	v_mfma_f32_32x32x16_bf16 v[80:95], v[232:235], v[120:123], v[80:95]
	v_mul_f32_e32 v147, v147, v148
	v_mul_f32_e32 v77, v77, v149
	v_mul_f32_e32 v76, v76, v148
	v_mov_b32_e32 v148, v147
	v_mov_b32_e32 v149, v147
	s_nop 1
	v_permlane32_swap_b32_e32 v148, v149
	s_waitcnt lgkmcnt(0)
	v_mfma_f32_32x32x16_bf16 v[96:111], v[236:239], v[120:123], v[96:111]
	v_cndmask_b32_e64 v148, v148, v149, s[0:1]
	v_mul_f32_e32 v149, v215, v148
	ds_read_b128 v[240:243], v203 offset:49152
	ds_read_b128 v[244:247], v203 offset:57344
	ds_read_b128 v[248:251], v212 offset:49152
	ds_read_b128 v[194:197], v212 offset:57344
	v_cndmask_b32_e64 v152, 0, v79, s[4:5]
	v_mul_f32_e32 v78, v150, v78
	v_cndmask_b32_e64 v149, v215, v149, s[0:1]
	v_cndmask_b32_e32 v79, v79, v152, vcc
	v_mul_f32_e32 v151, v77, v149
	v_mul_f32_e32 v152, v78, v149
	v_mov_b32_e32 v77, v146
	v_mov_b32_e32 v78, v146
	v_mul_f32_e32 v150, v76, v149
	v_mul_f32_e32 v76, v147, v148
	v_permlane32_swap_b32_e32 v77, v78
	s_waitcnt lgkmcnt(3)
	v_mfma_f32_32x32x16_bf16 v[80:95], v[240:243], v[116:119], v[80:95]
	v_mul_f32_e32 v76, v215, v76
	v_cndmask_b32_e64 v77, v77, v78, s[0:1]
	v_mul_f32_e32 v78, v76, v77
	v_cndmask_b32_e64 v78, v76, v78, s[0:1]
	v_mul_f32_e32 v77, v146, v77
	v_mul_f32_e32 v72, v72, v78
	v_mul_f32_e32 v73, v73, v78
	s_waitcnt lgkmcnt(2)
	v_mfma_f32_32x32x16_bf16 v[96:111], v[244:247], v[116:119], v[96:111]
	v_mul_f32_e32 v74, v74, v78
	v_mul_f32_e32 v75, v75, v78
	v_mul_f32_e32 v76, v76, v77
	v_mov_b32_e32 v77, v145
	v_mov_b32_e32 v78, v145
	s_nop 1
	v_permlane32_swap_b32_e32 v77, v78
	v_cndmask_b32_e64 v77, v77, v78, s[0:1]
	v_mul_f32_e32 v78, v76, v77
	v_cndmask_b32_e64 v78, v76, v78, s[0:1]
	v_mul_f32_e32 v77, v145, v77
	s_waitcnt lgkmcnt(1)
	v_mfma_f32_32x32x16_bf16 v[80:95], v[248:251], v[112:115], v[80:95]
	v_mul_f32_e32 v68, v68, v78
	v_mul_f32_e32 v69, v69, v78
	v_mul_f32_e32 v70, v70, v78
	v_mul_f32_e32 v71, v71, v78
	v_mul_f32_e32 v76, v76, v77
	v_mov_b32_e32 v77, v144
	v_mov_b32_e32 v78, v144
	s_waitcnt lgkmcnt(0)
	v_mfma_f32_32x32x16_bf16 v[96:111], v[194:197], v[112:115], v[96:111]
	v_permlane32_swap_b32_e32 v77, v78
	v_cndmask_b32_e64 v77, v77, v78, s[0:1]
	v_mul_f32_e32 v78, v76, v77
	v_cndmask_b32_e64 v78, v76, v78, s[0:1]
	v_mul_f32_e32 v64, v64, v78
	v_mul_f32_e32 v65, v65, v78
	v_mul_f32_e32 v66, v66, v78
	v_mul_f32_e32 v67, v67, v78
	v_mul_f32_e32 v77, v144, v77
	v_mul_f32_e32 v149, v79, v149
	v_mul_f32_e32 v194, v76, v77
	v_cvt_pk_bf16_f32 v76, v64, v65
	v_cvt_pk_bf16_f32 v77, v66, v67
	v_cvt_pk_bf16_f32 v78, v68, v69
	v_cvt_pk_bf16_f32 v79, v70, v71
	v_cvt_pk_bf16_f32 v72, v72, v73
	v_cvt_pk_bf16_f32 v73, v74, v75
	v_cvt_pk_bf16_f32 v74, v150, v151
	v_cvt_pk_bf16_f32 v75, v152, v149
	v_cvt_pk_bf16_f32 v68, v186, v187
	v_cvt_pk_bf16_f32 v69, v178, v179
	v_cvt_pk_bf16_f32 v70, v188, v189
	v_cvt_pk_bf16_f32 v71, v180, v181
	v_cvt_pk_bf16_f32 v64, v190, v191
	v_cvt_pk_bf16_f32 v65, v182, v183
	v_cvt_pk_bf16_f32 v66, v192, v193
	v_cvt_pk_bf16_f32 v67, v184, v185
	s_nop 0
	v_permlane32_swap_b32_e32 v76, v78
	v_permlane32_swap_b32_e32 v77, v79
	v_permlane32_swap_b32_e32 v72, v74
	v_permlane32_swap_b32_e32 v73, v75
	v_permlane32_swap_b32_e32 v68, v70
	v_permlane32_swap_b32_e32 v69, v71
	v_permlane32_swap_b32_e32 v64, v66
	v_permlane32_swap_b32_e32 v65, v67
	s_mov_b64 s[6:7], exec
	v_cmp_eq_f32_e32 vcc, 0, v194
	s_and_saveexec_b64 s[4:5], s[2:3]
	s_cbranch_execz .LBB0_1230
	s_cmp_eq_u64 vcc, s[6:7]
	s_cselect_b64 s[6:7], -1, 0
	v_cndmask_b32_e64 v144, 0, 1, s[6:7]
	ds_write_b32 v166, v144
; #define SBAR() __builtin_amdgcn_sched_barrier(0)
; template <int OFF> __device__ __forceinline__ s16x4 tr_read(int vb) {
;     s16x4 r; asm volatile("ds_read_b64_tr_b16 %0, %1 offset:%2" : "=&v"(r) : "v"(vb), "i"(OFF) : "memory"); return r;
; }
; template <int D0> __device__ __forceinline__ void pv_one(f32x16& od, int vb, bf16x8 pa0, bf16x8 pa1, bf16x8 pa2, bf16x8 pa3) {
;     const s16x4 l0 = tr_read<v_rd_off(D0, 0, 0)>(vb), h0 = tr_read<v_rd_off(D0, 0, 1)>(vb), l1 = tr_read<v_rd_off(D0, 1, 0)>(vb), h1 = tr_read<v_rd_off(D0, 1, 1)>(vb);
;     const s16x4 l2 = tr_read<v_rd_off(D0, 2, 0)>(vb), h2 = tr_read<v_rd_off(D0, 2, 1)>(vb), l3 = tr_read<v_rd_off(D0, 3, 0)>(vb), h3 = tr_read<v_rd_off(D0, 3, 1)>(vb);
;     asm volatile("s_waitcnt lgkmcnt(0)" ::: "memory"); SBAR();
;     ...
;     od = __builtin_amdgcn_mfma_f32_32x32x16_bf16(pa0, PK(l0, h0), od, 0, 0, 0);
;     od = __builtin_amdgcn_mfma_f32_32x32x16_bf16(pa1, PK(l1, h1), od, 0, 0, 0);
;     od = __builtin_amdgcn_mfma_f32_32x32x16_bf16(pa2, PK(l2, h2), od, 0, 0, 0);
;     od = __builtin_amdgcn_mfma_f32_32x32x16_bf16(pa3, PK(l3, h3), od, 0, 0, 0);
;     ...
; }
; __device__ __forceinline__ void pv_d0(f32x16* o, int vb, bf16x8 pa0, bf16x8 pa1, bf16x8 pa2, bf16x8 pa3) {
;     pv_one<0>(o[0], vb, pa0, pa1, pa2, pa3); pv_one<1>(o[1], vb, pa0, pa1, pa2, pa3); pv_one<2>(o[2], vb, pa0, pa1, pa2, pa3); pv_one<3>(o[3], vb, pa0, pa1, pa2, pa3);
; }
.LBB0_1230:
	s_or_b64 exec, exec, s[4:5]
	v_lshl_add_u64 v[152:153], v[172:173], 0, v[160:161]
	v_add_co_u32_e32 v144, vcc, 0x17a00000, v152
	v_lshl_add_u64 v[156:157], v[170:171], 0, v[160:161]
	s_nop 0
	v_addc_co_u32_e32 v145, vcc, 0, v153, vcc
	v_add_co_u32_e32 v148, vcc, 0x17a00000, v156
	global_load_dwordx4 v[144:147], v[144:145], off
	s_nop 0
	v_addc_co_u32_e32 v149, vcc, 0, v157, vcc
	v_add_co_u32_e32 v152, vcc, 0x15a00000, v152
	global_load_dwordx4 v[148:151], v[148:149], off
	s_nop 0
	v_addc_co_u32_e32 v153, vcc, 0, v153, vcc
	v_add_co_u32_e32 v156, vcc, 0x15a00000, v156
	global_load_dwordx4 v[152:155], v[152:153], off
	s_nop 0
	v_addc_co_u32_e32 v157, vcc, 0, v157, vcc
	global_load_dwordx4 v[156:159], v[156:157], off
	ds_read_b64_tr_b16 v[178:179], v198 offset:0
	ds_read_b64_tr_b16 v[180:181], v198 offset:0x800
	ds_read_b64_tr_b16 v[182:183], v198 offset:0x1000
	ds_read_b64_tr_b16 v[184:185], v198 offset:0x1800
	ds_read_b64_tr_b16 v[186:187], v198 offset:0x2000
	ds_read_b64_tr_b16 v[188:189], v198 offset:0x2800
	ds_read_b64_tr_b16 v[190:191], v198 offset:0x3000
	ds_read_b64_tr_b16 v[192:193], v198 offset:0x3800
	s_waitcnt lgkmcnt(0)
	s_nop 0
	v_mfma_f32_32x32x16_bf16 v[48:63], v[76:79], v[178:181], v[48:63]
	ds_read_b64_tr_b16 v[178:179], v198 offset:0x200
	ds_read_b64_tr_b16 v[180:181], v198 offset:0xa00
	v_mfma_f32_32x32x16_bf16 v[48:63], v[72:75], v[182:185], v[48:63]
	ds_read_b64_tr_b16 v[182:183], v198 offset:0x1200
	ds_read_b64_tr_b16 v[184:185], v198 offset:0x1a00
	v_mfma_f32_32x32x16_bf16 v[48:63], v[68:71], v[186:189], v[48:63]
	ds_read_b64_tr_b16 v[186:187], v198 offset:0x2200
	ds_read_b64_tr_b16 v[188:189], v198 offset:0x2a00
	ds_read_b64_tr_b16 v[216:217], v198 offset:0x3200
	ds_read_b64_tr_b16 v[218:219], v198 offset:0x3a00
	s_waitcnt lgkmcnt(0)
	v_mfma_f32_32x32x16_bf16 v[48:63], v[64:67], v[190:193], v[48:63]
	v_mfma_f32_32x32x16_bf16 v[32:47], v[76:79], v[178:181], v[32:47]
	ds_read_b64_tr_b16 v[178:179], v198 offset:0x400
	ds_read_b64_tr_b16 v[180:181], v198 offset:0xc00
	v_mfma_f32_32x32x16_bf16 v[32:47], v[72:75], v[182:185], v[32:47]
	ds_read_b64_tr_b16 v[182:183], v198 offset:0x1400
	ds_read_b64_tr_b16 v[184:185], v198 offset:0x1c00
	v_mfma_f32_32x32x16_bf16 v[32:47], v[68:71], v[186:189], v[32:47]
	ds_read_b64_tr_b16 v[186:187], v198 offset:0x2400
	ds_read_b64_tr_b16 v[188:189], v198 offset:0x2c00
	ds_read_b64_tr_b16 v[190:191], v198 offset:0x3400
	ds_read_b64_tr_b16 v[192:193], v198 offset:0x3c00
	s_waitcnt lgkmcnt(0)
	v_mfma_f32_32x32x16_bf16 v[32:47], v[64:67], v[216:219], v[32:47]
	v_mfma_f32_32x32x16_bf16 v[16:31], v[76:79], v[178:181], v[16:31]
	ds_read_b64_tr_b16 v[178:179], v198 offset:0x600
	ds_read_b64_tr_b16 v[180:181], v198 offset:0xe00
	ds_read_b64_tr_b16 v[218:219], v198 offset:0x1600
	ds_read_b64_tr_b16 v[220:221], v198 offset:0x1e00
	ds_read_b64_tr_b16 v[222:223], v198 offset:0x2600
	ds_read_b64_tr_b16 v[224:225], v198 offset:0x2e00
	ds_read_b64_tr_b16 v[226:227], v198 offset:0x3600
	v_mfma_f32_32x32x16_bf16 v[16:31], v[72:75], v[182:185], v[16:31]
	ds_read_b64_tr_b16 v[228:229], v198 offset:0x3e00
	s_waitcnt lgkmcnt(0)
	v_mfma_f32_32x32x16_bf16 v[16:31], v[68:71], v[186:189], v[16:31]
	v_mfma_f32_32x32x16_bf16 v[16:31], v[64:67], v[190:193], v[16:31]
	v_mfma_f32_32x32x16_bf16 v[0:15], v[76:79], v[178:181], v[0:15]
	s_cmp_lt_u32 s72, 4
	s_cselect_b64 vcc, -1, 0
	v_exp_f32_e32 v98, v98
	s_cmp_lg_u32 s41, -1
	s_cselect_b32 s20, s41, 0
	v_exp_f32_e32 v195, v97
	s_cselect_b32 s21, s47, 0
	v_mfma_f32_32x32x16_bf16 v[0:15], v[72:75], v[218:221], v[0:15]
	v_exp_f32_e32 v218, v99
	v_exp_f32_e32 v221, v101
	v_exp_f32_e32 v101, v102
	v_exp_f32_e32 v99, v100
	v_add_f32_e32 v73, 1.0, v98
	v_rcp_f32_e32 v188, v73
	v_add_u32_e32 v73, 0xa2, v214
	v_mfma_f32_32x32x16_bf16 v[0:15], v[68:71], v[222:225], v[0:15]
	v_add_f32_e32 v69, 1.0, v218
	v_exp_f32_e32 v223, v103
	v_rcp_f32_e32 v219, v69
	v_add_u32_e32 v69, 0xa3, v214
	v_cmp_lt_i32_e64 s[14:15], v69, v164
	v_exp_f32_e32 v103, v104
	v_cmp_lt_i32_e64 s[6:7], v73, v164
	v_mfma_f32_32x32x16_bf16 v[0:15], v[64:67], v[226:229], v[0:15]
	v_add_f32_e32 v66, 1.0, v101
	v_add_f32_e32 v67, 1.0, v223
	v_cndmask_b32_e64 v64, 1.0, v219, s[14:15]
	v_add_f32_e32 v65, 1.0, v221
	v_rcp_f32_e32 v102, v66
	v_rcp_f32_e32 v224, v67
	v_cndmask_b32_e32 v190, v219, v64, vcc
	v_add_f32_e32 v64, 1.0, v99
	v_rcp_f32_e32 v222, v65
	v_rcp_f32_e32 v100, v64
	v_add_u32_e32 v66, 0xaa, v214
	v_add_u32_e32 v67, 0xab, v214
	v_add_u32_e32 v65, 0xa9, v214
	v_cmp_lt_i32_e64 s[12:13], v66, v164
	v_cmp_lt_i32_e64 s[18:19], v67, v164
	v_add_u32_e32 v64, 0xa8, v214
	v_cmp_lt_i32_e64 s[16:17], v65, v164
	v_cndmask_b32_e64 v66, 1.0, v102, s[12:13]
	v_cndmask_b32_e64 v67, 1.0, v224, s[18:19]
	v_cmp_lt_i32_e64 s[8:9], v64, v164
	v_cndmask_b32_e64 v65, 1.0, v222, s[16:17]
	v_cndmask_b32_e32 v66, v102, v66, vcc
	v_cndmask_b32_e32 v217, v224, v67, vcc
	v_cndmask_b32_e64 v64, 1.0, v100, s[8:9]
	v_cndmask_b32_e32 v65, v222, v65, vcc
	v_mul_f32_e32 v225, v217, v66
	v_cndmask_b32_e32 v64, v100, v64, vcc
	v_mul_f32_e32 v104, v65, v225
	v_mul_f32_e32 v97, v64, v104
	v_mov_b32_e32 v64, s20
	s_add_i32 s20, 0, 0x10004
	s_cmp_lg_u32 s20, -1
	v_mov_b32_e32 v65, s21
	s_cselect_b32 s20, s20, 0
	s_waitcnt lgkmcnt(0)
	s_barrier
; __device__ __forceinline__ int crow(int r, int hi) { return (r & 3) + 8 * (r >> 2) + 4 * hi; }
; __device__ __forceinline__ void sb_half(f32x16& p, float& carry, bool masked, int krow0, int tq, int hi) {
;     float G[4];
; #pragma unroll
;     for (int g = 0; g < 4; ++g) {
;         float q[4];
; #pragma unroll
;         for (int i = 0; i < 4; ++i) { const int r = 4 * g + i; const float e = __builtin_amdgcn_exp2f(p[r]); float qq = __builtin_amdgcn_rcpf(1.0f + e); float b = e * qq;
;             if (masked) { const bool keep = (krow0 + crow(r, hi)) < tq; qq = keep ? qq : 1.0f; b = keep ? b : 0.0f; }
;             q[i] = qq; p[r] = b; }
;         const float s2 = q[3] * q[2], s1 = s2 * q[1]; G[g] = s1 * q[0];
;         p[4 * g + 2] *= q[3]; p[4 * g + 1] *= s2; p[4 * g] *= s1;
;     }
; __device__ __forceinline__ void sb_unit(const bf16* __restrict__ Qb, const bf16* __restrict__ Kh, const bf16* __restrict__ Vh, bf16* __restrict__ Ob, int q0, char* lds, const int wv0) {
;     ...
;         __syncthreads();
;         { unsigned a = 1u;
; #pragma unroll
;           for (int w = 0; w < 8; ++w) a &= votes[w];
;           if (a) { done = true; break; } }
	ds_read_b32 v67, v64
	s_cselect_b32 s21, s47, 0
	v_mov_b32_e32 v64, s20
	s_add_i32 s20, 0, 0x10008
	v_cndmask_b32_e64 v68, 1.0, v188, s[6:7]
	s_cmp_lg_u32 s20, -1
	v_cndmask_b32_e32 v68, v188, v68, vcc
	v_mov_b32_e32 v65, s21
	s_cselect_b32 s20, s20, 0
	v_mul_f32_e32 v220, v190, v68
	ds_read_b32 v68, v64
	s_cselect_b32 s21, s47, 0
	v_mov_b32_e32 v64, s20
	s_add_i32 s20, 0, 0x1000c
	s_cmp_lg_u32 s20, -1
	v_mov_b32_e32 v65, s21
	s_cselect_b32 s20, s20, 0
	ds_read_b32 v69, v64
	s_cselect_b32 s21, s47, 0
	v_mov_b32_e32 v64, s20
	s_add_i32 s20, 0, 0x10010
	s_cmp_lg_u32 s20, -1
	v_add_f32_e32 v77, 1.0, v195
	v_mov_b32_e32 v65, s21
	s_cselect_b32 s20, s20, 0
	v_rcp_f32_e32 v216, v77
	ds_read_b32 v70, v64
	s_cselect_b32 s21, s47, 0
	v_mov_b32_e32 v64, s20
	s_add_i32 s20, 0, 0x10014
	s_cmp_lg_u32 s20, -1
	v_add_u32_e32 v77, 0xa1, v214
	v_mov_b32_e32 v65, s21
	s_cselect_b32 s20, s20, 0
	v_cmp_lt_i32_e64 s[10:11], v77, v164
	ds_read_b32 v71, v64
	s_cselect_b32 s21, s47, 0
	v_mov_b32_e32 v64, s20
	s_add_i32 s20, 0, 0x10018
	v_cndmask_b32_e64 v72, 1.0, v216, s[10:11]
	s_cmp_lg_u32 s20, -1
	v_cndmask_b32_e32 v72, v216, v72, vcc
	v_mov_b32_e32 v65, s21
	s_cselect_b32 s20, s20, 0
	v_mul_f32_e32 v192, v72, v220
	ds_read_b32 v72, v64
	s_cselect_b32 s21, s47, 0
	v_mov_b32_e32 v64, s20
	s_add_i32 s20, 0, 0x1001c
	s_cmp_lg_u32 s20, -1
	v_mov_b32_e32 v65, s21
	s_cselect_b32 s20, s20, 0
	s_cselect_b32 s21, s47, 0
	ds_read_b32 v73, v64
	v_mov_b32_e32 v64, s20
	v_mov_b32_e32 v65, s21
	ds_read_b32 v64, v64
	v_exp_f32_e32 v229, v105
	v_exp_f32_e32 v105, v106
	v_exp_f32_e32 v232, v107
	v_add_f32_e32 v66, 1.0, v103
	v_rcp_f32_e32 v226, v66
	v_add_f32_e32 v74, 1.0, v105
	v_add_f32_e32 v75, 1.0, v232
	v_add_f32_e32 v66, 1.0, v229
	v_rcp_f32_e32 v227, v74
	v_rcp_f32_e32 v235, v75
	v_rcp_f32_e32 v230, v66
	v_add_u32_e32 v74, 0xb2, v214
	v_add_u32_e32 v75, 0xb3, v214
	v_exp_f32_e32 v233, v109
	v_exp_f32_e32 v109, v110
	v_exp_f32_e32 v237, v111
	v_add_u32_e32 v66, 0xb1, v214
	v_cmp_lt_i32_e64 s[22:23], v74, v164
	v_cmp_lt_i32_e64 s[30:31], v75, v164
	v_add_u32_e32 v65, 0xb0, v214
	v_cmp_lt_i32_e64 s[28:29], v66, v164
	v_cndmask_b32_e64 v74, 1.0, v227, s[22:23]
	v_cndmask_b32_e64 v75, 1.0, v235, s[30:31]
	v_exp_f32_e32 v106, v108
	v_cmp_lt_i32_e64 s[20:21], v65, v164
	v_cndmask_b32_e64 v66, 1.0, v230, s[28:29]
	v_cndmask_b32_e32 v74, v227, v74, vcc
	v_cndmask_b32_e32 v228, v235, v75, vcc
	v_exp_f32_e32 v184, v96
	v_cndmask_b32_e64 v65, 1.0, v226, s[20:21]
	v_cndmask_b32_e32 v66, v230, v66, vcc
	v_mul_f32_e32 v234, v228, v74
	v_add_f32_e32 v74, 1.0, v109
	v_add_f32_e32 v75, 1.0, v237
	v_cndmask_b32_e32 v65, v226, v65, vcc
	v_mul_f32_e32 v108, v66, v234
	v_add_f32_e32 v66, 1.0, v233
	v_rcp_f32_e32 v110, v74
	v_rcp_f32_e32 v239, v75
	v_mul_f32_e32 v180, v65, v108
	v_add_f32_e32 v65, 1.0, v106
	v_rcp_f32_e32 v236, v66
	v_rcp_f32_e32 v107, v65
	v_add_u32_e32 v74, 0xba, v214
	v_add_u32_e32 v75, 0xbb, v214
	v_add_f32_e32 v182, 1.0, v184
	v_add_u32_e32 v66, 0xb9, v214
	v_cmp_lt_i32_e64 s[26:27], v74, v164
	v_cmp_lt_i32_e64 s[36:37], v75, v164
	v_rcp_f32_e32 v186, v182
	v_add_u32_e32 v65, 0xb8, v214
	v_cmp_lt_i32_e64 s[34:35], v66, v164
	v_cndmask_b32_e64 v74, 1.0, v110, s[26:27]
	v_cndmask_b32_e64 v75, 1.0, v239, s[36:37]
	v_cmp_lt_i32_e64 s[24:25], v65, v164
	v_cndmask_b32_e64 v66, 1.0, v236, s[34:35]
	v_cndmask_b32_e32 v74, v110, v74, vcc
	v_cndmask_b32_e32 v231, v239, v75, vcc
	v_add_u32_e32 v96, 0xa0, v214
	v_cndmask_b32_e64 v65, 1.0, v107, s[24:25]
	v_cndmask_b32_e32 v66, v236, v66, vcc
	v_mul_f32_e32 v238, v231, v74
	v_cmp_lt_i32_e64 s[4:5], v96, v164
	v_cndmask_b32_e32 v65, v107, v65, vcc
	v_mul_f32_e32 v111, v66, v238
	v_cndmask_b32_e64 v76, 1.0, v186, s[4:5]
	v_mul_f32_e32 v96, v65, v111
	s_waitcnt lgkmcnt(0)
	v_bitop3_b32 v65, v67, v69, v68 bitop3:0x80
	v_cndmask_b32_e32 v76, v186, v76, vcc
	v_bitop3_b32 v65, v65, v71, v70 bitop3:0x80
	v_mul_f32_e32 v178, v76, v192
	v_mov_b32_e32 v241, v96
	v_mov_b32_e32 v243, v96
	v_mov_b32_e32 v242, v180
	v_mov_b32_e32 v244, v180
	v_mov_b32_e32 v245, v97
	v_bitop3_b32 v65, v65, v73, v72 bitop3:0x80
	v_mov_b32_e32 v246, v97
	v_mov_b32_e32 v182, v178
	v_mov_b32_e32 v240, v178
	v_bitop3_b32 v64, v65, 1, v64 bitop3:0x80
	v_permlane32_swap_b32_e32 v241, v243
	v_permlane32_swap_b32_e32 v242, v244
	v_permlane32_swap_b32_e32 v245, v246
	v_permlane32_swap_b32_e32 v182, v240
	v_cmp_eq_u32_e64 s[38:39], 0, v64
	s_mov_b64 s[70:71], -1
	v_readfirstlane_b32 s95, v0
	s_or_b64 s[66:67], s[66:67], exec
	s_and_saveexec_b64 s[68:69], s[38:39]
	s_cbranch_execz .LBB0_1227
; #define SBAR() __builtin_amdgcn_sched_barrier(0)
; #define SWRITE(b, i) do { *(bf16x8*)(V_lds + (b) * SHM_V + vst0) = sr_[i].vs0; *(bf16x8*)(V_lds + (b) * SHM_V + vst1) = sr_[i].vs1; const int kc = sc * 2; \
;     *(bf16x8*)(K_lds + (b) * SHM_K + KSWZ(sr, kc)) = sr_[i].ks0; *(bf16x8*)(K_lds + (b) * SHM_K + KSWZ(32 + sr, kc)) = sr_[i].ks1; } while (0)
; #define SWAIT() asm volatile("s_waitcnt vmcnt(0)" ::: "memory")
; __device__ __forceinline__ void qkt(f32x16& p0, f32x16& p1, const char* Ks, const bf16x8* qr, int r32, int hi) {
;     p0 = f32x16{}; p1 = f32x16{};
; #pragma unroll
;     for (int d0 = 0; d0 < 8; ++d0) { const int cb = (d0 * 16 + hi * 8) * 2;
;         const bf16x8 b0 = *reinterpret_cast<const bf16x8*>(Ks + KSWZ(r32, cb));
;         const bf16x8 b1 = *reinterpret_cast<const bf16x8*>(Ks + KSWZ(32 + r32, cb));
;         p0 = __builtin_amdgcn_mfma_f32_32x32x16_bf16(b0, qr[d0], p0, 0, 0, 0);
;         p1 = __builtin_amdgcn_mfma_f32_32x32x16_bf16(b1, qr[d0], p1, 0, 0, 0); }
; }
; __device__ __forceinline__ void sb_unit(const bf16* __restrict__ Qb, const bf16* __restrict__ Kh, const bf16* __restrict__ Vh, bf16* __restrict__ Ob, int q0, char* lds, const int wv0) {
;     ...
;         SWAIT(); SWRITE(0, SE);
;         __syncthreads();
;         SBAR(); qkt(pA0, pA1, K_lds, qr, r32, hi);
;         sb_half(pB0, carry, j < 4, K0(j), tq, hi); pack_p(pB0, pB1, pa0, pa1, pa2, pa3); SBAR();
	v_cndmask_b32_e64 v68, v241, v243, s[0:1]
	v_mul_f32_e32 v64, v96, v68
	v_cndmask_b32_e64 v69, v242, v244, s[0:1]
	v_mul_f32_e32 v96, v194, v64
	v_mul_f32_e32 v64, v180, v69
	v_cndmask_b32_e64 v65, v245, v246, s[0:1]
	v_pk_mul_f32 v[66:67], v[96:97], v[64:65]
	v_mul_f32_e32 v64, v218, v219
	v_pk_mul_f32 v[180:181], v[66:67], v[66:67] op_sel:[0,1] op_sel_hi:[1,0]
	v_cndmask_b32_e64 v182, v182, v240, s[0:1]
	v_cndmask_b32_e64 v67, 0, v64, s[14:15]
	v_cndmask_b32_e32 v64, v64, v67, vcc
	v_mul_f32_e32 v67, v180, v182
	v_cndmask_b32_e64 v67, v180, v67, s[0:1]
	v_mul_f32_e32 v196, v64, v67
	v_mul_f32_e32 v64, v195, v216
	v_cndmask_b32_e64 v70, 0, v64, s[10:11]
	v_cndmask_b32_e32 v64, v64, v70, vcc
	v_mul_f32_e32 v64, v220, v64
	v_mul_f32_e32 v197, v64, v67
	v_mul_f32_e32 v64, v223, v224
	v_cndmask_b32_e64 v70, 0, v64, s[18:19]
	v_mul_f32_e32 v65, v66, v65
	v_cndmask_b32_e32 v64, v64, v70, vcc
	v_cndmask_b32_e64 v65, v66, v65, s[0:1]
	v_mul_f32_e32 v215, v64, v65
	v_mul_f32_e32 v64, v221, v222
	v_cndmask_b32_e64 v66, 0, v64, s[16:17]
	v_cndmask_b32_e32 v64, v64, v66, vcc
	v_mul_f32_e32 v64, v225, v64
	v_mul_f32_e32 v240, v64, v65
	v_mul_f32_e32 v64, v232, v235
	v_cndmask_b32_e64 v66, 0, v64, s[30:31]
	v_cndmask_b32_e32 v64, v64, v66, vcc
	v_mul_f32_e32 v66, v96, v69
	v_cndmask_b32_e64 v66, v96, v66, s[0:1]
	v_mul_f32_e32 v241, v64, v66
	v_mul_f32_e32 v64, v229, v230
	v_cndmask_b32_e64 v69, 0, v64, s[28:29]
	v_cndmask_b32_e32 v64, v64, v69, vcc
	v_mul_f32_e32 v64, v234, v64
	v_mul_f32_e32 v242, v64, v66
	v_mul_f32_e32 v64, v237, v239
	v_cndmask_b32_e64 v69, 0, v64, s[36:37]
	v_mul_f32_e32 v68, v194, v68
	v_cndmask_b32_e32 v64, v64, v69, vcc
	v_cndmask_b32_e64 v68, v194, v68, s[0:1]
	v_mul_f32_e32 v243, v64, v68
	v_mul_f32_e32 v64, v233, v236
	v_cndmask_b32_e64 v69, 0, v64, s[34:35]
	v_cndmask_b32_e32 v64, v64, v69, vcc
	v_mul_f32_e32 v64, v238, v64
	v_mul_f32_e32 v244, v64, v68
	v_mul_f32_e32 v64, v98, v188
	v_cndmask_b32_e64 v69, 0, v64, s[6:7]
	v_cndmask_b32_e32 v64, v64, v69, vcc
	v_mul_f32_e32 v64, v190, v64
	v_mul_f32_e32 v245, v64, v67
	v_mul_f32_e32 v64, v184, v186
	v_cndmask_b32_e64 v69, 0, v64, s[4:5]
	v_cndmask_b32_e32 v64, v64, v69, vcc
	v_mul_f32_e32 v64, v64, v192
	v_mul_f32_e32 v246, v64, v67
	v_mul_f32_e32 v64, v101, v102
	v_cndmask_b32_e64 v67, 0, v64, s[12:13]
	v_cndmask_b32_e32 v64, v64, v67, vcc
	v_mul_f32_e32 v64, v217, v64
	v_mul_f32_e32 v247, v64, v65
	v_mul_f32_e32 v64, v99, v100
	v_cndmask_b32_e64 v67, 0, v64, s[8:9]
	v_cndmask_b32_e32 v64, v64, v67, vcc
	v_mul_f32_e32 v64, v64, v104
	v_mul_f32_e32 v248, v64, v65
	v_mul_f32_e32 v64, v105, v227
	v_cndmask_b32_e64 v65, 0, v64, s[22:23]
	v_cndmask_b32_e32 v64, v64, v65, vcc
	v_mul_f32_e32 v64, v228, v64
	v_mul_f32_e32 v249, v64, v66
	v_mul_f32_e32 v64, v103, v226
	v_cndmask_b32_e64 v65, 0, v64, s[20:21]
	v_cndmask_b32_e32 v64, v64, v65, vcc
	v_mul_f32_e32 v64, v64, v108
	v_mul_f32_e32 v250, v64, v66
	v_mul_f32_e32 v64, v109, v110
	v_cndmask_b32_e64 v65, 0, v64, s[26:27]
	v_cndmask_b32_e32 v64, v64, v65, vcc
	v_mul_f32_e32 v64, v231, v64
	v_mul_f32_e32 v251, v64, v68
	v_mul_f32_e32 v64, v106, v107
	v_cndmask_b32_e64 v65, 0, v64, s[24:25]
	s_waitcnt vmcnt(0)
	v_cndmask_b32_e32 v64, v64, v65, vcc
	v_mul_f32_e32 v64, v64, v111
	v_add_u32_e32 v179, 0x80, v214
	v_mul_f32_e32 v254, v64, v68
	ds_write_b128 v206, v[144:147]
	ds_write_b128 v207, v[148:151]
	ds_write_b128 v199, v[152:155] offset:32768
	ds_write_b128 v200, v[156:159] offset:32768
	s_waitcnt lgkmcnt(0)
	s_barrier
	ds_read_b128 v[64:67], v201 offset:32768
	ds_read_b128 v[96:99], v201 offset:40960
	v_exp_f32_e32 v80, v80
	v_exp_f32_e32 v81, v81
	ds_read_b128 v[144:147], v202 offset:32768
	ds_read_b128 v[148:151], v202 offset:40960
	ds_read_b128 v[152:155], v208 offset:32768
	ds_read_b128 v[156:159], v208 offset:40960
	ds_read_b128 v[184:187], v209 offset:32768
	ds_read_b128 v[188:191], v209 offset:40960
	ds_read_b128 v[192:195], v210 offset:32768
	ds_read_b128 v[216:219], v210 offset:40960
	s_waitcnt lgkmcnt(9)
	v_mfma_f32_32x32x16_bf16 v[64:79], v[64:67], v[140:143], 0
	v_add_f32_e32 v181, 1.0, v80
	v_exp_f32_e32 v82, v82
	v_rcp_f32_e32 v181, v181
	v_add_f32_e32 v183, 1.0, v81
	v_exp_f32_e32 v83, v83
	v_cmp_lt_i32_e64 s[4:5], v179, v164
	v_mul_f32_e32 v80, v80, v181
	s_waitcnt lgkmcnt(8)
	v_mfma_f32_32x32x16_bf16 v[96:111], v[96:99], v[140:143], 0
	v_cndmask_b32_e64 v179, 1.0, v181, s[4:5]
	v_exp_f32_e32 v84, v84
	ds_read_b128 v[220:223], v211 offset:32768
	ds_read_b128 v[224:227], v211 offset:40960
	ds_read_b128 v[228:231], v203 offset:32768
	ds_read_b128 v[232:235], v203 offset:40960
	s_waitcnt lgkmcnt(11)
	v_mfma_f32_32x32x16_bf16 v[64:79], v[144:147], v[136:139], v[64:79]
	ds_read_b128 v[144:147], v212 offset:32768
	ds_read_b128 v[236:239], v212 offset:40960
	s_waitcnt lgkmcnt(12)
	v_mfma_f32_32x32x16_bf16 v[96:111], v[148:151], v[136:139], v[96:111]
	v_rcp_f32_e32 v148, v183
	v_add_f32_e32 v151, 1.0, v82
	v_add_u32_e32 v150, 0x81, v214
	v_rcp_f32_e32 v151, v151
	v_cndmask_b32_e64 v149, 0, v80, s[4:5]
	v_mul_f32_e32 v81, v81, v148
	v_cmp_lt_i32_e64 s[4:5], v150, v164
	s_waitcnt lgkmcnt(11)
	v_mfma_f32_32x32x16_bf16 v[64:79], v[152:155], v[132:135], v[64:79]
	v_add_f32_e32 v153, 1.0, v83
	v_cndmask_b32_e64 v150, 1.0, v148, s[4:5]
	v_cndmask_b32_e64 v152, 0, v81, s[4:5]
	v_cndmask_b32_e32 v152, v81, v152, vcc
	v_cndmask_b32_e32 v81, v148, v150, vcc
	v_add_u32_e32 v148, 0x82, v214
	v_rcp_f32_e32 v153, v153
	v_mul_f32_e32 v82, v82, v151
	v_cmp_lt_i32_e64 s[4:5], v148, v164
	v_cndmask_b32_e32 v80, v80, v149, vcc
	v_mul_f32_e32 v83, v83, v153
	v_cndmask_b32_e64 v150, 0, v82, s[4:5]
	v_cndmask_b32_e32 v82, v82, v150, vcc
	v_add_u32_e32 v150, 0x83, v214
	v_cndmask_b32_e64 v148, 1.0, v151, s[4:5]
	v_cmp_lt_i32_e64 s[4:5], v150, v164
	v_cndmask_b32_e32 v148, v151, v148, vcc
	v_cndmask_b32_e32 v149, v181, v179, vcc
	v_cndmask_b32_e64 v150, 1.0, v153, s[4:5]
	v_cndmask_b32_e64 v151, 0, v83, s[4:5]
	v_cndmask_b32_e32 v151, v83, v151, vcc
	v_cndmask_b32_e32 v83, v153, v150, vcc
	v_mul_f32_e32 v148, v83, v148
	v_mul_f32_e32 v150, v81, v148
	s_waitcnt lgkmcnt(9)
; __device__ __forceinline__ int crow(int r, int hi) { return (r & 3) + 8 * (r >> 2) + 4 * hi; }
; __device__ __forceinline__ void qkt(f32x16& p0, f32x16& p1, const char* Ks, const bf16x8* qr, int r32, int hi) {
;     p0 = f32x16{}; p1 = f32x16{};
; #pragma unroll
;     for (int d0 = 0; d0 < 8; ++d0) { const int cb = (d0 * 16 + hi * 8) * 2;
;         const bf16x8 b0 = *reinterpret_cast<const bf16x8*>(Ks + KSWZ(r32, cb));
;         const bf16x8 b1 = *reinterpret_cast<const bf16x8*>(Ks + KSWZ(32 + r32, cb));
;         p0 = __builtin_amdgcn_mfma_f32_32x32x16_bf16(b0, qr[d0], p0, 0, 0, 0);
;         p1 = __builtin_amdgcn_mfma_f32_32x32x16_bf16(b1, qr[d0], p1, 0, 0, 0); }
; }
; __device__ __forceinline__ void sb_half(f32x16& p, float& carry, bool masked, int krow0, int tq, int hi) {
;     float G[4];
; #pragma unroll
;     for (int g = 0; g < 4; ++g) {
;         float q[4];
; #pragma unroll
;         for (int i = 0; i < 4; ++i) { const int r = 4 * g + i; const float e = __builtin_amdgcn_exp2f(p[r]); float qq = __builtin_amdgcn_rcpf(1.0f + e); float b = e * qq;
;             if (masked) { const bool keep = (krow0 + crow(r, hi)) < tq; qq = keep ? qq : 1.0f; b = keep ? b : 0.0f; }
;             q[i] = qq; p[r] = b; }
;         const float s2 = q[3] * q[2], s1 = s2 * q[1]; G[g] = s1 * q[0];
;         p[4 * g + 2] *= q[3]; p[4 * g + 1] *= s2; p[4 * g] *= s1;
;     }
;     float run = carry;
; #pragma unroll
;     for (int g = 3; g >= 0; --g) { const unsigned gu = __builtin_bit_cast(unsigned, G[g]); auto sw = __builtin_amdgcn_permlane32_swap(gu, gu, false, false);
;         const float partner = __builtin_bit_cast(float, hi ? sw[0] : sw[1]);
;         const float base = hi ? run : run * partner;
;         p[4 * g] *= base; p[4 * g + 1] *= base; p[4 * g + 2] *= base; p[4 * g + 3] *= base; run *= G[g] * partner; }
;     carry = run;
; }
	v_mfma_f32_32x32x16_bf16 v[64:79], v[184:187], v[128:131], v[64:79]
	v_mul_f32_e32 v81, v149, v150
	v_mul_f32_e32 v149, v83, v82
	v_add_f32_e32 v82, 1.0, v84
	v_rcp_f32_e32 v82, v82
	v_mul_f32_e32 v150, v80, v150
	v_add_u32_e32 v80, 0x88, v214
	v_cmp_lt_i32_e64 s[4:5], v80, v164
	v_mul_f32_e32 v83, v84, v82
	v_exp_f32_e32 v84, v85
	s_waitcnt lgkmcnt(7)
	v_mfma_f32_32x32x16_bf16 v[64:79], v[192:195], v[124:127], v[64:79]
	v_mul_f32_e32 v148, v148, v152
	v_cndmask_b32_e64 v152, 0, v83, s[4:5]
	v_add_f32_e32 v85, 1.0, v84
	v_rcp_f32_e32 v85, v85
	v_cndmask_b32_e64 v80, 1.0, v82, s[4:5]
	v_cndmask_b32_e32 v152, v83, v152, vcc
	v_add_u32_e32 v83, 0x89, v214
	v_cndmask_b32_e32 v80, v82, v80, vcc
	v_mul_f32_e32 v82, v84, v85
	v_exp_f32_e32 v84, v86
	v_cmp_lt_i32_e64 s[4:5], v83, v164
	s_waitcnt lgkmcnt(5)
	v_mfma_f32_32x32x16_bf16 v[64:79], v[220:223], v[120:123], v[64:79]
	v_add_f32_e32 v153, 1.0, v84
	v_cndmask_b32_e64 v86, 0, v82, s[4:5]
	v_cndmask_b32_e32 v82, v82, v86, vcc
	v_exp_f32_e32 v86, v87
	v_rcp_f32_e32 v153, v153
	v_cndmask_b32_e64 v83, 1.0, v85, s[4:5]
	v_cndmask_b32_e32 v83, v85, v83, vcc
	v_add_f32_e32 v87, 1.0, v86
	v_add_u32_e32 v85, 0x8a, v214
	v_rcp_f32_e32 v87, v87
	v_cmp_lt_i32_e64 s[4:5], v85, v164
	v_mul_f32_e32 v84, v84, v153
	s_waitcnt lgkmcnt(3)
	v_mfma_f32_32x32x16_bf16 v[64:79], v[228:231], v[116:119], v[64:79]
	v_cndmask_b32_e64 v85, 1.0, v153, s[4:5]
	v_cndmask_b32_e32 v85, v153, v85, vcc
	v_add_u32_e32 v153, 0x8b, v214
	v_cndmask_b32_e64 v154, 0, v84, s[4:5]
	v_mul_f32_e32 v86, v86, v87
	v_cmp_lt_i32_e64 s[4:5], v153, v164
	v_cndmask_b32_e32 v84, v84, v154, vcc
	s_waitcnt lgkmcnt(1)
	v_mfma_f32_32x32x16_bf16 v[64:79], v[144:147], v[112:115], v[64:79]
	v_cndmask_b32_e64 v153, 1.0, v87, s[4:5]
	v_cndmask_b32_e64 v154, 0, v86, s[4:5]
	v_cndmask_b32_e32 v154, v86, v154, vcc
	v_cndmask_b32_e32 v86, v87, v153, vcc
	v_mul_f32_e32 v85, v86, v85
	v_mul_f32_e32 v87, v83, v85
	v_mul_f32_e32 v83, v80, v87
	v_exp_f32_e32 v80, v88
	v_mul_f32_e32 v145, v85, v82
	v_exp_f32_e32 v85, v89
	v_mul_f32_e32 v144, v86, v84
	v_add_f32_e32 v82, 1.0, v80
	v_rcp_f32_e32 v82, v82
	v_add_f32_e32 v86, 1.0, v85
	v_rcp_f32_e32 v86, v86
	v_add_u32_e32 v84, 0x90, v214
	v_mul_f32_e32 v80, v80, v82
	v_cmp_lt_i32_e64 s[4:5], v84, v164
	v_mul_f32_e32 v146, v152, v87
	v_mfma_f32_32x32x16_bf16 v[96:111], v[156:159], v[132:135], v[96:111]
	v_cndmask_b32_e64 v84, 1.0, v82, s[4:5]
	v_cndmask_b32_e64 v87, 0, v80, s[4:5]
	v_cndmask_b32_e32 v80, v80, v87, vcc
	v_cndmask_b32_e32 v82, v82, v84, vcc
	v_mul_f32_e32 v84, v85, v86
	v_exp_f32_e32 v85, v90
	v_add_u32_e32 v87, 0x91, v214
	v_cmp_lt_i32_e64 s[4:5], v87, v164
	v_mfma_f32_32x32x16_bf16 v[96:111], v[188:191], v[128:131], v[96:111]
	v_add_f32_e32 v88, 1.0, v85
	v_cndmask_b32_e64 v87, 1.0, v86, s[4:5]
	v_cndmask_b32_e32 v86, v86, v87, vcc
	v_exp_f32_e32 v87, v91
	v_rcp_f32_e32 v88, v88
	v_cndmask_b32_e64 v89, 0, v84, s[4:5]
	v_cndmask_b32_e32 v84, v84, v89, vcc
	v_add_f32_e32 v90, 1.0, v87
	v_add_u32_e32 v89, 0x92, v214
	v_rcp_f32_e32 v90, v90
	v_mul_f32_e32 v85, v85, v88
	v_cmp_lt_i32_e64 s[4:5], v89, v164
	v_mfma_f32_32x32x16_bf16 v[96:111], v[216:219], v[124:127], v[96:111]
	v_mul_f32_e32 v87, v87, v90
	v_cndmask_b32_e64 v89, 1.0, v88, s[4:5]
	v_cndmask_b32_e64 v91, 0, v85, s[4:5]
	v_cndmask_b32_e32 v91, v85, v91, vcc
	v_cndmask_b32_e32 v85, v88, v89, vcc
	v_add_u32_e32 v88, 0x93, v214
	v_cmp_lt_i32_e64 s[4:5], v88, v164
	v_mfma_f32_32x32x16_bf16 v[96:111], v[224:227], v[120:123], v[96:111]
	s_nop 0
	v_cndmask_b32_e64 v89, 0, v87, s[4:5]
	v_cndmask_b32_e32 v147, v87, v89, vcc
	v_exp_f32_e32 v89, v92
	v_cndmask_b32_e64 v88, 1.0, v90, s[4:5]
	v_cndmask_b32_e32 v87, v90, v88, vcc
	v_mul_f32_e32 v88, v87, v85
	v_mul_f32_e32 v86, v86, v88
	v_mul_f32_e32 v90, v88, v84
	v_add_f32_e32 v84, 1.0, v89
	v_mul_f32_e32 v85, v82, v86
	v_mul_f32_e32 v82, v87, v91
	v_rcp_f32_e32 v84, v84
	v_exp_f32_e32 v87, v93
	v_mul_f32_e32 v80, v80, v86
	v_add_u32_e32 v86, 0x98, v214
	v_mul_f32_e32 v88, v89, v84
	v_add_f32_e32 v89, 1.0, v87
	v_rcp_f32_e32 v89, v89
	v_cmp_lt_i32_e64 s[4:5], v86, v164
	v_mfma_f32_32x32x16_bf16 v[96:111], v[232:235], v[116:119], v[96:111]
	s_nop 0
	v_cndmask_b32_e64 v86, 1.0, v84, s[4:5]
	v_cndmask_b32_e32 v179, v84, v86, vcc
	v_mul_f32_e32 v84, v87, v89
	v_exp_f32_e32 v86, v94
	v_add_u32_e32 v87, 0x99, v214
	v_cndmask_b32_e64 v91, 0, v88, s[4:5]
	v_cmp_lt_i32_e64 s[4:5], v87, v164
	v_cndmask_b32_e32 v88, v88, v91, vcc
	v_add_f32_e32 v91, 1.0, v86
	v_cndmask_b32_e64 v87, 1.0, v89, s[4:5]
	v_cndmask_b32_e32 v87, v89, v87, vcc
	v_exp_f32_e32 v89, v95
	v_rcp_f32_e32 v91, v91
	v_cndmask_b32_e64 v92, 0, v84, s[4:5]
	v_cndmask_b32_e32 v84, v84, v92, vcc
	v_add_u32_e32 v92, 0x9a, v214
	v_add_f32_e32 v93, 1.0, v89
	v_cmp_lt_i32_e64 s[4:5], v92, v164
	v_rcp_f32_e32 v93, v93
	v_mul_f32_e32 v86, v86, v91
	v_cndmask_b32_e64 v92, 1.0, v91, s[4:5]
	v_cndmask_b32_e32 v91, v91, v92, vcc
	v_add_u32_e32 v92, 0x9b, v214
	v_cndmask_b32_e64 v94, 0, v86, s[4:5]
	v_cmp_lt_i32_e64 s[4:5], v92, v164
	v_cndmask_b32_e32 v86, v86, v94, vcc
	v_mul_f32_e32 v89, v89, v93
	v_cndmask_b32_e64 v92, 1.0, v93, s[4:5]
	v_cndmask_b32_e32 v92, v93, v92, vcc
	v_mul_f32_e32 v91, v92, v91
	v_mul_f32_e32 v183, v87, v91
	v_mul_f32_e32 v92, v92, v86
	v_pk_mul_f32 v[86:87], v[178:179], v[182:183]
	v_mul_f32_e32 v84, v91, v84
	v_mov_b32_e32 v91, v87
	v_mov_b32_e32 v93, v87
	s_nop 1
	v_permlane32_swap_b32_e32 v91, v93
	v_cndmask_b32_e64 v181, v91, v93, s[0:1]
	v_pk_mul_f32 v[86:87], v[86:87], v[180:181]
	v_cndmask_b32_e64 v94, 0, v89, s[4:5]
	v_mul_f32_e32 v91, v86, v181
	v_mul_f32_e32 v88, v88, v183
	v_cndmask_b32_e64 v91, v86, v91, s[0:1]
	v_cndmask_b32_e32 v89, v89, v94, vcc
	v_mul_f32_e32 v93, v88, v91
	v_mul_f32_e32 v94, v84, v91
	v_mov_b32_e32 v84, v85
	v_mov_b32_e32 v88, v85
	s_nop 1
	v_permlane32_swap_b32_e32 v84, v88
	v_mul_f32_e32 v92, v92, v91
	v_mul_f32_e32 v91, v89, v91
	v_cndmask_b32_e64 v89, v84, v88, s[0:1]
	v_mov_b32_e32 v84, v86
	v_mov_b32_e32 v88, v87
	v_pk_mul_f32 v[84:85], v[84:85], v[88:89]
	s_waitcnt lgkmcnt(0)
; #define SBAR() __builtin_amdgcn_sched_barrier(0)
; #define SLOAD(i, k0) do { sr_[i].vs0 = *reinterpret_cast<const bf16x8*>(&Vh[(size_t)((k0) + sr) * LD + sc]); sr_[i].vs1 = *reinterpret_cast<const bf16x8*>(&Vh[(size_t)((k0) + 32 + sr) * LD + sc]); \
;     sr_[i].ks0 = *reinterpret_cast<const bf16x8*>(&Kh[(size_t)((k0) + sr) * LD + sc]); sr_[i].ks1 = *reinterpret_cast<const bf16x8*>(&Kh[(size_t)((k0) + 32 + sr) * LD + sc]); } while (0)
; __device__ __forceinline__ void pack_p(const f32x16& p0, const f32x16& p1, bf16x8& pa0, bf16x8& pa1, bf16x8& pa2, bf16x8& pa3) {
;     ...
;     PK4(p0, 0, pa0); PK4(p0, 8, pa1); PK4(p1, 0, pa2); PK4(p1, 8, pa3);
;     ...
; }
; __device__ __forceinline__ void sb_unit(const bf16* __restrict__ Qb, const bf16* __restrict__ Kh, const bf16* __restrict__ Vh, bf16* __restrict__ Ob, int q0, char* lds, const int wv0) {
;     ...
;         sb_half(pB0, carry, j < 4, K0(j), tq, hi); pack_p(pB0, pB1, pa0, pa1, pa2, pa3); SBAR();
;         { const int z = __all(carry == 0.0f); if (lane == 0) votes[8 + wid] = (unsigned)z; }
;         SLOAD(SE, K0(j + 2)); SBAR();
;         pv_d0(o, vb0 + (int)SHM_V, pa0, pa1, pa2, pa3); sb_half(pA1, carry, (j + 1) < 4, K0(j + 1) + 32, tq, hi);
;         __syncthreads();
	v_mfma_f32_32x32x16_bf16 v[96:111], v[236:239], v[112:115], v[96:111]
	v_mul_f32_e32 v86, v84, v89
	v_cndmask_b32_e64 v86, v84, v86, s[0:1]
	v_mul_f32_e32 v88, v80, v86
	v_mul_f32_e32 v89, v90, v86
	v_mul_f32_e32 v90, v82, v86
	v_mov_b32_e32 v80, v83
	v_mov_b32_e32 v82, v83
	s_nop 1
	v_permlane32_swap_b32_e32 v80, v82
	v_mul_f32_e32 v95, v147, v86
	v_cndmask_b32_e64 v87, v80, v82, s[0:1]
	v_mov_b32_e32 v82, v84
	v_mov_b32_e32 v86, v85
	v_pk_mul_f32 v[82:83], v[82:83], v[86:87]
	v_mov_b32_e32 v84, v81
	v_mul_f32_e32 v80, v82, v87
	v_cndmask_b32_e64 v80, v82, v80, s[0:1]
	v_mul_f32_e32 v86, v146, v80
	v_mul_f32_e32 v87, v145, v80
	v_mul_f32_e32 v144, v144, v80
	v_mul_f32_e32 v145, v154, v80
	v_mov_b32_e32 v80, v81
	s_nop 1
	v_permlane32_swap_b32_e32 v80, v84
	v_cndmask_b32_e64 v85, v80, v84, s[0:1]
	v_mov_b32_e32 v80, v82
	v_mov_b32_e32 v84, v83
	v_pk_mul_f32 v[80:81], v[80:81], v[84:85]
	s_nop 0
	v_mul_f32_e32 v82, v80, v85
	v_cndmask_b32_e64 v82, v80, v82, s[0:1]
	v_mul_f32_e32 v83, v150, v82
	v_mul_f32_e32 v84, v148, v82
	v_mul_f32_e32 v85, v149, v82
	v_mul_f32_e32 v82, v151, v82
	v_cvt_pk_bf16_f32 v156, v83, v84
	v_cvt_pk_bf16_f32 v157, v85, v82
	v_cvt_pk_bf16_f32 v158, v86, v87
	v_cvt_pk_bf16_f32 v159, v144, v145
	v_cvt_pk_bf16_f32 v152, v88, v89
	v_cvt_pk_bf16_f32 v153, v90, v95
	v_cvt_pk_bf16_f32 v154, v93, v94
	v_cvt_pk_bf16_f32 v155, v92, v91
	v_cvt_pk_bf16_f32 v148, v246, v197
	v_cvt_pk_bf16_f32 v149, v245, v196
	v_cvt_pk_bf16_f32 v150, v248, v240
	v_cvt_pk_bf16_f32 v151, v247, v215
	v_cvt_pk_bf16_f32 v144, v250, v242
	v_cvt_pk_bf16_f32 v145, v249, v241
	v_cvt_pk_bf16_f32 v146, v254, v244
	v_cvt_pk_bf16_f32 v147, v251, v243
	v_pk_mul_f32 v[194:195], v[80:81], v[80:81] op_sel:[0,1] op_sel_hi:[1,0]
	v_permlane32_swap_b32_e32 v156, v158
	v_permlane32_swap_b32_e32 v157, v159
	v_permlane32_swap_b32_e32 v152, v154
	v_permlane32_swap_b32_e32 v153, v155
	v_permlane32_swap_b32_e32 v148, v150
	v_permlane32_swap_b32_e32 v149, v151
	v_permlane32_swap_b32_e32 v144, v146
	v_permlane32_swap_b32_e32 v145, v147
	s_mov_b64 s[6:7], exec
	v_cmp_eq_f32_e32 vcc, 0, v194
	s_and_saveexec_b64 s[4:5], s[2:3]
	s_cbranch_execz .LBB0_1233
	s_cmp_eq_u64 vcc, s[6:7]
	s_cselect_b64 s[6:7], -1, 0
	v_cndmask_b32_e64 v80, 0, 1, s[6:7]
	ds_write_b32 v168, v80
.LBB0_1233:
	s_or_b64 exec, exec, s[4:5]
	v_lshl_add_u64 v[88:89], v[176:177], 0, v[160:161]
	v_add_co_u32_e32 v80, vcc, 0x17a00000, v88
	v_lshl_add_u64 v[92:93], v[174:175], 0, v[160:161]
	s_nop 0
	v_addc_co_u32_e32 v81, vcc, 0, v89, vcc
	v_add_co_u32_e32 v84, vcc, 0x17a00000, v92
	global_load_dwordx4 v[80:83], v[80:81], off
	s_nop 0
	v_addc_co_u32_e32 v85, vcc, 0, v93, vcc
	v_add_co_u32_e32 v88, vcc, 0x15a00000, v88
	global_load_dwordx4 v[84:87], v[84:85], off
	s_nop 0
	v_addc_co_u32_e32 v89, vcc, 0, v89, vcc
	v_add_co_u32_e32 v92, vcc, 0x15a00000, v92
	global_load_dwordx4 v[88:91], v[88:89], off
	s_nop 0
	v_addc_co_u32_e32 v93, vcc, 0, v93, vcc
	global_load_dwordx4 v[92:95], v[92:93], off
	ds_read_b64_tr_b16 v[178:179], v165 offset:0
	ds_read_b64_tr_b16 v[180:181], v165 offset:0x800
	ds_read_b64_tr_b16 v[182:183], v165 offset:0x1000
	ds_read_b64_tr_b16 v[184:185], v165 offset:0x1800
	ds_read_b64_tr_b16 v[186:187], v165 offset:0x2000
	ds_read_b64_tr_b16 v[188:189], v165 offset:0x2800
	ds_read_b64_tr_b16 v[190:191], v165 offset:0x3000
	ds_read_b64_tr_b16 v[192:193], v165 offset:0x3800
	s_waitcnt lgkmcnt(0)
	s_nop 0
	v_mfma_f32_32x32x16_bf16 v[48:63], v[156:159], v[178:181], v[48:63]
	ds_read_b64_tr_b16 v[178:179], v165 offset:0x200
	ds_read_b64_tr_b16 v[180:181], v165 offset:0xa00
	v_mfma_f32_32x32x16_bf16 v[48:63], v[152:155], v[182:185], v[48:63]
	ds_read_b64_tr_b16 v[182:183], v165 offset:0x1200
	ds_read_b64_tr_b16 v[184:185], v165 offset:0x1a00
	v_mfma_f32_32x32x16_bf16 v[48:63], v[148:151], v[186:189], v[48:63]
	ds_read_b64_tr_b16 v[186:187], v165 offset:0x2200
	ds_read_b64_tr_b16 v[188:189], v165 offset:0x2a00
	ds_read_b64_tr_b16 v[216:217], v165 offset:0x3200
	ds_read_b64_tr_b16 v[218:219], v165 offset:0x3a00
	s_waitcnt lgkmcnt(0)
	v_mfma_f32_32x32x16_bf16 v[48:63], v[144:147], v[190:193], v[48:63]
	v_mfma_f32_32x32x16_bf16 v[32:47], v[156:159], v[178:181], v[32:47]
	ds_read_b64_tr_b16 v[178:179], v165 offset:0x400
	ds_read_b64_tr_b16 v[180:181], v165 offset:0xc00
	v_mfma_f32_32x32x16_bf16 v[32:47], v[152:155], v[182:185], v[32:47]
	ds_read_b64_tr_b16 v[182:183], v165 offset:0x1400
	ds_read_b64_tr_b16 v[184:185], v165 offset:0x1c00
	v_mfma_f32_32x32x16_bf16 v[32:47], v[148:151], v[186:189], v[32:47]
	ds_read_b64_tr_b16 v[186:187], v165 offset:0x2400
	ds_read_b64_tr_b16 v[188:189], v165 offset:0x2c00
	ds_read_b64_tr_b16 v[190:191], v165 offset:0x3400
	ds_read_b64_tr_b16 v[192:193], v165 offset:0x3c00
	s_waitcnt lgkmcnt(0)
	v_mfma_f32_32x32x16_bf16 v[32:47], v[144:147], v[216:219], v[32:47]
	v_mfma_f32_32x32x16_bf16 v[16:31], v[156:159], v[178:181], v[16:31]
	v_mfma_f32_32x32x16_bf16 v[16:31], v[152:155], v[182:185], v[16:31]
	ds_read_b64_tr_b16 v[184:185], v165 offset:0x600
	v_mfma_f32_32x32x16_bf16 v[16:31], v[148:151], v[186:189], v[16:31]
	ds_read_b64_tr_b16 v[186:187], v165 offset:0xe00
	ds_read_b64_tr_b16 v[216:217], v165 offset:0x1600
	ds_read_b64_tr_b16 v[218:219], v165 offset:0x1e00
	ds_read_b64_tr_b16 v[220:221], v165 offset:0x2600
	ds_read_b64_tr_b16 v[222:223], v165 offset:0x2e00
	ds_read_b64_tr_b16 v[224:225], v165 offset:0x3600
	ds_read_b64_tr_b16 v[226:227], v165 offset:0x3e00
	v_mfma_f32_32x32x16_bf16 v[16:31], v[144:147], v[190:193], v[16:31]
	s_waitcnt lgkmcnt(0)
	v_exp_f32_e32 v180, v96
	s_cmp_lt_u32 s72, 3
	s_cselect_b64 vcc, -1, 0
	s_add_i32 s20, 0, 0x10020
	s_cmp_lg_u32 s20, -1
	v_add_f32_e32 v178, 1.0, v180
	s_cselect_b32 s20, s20, 0
	v_rcp_f32_e32 v182, v178
	s_cselect_b32 s21, s47, 0
	v_mov_b32_e32 v178, s20
	s_add_i32 s20, 0, 0x10024
	s_cmp_lg_u32 s20, -1
	v_mov_b32_e32 v179, s21
	s_cselect_b32 s20, s20, 0
	s_waitcnt lgkmcnt(0)
	s_barrier
; __device__ __forceinline__ int crow(int r, int hi) { return (r & 3) + 8 * (r >> 2) + 4 * hi; }
; #define SBAR() __builtin_amdgcn_sched_barrier(0)
; #define SLOAD(i, k0) do { sr_[i].vs0 = *reinterpret_cast<const bf16x8*>(&Vh[(size_t)((k0) + sr) * LD + sc]); sr_[i].vs1 = *reinterpret_cast<const bf16x8*>(&Vh[(size_t)((k0) + 32 + sr) * LD + sc]); \
;     sr_[i].ks0 = *reinterpret_cast<const bf16x8*>(&Kh[(size_t)((k0) + sr) * LD + sc]); sr_[i].ks1 = *reinterpret_cast<const bf16x8*>(&Kh[(size_t)((k0) + 32 + sr) * LD + sc]); } while (0)
; __device__ __forceinline__ void sb_half(f32x16& p, float& carry, bool masked, int krow0, int tq, int hi) {
;     float G[4];
; #pragma unroll
;     for (int g = 0; g < 4; ++g) {
;         float q[4];
; #pragma unroll
;         for (int i = 0; i < 4; ++i) { const int r = 4 * g + i; const float e = __builtin_amdgcn_exp2f(p[r]); float qq = __builtin_amdgcn_rcpf(1.0f + e); float b = e * qq;
;             if (masked) { const bool keep = (krow0 + crow(r, hi)) < tq; qq = keep ? qq : 1.0f; b = keep ? b : 0.0f; }
;             q[i] = qq; p[r] = b; }
;         const float s2 = q[3] * q[2], s1 = s2 * q[1]; G[g] = s1 * q[0];
;         p[4 * g + 2] *= q[3]; p[4 * g + 1] *= s2; p[4 * g] *= s1;
;     }
; __device__ __forceinline__ void sb_unit(const bf16* __restrict__ Qb, const bf16* __restrict__ Kh, const bf16* __restrict__ Vh, bf16* __restrict__ Ob, int q0, char* lds, const int wv0) {
;     ...
;         { const int z = __all(carry == 0.0f); if (lane == 0) votes[8 + wid] = (unsigned)z; }
;         SLOAD(SE, K0(j + 2)); SBAR();
;         pv_d0(o, vb0 + (int)SHM_V, pa0, pa1, pa2, pa3); sb_half(pA1, carry, (j + 1) < 4, K0(j + 1) + 32, tq, hi);
;         __syncthreads();
;         { unsigned a = 1u;
; #pragma unroll
;           for (int w = 0; w < 8; ++w) a &= votes[8 + w];
;           if (a) { done = true; break; } }
	ds_read_b32 v181, v178
	s_cselect_b32 s21, s47, 0
	v_mov_b32_e32 v178, s20
	s_add_i32 s20, 0, 0x10028
	s_cmp_lg_u32 s20, -1
	v_mov_b32_e32 v179, s21
	s_cselect_b32 s20, s20, 0
	ds_read_b32 v183, v178
	s_cselect_b32 s21, s47, 0
	v_mov_b32_e32 v178, s20
	s_add_i32 s20, 0, 0x1002c
	s_cmp_lg_u32 s20, -1
	v_mov_b32_e32 v179, s21
	s_cselect_b32 s20, s20, 0
	v_mfma_f32_32x32x16_bf16 v[0:15], v[156:159], v[184:187], v[0:15]
	ds_read_b32 v185, v178
	s_cselect_b32 s21, s47, 0
	v_mov_b32_e32 v178, s20
	s_add_i32 s20, 0, 0x10030
	s_cmp_lg_u32 s20, -1
	v_mov_b32_e32 v179, s21
	s_cselect_b32 s20, s20, 0
	ds_read_b32 v187, v178
	s_cselect_b32 s21, s47, 0
	v_mov_b32_e32 v178, s20
	s_add_i32 s20, 0, 0x10034
	s_cmp_lg_u32 s20, -1
	v_mov_b32_e32 v179, s21
	s_cselect_b32 s20, s20, 0
	ds_read_b32 v189, v178
	s_cselect_b32 s21, s47, 0
	v_mov_b32_e32 v178, s20
	s_add_i32 s20, 0, 0x10038
	s_cmp_lg_u32 s20, -1
	v_mov_b32_e32 v179, s21
	s_cselect_b32 s20, s20, 0
	ds_read_b32 v191, v178
	s_cselect_b32 s21, s47, 0
	v_mov_b32_e32 v178, s20
	s_add_i32 s20, 0, 0x1003c
	s_cmp_lg_u32 s20, -1
	v_mov_b32_e32 v179, s21
	s_cselect_b32 s20, s20, 0
	s_cselect_b32 s21, s47, 0
	ds_read_b32 v193, v178
	v_mov_b32_e32 v178, s20
	v_mov_b32_e32 v179, s21
	ds_read_b32 v179, v178
	v_mfma_f32_32x32x16_bf16 v[0:15], v[152:155], v[216:219], v[0:15]
	v_exp_f32_e32 v152, v98
	v_exp_f32_e32 v156, v97
	v_exp_f32_e32 v155, v103
	v_exp_f32_e32 v101, v101
	v_add_f32_e32 v98, 1.0, v152
	v_add_f32_e32 v97, 1.0, v156
	v_rcp_f32_e32 v153, v98
	v_mfma_f32_32x32x16_bf16 v[0:15], v[148:151], v[220:223], v[0:15]
	v_exp_f32_e32 v148, v99
	v_rcp_f32_e32 v157, v97
	v_add_u32_e32 v98, 0x62, v214
	v_exp_f32_e32 v151, v102
	v_add_f32_e32 v99, 1.0, v148
	v_rcp_f32_e32 v150, v99
	v_add_u32_e32 v99, 0x63, v214
	v_add_u32_e32 v97, 0x61, v214
	v_cmp_lt_i32_e64 s[10:11], v98, v164
	v_cmp_lt_i32_e64 s[14:15], v99, v164
	v_add_u32_e32 v96, 0x60, v214
	v_cmp_lt_i32_e64 s[6:7], v97, v164
	v_cndmask_b32_e64 v98, 1.0, v153, s[10:11]
	v_cndmask_b32_e64 v99, 1.0, v150, s[14:15]
	v_exp_f32_e32 v100, v100
	v_exp_f32_e32 v192, v106
	v_cmp_lt_i32_e64 s[4:5], v96, v164
	v_cndmask_b32_e64 v97, 1.0, v157, s[6:7]
	v_cndmask_b32_e32 v98, v153, v98, vcc
	v_cndmask_b32_e32 v149, v150, v99, vcc
	v_add_f32_e32 v102, 1.0, v155
	v_cndmask_b32_e64 v96, 1.0, v182, s[4:5]
	v_cndmask_b32_e32 v97, v157, v97, vcc
	v_mfma_f32_32x32x16_bf16 v[0:15], v[144:147], v[224:227], v[0:15]
	v_mul_f32_e32 v147, v149, v98
	v_add_f32_e32 v99, 1.0, v151
	v_rcp_f32_e32 v159, v102
	v_cndmask_b32_e32 v96, v182, v96, vcc
	v_mul_f32_e32 v146, v97, v147
	v_add_f32_e32 v98, 1.0, v101
	v_rcp_f32_e32 v154, v99
	v_exp_f32_e32 v219, v107
	v_mul_f32_e32 v97, v96, v146
	v_add_f32_e32 v96, 1.0, v100
	v_rcp_f32_e32 v145, v98
	v_add_u32_e32 v102, 0x6b, v214
	v_add_f32_e32 v106, 1.0, v192
	v_rcp_f32_e32 v144, v96
	v_add_u32_e32 v99, 0x6a, v214
	v_cmp_lt_i32_e64 s[18:19], v102, v164
	v_rcp_f32_e32 v217, v106
	v_add_u32_e32 v98, 0x69, v214
	v_cmp_lt_i32_e64 s[16:17], v99, v164
	v_cndmask_b32_e64 v102, 1.0, v159, s[18:19]
	v_exp_f32_e32 v105, v105
	v_add_u32_e32 v96, 0x68, v214
	v_cmp_lt_i32_e64 s[12:13], v98, v164
	v_cndmask_b32_e64 v99, 1.0, v154, s[16:17]
	v_cndmask_b32_e32 v158, v159, v102, vcc
	v_exp_f32_e32 v102, v104
	v_add_u32_e32 v106, 0x72, v214
	v_add_f32_e32 v107, 1.0, v219
	v_exp_f32_e32 v110, v110
	v_cmp_lt_i32_e64 s[8:9], v96, v164
	v_cndmask_b32_e64 v98, 1.0, v145, s[12:13]
	v_cndmask_b32_e32 v99, v154, v99, vcc
	v_cmp_lt_i32_e64 s[28:29], v106, v164
	v_rcp_f32_e32 v221, v107
	v_cndmask_b32_e64 v96, 1.0, v144, s[8:9]
	v_cndmask_b32_e32 v98, v145, v98, vcc
	v_mul_f32_e32 v104, v158, v99
	v_cndmask_b32_e64 v106, 1.0, v217, s[28:29]
	v_cndmask_b32_e32 v96, v144, v96, vcc
	v_mul_f32_e32 v103, v98, v104
	v_add_f32_e32 v98, 1.0, v105
	v_cndmask_b32_e32 v107, v217, v106, vcc
	v_add_u32_e32 v106, 0x73, v214
	v_mul_f32_e32 v99, v96, v103
	v_add_f32_e32 v96, 1.0, v102
	v_rcp_f32_e32 v190, v98
	v_cmp_lt_i32_e64 s[30:31], v106, v164
	v_add_f32_e32 v178, 1.0, v110
	v_rcp_f32_e32 v184, v96
	v_cndmask_b32_e64 v106, 1.0, v221, s[30:31]
	v_rcp_f32_e32 v222, v178
	v_exp_f32_e32 v178, v111
	v_add_u32_e32 v98, 0x71, v214
	v_cndmask_b32_e32 v220, v221, v106, vcc
	v_exp_f32_e32 v106, v108
	v_exp_f32_e32 v108, v109
	v_add_u32_e32 v96, 0x70, v214
	v_cmp_lt_i32_e64 s[22:23], v98, v164
	v_cmp_lt_i32_e64 s[20:21], v96, v164
	v_mul_f32_e32 v218, v220, v107
	v_cndmask_b32_e64 v98, 1.0, v190, s[22:23]
	v_cndmask_b32_e64 v96, 1.0, v184, s[20:21]
	v_cndmask_b32_e32 v98, v190, v98, vcc
	v_add_f32_e32 v186, 1.0, v178
	v_cndmask_b32_e32 v96, v184, v96, vcc
	v_mul_f32_e32 v216, v98, v218
	v_add_f32_e32 v98, 1.0, v108
	v_rcp_f32_e32 v186, v186
	v_mul_f32_e32 v195, v96, v216
	v_add_f32_e32 v96, 1.0, v106
	v_rcp_f32_e32 v109, v98
	v_rcp_f32_e32 v107, v96
	v_add_u32_e32 v111, 0x7a, v214
	v_add_u32_e32 v188, 0x7b, v214
	v_add_u32_e32 v98, 0x79, v214
	v_cmp_lt_i32_e64 s[34:35], v111, v164
	v_cmp_lt_i32_e64 s[36:37], v188, v164
	v_add_u32_e32 v96, 0x78, v214
	v_cmp_lt_i32_e64 s[26:27], v98, v164
	v_cndmask_b32_e64 v111, 1.0, v222, s[34:35]
	v_cndmask_b32_e64 v188, 1.0, v186, s[36:37]
	v_cmp_lt_i32_e64 s[24:25], v96, v164
	v_cndmask_b32_e64 v98, 1.0, v109, s[26:27]
	v_cndmask_b32_e32 v111, v222, v111, vcc
	v_cndmask_b32_e32 v223, v186, v188, vcc
	v_cndmask_b32_e64 v96, 1.0, v107, s[24:25]
	v_cndmask_b32_e32 v98, v109, v98, vcc
	v_mul_f32_e32 v214, v223, v111
	s_waitcnt lgkmcnt(0)
	v_bitop3_b32 v181, v181, v185, v183 bitop3:0x80
	v_cndmask_b32_e32 v96, v107, v96, vcc
	v_mul_f32_e32 v111, v98, v214
	v_bitop3_b32 v181, v181, v189, v187 bitop3:0x80
	v_mul_f32_e32 v98, v96, v111
	v_bitop3_b32 v181, v181, v193, v191 bitop3:0x80
	v_mov_b32_e32 v226, v98
	v_mov_b32_e32 v227, v98
	v_mov_b32_e32 v228, v195
	v_mov_b32_e32 v229, v195
	v_mov_b32_e32 v224, v99
	v_mov_b32_e32 v225, v99
	v_mov_b32_e32 v96, v97
	v_mov_b32_e32 v188, v97
	v_bitop3_b32 v179, v181, 1, v179 bitop3:0x80
	v_permlane32_swap_b32_e32 v226, v227
	v_permlane32_swap_b32_e32 v228, v229
	v_permlane32_swap_b32_e32 v224, v225
	v_permlane32_swap_b32_e32 v96, v188
	v_cmp_eq_u32_e64 s[38:39], 0, v179
	s_mov_b64 s[72:73], -1
	v_readfirstlane_b32 s95, v0
	s_mov_b64 s[74:75], -1
	s_and_saveexec_b64 s[70:71], s[38:39]
	s_cbranch_execz .LBB0_1226
; #define SWRITE(b, i) do { *(bf16x8*)(V_lds + (b) * SHM_V + vst0) = sr_[i].vs0; *(bf16x8*)(V_lds + (b) * SHM_V + vst1) = sr_[i].vs1; const int kc = sc * 2; \
;     *(bf16x8*)(K_lds + (b) * SHM_K + KSWZ(sr, kc)) = sr_[i].ks0; *(bf16x8*)(K_lds + (b) * SHM_K + KSWZ(32 + sr, kc)) = sr_[i].ks1; } while (0)
; #define SWAIT() asm volatile("s_waitcnt vmcnt(0)" ::: "memory")
; __device__ __forceinline__ void sb_half(f32x16& p, float& carry, bool masked, int krow0, int tq, int hi) {
;     ...
;     float run = carry;
; #pragma unroll
;     for (int g = 3; g >= 0; --g) { const unsigned gu = __builtin_bit_cast(unsigned, G[g]); auto sw = __builtin_amdgcn_permlane32_swap(gu, gu, false, false);
;         const float partner = __builtin_bit_cast(float, hi ? sw[0] : sw[1]);
;         const float base = hi ? run : run * partner;
;         p[4 * g] *= base; p[4 * g + 1] *= base; p[4 * g + 2] *= base; p[4 * g + 3] *= base; run *= G[g] * partner; }
;     carry = run;
; __device__ __forceinline__ void sb_unit(const bf16* __restrict__ Qb, const bf16* __restrict__ Kh, const bf16* __restrict__ Vh, bf16* __restrict__ Ob, int q0, char* lds, const int wv0) {
;     ...
;         SWAIT(); SWRITE(1, SO);
;         __syncthreads();
	v_cndmask_b32_e64 v179, v226, v227, s[0:1]
	v_mul_f32_e32 v196, v98, v179
	v_cndmask_b32_e64 v197, v228, v229, s[0:1]
	v_pk_mul_f32 v[226:227], v[194:195], v[196:197]
	v_cndmask_b32_e64 v225, v224, v225, s[0:1]
	v_mov_b32_e32 v98, v226
	v_mov_b32_e32 v224, v227
	v_pk_mul_f32 v[98:99], v[98:99], v[224:225]
	v_cndmask_b32_e64 v189, v96, v188, s[0:1]
	v_mov_b32_e32 v96, v98
	v_mov_b32_e32 v188, v99
	v_pk_mul_f32 v[96:97], v[96:97], v[188:189]
	s_add_i32 s95, s79, 2
	v_mul_f32_e32 v215, v96, v97
	v_mul_f32_e32 v97, v178, v186
	v_cndmask_b32_e64 v99, 0, v97, s[36:37]
	v_cndmask_b32_e32 v97, v97, v99, vcc
	v_mul_f32_e32 v99, v194, v179
	v_cndmask_b32_e64 v194, v194, v99, s[0:1]
	v_mul_f32_e32 v99, v148, v150
	v_cndmask_b32_e64 v148, 0, v99, s[14:15]
	v_cndmask_b32_e32 v179, v99, v148, vcc
	v_mul_f32_e32 v99, v96, v189
	v_cndmask_b32_e64 v96, v96, v99, s[0:1]
	v_mul_f32_e32 v99, v152, v153
	v_cndmask_b32_e64 v148, 0, v99, s[10:11]
	v_cndmask_b32_e32 v99, v99, v148, vcc
	v_mul_f32_e32 v178, v149, v99
	v_mul_f32_e32 v99, v156, v157
	v_cndmask_b32_e64 v148, 0, v99, s[6:7]
	v_cndmask_b32_e32 v99, v99, v148, vcc
	v_mul_f32_e32 v99, v147, v99
	v_mul_f32_e32 v187, v99, v96
	v_mul_f32_e32 v99, v180, v182
	v_cndmask_b32_e64 v147, 0, v99, s[4:5]
	v_cndmask_b32_e32 v99, v99, v147, vcc
	v_mul_f32_e32 v99, v99, v146
	v_pk_mul_f32 v[178:179], v[178:179], v[96:97] op_sel_hi:[1,0]
	v_mul_f32_e32 v186, v99, v96
	v_mul_f32_e32 v96, v155, v159
	v_cndmask_b32_e64 v99, 0, v96, s[18:19]
	v_cndmask_b32_e32 v99, v96, v99, vcc
	v_mul_f32_e32 v96, v98, v225
	v_cndmask_b32_e64 v96, v98, v96, s[0:1]
	v_mul_f32_e32 v98, v151, v154
	v_cndmask_b32_e64 v146, 0, v98, s[16:17]
	v_cndmask_b32_e32 v98, v98, v146, vcc
	v_mul_f32_e32 v98, v158, v98
	v_pk_mul_f32 v[180:181], v[98:99], v[96:97] op_sel_hi:[1,0]
	v_mul_f32_e32 v98, v101, v145
	v_cndmask_b32_e64 v99, 0, v98, s[12:13]
	v_cndmask_b32_e32 v98, v98, v99, vcc
	v_mul_f32_e32 v98, v104, v98
	v_mul_f32_e32 v189, v98, v96
	v_mul_f32_e32 v98, v100, v144
	v_cndmask_b32_e64 v99, 0, v98, s[8:9]
	v_cndmask_b32_e32 v98, v98, v99, vcc
	v_mul_f32_e32 v98, v98, v103
	v_mul_f32_e32 v188, v98, v96
	v_mul_f32_e32 v96, v219, v221
	v_cndmask_b32_e64 v98, 0, v96, s[30:31]
	v_cndmask_b32_e32 v99, v96, v98, vcc
	v_mul_f32_e32 v98, v192, v217
	v_cndmask_b32_e64 v100, 0, v98, s[28:29]
	v_mul_f32_e32 v96, v226, v197
	v_cndmask_b32_e32 v98, v98, v100, vcc
	v_cndmask_b32_e64 v96, v226, v96, s[0:1]
	v_mul_f32_e32 v98, v220, v98
	v_pk_mul_f32 v[182:183], v[98:99], v[96:97] op_sel_hi:[1,0]
	v_mul_f32_e32 v98, v105, v190
	v_cndmask_b32_e64 v99, 0, v98, s[22:23]
	v_cndmask_b32_e32 v98, v98, v99, vcc
	v_mul_f32_e32 v98, v218, v98
	v_mul_f32_e32 v191, v98, v96
	v_mul_f32_e32 v98, v102, v184
	v_cndmask_b32_e64 v99, 0, v98, s[20:21]
	v_cndmask_b32_e32 v98, v98, v99, vcc
	v_mul_f32_e32 v98, v98, v216
	v_mul_f32_e32 v190, v98, v96
	v_mul_f32_e32 v96, v110, v222
	v_cndmask_b32_e64 v98, 0, v96, s[34:35]
	v_cndmask_b32_e32 v96, v96, v98, vcc
	v_mul_f32_e32 v96, v223, v96
	v_pk_mul_f32 v[184:185], v[96:97], v[194:195] op_sel_hi:[1,0]
	v_mul_f32_e32 v96, v108, v109
	v_cndmask_b32_e64 v97, 0, v96, s[26:27]
	v_cndmask_b32_e32 v96, v96, v97, vcc
	v_mul_f32_e32 v96, v214, v96
	v_mul_f32_e32 v193, v96, v194
	v_mul_f32_e32 v96, v106, v107
	v_cndmask_b32_e64 v97, 0, v96, s[24:25]
	v_cndmask_b32_e32 v96, v96, v97, vcc
	s_waitcnt vmcnt(0)
	s_cmp_ge_u32 s95, s40
	v_mul_f32_e32 v96, v96, v111
	s_cselect_b64 s[4:5], -1, 0
	v_mul_f32_e32 v192, v96, v194
	v_add_u32_e32 v213, 0xffffff80, v213
	v_lshl_add_u64 v[170:171], v[170:171], 0, s[48:49]
	v_lshl_add_u64 v[172:173], v[172:173], 0, s[48:49]
	v_lshl_add_u64 v[174:175], v[174:175], 0, s[48:49]
	v_lshl_add_u64 v[176:177], v[176:177], 0, s[48:49]
	s_xor_b64 s[74:75], exec, -1
	s_orn2_b64 s[72:73], s[4:5], exec
	ds_write_b128 v206, v[80:83] offset:16384
	ds_write_b128 v207, v[84:87] offset:16384
	ds_write_b128 v199, v[88:91] offset:49152
	ds_write_b128 v200, v[92:95] offset:49152
	s_waitcnt lgkmcnt(0)
	s_barrier
	s_branch .LBB0_1226

;     __device__ __forceinline__ bool next(int i, Unit& u) const { int pm, pn; if (!to.get((long)i * G + c, pm, pn)) return false; u.pm = pm; u.pn = pn; u.aux = 0; u.a = A + (size_t)pm * ta; u.b = B + (size_t)pn * tb; return true; }
; template <class Epi, class Sched, bool ALIGN_EPI = false, bool SP2 = false>
; __device__ __forceinline__ void gemm_phase(PG8_LAS unsigned char* lds, const Gemm g, const Sched& S, const Epi& E, const int wv0) {
;     ...
;         PG8_STAGE(PG8_SB(0, 0), cB, voffB); PG8_STAGE(PG8_SB(0, 1), cB + hstepB, voffB); PG8_STAGE(PG8_SA(0, 0), cA, voffA); PG8_STAGE(PG8_SA(0, 1), cA + hstepA, voffA);
;         if (wr == 1) PG8_BAR;
;         PG8_WAIT_V(2); PG8_BAR;
;         PG8_STAGE(PG8_SB(1, 0), cB + kstep, voffB); PG8_STAGE(PG8_SA(1, 0), cA + kstep, voffA); PG8_STAGE(PG8_SB(1, 1), cB + hstepB + kstep, voffB);
;         PG8_WAIT_V(6); PG8_BAR;
;     } else {
;         PG8_STAGE(PG8_SB(0, 0), cB, voffB); PG8_STAGE(PG8_SA(0, 0), cA, voffA); PG8_STAGE(PG8_SB(0, 1), cB + hstepB, voffB); PG8_STAGE(PG8_SA(0, 1), cA + hstepA, voffA);
;         if (wr == 1) PG8_BAR;
;         PG8_WAIT_V(4); PG8_BAR;
;         PG8_STAGE(PG8_SB(1, 0), cB + kstep, voffB); PG8_STAGE(PG8_SA(1, 0), cA + kstep, voffA); PG8_STAGE(PG8_SB(1, 1), cB + hstepB + kstep, voffB);
;         PG8_WAIT_V(6); PG8_BAR;
;     }
;     for (;;) {
;         const bool has_next = S.next(ui + 1, nxt);
;         const char* nA = has_next ? nxt.a : cA; const char* nB = has_next ? nxt.b : cB;
;         for (int t = 0; t < nt; t += 2) {
;             const bool last = (t == nt - 2);
;             const char* a1 = cA + (size_t)(t + 1) * kstep;
;             const char* a2 = last ? nA : cA + (size_t)(t + 2) * kstep; const char* b2 = last ? nB : cB + (size_t)(t + 2) * kstep;
;             const char* a3 = a2 + kstep; const char* b3 = b2 + kstep;
;             if constexpr (SP2) {
;             PG8_LDB(B0, 0, 0); PG8_LDB(B1, 0, 1); PG8_SCHED; PG8_LDA(At, 0, 0); PG8_STAGE(PG8_SA(1, 1), a1 + hstepA, voffA);
;             PG8_WAIT_V(8); PG8_WAIT_L(0); PG8_BAR; PG8_MMA(0, 0, At, B0); PG8_MMA(0, 1, At, B1); PG8_BAR; PG8_SCHED;
;             PG8_LDA(At, 0, 1); PG8_STAGE(PG8_SB(0, 0), b2, voffB); PG8_STAGE(PG8_SB(0, 1), b2 + hstepB, voffB); PG8_STAGE(PG8_SA(0, 0), a2, voffA);
;             PG8_WAIT_V(8); PG8_WAIT_L(0); PG8_BAR; PG8_MMA(1, 0, At, B0); PG8_MMA(1, 1, At, B1); PG8_BAR; PG8_SCHED;
.LBB0_1299:
	s_and_b32 s51, s47, 3
	s_lshl_b32 s47, s50, 13
	s_lshl_b32 s48, s51, 12
	s_add_u32 s64, s61, 0x2e280080
	s_addc_u32 s65, s62, 0
	s_add_i32 s26, s36, s66
	v_lshl_add_u64 v[2:3], s[64:65], 0, v[128:129]
	s_mov_b32 m0, s26
	s_add_i32 s53, s26, 0x2000
	s_waitcnt vmcnt(2)
	s_barrier
	global_load_lds_dwordx4 v[2:3], off
	v_lshl_add_u64 v[4:5], s[64:65], 0, v[32:33]
	s_mov_b32 m0, s53
	s_add_i32 s27, s59, 0x8000
	s_add_i32 s54, s59, 0xa000
	global_load_lds_dwordx4 v[4:5], off
	v_lshl_add_u64 v[0:1], v[20:21], 0, s[10:11]
	s_mov_b32 m0, s27
	s_add_u32 s64, s61, 0x2e290080
	global_load_lds_dwordx4 v[0:1], off
	v_lshl_add_u64 v[6:7], v[22:23], 0, s[10:11]
	s_mov_b32 m0, s54
	s_addc_u32 s65, s62, 0
	s_add_i32 s57, s37, s66
	global_load_lds_dwordx4 v[6:7], off
	v_lshl_add_u64 v[8:9], s[64:65], 0, v[128:129]
	s_mov_b32 m0, s57
	s_add_i32 s58, s57, 0x2000
	global_load_lds_dwordx4 v[8:9], off
	v_lshl_add_u64 v[10:11], s[64:65], 0, v[32:33]
	s_mov_b32 m0, s58
	v_bfe_u32 v144, v34, 4, 2
	global_load_lds_dwordx4 v[10:11], off
	v_and_b32_e32 v143, 15, v34
	v_lshlrev_b32_e32 v35, 4, v144
	v_lshlrev_b32_e32 v34, 2, v34
	v_lshl_or_b32 v35, v143, 6, v35
	v_and_b32_e32 v34, 32, v34
	v_bitop3_b32 v66, v35, s48, v34 bitop3:0xde
	s_add_i32 s48, 0, 0x10000
	v_bitop3_b32 v36, v35, s47, v34 bitop3:0xde
	s_add_i32 s47, 0, 0x14000
	v_add_u32_e32 v203, s48, v66
	s_waitcnt vmcnt(6)
	s_barrier
	v_add_u32_e32 v145, 0, v36
	v_add_u32_e32 v202, s47, v66
	ds_read_b128 v[34:37], v203
	ds_read_b128 v[38:41], v203 offset:1024
	ds_read_b128 v[42:45], v203 offset:2048
	ds_read_b128 v[46:49], v203 offset:3072
	ds_read_b128 v[50:53], v202
	ds_read_b128 v[54:57], v202 offset:1024
	ds_read_b128 v[58:61], v202 offset:2048
	ds_read_b128 v[62:65], v202 offset:3072
	s_add_u32 s70, s61, 0x2e280100
	v_add_u32_e32 v246, s37, v66
	v_add_u32_e32 v247, s36, v66
	s_addc_u32 s71, s62, 0
	s_add_u32 s64, s24, 0x40080
	s_addc_u32 s65, s25, 0
	s_add_i32 s68, s59, 0xc000
	v_lshl_add_u64 v[98:99], s[64:65], 0, v[16:17]
	s_mov_b32 m0, s68
	s_add_i32 s63, s59, 0xe000
	ds_read_b128 v[66:69], v145
	ds_read_b128 v[70:73], v145 offset:1024
	ds_read_b128 v[74:77], v145 offset:2048
	ds_read_b128 v[78:81], v145 offset:3072
	ds_read_b128 v[82:85], v145 offset:4096
	ds_read_b128 v[86:89], v145 offset:5120
	ds_read_b128 v[90:93], v145 offset:6144
	ds_read_b128 v[94:97], v145 offset:7168
	global_load_lds_dwordx4 v[98:99], off
	v_lshl_add_u64 v[98:99], s[64:65], 0, v[30:31]
	s_mov_b32 m0, s63
	s_nop 0
	global_load_lds_dwordx4 v[98:99], off
	s_waitcnt vmcnt(8)
	s_waitcnt lgkmcnt(0)
	s_barrier
	s_setprio 1
	v_mfma_f32_16x16x32_bf16 v[98:101], v[34:37], v[66:69], 0
	v_mfma_f32_16x16x32_bf16 v[102:105], v[42:45], v[66:69], 0
	v_mfma_f32_16x16x32_bf16 v[106:109], v[34:37], v[74:77], 0
	v_mfma_f32_16x16x32_bf16 v[110:113], v[42:45], v[74:77], 0
	v_mfma_f32_16x16x32_bf16 v[114:117], v[34:37], v[82:85], 0
	v_mfma_f32_16x16x32_bf16 v[118:121], v[42:45], v[82:85], 0
	v_mfma_f32_16x16x32_bf16 v[122:125], v[34:37], v[90:93], 0
	v_mfma_f32_16x16x32_bf16 v[98:101], v[38:41], v[70:73], v[98:101]
	v_mfma_f32_16x16x32_bf16 v[102:105], v[46:49], v[70:73], v[102:105]
	v_mfma_f32_16x16x32_bf16 v[106:109], v[38:41], v[78:81], v[106:109]
	v_mfma_f32_16x16x32_bf16 v[110:113], v[46:49], v[78:81], v[110:113]
	v_mfma_f32_16x16x32_bf16 v[114:117], v[38:41], v[86:89], v[114:117]
	v_mfma_f32_16x16x32_bf16 v[118:121], v[46:49], v[86:89], v[118:121]
	v_mfma_f32_16x16x32_bf16 v[122:125], v[38:41], v[94:97], v[122:125]
	v_mfma_f32_16x16x32_bf16 v[130:133], v[42:45], v[90:93], 0
	v_mfma_f32_16x16x32_bf16 v[130:133], v[46:49], v[94:97], v[130:133]
	v_mfma_f32_16x16x32_bf16 v[134:137], v[50:53], v[66:69], 0
	v_mfma_f32_16x16x32_bf16 v[66:69], v[58:61], v[66:69], 0
	v_mfma_f32_16x16x32_bf16 v[134:137], v[54:57], v[70:73], v[134:137]
	v_mfma_f32_16x16x32_bf16 v[66:69], v[62:65], v[70:73], v[66:69]
	v_mfma_f32_16x16x32_bf16 v[70:73], v[50:53], v[74:77], 0
	v_mfma_f32_16x16x32_bf16 v[74:77], v[58:61], v[74:77], 0
	v_mfma_f32_16x16x32_bf16 v[70:73], v[54:57], v[78:81], v[70:73]
	v_mfma_f32_16x16x32_bf16 v[74:77], v[62:65], v[78:81], v[74:77]
	v_mfma_f32_16x16x32_bf16 v[78:81], v[50:53], v[82:85], 0
	v_mfma_f32_16x16x32_bf16 v[82:85], v[58:61], v[82:85], 0
	v_mfma_f32_16x16x32_bf16 v[78:81], v[54:57], v[86:89], v[78:81]
	v_mfma_f32_16x16x32_bf16 v[82:85], v[62:65], v[86:89], v[82:85]
	v_mfma_f32_16x16x32_bf16 v[86:89], v[50:53], v[90:93], 0
	v_mfma_f32_16x16x32_bf16 v[90:93], v[58:61], v[90:93], 0
	v_mfma_f32_16x16x32_bf16 v[86:89], v[54:57], v[94:97], v[86:89]
	v_mfma_f32_16x16x32_bf16 v[90:93], v[62:65], v[94:97], v[90:93]
	s_setprio 0
	s_barrier
	s_add_i32 s64, s48, s66
	v_lshl_add_u64 v[126:127], s[70:71], 0, v[128:129]
	s_mov_b32 m0, s64
	s_add_i32 s65, s64, 0x2000
	ds_read_b128 v[94:97], v145 offset:16384
	ds_read_b128 v[138:141], v145 offset:17408
	ds_read_b128 v[146:149], v145 offset:18432
	ds_read_b128 v[150:153], v145 offset:19456
	ds_read_b128 v[154:157], v145 offset:20480
	ds_read_b128 v[158:161], v145 offset:21504
	ds_read_b128 v[162:165], v145 offset:22528
	ds_read_b128 v[166:169], v145 offset:23552
	global_load_lds_dwordx4 v[126:127], off
	v_lshl_add_u64 v[126:127], s[70:71], 0, v[32:33]
	s_add_u32 s70, s61, 0x2e290100
	s_mov_b32 m0, s65
	s_addc_u32 s71, s62, 0
	s_add_i32 s66, s47, s66
	global_load_lds_dwordx4 v[126:127], off
	v_lshl_add_u64 v[126:127], s[70:71], 0, v[128:129]
	s_mov_b32 m0, s66
	s_add_i32 s67, s66, 0x2000
	global_load_lds_dwordx4 v[126:127], off
	v_lshl_add_u64 v[126:127], s[70:71], 0, v[32:33]
	s_mov_b32 m0, s67
	s_nop 0
	global_load_lds_dwordx4 v[126:127], off
	v_lshl_add_u64 v[126:127], v[20:21], 0, s[12:13]
	s_mov_b32 m0, s59
	s_nop 0
	global_load_lds_dwordx4 v[126:127], off
	v_lshl_add_u64 v[126:127], v[22:23], 0, s[12:13]
	s_mov_b32 m0, s60
	s_nop 0
	global_load_lds_dwordx4 v[126:127], off
	s_waitcnt vmcnt(8)
	s_waitcnt lgkmcnt(0)
	s_barrier
; #define PG8_STAGE(bufoff, gbase, voff) do { _Pragma("unroll") for (int _i = 0; _i < 2; ++_i) \
;         __builtin_amdgcn_global_load_lds((const unsigned*)((const char*)(gbase) + (voff)[_i]), (PG8_LAS unsigned*)(lds + (bufoff) + ldsw + _i * 8192), 16, 0, 0); } while (0)
; #define PG8_LDA(dst, b, h) do { _Pragma("unroll") for (int m = 0; m < 4; ++m) _Pragma("unroll") for (int k = 0; k < 2; ++k) dst[m][k] = *(const PG8_LAS bf16x8*)(lds + PG8_SA(b, h) + aoff + m * 2048 + k * 1024); } while (0)
; #define PG8_LDB(dst, b, h) do { _Pragma("unroll") for (int n = 0; n < 2; ++n) _Pragma("unroll") for (int k = 0; k < 2; ++k) dst[n][k] = *(const PG8_LAS bf16x8*)(lds + PG8_SB(b, h) + boff + n * 2048 + k * 1024); } while (0)
; #define PG8_MMA(ai, bj, At, Bt) do { __builtin_amdgcn_s_setprio(1); _Pragma("unroll") for (int m = 0; m < 4; ++m) _Pragma("unroll") for (int n = 0; n < 2; ++n) _Pragma("unroll") for (int k = 0; k < 2; ++k) \
;         acc[ai][bj][m][n] = __builtin_amdgcn_mfma_f32_16x16x32_bf16(Bt[n][k], At[m][k], acc[ai][bj][m][n], 0, 0, 0); __builtin_amdgcn_s_setprio(0); } while (0)
; #define PG8_WAIT_V(n) asm volatile("s_waitcnt vmcnt(" #n ")" ::: "memory")
; #define PG8_WAIT_L(n) asm volatile("s_waitcnt lgkmcnt(" #n ")" ::: "memory")
; #define PG8_BAR __builtin_amdgcn_s_barrier()
; #define PG8_SCHED __builtin_amdgcn_sched_barrier(0)
; template <class Epi, class Sched, bool ALIGN_EPI = false, bool SP2 = false>
; __device__ __forceinline__ void gemm_phase(PG8_LAS unsigned char* lds, const Gemm g, const Sched& S, const Epi& E, const int wv0) {
;     ...
;             PG8_WAIT_V(8); PG8_WAIT_L(0); PG8_BAR; PG8_MMA(0, 0, At, B0); PG8_MMA(0, 1, At, B1); PG8_BAR; PG8_SCHED;
;             PG8_LDA(At, 0, 1); PG8_STAGE(PG8_SB(0, 0), b2, voffB); PG8_STAGE(PG8_SB(0, 1), b2 + hstepB, voffB); PG8_STAGE(PG8_SA(0, 0), a2, voffA);
;             PG8_WAIT_V(8); PG8_WAIT_L(0); PG8_BAR; PG8_MMA(1, 0, At, B0); PG8_MMA(1, 1, At, B1); PG8_BAR; PG8_SCHED;
;             PG8_LDB(B0, 1, 0); PG8_LDB(B1, 1, 1); PG8_SCHED; PG8_LDA(At, 1, 0); PG8_STAGE(PG8_SA(0, 1), a2 + hstepA, voffA);
;             PG8_WAIT_V(8); PG8_WAIT_L(0); PG8_BAR; PG8_MMA(0, 0, At, B0); PG8_MMA(0, 1, At, B1); PG8_BAR; PG8_SCHED;
	s_setprio 1
	v_mfma_f32_16x16x32_bf16 v[170:173], v[34:37], v[94:97], 0
	v_mfma_f32_16x16x32_bf16 v[178:181], v[34:37], v[146:149], 0
	v_mfma_f32_16x16x32_bf16 v[186:189], v[34:37], v[154:157], 0
	v_mfma_f32_16x16x32_bf16 v[34:37], v[34:37], v[162:165], 0
	v_mfma_f32_16x16x32_bf16 v[170:173], v[38:41], v[138:141], v[170:173]
	v_mfma_f32_16x16x32_bf16 v[178:181], v[38:41], v[150:153], v[178:181]
	v_mfma_f32_16x16x32_bf16 v[186:189], v[38:41], v[158:161], v[186:189]
	v_mfma_f32_16x16x32_bf16 v[34:37], v[38:41], v[166:169], v[34:37]
	v_mfma_f32_16x16x32_bf16 v[38:41], v[42:45], v[162:165], 0
	v_mfma_f32_16x16x32_bf16 v[174:177], v[42:45], v[94:97], 0
	v_mfma_f32_16x16x32_bf16 v[182:185], v[42:45], v[146:149], 0
	v_mfma_f32_16x16x32_bf16 v[190:193], v[42:45], v[154:157], 0
	v_mfma_f32_16x16x32_bf16 v[38:41], v[46:49], v[166:169], v[38:41]
	v_mfma_f32_16x16x32_bf16 v[174:177], v[46:49], v[138:141], v[174:177]
	v_mfma_f32_16x16x32_bf16 v[182:185], v[46:49], v[150:153], v[182:185]
	v_mfma_f32_16x16x32_bf16 v[190:193], v[46:49], v[158:161], v[190:193]
	v_mfma_f32_16x16x32_bf16 v[42:45], v[50:53], v[94:97], 0
	v_mfma_f32_16x16x32_bf16 v[46:49], v[58:61], v[94:97], 0
	v_mfma_f32_16x16x32_bf16 v[42:45], v[54:57], v[138:141], v[42:45]
	v_mfma_f32_16x16x32_bf16 v[46:49], v[62:65], v[138:141], v[46:49]
	v_mfma_f32_16x16x32_bf16 v[94:97], v[50:53], v[146:149], 0
	v_mfma_f32_16x16x32_bf16 v[138:141], v[58:61], v[146:149], 0
	v_mfma_f32_16x16x32_bf16 v[146:149], v[50:53], v[154:157], 0
	v_mfma_f32_16x16x32_bf16 v[50:53], v[50:53], v[162:165], 0
	v_mfma_f32_16x16x32_bf16 v[94:97], v[54:57], v[150:153], v[94:97]
	v_mfma_f32_16x16x32_bf16 v[146:149], v[54:57], v[158:161], v[146:149]
	v_mfma_f32_16x16x32_bf16 v[50:53], v[54:57], v[166:169], v[50:53]
	v_mfma_f32_16x16x32_bf16 v[54:57], v[58:61], v[162:165], 0
	v_mfma_f32_16x16x32_bf16 v[138:141], v[62:65], v[150:153], v[138:141]
	v_mfma_f32_16x16x32_bf16 v[150:153], v[58:61], v[154:157], 0
	v_mfma_f32_16x16x32_bf16 v[54:57], v[62:65], v[166:169], v[54:57]
	v_mfma_f32_16x16x32_bf16 v[150:153], v[62:65], v[158:161], v[150:153]
	s_setprio 0
	s_barrier
	ds_read_b128 v[58:61], v247
	ds_read_b128 v[62:65], v247 offset:1024
	ds_read_b128 v[154:157], v247 offset:2048
	ds_read_b128 v[158:161], v247 offset:3072
	ds_read_b128 v[162:165], v246
	ds_read_b128 v[166:169], v246 offset:1024
	ds_read_b128 v[194:197], v246 offset:2048
	ds_read_b128 v[198:201], v246 offset:3072
	s_add_u32 s70, s24, 0x40100
	s_addc_u32 s71, s25, 0
	s_mov_b32 m0, s55
	v_lshl_add_u64 v[126:127], s[70:71], 0, v[16:17]
	ds_read_b128 v[206:209], v145 offset:32768
	ds_read_b128 v[210:213], v145 offset:33792
	ds_read_b128 v[214:217], v145 offset:34816
	ds_read_b128 v[218:221], v145 offset:35840
	ds_read_b128 v[222:225], v145 offset:36864
	ds_read_b128 v[226:229], v145 offset:37888
	ds_read_b128 v[230:233], v145 offset:38912
	ds_read_b128 v[234:237], v145 offset:39936
	global_load_lds_dwordx4 v[126:127], off
	v_lshl_add_u64 v[126:127], s[70:71], 0, v[30:31]
	s_mov_b32 m0, s56
	s_nop 0
	global_load_lds_dwordx4 v[126:127], off
	s_waitcnt vmcnt(8)
	s_waitcnt lgkmcnt(0)
	s_barrier
	s_setprio 1
	v_mfma_f32_16x16x32_bf16 v[98:101], v[58:61], v[206:209], v[98:101]
	v_mfma_f32_16x16x32_bf16 v[102:105], v[154:157], v[206:209], v[102:105]
	v_mfma_f32_16x16x32_bf16 v[106:109], v[58:61], v[214:217], v[106:109]
	v_mfma_f32_16x16x32_bf16 v[110:113], v[154:157], v[214:217], v[110:113]
	v_mfma_f32_16x16x32_bf16 v[114:117], v[58:61], v[222:225], v[114:117]
	v_mfma_f32_16x16x32_bf16 v[118:121], v[154:157], v[222:225], v[118:121]
	v_mfma_f32_16x16x32_bf16 v[122:125], v[58:61], v[230:233], v[122:125]
	v_mfma_f32_16x16x32_bf16 v[98:101], v[62:65], v[210:213], v[98:101]
	v_mfma_f32_16x16x32_bf16 v[102:105], v[158:161], v[210:213], v[102:105]
	v_mfma_f32_16x16x32_bf16 v[106:109], v[62:65], v[218:221], v[106:109]
	v_mfma_f32_16x16x32_bf16 v[110:113], v[158:161], v[218:221], v[110:113]
	v_mfma_f32_16x16x32_bf16 v[114:117], v[62:65], v[226:229], v[114:117]
	v_mfma_f32_16x16x32_bf16 v[118:121], v[158:161], v[226:229], v[118:121]
	v_mfma_f32_16x16x32_bf16 v[122:125], v[62:65], v[234:237], v[122:125]
	v_mfma_f32_16x16x32_bf16 v[130:133], v[154:157], v[230:233], v[130:133]
	v_mfma_f32_16x16x32_bf16 v[130:133], v[158:161], v[234:237], v[130:133]
	v_mfma_f32_16x16x32_bf16 v[66:69], v[194:197], v[206:209], v[66:69]
	v_mfma_f32_16x16x32_bf16 v[70:73], v[162:165], v[214:217], v[70:73]
	v_mfma_f32_16x16x32_bf16 v[74:77], v[194:197], v[214:217], v[74:77]
	v_mfma_f32_16x16x32_bf16 v[78:81], v[162:165], v[222:225], v[78:81]
	v_mfma_f32_16x16x32_bf16 v[82:85], v[194:197], v[222:225], v[82:85]
	v_mfma_f32_16x16x32_bf16 v[86:89], v[162:165], v[230:233], v[86:89]
	v_mfma_f32_16x16x32_bf16 v[90:93], v[194:197], v[230:233], v[90:93]
	v_mfma_f32_16x16x32_bf16 v[134:137], v[162:165], v[206:209], v[134:137]
	v_mfma_f32_16x16x32_bf16 v[66:69], v[198:201], v[210:213], v[66:69]
	v_mfma_f32_16x16x32_bf16 v[70:73], v[166:169], v[218:221], v[70:73]
	v_mfma_f32_16x16x32_bf16 v[74:77], v[198:201], v[218:221], v[74:77]
	v_mfma_f32_16x16x32_bf16 v[78:81], v[166:169], v[226:229], v[78:81]
	v_mfma_f32_16x16x32_bf16 v[82:85], v[198:201], v[226:229], v[82:85]
	v_mfma_f32_16x16x32_bf16 v[86:89], v[166:169], v[234:237], v[86:89]
	v_mfma_f32_16x16x32_bf16 v[90:93], v[198:201], v[234:237], v[90:93]
	v_mfma_f32_16x16x32_bf16 v[134:137], v[166:169], v[210:213], v[134:137]
	s_setprio 0
	s_barrier
; #define PG8_STAGE(bufoff, gbase, voff) do { _Pragma("unroll") for (int _i = 0; _i < 2; ++_i) \
;         __builtin_amdgcn_global_load_lds((const unsigned*)((const char*)(gbase) + (voff)[_i]), (PG8_LAS unsigned*)(lds + (bufoff) + ldsw + _i * 8192), 16, 0, 0); } while (0)
; #define PG8_LDA(dst, b, h) do { _Pragma("unroll") for (int m = 0; m < 4; ++m) _Pragma("unroll") for (int k = 0; k < 2; ++k) dst[m][k] = *(const PG8_LAS bf16x8*)(lds + PG8_SA(b, h) + aoff + m * 2048 + k * 1024); } while (0)
; #define PG8_LDB(dst, b, h) do { _Pragma("unroll") for (int n = 0; n < 2; ++n) _Pragma("unroll") for (int k = 0; k < 2; ++k) dst[n][k] = *(const PG8_LAS bf16x8*)(lds + PG8_SB(b, h) + boff + n * 2048 + k * 1024); } while (0)
; #define PG8_MMA(ai, bj, At, Bt) do { __builtin_amdgcn_s_setprio(1); _Pragma("unroll") for (int m = 0; m < 4; ++m) _Pragma("unroll") for (int n = 0; n < 2; ++n) _Pragma("unroll") for (int k = 0; k < 2; ++k) \
;         acc[ai][bj][m][n] = __builtin_amdgcn_mfma_f32_16x16x32_bf16(Bt[n][k], At[m][k], acc[ai][bj][m][n], 0, 0, 0); __builtin_amdgcn_s_setprio(0); } while (0)
; #define PG8_BAR __builtin_amdgcn_s_barrier()
; template <class Epi, class Sched, bool ALIGN_EPI = false, bool SP2 = false>
; __device__ __forceinline__ void gemm_phase(PG8_LAS unsigned char* lds, const Gemm g, const Sched& S, const Epi& E, const int wv0) {
;     ...
;             PG8_LDB(B0, 0, 0); PG8_LDB(B1, 0, 1); PG8_SCHED; PG8_LDA(At, 0, 0); PG8_STAGE(PG8_SA(1, 1), a1 + hstepA, voffA);
;             PG8_WAIT_V(8); PG8_WAIT_L(0); PG8_BAR; PG8_MMA(0, 0, At, B0); PG8_MMA(0, 1, At, B1); PG8_BAR; PG8_SCHED;
;             PG8_LDA(At, 0, 1); PG8_STAGE(PG8_SB(0, 0), b2, voffB); PG8_STAGE(PG8_SB(0, 1), b2 + hstepB, voffB); PG8_STAGE(PG8_SA(0, 0), a2, voffA);
;             PG8_WAIT_V(8); PG8_WAIT_L(0); PG8_BAR; PG8_MMA(1, 0, At, B0); PG8_MMA(1, 1, At, B1); PG8_BAR; PG8_SCHED;
;             PG8_LDB(B0, 1, 0); PG8_LDB(B1, 1, 1); PG8_SCHED; PG8_LDA(At, 1, 0); PG8_STAGE(PG8_SA(0, 1), a2 + hstepA, voffA);
;             PG8_WAIT_V(8); PG8_WAIT_L(0); PG8_BAR; PG8_MMA(0, 0, At, B0); PG8_MMA(0, 1, At, B1); PG8_BAR; PG8_SCHED;
;             PG8_LDA(At, 1, 1); PG8_STAGE(PG8_SB(1, 0), b3, voffB); PG8_STAGE(PG8_SB(1, 1), b3 + hstepB, voffB); PG8_STAGE(PG8_SA(1, 0), a3, voffA);
;             PG8_WAIT_V(8); PG8_WAIT_L(0); PG8_BAR; PG8_MMA(1, 0, At, B0); PG8_MMA(1, 1, At, B1); PG8_BAR; PG8_SCHED;
	s_add_u32 s70, s61, 0x2e280180
	s_addc_u32 s71, s62, 0
	s_mov_b32 m0, s26
	v_lshl_add_u64 v[126:127], s[70:71], 0, v[128:129]
	ds_read_b128 v[206:209], v145 offset:49152
	ds_read_b128 v[210:213], v145 offset:50176
	ds_read_b128 v[214:217], v145 offset:51200
	ds_read_b128 v[218:221], v145 offset:52224
	ds_read_b128 v[222:225], v145 offset:53248
	ds_read_b128 v[226:229], v145 offset:54272
	ds_read_b128 v[230:233], v145 offset:55296
	ds_read_b128 v[234:237], v145 offset:56320
	global_load_lds_dwordx4 v[126:127], off
	v_lshl_add_u64 v[126:127], s[70:71], 0, v[32:33]
	s_add_u32 s70, s61, 0x2e290180
	s_mov_b32 m0, s53
	s_addc_u32 s71, s62, 0
	global_load_lds_dwordx4 v[126:127], off
	v_lshl_add_u64 v[126:127], s[70:71], 0, v[128:129]
	s_mov_b32 m0, s57
	v_lshl_add_u64 v[32:33], s[70:71], 0, v[32:33]
	global_load_lds_dwordx4 v[126:127], off
	s_mov_b32 m0, s58
	s_nop 0
	global_load_lds_dwordx4 v[32:33], off
	v_lshl_add_u64 v[32:33], v[20:21], 0, s[14:15]
	s_mov_b32 m0, s27
	s_nop 0
	global_load_lds_dwordx4 v[32:33], off
	v_lshl_add_u64 v[32:33], v[22:23], 0, s[14:15]
	s_mov_b32 m0, s54
	s_nop 0
	global_load_lds_dwordx4 v[32:33], off
	s_waitcnt vmcnt(8)
	s_waitcnt lgkmcnt(0)
	s_barrier
	s_setprio 1
	v_mfma_f32_16x16x32_bf16 v[32:35], v[58:61], v[230:233], v[34:37]
	v_mfma_f32_16x16x32_bf16 v[36:39], v[154:157], v[230:233], v[38:41]
	v_mfma_f32_16x16x32_bf16 v[170:173], v[58:61], v[206:209], v[170:173]
	v_mfma_f32_16x16x32_bf16 v[174:177], v[154:157], v[206:209], v[174:177]
	v_mfma_f32_16x16x32_bf16 v[178:181], v[58:61], v[214:217], v[178:181]
	v_mfma_f32_16x16x32_bf16 v[182:185], v[154:157], v[214:217], v[182:185]
	v_mfma_f32_16x16x32_bf16 v[186:189], v[58:61], v[222:225], v[186:189]
	v_mfma_f32_16x16x32_bf16 v[190:193], v[154:157], v[222:225], v[190:193]
	v_mfma_f32_16x16x32_bf16 v[32:35], v[62:65], v[234:237], v[32:35]
	v_mfma_f32_16x16x32_bf16 v[36:39], v[158:161], v[234:237], v[36:39]
	v_mfma_f32_16x16x32_bf16 v[170:173], v[62:65], v[210:213], v[170:173]
	v_mfma_f32_16x16x32_bf16 v[174:177], v[158:161], v[210:213], v[174:177]
	v_mfma_f32_16x16x32_bf16 v[178:181], v[62:65], v[218:221], v[178:181]
	v_mfma_f32_16x16x32_bf16 v[182:185], v[158:161], v[218:221], v[182:185]
	v_mfma_f32_16x16x32_bf16 v[186:189], v[62:65], v[226:229], v[186:189]
	v_mfma_f32_16x16x32_bf16 v[190:193], v[158:161], v[226:229], v[190:193]
	v_mfma_f32_16x16x32_bf16 v[40:43], v[162:165], v[206:209], v[42:45]
	v_mfma_f32_16x16x32_bf16 v[44:47], v[194:197], v[206:209], v[46:49]
	v_mfma_f32_16x16x32_bf16 v[58:61], v[162:165], v[214:217], v[94:97]
	v_mfma_f32_16x16x32_bf16 v[62:65], v[194:197], v[214:217], v[138:141]
	v_mfma_f32_16x16x32_bf16 v[94:97], v[162:165], v[222:225], v[146:149]
	v_mfma_f32_16x16x32_bf16 v[48:51], v[162:165], v[230:233], v[50:53]
	v_mfma_f32_16x16x32_bf16 v[52:55], v[194:197], v[230:233], v[54:57]
	v_mfma_f32_16x16x32_bf16 v[40:43], v[166:169], v[210:213], v[40:43]
	v_mfma_f32_16x16x32_bf16 v[44:47], v[198:201], v[210:213], v[44:47]
	v_mfma_f32_16x16x32_bf16 v[58:61], v[166:169], v[218:221], v[58:61]
	v_mfma_f32_16x16x32_bf16 v[62:65], v[198:201], v[218:221], v[62:65]
	v_mfma_f32_16x16x32_bf16 v[94:97], v[166:169], v[226:229], v[94:97]
	v_mfma_f32_16x16x32_bf16 v[138:141], v[194:197], v[222:225], v[150:153]
	v_mfma_f32_16x16x32_bf16 v[48:51], v[166:169], v[234:237], v[48:51]
	v_mfma_f32_16x16x32_bf16 v[52:55], v[198:201], v[234:237], v[52:55]
	v_mfma_f32_16x16x32_bf16 v[138:141], v[198:201], v[226:229], v[138:141]
	s_setprio 0
	s_barrier
	ds_read_b128 v[146:149], v203
	ds_read_b128 v[150:153], v203 offset:1024
	ds_read_b128 v[154:157], v203 offset:2048
	ds_read_b128 v[158:161], v203 offset:3072
	ds_read_b128 v[162:165], v202
	ds_read_b128 v[166:169], v202 offset:1024
	ds_read_b128 v[194:197], v202 offset:2048
	ds_read_b128 v[198:201], v202 offset:3072
	s_add_u32 s24, s24, 0x40180
	s_addc_u32 s25, s25, 0
	s_mov_b32 m0, s68
	v_lshl_add_u64 v[16:17], s[24:25], 0, v[16:17]
	ds_read_b128 v[206:209], v145
	ds_read_b128 v[210:213], v145 offset:1024
	ds_read_b128 v[214:217], v145 offset:2048
	ds_read_b128 v[218:221], v145 offset:3072
	ds_read_b128 v[222:225], v145 offset:4096
	ds_read_b128 v[226:229], v145 offset:5120
	ds_read_b128 v[230:233], v145 offset:6144
	ds_read_b128 v[234:237], v145 offset:7168
	global_load_lds_dwordx4 v[16:17], off
	v_lshl_add_u64 v[16:17], s[24:25], 0, v[30:31]
	s_mov_b32 m0, s63
	s_nop 0
	global_load_lds_dwordx4 v[16:17], off
	s_waitcnt vmcnt(8)
	s_waitcnt lgkmcnt(0)
	s_barrier
	s_setprio 1
	v_mfma_f32_16x16x32_bf16 v[114:117], v[146:149], v[222:225], v[114:117]
	v_mfma_f32_16x16x32_bf16 v[238:241], v[150:153], v[226:229], v[114:117]
	v_mfma_f32_16x16x32_bf16 v[114:117], v[154:157], v[222:225], v[118:121]
	v_mfma_f32_16x16x32_bf16 v[98:101], v[146:149], v[206:209], v[98:101]
	v_mfma_f32_16x16x32_bf16 v[102:105], v[154:157], v[206:209], v[102:105]
	v_mfma_f32_16x16x32_bf16 v[106:109], v[146:149], v[214:217], v[106:109]
	v_mfma_f32_16x16x32_bf16 v[110:113], v[154:157], v[214:217], v[110:113]
	v_mfma_f32_16x16x32_bf16 v[242:245], v[158:161], v[226:229], v[114:117]
	v_mfma_f32_16x16x32_bf16 v[114:117], v[146:149], v[230:233], v[122:125]
	v_mfma_f32_16x16x32_bf16 v[98:101], v[150:153], v[210:213], v[98:101]
	v_mfma_f32_16x16x32_bf16 v[102:105], v[158:161], v[210:213], v[102:105]
	v_mfma_f32_16x16x32_bf16 v[106:109], v[150:153], v[218:221], v[106:109]
	v_mfma_f32_16x16x32_bf16 v[110:113], v[158:161], v[218:221], v[110:113]
	v_mfma_f32_16x16x32_bf16 v[124:127], v[150:153], v[234:237], v[114:117]
	v_mfma_f32_16x16x32_bf16 v[114:117], v[154:157], v[230:233], v[130:133]
	v_mfma_f32_16x16x32_bf16 v[130:133], v[158:161], v[234:237], v[114:117]
	v_mfma_f32_16x16x32_bf16 v[66:69], v[194:197], v[206:209], v[66:69]
	v_mfma_f32_16x16x32_bf16 v[114:117], v[162:165], v[206:209], v[134:137]
	v_mfma_f32_16x16x32_bf16 v[206:209], v[198:201], v[210:213], v[66:69]
	v_mfma_f32_16x16x32_bf16 v[66:69], v[162:165], v[214:217], v[70:73]
	v_mfma_f32_16x16x32_bf16 v[134:137], v[166:169], v[210:213], v[114:117]
	v_mfma_f32_16x16x32_bf16 v[210:213], v[166:169], v[218:221], v[66:69]
	v_mfma_f32_16x16x32_bf16 v[66:69], v[194:197], v[214:217], v[74:77]
	v_mfma_f32_16x16x32_bf16 v[214:217], v[198:201], v[218:221], v[66:69]
	v_mfma_f32_16x16x32_bf16 v[66:69], v[162:165], v[222:225], v[78:81]
	v_mfma_f32_16x16x32_bf16 v[76:79], v[166:169], v[226:229], v[66:69]
	v_mfma_f32_16x16x32_bf16 v[66:69], v[194:197], v[222:225], v[82:85]
	v_mfma_f32_16x16x32_bf16 v[80:83], v[198:201], v[226:229], v[66:69]
	v_mfma_f32_16x16x32_bf16 v[66:69], v[162:165], v[230:233], v[86:89]
	v_mfma_f32_16x16x32_bf16 v[218:221], v[166:169], v[234:237], v[66:69]
	v_mfma_f32_16x16x32_bf16 v[66:69], v[194:197], v[230:233], v[90:93]
	v_mfma_f32_16x16x32_bf16 v[222:225], v[198:201], v[234:237], v[66:69]
	s_setprio 0
	s_barrier
; #define PG8_STAGE(bufoff, gbase, voff) do { _Pragma("unroll") for (int _i = 0; _i < 2; ++_i) \
;         __builtin_amdgcn_global_load_lds((const unsigned*)((const char*)(gbase) + (voff)[_i]), (PG8_LAS unsigned*)(lds + (bufoff) + ldsw + _i * 8192), 16, 0, 0); } while (0)
; #define PG8_LDA(dst, b, h) do { _Pragma("unroll") for (int m = 0; m < 4; ++m) _Pragma("unroll") for (int k = 0; k < 2; ++k) dst[m][k] = *(const PG8_LAS bf16x8*)(lds + PG8_SA(b, h) + aoff + m * 2048 + k * 1024); } while (0)
; #define PG8_LDB(dst, b, h) do { _Pragma("unroll") for (int n = 0; n < 2; ++n) _Pragma("unroll") for (int k = 0; k < 2; ++k) dst[n][k] = *(const PG8_LAS bf16x8*)(lds + PG8_SB(b, h) + boff + n * 2048 + k * 1024); } while (0)
; #define PG8_MMA(ai, bj, At, Bt) do { __builtin_amdgcn_s_setprio(1); _Pragma("unroll") for (int m = 0; m < 4; ++m) _Pragma("unroll") for (int n = 0; n < 2; ++n) _Pragma("unroll") for (int k = 0; k < 2; ++k) \
;         acc[ai][bj][m][n] = __builtin_amdgcn_mfma_f32_16x16x32_bf16(Bt[n][k], At[m][k], acc[ai][bj][m][n], 0, 0, 0); __builtin_amdgcn_s_setprio(0); } while (0)
; #define PG8_WAIT_V(n) asm volatile("s_waitcnt vmcnt(" #n ")" ::: "memory")
; #define PG8_WAIT_L(n) asm volatile("s_waitcnt lgkmcnt(" #n ")" ::: "memory")
; #define PG8_BAR __builtin_amdgcn_s_barrier()
; #define PG8_SCHED __builtin_amdgcn_sched_barrier(0)
; template <class Epi, class Sched, bool ALIGN_EPI = false, bool SP2 = false>
; __device__ __forceinline__ void gemm_phase(PG8_LAS unsigned char* lds, const Gemm g, const Sched& S, const Epi& E, const int wv0) {
;     ...
;             PG8_LDA(At, 0, 1); PG8_STAGE(PG8_SB(0, 0), b2, voffB); PG8_STAGE(PG8_SB(0, 1), b2 + hstepB, voffB); PG8_STAGE(PG8_SA(0, 0), a2, voffA);
;             PG8_WAIT_V(8); PG8_WAIT_L(0); PG8_BAR; PG8_MMA(1, 0, At, B0); PG8_MMA(1, 1, At, B1); PG8_BAR; PG8_SCHED;
;             PG8_LDB(B0, 1, 0); PG8_LDB(B1, 1, 1); PG8_SCHED; PG8_LDA(At, 1, 0); PG8_STAGE(PG8_SA(0, 1), a2 + hstepA, voffA);
;             PG8_WAIT_V(8); PG8_WAIT_L(0); PG8_BAR; PG8_MMA(0, 0, At, B0); PG8_MMA(0, 1, At, B1); PG8_BAR; PG8_SCHED;
	s_mov_b32 m0, s64
	s_nop 3
	ds_read_b128 v[66:69], v145 offset:16384
	ds_read_b128 v[70:73], v145 offset:17408
	ds_read_b128 v[84:87], v145 offset:18432
	ds_read_b128 v[88:91], v145 offset:19456
	ds_read_b128 v[114:117], v145 offset:20480
	ds_read_b128 v[118:121], v145 offset:21504
	ds_read_b128 v[226:229], v145 offset:22528
	ds_read_b128 v[230:233], v145 offset:23552
	global_load_lds_dwordx4 v[26:27], off
	s_mov_b32 m0, s65
	s_nop 0
	global_load_lds_dwordx4 v[28:29], off
	s_mov_b32 m0, s66
	s_nop 0
	global_load_lds_dwordx4 v[24:25], off
	s_mov_b32 m0, s67
	s_nop 0
	global_load_lds_dwordx4 v[18:19], off
	s_mov_b32 m0, s59
	s_nop 0
	global_load_lds_dwordx4 v[20:21], off
	s_mov_b32 m0, s60
	s_nop 0
	global_load_lds_dwordx4 v[22:23], off
	s_waitcnt vmcnt(8)
	s_waitcnt lgkmcnt(0)
	s_barrier
	s_setprio 1
	v_mfma_f32_16x16x32_bf16 v[16:19], v[146:149], v[66:69], v[170:173]
	v_mfma_f32_16x16x32_bf16 v[20:23], v[154:157], v[66:69], v[174:177]
	v_mfma_f32_16x16x32_bf16 v[24:27], v[146:149], v[84:87], v[178:181]
	v_mfma_f32_16x16x32_bf16 v[28:31], v[154:157], v[84:87], v[182:185]
	v_mfma_f32_16x16x32_bf16 v[32:35], v[146:149], v[226:229], v[32:35]
	v_mfma_f32_16x16x32_bf16 v[16:19], v[150:153], v[70:73], v[16:19]
	v_mfma_f32_16x16x32_bf16 v[20:23], v[158:161], v[70:73], v[20:23]
	v_mfma_f32_16x16x32_bf16 v[24:27], v[150:153], v[88:91], v[24:27]
	v_mfma_f32_16x16x32_bf16 v[28:31], v[158:161], v[88:91], v[28:31]
	v_mfma_f32_16x16x32_bf16 v[170:173], v[146:149], v[114:117], v[186:189]
	v_mfma_f32_16x16x32_bf16 v[174:177], v[154:157], v[114:117], v[190:193]
	v_mfma_f32_16x16x32_bf16 v[32:35], v[150:153], v[230:233], v[32:35]
	v_mfma_f32_16x16x32_bf16 v[36:39], v[154:157], v[226:229], v[36:39]
	v_mfma_f32_16x16x32_bf16 v[170:173], v[150:153], v[118:121], v[170:173]
	v_mfma_f32_16x16x32_bf16 v[174:177], v[158:161], v[118:121], v[174:177]
	v_mfma_f32_16x16x32_bf16 v[146:149], v[158:161], v[230:233], v[36:39]
	v_mfma_f32_16x16x32_bf16 v[36:39], v[162:165], v[66:69], v[40:43]
	v_mfma_f32_16x16x32_bf16 v[150:153], v[166:169], v[70:73], v[36:39]
	v_mfma_f32_16x16x32_bf16 v[36:39], v[194:197], v[66:69], v[44:47]
	v_mfma_f32_16x16x32_bf16 v[44:47], v[198:201], v[70:73], v[36:39]
	v_mfma_f32_16x16x32_bf16 v[36:39], v[162:165], v[84:87], v[58:61]
	v_mfma_f32_16x16x32_bf16 v[154:157], v[166:169], v[88:91], v[36:39]
	v_mfma_f32_16x16x32_bf16 v[36:39], v[194:197], v[84:87], v[62:65]
	v_mfma_f32_16x16x32_bf16 v[158:161], v[198:201], v[88:91], v[36:39]
	v_mfma_f32_16x16x32_bf16 v[36:39], v[162:165], v[114:117], v[94:97]
	v_mfma_f32_16x16x32_bf16 v[178:181], v[166:169], v[118:121], v[36:39]
	v_mfma_f32_16x16x32_bf16 v[36:39], v[194:197], v[114:117], v[138:141]
	v_mfma_f32_16x16x32_bf16 v[138:141], v[198:201], v[118:121], v[36:39]
	v_mfma_f32_16x16x32_bf16 v[36:39], v[162:165], v[226:229], v[48:51]
	v_mfma_f32_16x16x32_bf16 v[162:165], v[166:169], v[230:233], v[36:39]
	v_mfma_f32_16x16x32_bf16 v[36:39], v[194:197], v[226:229], v[52:55]
	v_mfma_f32_16x16x32_bf16 v[166:169], v[198:201], v[230:233], v[36:39]
	s_setprio 0
	s_barrier
	ds_read_b128 v[48:51], v247
	ds_read_b128 v[64:67], v247 offset:1024
	ds_read_b128 v[182:185], v247 offset:2048
	ds_read_b128 v[186:189], v247 offset:3072
	ds_read_b128 v[190:193], v246
	ds_read_b128 v[194:197], v246 offset:1024
	ds_read_b128 v[198:201], v246 offset:2048
	ds_read_b128 v[226:229], v246 offset:3072
	s_mov_b32 m0, s55
	ds_read_b128 v[36:39], v145 offset:32768
	ds_read_b128 v[40:43], v145 offset:33792
	ds_read_b128 v[52:55], v145 offset:34816
	ds_read_b128 v[56:59], v145 offset:35840
	ds_read_b128 v[60:63], v145 offset:36864
	ds_read_b128 v[230:233], v145 offset:37888
	ds_read_b128 v[234:237], v145 offset:38912
	ds_read_b128 v[246:249], v145 offset:39936
	global_load_lds_dwordx4 v[12:13], off
	s_mov_b32 m0, s56
	s_nop 0
	global_load_lds_dwordx4 v[14:15], off
	s_waitcnt vmcnt(8)
	s_waitcnt lgkmcnt(0)
	s_barrier
; #define PG8_STAGE(bufoff, gbase, voff) do { _Pragma("unroll") for (int _i = 0; _i < 2; ++_i) \
;         __builtin_amdgcn_global_load_lds((const unsigned*)((const char*)(gbase) + (voff)[_i]), (PG8_LAS unsigned*)(lds + (bufoff) + ldsw + _i * 8192), 16, 0, 0); } while (0)
; #define PG8_LDA(dst, b, h) do { _Pragma("unroll") for (int m = 0; m < 4; ++m) _Pragma("unroll") for (int k = 0; k < 2; ++k) dst[m][k] = *(const PG8_LAS bf16x8*)(lds + PG8_SA(b, h) + aoff + m * 2048 + k * 1024); } while (0)
; #define PG8_MMA(ai, bj, At, Bt) do { __builtin_amdgcn_s_setprio(1); _Pragma("unroll") for (int m = 0; m < 4; ++m) _Pragma("unroll") for (int n = 0; n < 2; ++n) _Pragma("unroll") for (int k = 0; k < 2; ++k) \
;         acc[ai][bj][m][n] = __builtin_amdgcn_mfma_f32_16x16x32_bf16(Bt[n][k], At[m][k], acc[ai][bj][m][n], 0, 0, 0); __builtin_amdgcn_s_setprio(0); } while (0)
; #define PG8_WAIT_V(n) asm volatile("s_waitcnt vmcnt(" #n ")" ::: "memory")
; #define PG8_WAIT_L(n) asm volatile("s_waitcnt lgkmcnt(" #n ")" ::: "memory")
; #define PG8_BAR __builtin_amdgcn_s_barrier()
; #define PG8_SCHED __builtin_amdgcn_sched_barrier(0)
; template <class Epi, class Sched, bool ALIGN_EPI = false, bool SP2 = false>
; __device__ __forceinline__ void gemm_phase(PG8_LAS unsigned char* lds, const Gemm g, const Sched& S, const Epi& E, const int wv0) {
;     ...
;             PG8_WAIT_V(8); PG8_WAIT_L(0); PG8_BAR; PG8_MMA(0, 0, At, B0); PG8_MMA(0, 1, At, B1); PG8_BAR; PG8_SCHED;
;             PG8_LDA(At, 1, 1); PG8_STAGE(PG8_SB(1, 0), b3, voffB); PG8_STAGE(PG8_SB(1, 1), b3 + hstepB, voffB); PG8_STAGE(PG8_SA(1, 0), a3, voffA);
;             PG8_WAIT_V(8); PG8_WAIT_L(0); PG8_BAR; PG8_MMA(1, 0, At, B0); PG8_MMA(1, 1, At, B1); PG8_BAR; PG8_SCHED;
;     ...
;     PG8_WAIT_V(0);
;     if constexpr (!ALIGN_EPI) { if (wr == 0) PG8_BAR; }
;     PG8_BAR;
	s_setprio 1
	v_mfma_f32_16x16x32_bf16 v[12:15], v[48:51], v[36:39], v[98:101]
	v_mfma_f32_16x16x32_bf16 v[120:123], v[64:67], v[40:43], v[12:15]
	v_mfma_f32_16x16x32_bf16 v[12:15], v[182:185], v[36:39], v[102:105]
	v_mfma_f32_16x16x32_bf16 v[116:119], v[186:189], v[40:43], v[12:15]
	v_mfma_f32_16x16x32_bf16 v[12:15], v[48:51], v[52:55], v[106:109]
	v_mfma_f32_16x16x32_bf16 v[104:107], v[64:67], v[56:59], v[12:15]
	v_mfma_f32_16x16x32_bf16 v[12:15], v[182:185], v[52:55], v[110:113]
	v_mfma_f32_16x16x32_bf16 v[100:103], v[186:189], v[56:59], v[12:15]
	v_mfma_f32_16x16x32_bf16 v[12:15], v[48:51], v[60:63], v[238:241]
	v_mfma_f32_16x16x32_bf16 v[88:91], v[64:67], v[230:233], v[12:15]
	v_mfma_f32_16x16x32_bf16 v[12:15], v[182:185], v[60:63], v[242:245]
	v_mfma_f32_16x16x32_bf16 v[84:87], v[186:189], v[230:233], v[12:15]
	v_mfma_f32_16x16x32_bf16 v[12:15], v[48:51], v[234:237], v[124:127]
	v_mfma_f32_16x16x32_bf16 v[72:75], v[64:67], v[246:249], v[12:15]
	v_mfma_f32_16x16x32_bf16 v[12:15], v[182:185], v[234:237], v[130:133]
	v_mfma_f32_16x16x32_bf16 v[68:71], v[186:189], v[246:249], v[12:15]
	v_mfma_f32_16x16x32_bf16 v[12:15], v[190:193], v[36:39], v[134:137]
	v_mfma_f32_16x16x32_bf16 v[124:127], v[194:197], v[40:43], v[12:15]
	v_mfma_f32_16x16x32_bf16 v[12:15], v[198:201], v[36:39], v[206:209]
	v_mfma_f32_16x16x32_bf16 v[112:115], v[226:229], v[40:43], v[12:15]
	v_mfma_f32_16x16x32_bf16 v[12:15], v[190:193], v[52:55], v[210:213]
	v_mfma_f32_16x16x32_bf16 v[108:111], v[194:197], v[56:59], v[12:15]
	v_mfma_f32_16x16x32_bf16 v[12:15], v[198:201], v[52:55], v[214:217]
	v_mfma_f32_16x16x32_bf16 v[96:99], v[226:229], v[56:59], v[12:15]
	v_mfma_f32_16x16x32_bf16 v[12:15], v[190:193], v[60:63], v[76:79]
	v_mfma_f32_16x16x32_bf16 v[92:95], v[194:197], v[230:233], v[12:15]
	v_mfma_f32_16x16x32_bf16 v[12:15], v[198:201], v[60:63], v[80:83]
	v_mfma_f32_16x16x32_bf16 v[80:83], v[226:229], v[230:233], v[12:15]
	v_mfma_f32_16x16x32_bf16 v[12:15], v[190:193], v[234:237], v[218:221]
	v_mfma_f32_16x16x32_bf16 v[76:79], v[194:197], v[246:249], v[12:15]
	v_mfma_f32_16x16x32_bf16 v[12:15], v[198:201], v[234:237], v[222:225]
	v_mfma_f32_16x16x32_bf16 v[56:59], v[226:229], v[246:249], v[12:15]
	s_setprio 0
	s_barrier
	s_mov_b32 m0, s26
	s_nop 3
	ds_read_b128 v[12:15], v145 offset:49152
	ds_read_b128 v[130:133], v145 offset:50176
	ds_read_b128 v[134:137], v145 offset:51200
	ds_read_b128 v[206:209], v145 offset:52224
	ds_read_b128 v[210:213], v145 offset:53248
	ds_read_b128 v[214:217], v145 offset:54272
	ds_read_b128 v[218:221], v145 offset:55296
	ds_read_b128 v[222:225], v145 offset:56320
	global_load_lds_dwordx4 v[2:3], off
	s_mov_b32 m0, s53
	s_nop 0
	global_load_lds_dwordx4 v[4:5], off
	s_mov_b32 m0, s57
	s_nop 0
	global_load_lds_dwordx4 v[8:9], off
	s_mov_b32 m0, s58
	s_nop 0
	global_load_lds_dwordx4 v[10:11], off
	s_mov_b32 m0, s27
	s_nop 0
	global_load_lds_dwordx4 v[0:1], off
	s_mov_b32 m0, s54
	s_nop 0
	global_load_lds_dwordx4 v[6:7], off
	s_waitcnt vmcnt(8)
	s_waitcnt lgkmcnt(0)
	s_barrier
	s_setprio 1
	v_mfma_f32_16x16x32_bf16 v[0:3], v[48:51], v[12:15], v[16:19]
	v_mfma_f32_16x16x32_bf16 v[60:63], v[64:67], v[130:133], v[0:3]
	v_mfma_f32_16x16x32_bf16 v[0:3], v[182:185], v[12:15], v[20:23]
	v_mfma_f32_16x16x32_bf16 v[52:55], v[186:189], v[130:133], v[0:3]
	v_mfma_f32_16x16x32_bf16 v[0:3], v[48:51], v[134:137], v[24:27]
	v_mfma_f32_16x16x32_bf16 v[40:43], v[64:67], v[206:209], v[0:3]
	v_mfma_f32_16x16x32_bf16 v[0:3], v[182:185], v[134:137], v[28:31]
	v_mfma_f32_16x16x32_bf16 v[36:39], v[186:189], v[206:209], v[0:3]
	v_mfma_f32_16x16x32_bf16 v[0:3], v[48:51], v[210:213], v[170:173]
	v_mfma_f32_16x16x32_bf16 v[24:27], v[64:67], v[214:217], v[0:3]
	v_mfma_f32_16x16x32_bf16 v[0:3], v[182:185], v[210:213], v[174:177]
	v_mfma_f32_16x16x32_bf16 v[20:23], v[186:189], v[214:217], v[0:3]
	v_mfma_f32_16x16x32_bf16 v[0:3], v[48:51], v[218:221], v[32:35]
	v_mfma_f32_16x16x32_bf16 v[8:11], v[64:67], v[222:225], v[0:3]
	v_mfma_f32_16x16x32_bf16 v[0:3], v[182:185], v[218:221], v[146:149]
	v_mfma_f32_16x16x32_bf16 v[4:7], v[186:189], v[222:225], v[0:3]
	v_mfma_f32_16x16x32_bf16 v[0:3], v[190:193], v[12:15], v[150:153]
	v_mfma_f32_16x16x32_bf16 v[64:67], v[194:197], v[130:133], v[0:3]
	v_mfma_f32_16x16x32_bf16 v[0:3], v[198:201], v[12:15], v[44:47]
	v_mfma_f32_16x16x32_bf16 v[48:51], v[226:229], v[130:133], v[0:3]
	v_mfma_f32_16x16x32_bf16 v[0:3], v[190:193], v[134:137], v[154:157]
	v_mfma_f32_16x16x32_bf16 v[44:47], v[194:197], v[206:209], v[0:3]
	v_mfma_f32_16x16x32_bf16 v[0:3], v[198:201], v[134:137], v[158:161]
	v_mfma_f32_16x16x32_bf16 v[32:35], v[226:229], v[206:209], v[0:3]
	v_mfma_f32_16x16x32_bf16 v[0:3], v[190:193], v[210:213], v[178:181]
	v_mfma_f32_16x16x32_bf16 v[28:31], v[194:197], v[214:217], v[0:3]
	v_mfma_f32_16x16x32_bf16 v[0:3], v[198:201], v[210:213], v[138:141]
	v_mfma_f32_16x16x32_bf16 v[16:19], v[226:229], v[214:217], v[0:3]
	v_mfma_f32_16x16x32_bf16 v[0:3], v[190:193], v[218:221], v[162:165]
	v_mfma_f32_16x16x32_bf16 v[12:15], v[194:197], v[222:225], v[0:3]
	v_mfma_f32_16x16x32_bf16 v[0:3], v[198:201], v[218:221], v[166:169]
	v_mfma_f32_16x16x32_bf16 v[0:3], v[226:229], v[222:225], v[0:3]
	s_setprio 0
	s_barrier
	s_waitcnt vmcnt(0)
	s_cmpk_gt_u32 s52, 0xff
	s_cbranch_scc1 .LBB0_1301
	s_barrier

;     __device__ __forceinline__ bool next(int i, Unit& u) const { int pm, pn; if (!to.get((long)i * G + c, pm, pn)) return false; u.pm = pm; u.pn = pn; u.aux = 0; u.a = A + (size_t)pm * ta; u.b = B + (size_t)pn * tb; return true; }
;     __device__ __forceinline__ bool next(int i, Unit& u) const { if (i != 0) return false; u = one; return true; }
; #define PG8_STAGE(bufoff, gbase, voff) do { _Pragma("unroll") for (int _i = 0; _i < 2; ++_i) \
;         __builtin_amdgcn_global_load_lds((const unsigned*)((const char*)(gbase) + (voff)[_i]), (PG8_LAS unsigned*)(lds + (bufoff) + ldsw + _i * 8192), 16, 0, 0); } while (0)
; #define PG8_WAIT_V(n) asm volatile("s_waitcnt vmcnt(" #n ")" ::: "memory")
; #define PG8_BAR __builtin_amdgcn_s_barrier()
; template <class Epi, class Sched, bool ALIGN_EPI = false, bool SP2 = false>
; __device__ __forceinline__ void gemm_phase(PG8_LAS unsigned char* lds, const Gemm g, const Sched& S, const Epi& E, const int wv0) {
;     ...
;         PG8_STAGE(PG8_SB(1, 0), cB + kstep, voffB); PG8_STAGE(PG8_SA(1, 0), cA + kstep, voffA); PG8_STAGE(PG8_SB(1, 1), cB + hstepB + kstep, voffB);
;         PG8_WAIT_V(6); PG8_BAR;
;     } else {
;         PG8_STAGE(PG8_SB(0, 0), cB, voffB); PG8_STAGE(PG8_SA(0, 0), cA, voffA); PG8_STAGE(PG8_SB(0, 1), cB + hstepB, voffB); PG8_STAGE(PG8_SA(0, 1), cA + hstepA, voffA);
;         if (wr == 1) PG8_BAR;
;         PG8_WAIT_V(4); PG8_BAR;
;         PG8_STAGE(PG8_SB(1, 0), cB + kstep, voffB); PG8_STAGE(PG8_SA(1, 0), cA + kstep, voffA); PG8_STAGE(PG8_SB(1, 1), cB + hstepB + kstep, voffB);
;         PG8_WAIT_V(6); PG8_BAR;
;     }
;     for (;;) {
;         const bool has_next = S.next(ui + 1, nxt);
;         const char* nA = has_next ? nxt.a : cA; const char* nB = has_next ? nxt.b : cB;
;         for (int t = 0; t < nt; t += 2) {
;             const bool last = (t == nt - 2);
;             const char* a1 = cA + (size_t)(t + 1) * kstep;
;             const char* a2 = last ? nA : cA + (size_t)(t + 2) * kstep; const char* b2 = last ? nB : cB + (size_t)(t + 2) * kstep;
;             const char* a3 = a2 + kstep; const char* b3 = b2 + kstep;
;             if constexpr (SP2) {
;             PG8_LDB(B0, 0, 0); PG8_LDB(B1, 0, 1); PG8_SCHED; PG8_LDA(At, 0, 0); PG8_STAGE(PG8_SA(1, 1), a1 + hstepA, voffA);
;             PG8_WAIT_V(8); PG8_WAIT_L(0); PG8_BAR; PG8_MMA(0, 0, At, B0); PG8_MMA(0, 1, At, B1); PG8_BAR; PG8_SCHED;
.LBB0_1319:
	s_lshl_b32 s50, s50, 5
	s_add_i32 s51, s36, s63
	s_and_b32 s50, s50, 0x60
	v_lshl_add_u64 v[2:3], v[26:27], 0, s[10:11]
	s_mov_b32 m0, s51
	s_add_i32 s53, s51, 0x2000
	s_lshl_b32 s62, s61, 13
	s_lshl_b32 s66, s50, 7
	s_waitcnt vmcnt(2)
	s_barrier
	global_load_lds_dwordx4 v[2:3], off
	v_lshl_add_u64 v[4:5], v[28:29], 0, s[10:11]
	s_mov_b32 m0, s53
	s_add_i32 s52, s59, 0x8000
	s_add_i32 s54, s59, 0xa000
	global_load_lds_dwordx4 v[4:5], off
	v_lshl_add_u64 v[0:1], v[20:21], 0, s[10:11]
	s_mov_b32 m0, s52
	s_add_u32 s64, s24, 0x10080
	global_load_lds_dwordx4 v[0:1], off
	v_lshl_add_u64 v[6:7], v[22:23], 0, s[10:11]
	s_mov_b32 m0, s54
	s_addc_u32 s65, s25, 0
	s_add_i32 s57, s37, s63
	global_load_lds_dwordx4 v[6:7], off
	v_lshl_add_u64 v[8:9], s[64:65], 0, v[128:129]
	s_mov_b32 m0, s57
	s_add_i32 s58, s57, 0x2000
	global_load_lds_dwordx4 v[8:9], off
	v_lshl_add_u64 v[10:11], s[64:65], 0, v[32:33]
	s_mov_b32 m0, s58
	v_lshrrev_b32_e32 v37, 1, v34
	global_load_lds_dwordx4 v[10:11], off
	v_and_b32_e32 v37, 24, v37
	v_and_b32_e32 v35, 15, v34
	v_lshlrev_b32_e32 v38, 1, v37
	v_lshlrev_b32_e32 v34, 2, v34
	v_lshl_or_b32 v36, s61, 6, v35
	v_lshl_or_b32 v35, v35, 6, v38
	v_and_b32_e32 v34, 32, v34
	v_bitop3_b32 v70, v35, s66, v34 bitop3:0xde
	v_add_u32_e32 v127, s48, v70
	s_waitcnt vmcnt(6)
	s_barrier
	v_add_u32_e32 v126, s47, v70
	ds_read_b128 v[38:41], v127
	ds_read_b128 v[42:45], v127 offset:1024
	ds_read_b128 v[46:49], v127 offset:2048
	ds_read_b128 v[50:53], v127 offset:3072
	ds_read_b128 v[54:57], v126
	ds_read_b128 v[58:61], v126 offset:1024
	ds_read_b128 v[62:65], v126 offset:2048
	ds_read_b128 v[66:69], v126 offset:3072
	v_bitop3_b32 v34, v35, s62, v34 bitop3:0xde
	v_add_u32_e32 v143, 0, v34
	v_add_u32_e32 v238, s37, v70
	v_add_u32_e32 v239, s36, v70
	s_add_u32 s66, s22, 0x40080
	s_addc_u32 s67, s23, 0
	s_add_i32 s64, s59, 0xc000
	v_lshl_add_u64 v[34:35], s[66:67], 0, v[16:17]
	s_mov_b32 m0, s64
	s_add_i32 s61, s59, 0xe000
	ds_read_b128 v[70:73], v143
	ds_read_b128 v[74:77], v143 offset:1024
	ds_read_b128 v[78:81], v143 offset:2048
	ds_read_b128 v[82:85], v143 offset:3072
	ds_read_b128 v[86:89], v143 offset:4096
	ds_read_b128 v[90:93], v143 offset:5120
	ds_read_b128 v[94:97], v143 offset:6144
	ds_read_b128 v[98:101], v143 offset:7168
	global_load_lds_dwordx4 v[34:35], off
	v_lshl_add_u64 v[34:35], s[66:67], 0, v[30:31]
	s_mov_b32 m0, s61
	s_nop 0
	global_load_lds_dwordx4 v[34:35], off
	s_waitcnt vmcnt(8)
	s_waitcnt lgkmcnt(0)
	s_barrier
	s_setprio 1
	v_mfma_f32_16x16x32_bf16 v[102:105], v[38:41], v[70:73], 0
	v_mfma_f32_16x16x32_bf16 v[106:109], v[46:49], v[70:73], 0
	v_mfma_f32_16x16x32_bf16 v[110:113], v[38:41], v[78:81], 0
	v_mfma_f32_16x16x32_bf16 v[114:117], v[46:49], v[78:81], 0
	v_mfma_f32_16x16x32_bf16 v[118:121], v[38:41], v[86:89], 0
	v_mfma_f32_16x16x32_bf16 v[122:125], v[46:49], v[86:89], 0
	v_mfma_f32_16x16x32_bf16 v[130:133], v[38:41], v[94:97], 0
	v_mfma_f32_16x16x32_bf16 v[134:137], v[46:49], v[94:97], 0
	v_mfma_f32_16x16x32_bf16 v[102:105], v[42:45], v[74:77], v[102:105]
	v_mfma_f32_16x16x32_bf16 v[106:109], v[50:53], v[74:77], v[106:109]
	v_mfma_f32_16x16x32_bf16 v[110:113], v[42:45], v[82:85], v[110:113]
	v_mfma_f32_16x16x32_bf16 v[114:117], v[50:53], v[82:85], v[114:117]
	v_mfma_f32_16x16x32_bf16 v[118:121], v[42:45], v[90:93], v[118:121]
	v_mfma_f32_16x16x32_bf16 v[122:125], v[50:53], v[90:93], v[122:125]
	v_mfma_f32_16x16x32_bf16 v[130:133], v[42:45], v[98:101], v[130:133]
	v_mfma_f32_16x16x32_bf16 v[134:137], v[50:53], v[98:101], v[134:137]
	v_mfma_f32_16x16x32_bf16 v[138:141], v[54:57], v[70:73], 0
	v_mfma_f32_16x16x32_bf16 v[70:73], v[62:65], v[70:73], 0
	v_mfma_f32_16x16x32_bf16 v[138:141], v[58:61], v[74:77], v[138:141]
	v_mfma_f32_16x16x32_bf16 v[70:73], v[66:69], v[74:77], v[70:73]
	v_mfma_f32_16x16x32_bf16 v[74:77], v[54:57], v[78:81], 0
	v_mfma_f32_16x16x32_bf16 v[78:81], v[62:65], v[78:81], 0
	v_mfma_f32_16x16x32_bf16 v[74:77], v[58:61], v[82:85], v[74:77]
	v_mfma_f32_16x16x32_bf16 v[78:81], v[66:69], v[82:85], v[78:81]
	v_mfma_f32_16x16x32_bf16 v[82:85], v[54:57], v[86:89], 0
	v_mfma_f32_16x16x32_bf16 v[86:89], v[62:65], v[86:89], 0
	v_mfma_f32_16x16x32_bf16 v[82:85], v[58:61], v[90:93], v[82:85]
	v_mfma_f32_16x16x32_bf16 v[86:89], v[66:69], v[90:93], v[86:89]
	v_mfma_f32_16x16x32_bf16 v[90:93], v[54:57], v[94:97], 0
	v_mfma_f32_16x16x32_bf16 v[94:97], v[62:65], v[94:97], 0
	v_mfma_f32_16x16x32_bf16 v[90:93], v[58:61], v[98:101], v[90:93]
	v_mfma_f32_16x16x32_bf16 v[94:97], v[66:69], v[98:101], v[94:97]
	s_setprio 0
	s_barrier
	s_add_i32 s48, s48, s63
	s_add_i32 s62, s48, 0x2000
	v_lshl_add_u64 v[34:35], v[26:27], 0, s[12:13]
	s_mov_b32 m0, s48
	s_add_u32 s66, s24, 0x10100
	ds_read_b128 v[98:101], v143 offset:16384
	ds_read_b128 v[144:147], v143 offset:17408
	ds_read_b128 v[148:151], v143 offset:18432
	ds_read_b128 v[152:155], v143 offset:19456
	ds_read_b128 v[156:159], v143 offset:20480
	ds_read_b128 v[160:163], v143 offset:21504
	ds_read_b128 v[164:167], v143 offset:22528
	ds_read_b128 v[168:171], v143 offset:23552
	global_load_lds_dwordx4 v[34:35], off
	v_lshl_add_u64 v[34:35], v[28:29], 0, s[12:13]
	s_mov_b32 m0, s62
	s_addc_u32 s67, s25, 0
	s_add_i32 s47, s47, s63
	global_load_lds_dwordx4 v[34:35], off
	v_lshl_add_u64 v[34:35], s[66:67], 0, v[128:129]
	s_mov_b32 m0, s47
	s_add_i32 s63, s47, 0x2000
	global_load_lds_dwordx4 v[34:35], off
	v_lshl_add_u64 v[34:35], s[66:67], 0, v[32:33]
	s_mov_b32 m0, s63
	s_nop 0
	global_load_lds_dwordx4 v[34:35], off
	v_lshl_add_u64 v[34:35], v[20:21], 0, s[12:13]
	s_mov_b32 m0, s59
	s_nop 0
	global_load_lds_dwordx4 v[34:35], off
	v_lshl_add_u64 v[34:35], v[22:23], 0, s[12:13]
	s_mov_b32 m0, s60
	s_nop 0
	global_load_lds_dwordx4 v[34:35], off
	s_waitcnt vmcnt(8)
	s_waitcnt lgkmcnt(0)
	s_barrier
; #define PG8_STAGE(bufoff, gbase, voff) do { _Pragma("unroll") for (int _i = 0; _i < 2; ++_i) \
;         __builtin_amdgcn_global_load_lds((const unsigned*)((const char*)(gbase) + (voff)[_i]), (PG8_LAS unsigned*)(lds + (bufoff) + ldsw + _i * 8192), 16, 0, 0); } while (0)
; #define PG8_LDA(dst, b, h) do { _Pragma("unroll") for (int m = 0; m < 4; ++m) _Pragma("unroll") for (int k = 0; k < 2; ++k) dst[m][k] = *(const PG8_LAS bf16x8*)(lds + PG8_SA(b, h) + aoff + m * 2048 + k * 1024); } while (0)
; #define PG8_LDB(dst, b, h) do { _Pragma("unroll") for (int n = 0; n < 2; ++n) _Pragma("unroll") for (int k = 0; k < 2; ++k) dst[n][k] = *(const PG8_LAS bf16x8*)(lds + PG8_SB(b, h) + boff + n * 2048 + k * 1024); } while (0)
; #define PG8_MMA(ai, bj, At, Bt) do { __builtin_amdgcn_s_setprio(1); _Pragma("unroll") for (int m = 0; m < 4; ++m) _Pragma("unroll") for (int n = 0; n < 2; ++n) _Pragma("unroll") for (int k = 0; k < 2; ++k) \
;         acc[ai][bj][m][n] = __builtin_amdgcn_mfma_f32_16x16x32_bf16(Bt[n][k], At[m][k], acc[ai][bj][m][n], 0, 0, 0); __builtin_amdgcn_s_setprio(0); } while (0)
; #define PG8_WAIT_V(n) asm volatile("s_waitcnt vmcnt(" #n ")" ::: "memory")
; #define PG8_WAIT_L(n) asm volatile("s_waitcnt lgkmcnt(" #n ")" ::: "memory")
; #define PG8_BAR __builtin_amdgcn_s_barrier()
; #define PG8_SCHED __builtin_amdgcn_sched_barrier(0)
; template <class Epi, class Sched, bool ALIGN_EPI = false, bool SP2 = false>
; __device__ __forceinline__ void gemm_phase(PG8_LAS unsigned char* lds, const Gemm g, const Sched& S, const Epi& E, const int wv0) {
;     ...
;             PG8_WAIT_V(8); PG8_WAIT_L(0); PG8_BAR; PG8_MMA(0, 0, At, B0); PG8_MMA(0, 1, At, B1); PG8_BAR; PG8_SCHED;
;             PG8_LDA(At, 0, 1); PG8_STAGE(PG8_SB(0, 0), b2, voffB); PG8_STAGE(PG8_SB(0, 1), b2 + hstepB, voffB); PG8_STAGE(PG8_SA(0, 0), a2, voffA);
;             PG8_WAIT_V(8); PG8_WAIT_L(0); PG8_BAR; PG8_MMA(1, 0, At, B0); PG8_MMA(1, 1, At, B1); PG8_BAR; PG8_SCHED;
;             PG8_LDB(B0, 1, 0); PG8_LDB(B1, 1, 1); PG8_SCHED; PG8_LDA(At, 1, 0); PG8_STAGE(PG8_SA(0, 1), a2 + hstepA, voffA);
;             PG8_WAIT_V(8); PG8_WAIT_L(0); PG8_BAR; PG8_MMA(0, 0, At, B0); PG8_MMA(0, 1, At, B1); PG8_BAR; PG8_SCHED;
	s_setprio 1
	v_mfma_f32_16x16x32_bf16 v[172:175], v[38:41], v[98:101], 0
	v_mfma_f32_16x16x32_bf16 v[180:183], v[38:41], v[148:151], 0
	v_mfma_f32_16x16x32_bf16 v[188:191], v[38:41], v[156:159], 0
	v_mfma_f32_16x16x32_bf16 v[38:41], v[38:41], v[164:167], 0
	v_mfma_f32_16x16x32_bf16 v[172:175], v[42:45], v[144:147], v[172:175]
	v_mfma_f32_16x16x32_bf16 v[176:179], v[46:49], v[98:101], 0
	v_mfma_f32_16x16x32_bf16 v[180:183], v[42:45], v[152:155], v[180:183]
	v_mfma_f32_16x16x32_bf16 v[184:187], v[46:49], v[148:151], 0
	v_mfma_f32_16x16x32_bf16 v[188:191], v[42:45], v[160:163], v[188:191]
	v_mfma_f32_16x16x32_bf16 v[192:195], v[46:49], v[156:159], 0
	v_mfma_f32_16x16x32_bf16 v[38:41], v[42:45], v[168:171], v[38:41]
	v_mfma_f32_16x16x32_bf16 v[42:45], v[46:49], v[164:167], 0
	v_mfma_f32_16x16x32_bf16 v[176:179], v[50:53], v[144:147], v[176:179]
	v_mfma_f32_16x16x32_bf16 v[184:187], v[50:53], v[152:155], v[184:187]
	v_mfma_f32_16x16x32_bf16 v[192:195], v[50:53], v[160:163], v[192:195]
	v_mfma_f32_16x16x32_bf16 v[42:45], v[50:53], v[168:171], v[42:45]
	v_mfma_f32_16x16x32_bf16 v[46:49], v[54:57], v[98:101], 0
	v_mfma_f32_16x16x32_bf16 v[50:53], v[62:65], v[98:101], 0
	v_mfma_f32_16x16x32_bf16 v[46:49], v[58:61], v[144:147], v[46:49]
	v_mfma_f32_16x16x32_bf16 v[50:53], v[66:69], v[144:147], v[50:53]
	v_mfma_f32_16x16x32_bf16 v[98:101], v[54:57], v[148:151], 0
	v_mfma_f32_16x16x32_bf16 v[144:147], v[62:65], v[148:151], 0
	v_mfma_f32_16x16x32_bf16 v[148:151], v[54:57], v[156:159], 0
	v_mfma_f32_16x16x32_bf16 v[54:57], v[54:57], v[164:167], 0
	v_mfma_f32_16x16x32_bf16 v[98:101], v[58:61], v[152:155], v[98:101]
	v_mfma_f32_16x16x32_bf16 v[144:147], v[66:69], v[152:155], v[144:147]
	v_mfma_f32_16x16x32_bf16 v[148:151], v[58:61], v[160:163], v[148:151]
	v_mfma_f32_16x16x32_bf16 v[152:155], v[62:65], v[156:159], 0
	v_mfma_f32_16x16x32_bf16 v[54:57], v[58:61], v[168:171], v[54:57]
	v_mfma_f32_16x16x32_bf16 v[58:61], v[62:65], v[164:167], 0
	v_mfma_f32_16x16x32_bf16 v[152:155], v[66:69], v[160:163], v[152:155]
	v_mfma_f32_16x16x32_bf16 v[58:61], v[66:69], v[168:171], v[58:61]
	s_setprio 0
	s_barrier
	ds_read_b128 v[62:65], v239
	ds_read_b128 v[66:69], v239 offset:1024
	ds_read_b128 v[156:159], v239 offset:2048
	ds_read_b128 v[160:163], v239 offset:3072
	ds_read_b128 v[164:167], v238
	ds_read_b128 v[168:171], v238 offset:1024
	ds_read_b128 v[196:199], v238 offset:2048
	ds_read_b128 v[200:203], v238 offset:3072
	s_add_u32 s66, s22, 0x40100
	s_addc_u32 s67, s23, 0
	s_mov_b32 m0, s55
	v_lshl_add_u64 v[34:35], s[66:67], 0, v[16:17]
	ds_read_b128 v[206:209], v143 offset:32768
	ds_read_b128 v[210:213], v143 offset:33792
	ds_read_b128 v[214:217], v143 offset:34816
	ds_read_b128 v[218:221], v143 offset:35840
	ds_read_b128 v[222:225], v143 offset:36864
	ds_read_b128 v[226:229], v143 offset:37888
	ds_read_b128 v[230:233], v143 offset:38912
	ds_read_b128 v[234:237], v143 offset:39936
	global_load_lds_dwordx4 v[34:35], off
	v_lshl_add_u64 v[34:35], s[66:67], 0, v[30:31]
	s_mov_b32 m0, s56
	s_nop 0
	global_load_lds_dwordx4 v[34:35], off
	s_waitcnt vmcnt(8)
	s_waitcnt lgkmcnt(0)
	s_barrier
	s_setprio 1
	v_mfma_f32_16x16x32_bf16 v[102:105], v[62:65], v[206:209], v[102:105]
	v_mfma_f32_16x16x32_bf16 v[106:109], v[156:159], v[206:209], v[106:109]
	v_mfma_f32_16x16x32_bf16 v[110:113], v[62:65], v[214:217], v[110:113]
	v_mfma_f32_16x16x32_bf16 v[114:117], v[156:159], v[214:217], v[114:117]
	v_mfma_f32_16x16x32_bf16 v[118:121], v[62:65], v[222:225], v[118:121]
	v_mfma_f32_16x16x32_bf16 v[122:125], v[156:159], v[222:225], v[122:125]
	v_mfma_f32_16x16x32_bf16 v[130:133], v[62:65], v[230:233], v[130:133]
	v_mfma_f32_16x16x32_bf16 v[134:137], v[156:159], v[230:233], v[134:137]
	v_mfma_f32_16x16x32_bf16 v[102:105], v[66:69], v[210:213], v[102:105]
	v_mfma_f32_16x16x32_bf16 v[106:109], v[160:163], v[210:213], v[106:109]
	v_mfma_f32_16x16x32_bf16 v[110:113], v[66:69], v[218:221], v[110:113]
	v_mfma_f32_16x16x32_bf16 v[114:117], v[160:163], v[218:221], v[114:117]
	v_mfma_f32_16x16x32_bf16 v[118:121], v[66:69], v[226:229], v[118:121]
	v_mfma_f32_16x16x32_bf16 v[122:125], v[160:163], v[226:229], v[122:125]
	v_mfma_f32_16x16x32_bf16 v[130:133], v[66:69], v[234:237], v[130:133]
	v_mfma_f32_16x16x32_bf16 v[134:137], v[160:163], v[234:237], v[134:137]
	v_mfma_f32_16x16x32_bf16 v[138:141], v[164:167], v[206:209], v[138:141]
	v_mfma_f32_16x16x32_bf16 v[70:73], v[196:199], v[206:209], v[70:73]
	v_mfma_f32_16x16x32_bf16 v[74:77], v[164:167], v[214:217], v[74:77]
	v_mfma_f32_16x16x32_bf16 v[78:81], v[196:199], v[214:217], v[78:81]
	v_mfma_f32_16x16x32_bf16 v[82:85], v[164:167], v[222:225], v[82:85]
	v_mfma_f32_16x16x32_bf16 v[86:89], v[196:199], v[222:225], v[86:89]
	v_mfma_f32_16x16x32_bf16 v[90:93], v[164:167], v[230:233], v[90:93]
	v_mfma_f32_16x16x32_bf16 v[94:97], v[196:199], v[230:233], v[94:97]
	v_mfma_f32_16x16x32_bf16 v[138:141], v[168:171], v[210:213], v[138:141]
	v_mfma_f32_16x16x32_bf16 v[70:73], v[200:203], v[210:213], v[70:73]
	v_mfma_f32_16x16x32_bf16 v[74:77], v[168:171], v[218:221], v[74:77]
	v_mfma_f32_16x16x32_bf16 v[78:81], v[200:203], v[218:221], v[78:81]
	v_mfma_f32_16x16x32_bf16 v[82:85], v[168:171], v[226:229], v[82:85]
	v_mfma_f32_16x16x32_bf16 v[86:89], v[200:203], v[226:229], v[86:89]
	v_mfma_f32_16x16x32_bf16 v[90:93], v[168:171], v[234:237], v[90:93]
	v_mfma_f32_16x16x32_bf16 v[94:97], v[200:203], v[234:237], v[94:97]
	s_setprio 0
	s_barrier
; #define PG8_STAGE(bufoff, gbase, voff) do { _Pragma("unroll") for (int _i = 0; _i < 2; ++_i) \
;         __builtin_amdgcn_global_load_lds((const unsigned*)((const char*)(gbase) + (voff)[_i]), (PG8_LAS unsigned*)(lds + (bufoff) + ldsw + _i * 8192), 16, 0, 0); } while (0)
; #define PG8_LDA(dst, b, h) do { _Pragma("unroll") for (int m = 0; m < 4; ++m) _Pragma("unroll") for (int k = 0; k < 2; ++k) dst[m][k] = *(const PG8_LAS bf16x8*)(lds + PG8_SA(b, h) + aoff + m * 2048 + k * 1024); } while (0)
; #define PG8_LDB(dst, b, h) do { _Pragma("unroll") for (int n = 0; n < 2; ++n) _Pragma("unroll") for (int k = 0; k < 2; ++k) dst[n][k] = *(const PG8_LAS bf16x8*)(lds + PG8_SB(b, h) + boff + n * 2048 + k * 1024); } while (0)
; #define PG8_MMA(ai, bj, At, Bt) do { __builtin_amdgcn_s_setprio(1); _Pragma("unroll") for (int m = 0; m < 4; ++m) _Pragma("unroll") for (int n = 0; n < 2; ++n) _Pragma("unroll") for (int k = 0; k < 2; ++k) \
;         acc[ai][bj][m][n] = __builtin_amdgcn_mfma_f32_16x16x32_bf16(Bt[n][k], At[m][k], acc[ai][bj][m][n], 0, 0, 0); __builtin_amdgcn_s_setprio(0); } while (0)
; #define PG8_BAR __builtin_amdgcn_s_barrier()
; template <class Epi, class Sched, bool ALIGN_EPI = false, bool SP2 = false>
; __device__ __forceinline__ void gemm_phase(PG8_LAS unsigned char* lds, const Gemm g, const Sched& S, const Epi& E, const int wv0) {
;     ...
;             PG8_LDB(B0, 0, 0); PG8_LDB(B1, 0, 1); PG8_SCHED; PG8_LDA(At, 0, 0); PG8_STAGE(PG8_SA(1, 1), a1 + hstepA, voffA);
;             PG8_WAIT_V(8); PG8_WAIT_L(0); PG8_BAR; PG8_MMA(0, 0, At, B0); PG8_MMA(0, 1, At, B1); PG8_BAR; PG8_SCHED;
;             PG8_LDA(At, 0, 1); PG8_STAGE(PG8_SB(0, 0), b2, voffB); PG8_STAGE(PG8_SB(0, 1), b2 + hstepB, voffB); PG8_STAGE(PG8_SA(0, 0), a2, voffA);
;             PG8_WAIT_V(8); PG8_WAIT_L(0); PG8_BAR; PG8_MMA(1, 0, At, B0); PG8_MMA(1, 1, At, B1); PG8_BAR; PG8_SCHED;
;             PG8_LDB(B0, 1, 0); PG8_LDB(B1, 1, 1); PG8_SCHED; PG8_LDA(At, 1, 0); PG8_STAGE(PG8_SA(0, 1), a2 + hstepA, voffA);
;             PG8_WAIT_V(8); PG8_WAIT_L(0); PG8_BAR; PG8_MMA(0, 0, At, B0); PG8_MMA(0, 1, At, B1); PG8_BAR; PG8_SCHED;
;             PG8_LDA(At, 1, 1); PG8_STAGE(PG8_SB(1, 0), b3, voffB); PG8_STAGE(PG8_SB(1, 1), b3 + hstepB, voffB); PG8_STAGE(PG8_SA(1, 0), a3, voffA);
;             PG8_WAIT_V(8); PG8_WAIT_L(0); PG8_BAR; PG8_MMA(1, 0, At, B0); PG8_MMA(1, 1, At, B1); PG8_BAR; PG8_SCHED;
	s_mov_b32 m0, s51
	v_lshl_add_u64 v[34:35], v[26:27], 0, s[14:15]
	s_add_u32 s24, s24, 0x10180
	ds_read_b128 v[206:209], v143 offset:49152
	ds_read_b128 v[210:213], v143 offset:50176
	ds_read_b128 v[214:217], v143 offset:51200
	ds_read_b128 v[218:221], v143 offset:52224
	ds_read_b128 v[222:225], v143 offset:53248
	ds_read_b128 v[226:229], v143 offset:54272
	ds_read_b128 v[230:233], v143 offset:55296
	ds_read_b128 v[234:237], v143 offset:56320
	global_load_lds_dwordx4 v[34:35], off
	v_lshl_add_u64 v[34:35], v[28:29], 0, s[14:15]
	s_mov_b32 m0, s53
	s_addc_u32 s25, s25, 0
	global_load_lds_dwordx4 v[34:35], off
	v_lshl_add_u64 v[34:35], s[24:25], 0, v[128:129]
	s_mov_b32 m0, s57
	v_lshl_add_u64 v[32:33], s[24:25], 0, v[32:33]
	global_load_lds_dwordx4 v[34:35], off
	s_mov_b32 m0, s58
	s_nop 0
	global_load_lds_dwordx4 v[32:33], off
	v_lshl_add_u64 v[32:33], v[20:21], 0, s[14:15]
	s_mov_b32 m0, s52
	s_nop 0
	global_load_lds_dwordx4 v[32:33], off
	v_lshl_add_u64 v[32:33], v[22:23], 0, s[14:15]
	s_mov_b32 m0, s54
	s_nop 0
	global_load_lds_dwordx4 v[32:33], off
	s_waitcnt vmcnt(8)
	s_waitcnt lgkmcnt(0)
	s_barrier
	s_setprio 1
	v_mfma_f32_16x16x32_bf16 v[32:35], v[62:65], v[206:209], v[172:175]
	v_mfma_f32_16x16x32_bf16 v[172:175], v[156:159], v[206:209], v[176:179]
	v_mfma_f32_16x16x32_bf16 v[176:179], v[62:65], v[214:217], v[180:183]
	v_mfma_f32_16x16x32_bf16 v[180:183], v[156:159], v[214:217], v[184:187]
	v_mfma_f32_16x16x32_bf16 v[184:187], v[62:65], v[222:225], v[188:191]
	v_mfma_f32_16x16x32_bf16 v[188:191], v[156:159], v[222:225], v[192:195]
	v_mfma_f32_16x16x32_bf16 v[38:41], v[62:65], v[230:233], v[38:41]
	v_mfma_f32_16x16x32_bf16 v[42:45], v[156:159], v[230:233], v[42:45]
	v_mfma_f32_16x16x32_bf16 v[32:35], v[66:69], v[210:213], v[32:35]
	v_mfma_f32_16x16x32_bf16 v[172:175], v[160:163], v[210:213], v[172:175]
	v_mfma_f32_16x16x32_bf16 v[176:179], v[66:69], v[218:221], v[176:179]
	v_mfma_f32_16x16x32_bf16 v[180:183], v[160:163], v[218:221], v[180:183]
	v_mfma_f32_16x16x32_bf16 v[184:187], v[66:69], v[226:229], v[184:187]
	v_mfma_f32_16x16x32_bf16 v[188:191], v[160:163], v[226:229], v[188:191]
	v_mfma_f32_16x16x32_bf16 v[38:41], v[66:69], v[234:237], v[38:41]
	v_mfma_f32_16x16x32_bf16 v[42:45], v[160:163], v[234:237], v[42:45]
	v_mfma_f32_16x16x32_bf16 v[46:49], v[164:167], v[206:209], v[46:49]
	v_mfma_f32_16x16x32_bf16 v[50:53], v[196:199], v[206:209], v[50:53]
	v_mfma_f32_16x16x32_bf16 v[62:65], v[164:167], v[214:217], v[98:101]
	v_mfma_f32_16x16x32_bf16 v[66:69], v[196:199], v[214:217], v[144:147]
	v_mfma_f32_16x16x32_bf16 v[98:101], v[164:167], v[222:225], v[148:151]
	v_mfma_f32_16x16x32_bf16 v[144:147], v[196:199], v[222:225], v[152:155]
	v_mfma_f32_16x16x32_bf16 v[54:57], v[164:167], v[230:233], v[54:57]
	v_mfma_f32_16x16x32_bf16 v[58:61], v[196:199], v[230:233], v[58:61]
	v_mfma_f32_16x16x32_bf16 v[46:49], v[168:171], v[210:213], v[46:49]
	v_mfma_f32_16x16x32_bf16 v[50:53], v[200:203], v[210:213], v[50:53]
	v_mfma_f32_16x16x32_bf16 v[62:65], v[168:171], v[218:221], v[62:65]
	v_mfma_f32_16x16x32_bf16 v[66:69], v[200:203], v[218:221], v[66:69]
	v_mfma_f32_16x16x32_bf16 v[98:101], v[168:171], v[226:229], v[98:101]
	v_mfma_f32_16x16x32_bf16 v[144:147], v[200:203], v[226:229], v[144:147]
	v_mfma_f32_16x16x32_bf16 v[54:57], v[168:171], v[234:237], v[54:57]
	v_mfma_f32_16x16x32_bf16 v[58:61], v[200:203], v[234:237], v[58:61]
	s_setprio 0
	s_barrier
	ds_read_b128 v[148:151], v127
	ds_read_b128 v[152:155], v127 offset:1024
	ds_read_b128 v[156:159], v127 offset:2048
	ds_read_b128 v[160:163], v127 offset:3072
	ds_read_b128 v[164:167], v126
	ds_read_b128 v[168:171], v126 offset:1024
	ds_read_b128 v[192:195], v126 offset:2048
	ds_read_b128 v[196:199], v126 offset:3072
	s_add_u32 s22, s22, 0x40180
	s_addc_u32 s23, s23, 0
	s_mov_b32 m0, s64
	v_lshl_add_u64 v[16:17], s[22:23], 0, v[16:17]
	ds_read_b128 v[200:203], v143
	ds_read_b128 v[206:209], v143 offset:1024
	ds_read_b128 v[210:213], v143 offset:2048
	ds_read_b128 v[214:217], v143 offset:3072
	ds_read_b128 v[218:221], v143 offset:4096
	ds_read_b128 v[222:225], v143 offset:5120
	ds_read_b128 v[226:229], v143 offset:6144
	ds_read_b128 v[230:233], v143 offset:7168
	global_load_lds_dwordx4 v[16:17], off
	v_lshl_add_u64 v[16:17], s[22:23], 0, v[30:31]
	s_mov_b32 m0, s61
	s_nop 0
	global_load_lds_dwordx4 v[16:17], off
	s_waitcnt vmcnt(8)
	s_waitcnt lgkmcnt(0)
	s_barrier
	s_setprio 1
	v_mfma_f32_16x16x32_bf16 v[102:105], v[148:151], v[200:203], v[102:105]
	v_mfma_f32_16x16x32_bf16 v[106:109], v[156:159], v[200:203], v[106:109]
	v_mfma_f32_16x16x32_bf16 v[110:113], v[148:151], v[210:213], v[110:113]
	v_mfma_f32_16x16x32_bf16 v[114:117], v[156:159], v[210:213], v[114:117]
	v_mfma_f32_16x16x32_bf16 v[118:121], v[148:151], v[218:221], v[118:121]
	v_mfma_f32_16x16x32_bf16 v[122:125], v[156:159], v[218:221], v[122:125]
	v_mfma_f32_16x16x32_bf16 v[130:133], v[148:151], v[226:229], v[130:133]
	v_mfma_f32_16x16x32_bf16 v[134:137], v[156:159], v[226:229], v[134:137]
	v_mfma_f32_16x16x32_bf16 v[102:105], v[152:155], v[206:209], v[102:105]
	v_mfma_f32_16x16x32_bf16 v[106:109], v[160:163], v[206:209], v[106:109]
	v_mfma_f32_16x16x32_bf16 v[110:113], v[152:155], v[214:217], v[110:113]
	v_mfma_f32_16x16x32_bf16 v[114:117], v[160:163], v[214:217], v[114:117]
	v_mfma_f32_16x16x32_bf16 v[118:121], v[152:155], v[222:225], v[118:121]
	v_mfma_f32_16x16x32_bf16 v[122:125], v[160:163], v[222:225], v[122:125]
	v_mfma_f32_16x16x32_bf16 v[130:133], v[152:155], v[230:233], v[130:133]
	v_mfma_f32_16x16x32_bf16 v[134:137], v[160:163], v[230:233], v[134:137]
	v_mfma_f32_16x16x32_bf16 v[138:141], v[164:167], v[200:203], v[138:141]
	v_mfma_f32_16x16x32_bf16 v[70:73], v[192:195], v[200:203], v[70:73]
	v_mfma_f32_16x16x32_bf16 v[74:77], v[164:167], v[210:213], v[74:77]
	v_mfma_f32_16x16x32_bf16 v[78:81], v[192:195], v[210:213], v[78:81]
	v_mfma_f32_16x16x32_bf16 v[82:85], v[164:167], v[218:221], v[82:85]
	v_mfma_f32_16x16x32_bf16 v[86:89], v[192:195], v[218:221], v[86:89]
	v_mfma_f32_16x16x32_bf16 v[90:93], v[164:167], v[226:229], v[90:93]
	v_mfma_f32_16x16x32_bf16 v[94:97], v[192:195], v[226:229], v[94:97]
	v_mfma_f32_16x16x32_bf16 v[138:141], v[168:171], v[206:209], v[138:141]
	v_mfma_f32_16x16x32_bf16 v[70:73], v[196:199], v[206:209], v[70:73]
	v_mfma_f32_16x16x32_bf16 v[74:77], v[168:171], v[214:217], v[74:77]
	v_mfma_f32_16x16x32_bf16 v[78:81], v[196:199], v[214:217], v[78:81]
	v_mfma_f32_16x16x32_bf16 v[82:85], v[168:171], v[222:225], v[82:85]
	v_mfma_f32_16x16x32_bf16 v[86:89], v[196:199], v[222:225], v[86:89]
	v_mfma_f32_16x16x32_bf16 v[90:93], v[168:171], v[230:233], v[90:93]
	v_mfma_f32_16x16x32_bf16 v[94:97], v[196:199], v[230:233], v[94:97]
	s_setprio 0
	s_barrier
; #define PG8_STAGE(bufoff, gbase, voff) do { _Pragma("unroll") for (int _i = 0; _i < 2; ++_i) \
;         __builtin_amdgcn_global_load_lds((const unsigned*)((const char*)(gbase) + (voff)[_i]), (PG8_LAS unsigned*)(lds + (bufoff) + ldsw + _i * 8192), 16, 0, 0); } while (0)
; #define PG8_LDA(dst, b, h) do { _Pragma("unroll") for (int m = 0; m < 4; ++m) _Pragma("unroll") for (int k = 0; k < 2; ++k) dst[m][k] = *(const PG8_LAS bf16x8*)(lds + PG8_SA(b, h) + aoff + m * 2048 + k * 1024); } while (0)
; #define PG8_LDB(dst, b, h) do { _Pragma("unroll") for (int n = 0; n < 2; ++n) _Pragma("unroll") for (int k = 0; k < 2; ++k) dst[n][k] = *(const PG8_LAS bf16x8*)(lds + PG8_SB(b, h) + boff + n * 2048 + k * 1024); } while (0)
; #define PG8_MMA(ai, bj, At, Bt) do { __builtin_amdgcn_s_setprio(1); _Pragma("unroll") for (int m = 0; m < 4; ++m) _Pragma("unroll") for (int n = 0; n < 2; ++n) _Pragma("unroll") for (int k = 0; k < 2; ++k) \
;         acc[ai][bj][m][n] = __builtin_amdgcn_mfma_f32_16x16x32_bf16(Bt[n][k], At[m][k], acc[ai][bj][m][n], 0, 0, 0); __builtin_amdgcn_s_setprio(0); } while (0)
; #define PG8_WAIT_V(n) asm volatile("s_waitcnt vmcnt(" #n ")" ::: "memory")
; #define PG8_WAIT_L(n) asm volatile("s_waitcnt lgkmcnt(" #n ")" ::: "memory")
; #define PG8_BAR __builtin_amdgcn_s_barrier()
; #define PG8_SCHED __builtin_amdgcn_sched_barrier(0)
; template <class Epi, class Sched, bool ALIGN_EPI = false, bool SP2 = false>
; __device__ __forceinline__ void gemm_phase(PG8_LAS unsigned char* lds, const Gemm g, const Sched& S, const Epi& E, const int wv0) {
;     ...
;             PG8_LDA(At, 0, 1); PG8_STAGE(PG8_SB(0, 0), b2, voffB); PG8_STAGE(PG8_SB(0, 1), b2 + hstepB, voffB); PG8_STAGE(PG8_SA(0, 0), a2, voffA);
;             PG8_WAIT_V(8); PG8_WAIT_L(0); PG8_BAR; PG8_MMA(1, 0, At, B0); PG8_MMA(1, 1, At, B1); PG8_BAR; PG8_SCHED;
;             PG8_LDB(B0, 1, 0); PG8_LDB(B1, 1, 1); PG8_SCHED; PG8_LDA(At, 1, 0); PG8_STAGE(PG8_SA(0, 1), a2 + hstepA, voffA);
;             PG8_WAIT_V(8); PG8_WAIT_L(0); PG8_BAR; PG8_MMA(0, 0, At, B0); PG8_MMA(0, 1, At, B1); PG8_BAR; PG8_SCHED;
	s_mov_b32 m0, s48
	ds_read_b128 v[200:203], v143 offset:16384
	ds_read_b128 v[206:209], v143 offset:17408
	ds_read_b128 v[210:213], v143 offset:18432
	ds_read_b128 v[214:217], v143 offset:19456
	ds_read_b128 v[218:221], v143 offset:20480
	ds_read_b128 v[222:225], v143 offset:21504
	ds_read_b128 v[226:229], v143 offset:22528
	ds_read_b128 v[230:233], v143 offset:23552
	global_load_lds_dwordx4 v[26:27], off
	s_mov_b32 m0, s62
	s_nop 0
	global_load_lds_dwordx4 v[28:29], off
	s_mov_b32 m0, s47
	s_nop 0
	global_load_lds_dwordx4 v[24:25], off
	s_mov_b32 m0, s63
	s_nop 0
	global_load_lds_dwordx4 v[18:19], off
	s_mov_b32 m0, s59
	s_nop 0
	global_load_lds_dwordx4 v[20:21], off
	s_mov_b32 m0, s60
	s_nop 0
	global_load_lds_dwordx4 v[22:23], off
	s_waitcnt vmcnt(8)
	s_waitcnt lgkmcnt(0)
	s_barrier
	s_setprio 1
	v_mfma_f32_16x16x32_bf16 v[16:19], v[148:151], v[200:203], v[32:35]
	v_mfma_f32_16x16x32_bf16 v[20:23], v[156:159], v[200:203], v[172:175]
	v_mfma_f32_16x16x32_bf16 v[24:27], v[148:151], v[210:213], v[176:179]
	v_mfma_f32_16x16x32_bf16 v[28:31], v[156:159], v[210:213], v[180:183]
	v_mfma_f32_16x16x32_bf16 v[32:35], v[148:151], v[218:221], v[184:187]
	v_mfma_f32_16x16x32_bf16 v[172:175], v[156:159], v[218:221], v[188:191]
	v_mfma_f32_16x16x32_bf16 v[38:41], v[148:151], v[226:229], v[38:41]
	v_mfma_f32_16x16x32_bf16 v[42:45], v[156:159], v[226:229], v[42:45]
	v_mfma_f32_16x16x32_bf16 v[16:19], v[152:155], v[206:209], v[16:19]
	v_mfma_f32_16x16x32_bf16 v[20:23], v[160:163], v[206:209], v[20:23]
	v_mfma_f32_16x16x32_bf16 v[24:27], v[152:155], v[214:217], v[24:27]
	v_mfma_f32_16x16x32_bf16 v[28:31], v[160:163], v[214:217], v[28:31]
	v_mfma_f32_16x16x32_bf16 v[32:35], v[152:155], v[222:225], v[32:35]
	v_mfma_f32_16x16x32_bf16 v[172:175], v[160:163], v[222:225], v[172:175]
	v_mfma_f32_16x16x32_bf16 v[38:41], v[152:155], v[230:233], v[38:41]
	v_mfma_f32_16x16x32_bf16 v[42:45], v[160:163], v[230:233], v[42:45]
	v_mfma_f32_16x16x32_bf16 v[46:49], v[164:167], v[200:203], v[46:49]
	v_mfma_f32_16x16x32_bf16 v[50:53], v[192:195], v[200:203], v[50:53]
	v_mfma_f32_16x16x32_bf16 v[62:65], v[164:167], v[210:213], v[62:65]
	v_mfma_f32_16x16x32_bf16 v[66:69], v[192:195], v[210:213], v[66:69]
	v_mfma_f32_16x16x32_bf16 v[98:101], v[164:167], v[218:221], v[98:101]
	v_mfma_f32_16x16x32_bf16 v[144:147], v[192:195], v[218:221], v[144:147]
	v_mfma_f32_16x16x32_bf16 v[54:57], v[164:167], v[226:229], v[54:57]
	v_mfma_f32_16x16x32_bf16 v[58:61], v[192:195], v[226:229], v[58:61]
	v_mfma_f32_16x16x32_bf16 v[46:49], v[168:171], v[206:209], v[46:49]
	v_mfma_f32_16x16x32_bf16 v[50:53], v[196:199], v[206:209], v[50:53]
	v_mfma_f32_16x16x32_bf16 v[62:65], v[168:171], v[214:217], v[62:65]
	v_mfma_f32_16x16x32_bf16 v[66:69], v[196:199], v[214:217], v[66:69]
	v_mfma_f32_16x16x32_bf16 v[98:101], v[168:171], v[222:225], v[98:101]
	v_mfma_f32_16x16x32_bf16 v[144:147], v[196:199], v[222:225], v[144:147]
	v_mfma_f32_16x16x32_bf16 v[54:57], v[168:171], v[230:233], v[54:57]
	v_mfma_f32_16x16x32_bf16 v[58:61], v[196:199], v[230:233], v[58:61]
	s_setprio 0
	s_barrier
	ds_read_b128 v[148:151], v239
	ds_read_b128 v[152:155], v239 offset:1024
	ds_read_b128 v[156:159], v239 offset:2048
	ds_read_b128 v[160:163], v239 offset:3072
	ds_read_b128 v[164:167], v238
	ds_read_b128 v[168:171], v238 offset:1024
	ds_read_b128 v[176:179], v238 offset:2048
	ds_read_b128 v[180:183], v238 offset:3072
	s_mov_b32 m0, s55
	ds_read_b128 v[184:187], v143 offset:32768
	ds_read_b128 v[188:191], v143 offset:33792
	ds_read_b128 v[192:195], v143 offset:34816
	ds_read_b128 v[196:199], v143 offset:35840
	ds_read_b128 v[200:203], v143 offset:36864
	ds_read_b128 v[206:209], v143 offset:37888
	ds_read_b128 v[210:213], v143 offset:38912
	ds_read_b128 v[214:217], v143 offset:39936
	global_load_lds_dwordx4 v[12:13], off
	s_mov_b32 m0, s56
	s_nop 0
	global_load_lds_dwordx4 v[14:15], off
	s_waitcnt vmcnt(8)
	s_waitcnt lgkmcnt(0)
	s_barrier
	s_setprio 1
	v_mfma_f32_16x16x32_bf16 v[12:15], v[148:151], v[184:187], v[102:105]
	v_mfma_f32_16x16x32_bf16 v[102:105], v[152:155], v[188:191], v[12:15]
	v_mfma_f32_16x16x32_bf16 v[12:15], v[156:159], v[184:187], v[106:109]
	v_mfma_f32_16x16x32_bf16 v[106:109], v[160:163], v[188:191], v[12:15]
	v_mfma_f32_16x16x32_bf16 v[12:15], v[148:151], v[192:195], v[110:113]
	v_mfma_f32_16x16x32_bf16 v[110:113], v[152:155], v[196:199], v[12:15]
	v_mfma_f32_16x16x32_bf16 v[12:15], v[156:159], v[192:195], v[114:117]
	v_mfma_f32_16x16x32_bf16 v[114:117], v[160:163], v[196:199], v[12:15]
	v_mfma_f32_16x16x32_bf16 v[12:15], v[148:151], v[200:203], v[118:121]
	v_mfma_f32_16x16x32_bf16 v[118:121], v[152:155], v[206:209], v[12:15]
	v_mfma_f32_16x16x32_bf16 v[12:15], v[156:159], v[200:203], v[122:125]
	v_mfma_f32_16x16x32_bf16 v[122:125], v[160:163], v[206:209], v[12:15]
	v_mfma_f32_16x16x32_bf16 v[12:15], v[148:151], v[210:213], v[130:133]
	v_mfma_f32_16x16x32_bf16 v[130:133], v[152:155], v[214:217], v[12:15]
	v_mfma_f32_16x16x32_bf16 v[12:15], v[156:159], v[210:213], v[134:137]
	v_mfma_f32_16x16x32_bf16 v[134:137], v[160:163], v[214:217], v[12:15]
	v_mfma_f32_16x16x32_bf16 v[12:15], v[164:167], v[184:187], v[138:141]
	v_mfma_f32_16x16x32_bf16 v[138:141], v[168:171], v[188:191], v[12:15]
	v_mfma_f32_16x16x32_bf16 v[12:15], v[176:179], v[184:187], v[70:73]
	v_mfma_f32_16x16x32_bf16 v[70:73], v[180:183], v[188:191], v[12:15]
	v_mfma_f32_16x16x32_bf16 v[12:15], v[164:167], v[192:195], v[74:77]
	v_mfma_f32_16x16x32_bf16 v[74:77], v[168:171], v[196:199], v[12:15]
	v_mfma_f32_16x16x32_bf16 v[12:15], v[176:179], v[192:195], v[78:81]
	v_mfma_f32_16x16x32_bf16 v[78:81], v[180:183], v[196:199], v[12:15]
	v_mfma_f32_16x16x32_bf16 v[12:15], v[164:167], v[200:203], v[82:85]
	v_mfma_f32_16x16x32_bf16 v[82:85], v[168:171], v[206:209], v[12:15]
	v_mfma_f32_16x16x32_bf16 v[12:15], v[176:179], v[200:203], v[86:89]
	v_mfma_f32_16x16x32_bf16 v[86:89], v[180:183], v[206:209], v[12:15]
	v_mfma_f32_16x16x32_bf16 v[12:15], v[164:167], v[210:213], v[90:93]
	v_mfma_f32_16x16x32_bf16 v[90:93], v[168:171], v[214:217], v[12:15]
	v_mfma_f32_16x16x32_bf16 v[12:15], v[176:179], v[210:213], v[94:97]
	v_mfma_f32_16x16x32_bf16 v[94:97], v[180:183], v[214:217], v[12:15]
	s_setprio 0
	s_barrier
; #define PG8_STAGE(bufoff, gbase, voff) do { _Pragma("unroll") for (int _i = 0; _i < 2; ++_i) \
;         __builtin_amdgcn_global_load_lds((const unsigned*)((const char*)(gbase) + (voff)[_i]), (PG8_LAS unsigned*)(lds + (bufoff) + ldsw + _i * 8192), 16, 0, 0); } while (0)
; #define PG8_LDA(dst, b, h) do { _Pragma("unroll") for (int m = 0; m < 4; ++m) _Pragma("unroll") for (int k = 0; k < 2; ++k) dst[m][k] = *(const PG8_LAS bf16x8*)(lds + PG8_SA(b, h) + aoff + m * 2048 + k * 1024); } while (0)
; #define PG8_MMA(ai, bj, At, Bt) do { __builtin_amdgcn_s_setprio(1); _Pragma("unroll") for (int m = 0; m < 4; ++m) _Pragma("unroll") for (int n = 0; n < 2; ++n) _Pragma("unroll") for (int k = 0; k < 2; ++k) \
;         acc[ai][bj][m][n] = __builtin_amdgcn_mfma_f32_16x16x32_bf16(Bt[n][k], At[m][k], acc[ai][bj][m][n], 0, 0, 0); __builtin_amdgcn_s_setprio(0); } while (0)
; #define PG8_WAIT_V(n) asm volatile("s_waitcnt vmcnt(" #n ")" ::: "memory")
; #define PG8_WAIT_L(n) asm volatile("s_waitcnt lgkmcnt(" #n ")" ::: "memory")
; #define PG8_BAR __builtin_amdgcn_s_barrier()
; #define PG8_SCHED __builtin_amdgcn_sched_barrier(0)
; template <class Epi, class Sched, bool ALIGN_EPI = false, bool SP2 = false>
; __device__ __forceinline__ void gemm_phase(PG8_LAS unsigned char* lds, const Gemm g, const Sched& S, const Epi& E, const int wv0) {
;     ...
;             PG8_LDA(At, 1, 1); PG8_STAGE(PG8_SB(1, 0), b3, voffB); PG8_STAGE(PG8_SB(1, 1), b3 + hstepB, voffB); PG8_STAGE(PG8_SA(1, 0), a3, voffA);
;             PG8_WAIT_V(8); PG8_WAIT_L(0); PG8_BAR; PG8_MMA(1, 0, At, B0); PG8_MMA(1, 1, At, B1); PG8_BAR; PG8_SCHED;
	s_mov_b32 m0, s51
	ds_read_b128 v[184:187], v143 offset:49152
	ds_read_b128 v[188:191], v143 offset:50176
	ds_read_b128 v[192:195], v143 offset:51200
	ds_read_b128 v[196:199], v143 offset:52224
	ds_read_b128 v[200:203], v143 offset:53248
	ds_read_b128 v[206:209], v143 offset:54272
	ds_read_b128 v[210:213], v143 offset:55296
	ds_read_b128 v[214:217], v143 offset:56320
	global_load_lds_dwordx4 v[2:3], off
	s_mov_b32 m0, s53
	s_nop 0
	global_load_lds_dwordx4 v[4:5], off
	s_mov_b32 m0, s57
	s_nop 0
	global_load_lds_dwordx4 v[8:9], off
	s_mov_b32 m0, s58
	s_nop 0
	global_load_lds_dwordx4 v[10:11], off
	s_mov_b32 m0, s52
	s_nop 0
	global_load_lds_dwordx4 v[0:1], off
	s_mov_b32 m0, s54
	s_nop 0
	global_load_lds_dwordx4 v[6:7], off
	s_waitcnt vmcnt(8)
	s_waitcnt lgkmcnt(0)
	s_barrier
	s_setprio 1
	v_mfma_f32_16x16x32_bf16 v[0:3], v[148:151], v[184:187], v[16:19]
	v_mfma_f32_16x16x32_bf16 v[218:221], v[152:155], v[188:191], v[0:3]
	v_mfma_f32_16x16x32_bf16 v[0:3], v[156:159], v[184:187], v[20:23]
	v_mfma_f32_16x16x32_bf16 v[222:225], v[160:163], v[188:191], v[0:3]
	v_mfma_f32_16x16x32_bf16 v[0:3], v[148:151], v[192:195], v[24:27]
	v_mfma_f32_16x16x32_bf16 v[226:229], v[152:155], v[196:199], v[0:3]
	v_mfma_f32_16x16x32_bf16 v[0:3], v[156:159], v[192:195], v[28:31]
	v_mfma_f32_16x16x32_bf16 v[230:233], v[160:163], v[196:199], v[0:3]
	v_mfma_f32_16x16x32_bf16 v[0:3], v[148:151], v[200:203], v[32:35]
	v_mfma_f32_16x16x32_bf16 v[28:31], v[152:155], v[206:209], v[0:3]
	v_mfma_f32_16x16x32_bf16 v[0:3], v[156:159], v[200:203], v[172:175]
	v_mfma_f32_16x16x32_bf16 v[20:23], v[160:163], v[206:209], v[0:3]
	v_mfma_f32_16x16x32_bf16 v[0:3], v[148:151], v[210:213], v[38:41]
	v_mfma_f32_16x16x32_bf16 v[12:15], v[152:155], v[214:217], v[0:3]
	v_mfma_f32_16x16x32_bf16 v[0:3], v[156:159], v[210:213], v[42:45]
	v_mfma_f32_16x16x32_bf16 v[4:7], v[160:163], v[214:217], v[0:3]
	v_mfma_f32_16x16x32_bf16 v[0:3], v[164:167], v[184:187], v[46:49]
	v_mfma_f32_16x16x32_bf16 v[38:41], v[168:171], v[188:191], v[0:3]
	v_mfma_f32_16x16x32_bf16 v[0:3], v[176:179], v[184:187], v[50:53]
	v_mfma_f32_16x16x32_bf16 v[42:45], v[180:183], v[188:191], v[0:3]
	v_mfma_f32_16x16x32_bf16 v[0:3], v[164:167], v[192:195], v[62:65]
	v_mfma_f32_16x16x32_bf16 v[46:49], v[168:171], v[196:199], v[0:3]
	v_mfma_f32_16x16x32_bf16 v[0:3], v[176:179], v[192:195], v[66:69]
	v_mfma_f32_16x16x32_bf16 v[32:35], v[180:183], v[196:199], v[0:3]
	v_mfma_f32_16x16x32_bf16 v[0:3], v[164:167], v[200:203], v[98:101]
	v_mfma_f32_16x16x32_bf16 v[24:27], v[168:171], v[206:209], v[0:3]
	v_mfma_f32_16x16x32_bf16 v[0:3], v[176:179], v[200:203], v[144:147]
	v_mfma_f32_16x16x32_bf16 v[16:19], v[180:183], v[206:209], v[0:3]
	v_mfma_f32_16x16x32_bf16 v[0:3], v[164:167], v[210:213], v[54:57]
	v_mfma_f32_16x16x32_bf16 v[8:11], v[168:171], v[214:217], v[0:3]
	v_mfma_f32_16x16x32_bf16 v[0:3], v[176:179], v[210:213], v[58:61]
	v_mfma_f32_16x16x32_bf16 v[0:3], v[180:183], v[214:217], v[0:3]
	s_setprio 0
	s_barrier
; __device__ __forceinline__ unsigned cvtpk(float lo, float hi) { unsigned r; asm volatile("v_cvt_pk_bf16_f32 %0, %1, %2" : "=v"(r) : "v"(lo), "v"(hi)); return r; }
; #define PG8_WAIT_V(n) asm volatile("s_waitcnt vmcnt(" #n ")" ::: "memory")
; #define PG8_BAR __builtin_amdgcn_s_barrier()
;     __device__ __forceinline__ void operator()(const f32x4 (&acc)[2][2][4][2], const Unit& u, int wr, int wc, int fr, int fq) const {
;         const int row0 = u.pm * BM + wr * 64 + fr; const int col0 = u.pn * BM + wc * 32 + 8 * fq;
; #pragma unroll
;         for (int ai = 0; ai < 2; ++ai)
; #pragma unroll
;             for (int m = 0; m < 4; ++m) { bf16* rowp = O + (size_t)(row0 + ai * HALF + m * 16) * ldc + col0;
; #pragma unroll
;                 for (int bj = 0; bj < 2; ++bj) { const f32x4 v0 = acc[ai][bj][m][0], v1 = acc[ai][bj][m][1];
;                     u32x4 w; w.x = cvtpk(v0[0], v0[1]); w.y = cvtpk(v0[2], v0[3]); w.z = cvtpk(v1[0], v1[1]); w.w = cvtpk(v1[2], v1[3]);
;                     *(u32x4*)(rowp + bj * HALF) = w; } }
;     }
; template <class Epi, class Sched, bool ALIGN_EPI = false, bool SP2 = false>
; __device__ __forceinline__ void gemm_phase(PG8_LAS unsigned char* lds, const Gemm g, const Sched& S, const Epi& E, const int wv0) {
;     ...
;     PG8_WAIT_V(0);
;     if constexpr (!ALIGN_EPI) { if (wr == 0) PG8_BAR; }
;     PG8_BAR;
	v_add_u32_e32 v54, s26, v36
	v_or_b32_e32 v36, s49, v37
	v_ashrrev_i32_e32 v55, 31, v54
	v_or_b32_e32 v50, s50, v36
	v_lshlrev_b64 v[36:37], 11, v[54:55]
	v_lshl_add_u64 v[36:37], s[6:7], 0, v[36:37]
	v_lshlrev_b32_e32 v128, 1, v50
	v_lshl_add_u64 v[36:37], v[36:37], 0, v[128:129]
	v_cvt_pk_bf16_f32 v50, v102, v103
	v_cvt_pk_bf16_f32 v51, v104, v105
	v_cvt_pk_bf16_f32 v52, v106, v107
	v_cvt_pk_bf16_f32 v53, v108, v109
	global_store_dwordx4 v[36:37], v[50:53], off
	s_cmpk_gt_u32 s27, 0xff
	s_nop 0
	v_cvt_pk_bf16_f32 v50, v138, v139
	v_cvt_pk_bf16_f32 v51, v140, v141
	v_cvt_pk_bf16_f32 v52, v70, v71
	v_cvt_pk_bf16_f32 v53, v72, v73
	global_store_dwordx4 v[36:37], v[50:53], off offset:256
	s_nop 1
	v_or_b32_e32 v50, 16, v54
	v_ashrrev_i32_e32 v51, 31, v50
	v_lshlrev_b64 v[50:51], 11, v[50:51]
	v_lshl_add_u64 v[50:51], s[6:7], 0, v[50:51]
	v_lshl_add_u64 v[56:57], v[50:51], 0, v[128:129]
	v_cvt_pk_bf16_f32 v50, v110, v111
	v_cvt_pk_bf16_f32 v51, v112, v113
	v_cvt_pk_bf16_f32 v52, v114, v115
	v_cvt_pk_bf16_f32 v53, v116, v117
	global_store_dwordx4 v[56:57], v[50:53], off
	s_nop 1
	v_cvt_pk_bf16_f32 v50, v74, v75
	v_cvt_pk_bf16_f32 v51, v76, v77
	v_cvt_pk_bf16_f32 v52, v78, v79
	v_cvt_pk_bf16_f32 v53, v80, v81
	global_store_dwordx4 v[56:57], v[50:53], off offset:256
	s_nop 1
	v_or_b32_e32 v50, 32, v54
	v_ashrrev_i32_e32 v51, 31, v50
	v_lshlrev_b64 v[50:51], 11, v[50:51]
	v_lshl_add_u64 v[50:51], s[6:7], 0, v[50:51]
	v_lshl_add_u64 v[56:57], v[50:51], 0, v[128:129]
	v_cvt_pk_bf16_f32 v50, v118, v119
	v_cvt_pk_bf16_f32 v51, v120, v121
	v_cvt_pk_bf16_f32 v52, v122, v123
	v_cvt_pk_bf16_f32 v53, v124, v125
	global_store_dwordx4 v[56:57], v[50:53], off
	s_nop 1
	v_cvt_pk_bf16_f32 v50, v82, v83
	v_cvt_pk_bf16_f32 v51, v84, v85
	v_cvt_pk_bf16_f32 v52, v86, v87
	v_cvt_pk_bf16_f32 v53, v88, v89
	global_store_dwordx4 v[56:57], v[50:53], off offset:256
	v_add_co_u32_e32 v56, vcc, s39, v36
	s_nop 0
	v_or_b32_e32 v50, 48, v54
	v_ashrrev_i32_e32 v51, 31, v50
	v_lshlrev_b64 v[50:51], 11, v[50:51]
	v_lshl_add_u64 v[50:51], s[6:7], 0, v[50:51]
	v_lshl_add_u64 v[54:55], v[50:51], 0, v[128:129]
	v_cvt_pk_bf16_f32 v50, v130, v131
	v_cvt_pk_bf16_f32 v51, v132, v133
	v_cvt_pk_bf16_f32 v52, v134, v135
	v_cvt_pk_bf16_f32 v53, v136, v137
	global_store_dwordx4 v[54:55], v[50:53], off
	v_addc_co_u32_e32 v57, vcc, 0, v37, vcc
	s_nop 0
	v_cvt_pk_bf16_f32 v50, v90, v91
	v_cvt_pk_bf16_f32 v51, v92, v93
	v_cvt_pk_bf16_f32 v52, v94, v95
	v_cvt_pk_bf16_f32 v53, v96, v97
	global_store_dwordx4 v[54:55], v[50:53], off offset:256
	v_lshl_add_u64 v[54:55], v[36:37], 0, s[8:9]
	s_nop 0
	v_cvt_pk_bf16_f32 v50, v218, v219
	v_cvt_pk_bf16_f32 v51, v220, v221
	v_cvt_pk_bf16_f32 v52, v222, v223
	v_cvt_pk_bf16_f32 v53, v224, v225
	global_store_dwordx4 v[56:57], v[50:53], off
	v_cvt_pk_bf16_f32 v38, v38, v39
	v_cvt_pk_bf16_f32 v39, v40, v41
	v_cvt_pk_bf16_f32 v40, v42, v43
	v_cvt_pk_bf16_f32 v41, v44, v45
	v_add_co_u32_e32 v44, vcc, s40, v36
	global_store_dwordx4 v[54:55], v[38:41], off offset:256
	v_lshl_add_u64 v[42:43], v[36:37], 0, s[16:17]
	v_addc_co_u32_e32 v45, vcc, 0, v37, vcc
	v_cvt_pk_bf16_f32 v38, v226, v227
	v_cvt_pk_bf16_f32 v39, v228, v229
	v_cvt_pk_bf16_f32 v40, v230, v231
	v_cvt_pk_bf16_f32 v41, v232, v233
	global_store_dwordx4 v[44:45], v[38:41], off
	s_nop 1
	v_cvt_pk_bf16_f32 v38, v46, v47
	v_cvt_pk_bf16_f32 v39, v48, v49
	v_cvt_pk_bf16_f32 v40, v32, v33
	v_cvt_pk_bf16_f32 v41, v34, v35
	global_store_dwordx4 v[42:43], v[38:41], off offset:256
	v_cvt_pk_bf16_f32 v28, v28, v29
	v_cvt_pk_bf16_f32 v29, v30, v31
	v_cvt_pk_bf16_f32 v30, v20, v21
	v_add_co_u32_e32 v20, vcc, s41, v36
	v_lshl_add_u64 v[32:33], v[36:37], 0, s[18:19]
	s_nop 0
	v_addc_co_u32_e32 v21, vcc, 0, v37, vcc
	v_cvt_pk_bf16_f32 v31, v22, v23
	global_store_dwordx4 v[20:21], v[28:31], off
	v_cvt_pk_bf16_f32 v20, v24, v25
	v_cvt_pk_bf16_f32 v21, v26, v27
	v_cvt_pk_bf16_f32 v22, v16, v17
	v_cvt_pk_bf16_f32 v23, v18, v19
	global_store_dwordx4 v[32:33], v[20:23], off offset:256
	v_cvt_pk_bf16_f32 v12, v12, v13
	v_cvt_pk_bf16_f32 v13, v14, v15
	v_cvt_pk_bf16_f32 v14, v4, v5
	v_add_co_u32_e32 v4, vcc, s45, v36
	v_lshl_add_u64 v[16:17], v[36:37], 0, s[20:21]
	s_nop 0
	v_addc_co_u32_e32 v5, vcc, 0, v37, vcc
	v_cvt_pk_bf16_f32 v15, v6, v7
	global_store_dwordx4 v[4:5], v[12:15], off
	v_cvt_pk_bf16_f32 v4, v8, v9
	v_cvt_pk_bf16_f32 v5, v10, v11
	v_cvt_pk_bf16_f32 v6, v0, v1
	v_cvt_pk_bf16_f32 v7, v2, v3
	global_store_dwordx4 v[16:17], v[4:7], off offset:256
	s_waitcnt vmcnt(0)
	s_cbranch_scc1 .LBB0_1296
	s_barrier
	s_branch .LBB0_1296

; #define PG8_STAGE(bufoff, gbase, voff) do { _Pragma("unroll") for (int _i = 0; _i < 2; ++_i) \
;         __builtin_amdgcn_global_load_lds((const unsigned*)((const char*)(gbase) + (voff)[_i]), (PG8_LAS unsigned*)(lds + (bufoff) + ldsw + _i * 8192), 16, 0, 0); } while (0)
; #define PG8_LDA(dst, b, h) do { _Pragma("unroll") for (int m = 0; m < 4; ++m) _Pragma("unroll") for (int k = 0; k < 2; ++k) dst[m][k] = *(const PG8_LAS bf16x8*)(lds + PG8_SA(b, h) + aoff + m * 2048 + k * 1024); } while (0)
; #define PG8_LDB(dst, b, h) do { _Pragma("unroll") for (int n = 0; n < 2; ++n) _Pragma("unroll") for (int k = 0; k < 2; ++k) dst[n][k] = *(const PG8_LAS bf16x8*)(lds + PG8_SB(b, h) + boff + n * 2048 + k * 1024); } while (0)
; #define PG8_MMA(ai, bj, At, Bt) do { __builtin_amdgcn_s_setprio(1); _Pragma("unroll") for (int m = 0; m < 4; ++m) _Pragma("unroll") for (int n = 0; n < 2; ++n) _Pragma("unroll") for (int k = 0; k < 2; ++k) \
;         acc[ai][bj][m][n] = __builtin_amdgcn_mfma_f32_16x16x32_bf16(Bt[n][k], At[m][k], acc[ai][bj][m][n], 0, 0, 0); __builtin_amdgcn_s_setprio(0); } while (0)
; #define PG8_WAIT_V(n) asm volatile("s_waitcnt vmcnt(" #n ")" ::: "memory")
; #define PG8_WAIT_L(n) asm volatile("s_waitcnt lgkmcnt(" #n ")" ::: "memory")
; #define PG8_BAR __builtin_amdgcn_s_barrier()
; #define PG8_SCHED __builtin_amdgcn_sched_barrier(0)
; template <class Epi, class Sched, bool ALIGN_EPI = false, bool SP2 = false>
; __device__ __forceinline__ void gemm_phase(PG8_LAS unsigned char* lds, const Gemm g, const Sched& S, const Epi& E, const int wv0) {
;     ...
;             PG8_LDB(B0, 0, 0); PG8_LDB(B1, 0, 1); PG8_SCHED; PG8_LDA(At, 0, 0); PG8_STAGE(PG8_SA(1, 1), a1 + hstepA, voffA);
;             PG8_WAIT_V(8); PG8_WAIT_L(0); PG8_BAR; PG8_MMA(0, 0, At, B0); PG8_MMA(0, 1, At, B1); PG8_BAR; PG8_SCHED;
;             PG8_LDA(At, 0, 1); PG8_STAGE(PG8_SB(0, 0), b2, voffB); PG8_STAGE(PG8_SB(0, 1), b2 + hstepB, voffB); PG8_STAGE(PG8_SA(0, 0), a2, voffA);
.LBB0_1608:
	ds_read_b128 v[144:147], v155
	ds_read_b128 v[148:151], v155 offset:1024
	ds_read_b128 v[158:161], v155 offset:2048
	ds_read_b128 v[162:165], v155 offset:3072
	ds_read_b128 v[166:169], v156
	ds_read_b128 v[170:173], v156 offset:1024
	ds_read_b128 v[174:177], v156 offset:2048
	ds_read_b128 v[178:181], v156 offset:3072
	s_add_u32 s30, s28, 0xfff80080
	s_addc_u32 s31, s29, -1
	s_cmp_eq_u32 s56, 28
	s_cselect_b32 s35, s23, s31
	s_cselect_b32 s34, s22, s30
	s_cselect_b32 s31, s25, s21
	s_cselect_b32 s30, s24, s19
	v_lshl_add_u64 v[202:203], s[28:29], 0, v[138:139]
	s_add_i32 m0, s27, 0xc000
	ds_read_b128 v[182:185], v157
	ds_read_b128 v[186:189], v157 offset:1024
	ds_read_b128 v[190:193], v157 offset:2048
	ds_read_b128 v[194:197], v157 offset:3072
	ds_read_b128 v[198:201], v157 offset:4096
	ds_read_b128 v[206:209], v157 offset:5120
	ds_read_b128 v[210:213], v157 offset:6144
	ds_read_b128 v[214:217], v157 offset:7168
	global_load_lds_dwordx4 v[202:203], off
	v_lshl_add_u64 v[202:203], s[28:29], 0, v[136:137]
	s_add_i32 m0, s27, 0xe000
	s_nop 0
	global_load_lds_dwordx4 v[202:203], off
	s_waitcnt vmcnt(8)
	s_waitcnt lgkmcnt(0)
	s_barrier
	s_setprio 1
	v_mfma_f32_16x16x32_bf16 v[124:127], v[144:147], v[182:185], v[124:127]
	v_mfma_f32_16x16x32_bf16 v[120:123], v[158:161], v[182:185], v[120:123]
	v_mfma_f32_16x16x32_bf16 v[116:119], v[144:147], v[190:193], v[116:119]
	v_mfma_f32_16x16x32_bf16 v[112:115], v[158:161], v[190:193], v[112:115]
	v_mfma_f32_16x16x32_bf16 v[92:95], v[144:147], v[198:201], v[92:95]
	v_mfma_f32_16x16x32_bf16 v[88:91], v[158:161], v[198:201], v[88:91]
	v_mfma_f32_16x16x32_bf16 v[84:87], v[144:147], v[210:213], v[84:87]
	v_mfma_f32_16x16x32_bf16 v[80:83], v[158:161], v[210:213], v[80:83]
	v_mfma_f32_16x16x32_bf16 v[124:127], v[148:151], v[186:189], v[124:127]
	v_mfma_f32_16x16x32_bf16 v[120:123], v[162:165], v[186:189], v[120:123]
	v_mfma_f32_16x16x32_bf16 v[116:119], v[148:151], v[194:197], v[116:119]
	v_mfma_f32_16x16x32_bf16 v[112:115], v[162:165], v[194:197], v[112:115]
	v_mfma_f32_16x16x32_bf16 v[92:95], v[148:151], v[206:209], v[92:95]
	v_mfma_f32_16x16x32_bf16 v[88:91], v[162:165], v[206:209], v[88:91]
	v_mfma_f32_16x16x32_bf16 v[84:87], v[148:151], v[214:217], v[84:87]
	v_mfma_f32_16x16x32_bf16 v[80:83], v[162:165], v[214:217], v[80:83]
	v_mfma_f32_16x16x32_bf16 v[108:111], v[166:169], v[182:185], v[108:111]
	v_mfma_f32_16x16x32_bf16 v[104:107], v[174:177], v[182:185], v[104:107]
	v_mfma_f32_16x16x32_bf16 v[100:103], v[166:169], v[190:193], v[100:103]
	v_mfma_f32_16x16x32_bf16 v[96:99], v[174:177], v[190:193], v[96:99]
	v_mfma_f32_16x16x32_bf16 v[76:79], v[166:169], v[198:201], v[76:79]
	v_mfma_f32_16x16x32_bf16 v[72:75], v[174:177], v[198:201], v[72:75]
	v_mfma_f32_16x16x32_bf16 v[68:71], v[166:169], v[210:213], v[68:71]
	v_mfma_f32_16x16x32_bf16 v[64:67], v[174:177], v[210:213], v[64:67]
	v_mfma_f32_16x16x32_bf16 v[108:111], v[170:173], v[186:189], v[108:111]
	v_mfma_f32_16x16x32_bf16 v[104:107], v[178:181], v[186:189], v[104:107]
	v_mfma_f32_16x16x32_bf16 v[100:103], v[170:173], v[194:197], v[100:103]
	v_mfma_f32_16x16x32_bf16 v[96:99], v[178:181], v[194:197], v[96:99]
	v_mfma_f32_16x16x32_bf16 v[76:79], v[170:173], v[206:209], v[76:79]
	v_mfma_f32_16x16x32_bf16 v[72:75], v[178:181], v[206:209], v[72:75]
	v_mfma_f32_16x16x32_bf16 v[68:71], v[170:173], v[214:217], v[68:71]
	v_mfma_f32_16x16x32_bf16 v[64:67], v[178:181], v[214:217], v[64:67]
	s_setprio 0
	s_barrier
	s_add_i32 s57, s53, s45
	v_lshl_add_u64 v[202:203], s[30:31], 0, v[130:131]
	s_mov_b32 m0, s57
	ds_read_b128 v[182:185], v157 offset:16384
	ds_read_b128 v[186:189], v157 offset:17408
	ds_read_b128 v[190:193], v157 offset:18432
	ds_read_b128 v[194:197], v157 offset:19456
	ds_read_b128 v[198:201], v157 offset:20480
	ds_read_b128 v[206:209], v157 offset:21504
	ds_read_b128 v[210:213], v157 offset:22528
	ds_read_b128 v[214:217], v157 offset:23552
	global_load_lds_dwordx4 v[202:203], off
	s_add_i32 m0, s57, 0x2000
	s_add_u32 s58, s30, 0x80000
	v_lshl_add_u64 v[218:219], s[30:31], 0, v[134:135]
	s_addc_u32 s59, s31, 0
	s_add_i32 s57, s54, s45
	global_load_lds_dwordx4 v[218:219], off
	v_lshl_add_u64 v[220:221], s[58:59], 0, v[130:131]
	s_mov_b32 m0, s57
	v_lshl_add_u64 v[222:223], s[34:35], 0, v[132:133]
	global_load_lds_dwordx4 v[220:221], off
	v_lshl_add_u64 v[220:221], s[58:59], 0, v[134:135]
	s_add_i32 m0, s57, 0x2000
	s_nop 0
	global_load_lds_dwordx4 v[220:221], off
	v_lshl_add_u64 v[220:221], s[34:35], 0, v[128:129]
	s_mov_b32 m0, s27
	s_nop 0
	global_load_lds_dwordx4 v[220:221], off
	s_mov_b32 m0, s46
	s_nop 0
	global_load_lds_dwordx4 v[222:223], off
	s_waitcnt vmcnt(8)
	s_waitcnt lgkmcnt(0)
	s_barrier
; #define PG8_STAGE(bufoff, gbase, voff) do { _Pragma("unroll") for (int _i = 0; _i < 2; ++_i) \
;         __builtin_amdgcn_global_load_lds((const unsigned*)((const char*)(gbase) + (voff)[_i]), (PG8_LAS unsigned*)(lds + (bufoff) + ldsw + _i * 8192), 16, 0, 0); } while (0)
; #define PG8_LDA(dst, b, h) do { _Pragma("unroll") for (int m = 0; m < 4; ++m) _Pragma("unroll") for (int k = 0; k < 2; ++k) dst[m][k] = *(const PG8_LAS bf16x8*)(lds + PG8_SA(b, h) + aoff + m * 2048 + k * 1024); } while (0)
; #define PG8_LDB(dst, b, h) do { _Pragma("unroll") for (int n = 0; n < 2; ++n) _Pragma("unroll") for (int k = 0; k < 2; ++k) dst[n][k] = *(const PG8_LAS bf16x8*)(lds + PG8_SB(b, h) + boff + n * 2048 + k * 1024); } while (0)
; #define PG8_MMA(ai, bj, At, Bt) do { __builtin_amdgcn_s_setprio(1); _Pragma("unroll") for (int m = 0; m < 4; ++m) _Pragma("unroll") for (int n = 0; n < 2; ++n) _Pragma("unroll") for (int k = 0; k < 2; ++k) \
;         acc[ai][bj][m][n] = __builtin_amdgcn_mfma_f32_16x16x32_bf16(Bt[n][k], At[m][k], acc[ai][bj][m][n], 0, 0, 0); __builtin_amdgcn_s_setprio(0); } while (0)
; #define PG8_WAIT_V(n) asm volatile("s_waitcnt vmcnt(" #n ")" ::: "memory")
; #define PG8_WAIT_L(n) asm volatile("s_waitcnt lgkmcnt(" #n ")" ::: "memory")
; #define PG8_BAR __builtin_amdgcn_s_barrier()
; #define PG8_SCHED __builtin_amdgcn_sched_barrier(0)
; template <class Epi, class Sched, bool ALIGN_EPI = false, bool SP2 = false>
; __device__ __forceinline__ void gemm_phase(PG8_LAS unsigned char* lds, const Gemm g, const Sched& S, const Epi& E, const int wv0) {
;     ...
;             PG8_WAIT_V(8); PG8_WAIT_L(0); PG8_BAR; PG8_MMA(1, 0, At, B0); PG8_MMA(1, 1, At, B1); PG8_BAR; PG8_SCHED;
;             PG8_LDB(B0, 1, 0); PG8_LDB(B1, 1, 1); PG8_SCHED; PG8_LDA(At, 1, 0); PG8_STAGE(PG8_SA(0, 1), a2 + hstepA, voffA);
;             PG8_WAIT_V(8); PG8_WAIT_L(0); PG8_BAR; PG8_MMA(0, 0, At, B0); PG8_MMA(0, 1, At, B1); PG8_BAR; PG8_SCHED;
	s_setprio 1
	v_mfma_f32_16x16x32_bf16 v[60:63], v[144:147], v[182:185], v[60:63]
	v_mfma_f32_16x16x32_bf16 v[56:59], v[158:161], v[182:185], v[56:59]
	v_mfma_f32_16x16x32_bf16 v[52:55], v[144:147], v[190:193], v[52:55]
	v_mfma_f32_16x16x32_bf16 v[48:51], v[158:161], v[190:193], v[48:51]
	v_mfma_f32_16x16x32_bf16 v[28:31], v[144:147], v[198:201], v[28:31]
	v_mfma_f32_16x16x32_bf16 v[24:27], v[158:161], v[198:201], v[24:27]
	v_mfma_f32_16x16x32_bf16 v[20:23], v[144:147], v[210:213], v[20:23]
	v_mfma_f32_16x16x32_bf16 v[16:19], v[158:161], v[210:213], v[16:19]
	v_mfma_f32_16x16x32_bf16 v[60:63], v[148:151], v[186:189], v[60:63]
	v_mfma_f32_16x16x32_bf16 v[56:59], v[162:165], v[186:189], v[56:59]
	v_mfma_f32_16x16x32_bf16 v[52:55], v[148:151], v[194:197], v[52:55]
	v_mfma_f32_16x16x32_bf16 v[48:51], v[162:165], v[194:197], v[48:51]
	v_mfma_f32_16x16x32_bf16 v[28:31], v[148:151], v[206:209], v[28:31]
	v_mfma_f32_16x16x32_bf16 v[24:27], v[162:165], v[206:209], v[24:27]
	v_mfma_f32_16x16x32_bf16 v[20:23], v[148:151], v[214:217], v[20:23]
	v_mfma_f32_16x16x32_bf16 v[16:19], v[162:165], v[214:217], v[16:19]
	v_mfma_f32_16x16x32_bf16 v[44:47], v[166:169], v[182:185], v[44:47]
	v_mfma_f32_16x16x32_bf16 v[40:43], v[174:177], v[182:185], v[40:43]
	v_mfma_f32_16x16x32_bf16 v[36:39], v[166:169], v[190:193], v[36:39]
	v_mfma_f32_16x16x32_bf16 v[32:35], v[174:177], v[190:193], v[32:35]
	v_mfma_f32_16x16x32_bf16 v[12:15], v[166:169], v[198:201], v[12:15]
	v_mfma_f32_16x16x32_bf16 v[8:11], v[174:177], v[198:201], v[8:11]
	v_mfma_f32_16x16x32_bf16 v[4:7], v[166:169], v[210:213], v[4:7]
	v_mfma_f32_16x16x32_bf16 v[0:3], v[174:177], v[210:213], v[0:3]
	v_mfma_f32_16x16x32_bf16 v[44:47], v[170:173], v[186:189], v[44:47]
	v_mfma_f32_16x16x32_bf16 v[40:43], v[178:181], v[186:189], v[40:43]
	v_mfma_f32_16x16x32_bf16 v[36:39], v[170:173], v[194:197], v[36:39]
	v_mfma_f32_16x16x32_bf16 v[32:35], v[178:181], v[194:197], v[32:35]
	v_mfma_f32_16x16x32_bf16 v[12:15], v[170:173], v[206:209], v[12:15]
	v_mfma_f32_16x16x32_bf16 v[8:11], v[178:181], v[206:209], v[8:11]
	v_mfma_f32_16x16x32_bf16 v[4:7], v[170:173], v[214:217], v[4:7]
	v_mfma_f32_16x16x32_bf16 v[0:3], v[178:181], v[214:217], v[0:3]
	s_setprio 0
	s_barrier
	s_add_i32 s57, 0, 0x18000
	s_add_i32 s58, 0, 0x1c000
	v_add_u32_e32 v162, s57, v153
	v_add_u32_e32 v178, s58, v153
	ds_read_b128 v[144:147], v162
	ds_read_b128 v[148:151], v162 offset:1024
	ds_read_b128 v[158:161], v162 offset:2048
	ds_read_b128 v[162:165], v162 offset:3072
	ds_read_b128 v[166:169], v178
	ds_read_b128 v[170:173], v178 offset:1024
	ds_read_b128 v[174:177], v178 offset:2048
	ds_read_b128 v[178:181], v178 offset:3072
	s_add_u32 s34, s34, 0x80000
	s_addc_u32 s35, s35, 0
	s_mov_b32 m0, s47
	v_lshl_add_u64 v[224:225], s[34:35], 0, v[128:129]
	ds_read_b128 v[182:185], v157 offset:32768
	ds_read_b128 v[186:189], v157 offset:33792
	ds_read_b128 v[190:193], v157 offset:34816
	ds_read_b128 v[194:197], v157 offset:35840
	ds_read_b128 v[198:201], v157 offset:36864
	ds_read_b128 v[206:209], v157 offset:37888
	ds_read_b128 v[210:213], v157 offset:38912
	ds_read_b128 v[214:217], v157 offset:39936
	global_load_lds_dwordx4 v[224:225], off
	v_lshl_add_u64 v[224:225], s[34:35], 0, v[132:133]
	s_mov_b32 m0, s48
	s_nop 0
	global_load_lds_dwordx4 v[224:225], off
	s_waitcnt vmcnt(8)
	s_waitcnt lgkmcnt(0)
	s_barrier
	s_setprio 1
	v_mfma_f32_16x16x32_bf16 v[124:127], v[144:147], v[182:185], v[124:127]
	v_mfma_f32_16x16x32_bf16 v[120:123], v[158:161], v[182:185], v[120:123]
	v_mfma_f32_16x16x32_bf16 v[116:119], v[144:147], v[190:193], v[116:119]
	v_mfma_f32_16x16x32_bf16 v[112:115], v[158:161], v[190:193], v[112:115]
	v_mfma_f32_16x16x32_bf16 v[92:95], v[144:147], v[198:201], v[92:95]
	v_mfma_f32_16x16x32_bf16 v[88:91], v[158:161], v[198:201], v[88:91]
	v_mfma_f32_16x16x32_bf16 v[84:87], v[144:147], v[210:213], v[84:87]
	v_mfma_f32_16x16x32_bf16 v[80:83], v[158:161], v[210:213], v[80:83]
	v_mfma_f32_16x16x32_bf16 v[124:127], v[148:151], v[186:189], v[124:127]
	v_mfma_f32_16x16x32_bf16 v[120:123], v[162:165], v[186:189], v[120:123]
	v_mfma_f32_16x16x32_bf16 v[116:119], v[148:151], v[194:197], v[116:119]
	v_mfma_f32_16x16x32_bf16 v[112:115], v[162:165], v[194:197], v[112:115]
	v_mfma_f32_16x16x32_bf16 v[92:95], v[148:151], v[206:209], v[92:95]
	v_mfma_f32_16x16x32_bf16 v[88:91], v[162:165], v[206:209], v[88:91]
	v_mfma_f32_16x16x32_bf16 v[84:87], v[148:151], v[214:217], v[84:87]
	v_mfma_f32_16x16x32_bf16 v[80:83], v[162:165], v[214:217], v[80:83]
	v_mfma_f32_16x16x32_bf16 v[108:111], v[166:169], v[182:185], v[108:111]
	v_mfma_f32_16x16x32_bf16 v[104:107], v[174:177], v[182:185], v[104:107]
	v_mfma_f32_16x16x32_bf16 v[100:103], v[166:169], v[190:193], v[100:103]
	v_mfma_f32_16x16x32_bf16 v[96:99], v[174:177], v[190:193], v[96:99]
	v_mfma_f32_16x16x32_bf16 v[76:79], v[166:169], v[198:201], v[76:79]
	v_mfma_f32_16x16x32_bf16 v[72:75], v[174:177], v[198:201], v[72:75]
	v_mfma_f32_16x16x32_bf16 v[68:71], v[166:169], v[210:213], v[68:71]
	v_mfma_f32_16x16x32_bf16 v[64:67], v[174:177], v[210:213], v[64:67]
	v_mfma_f32_16x16x32_bf16 v[108:111], v[170:173], v[186:189], v[108:111]
	v_mfma_f32_16x16x32_bf16 v[104:107], v[178:181], v[186:189], v[104:107]
	v_mfma_f32_16x16x32_bf16 v[100:103], v[170:173], v[194:197], v[100:103]
	v_mfma_f32_16x16x32_bf16 v[96:99], v[178:181], v[194:197], v[96:99]
	v_mfma_f32_16x16x32_bf16 v[76:79], v[170:173], v[206:209], v[76:79]
	v_mfma_f32_16x16x32_bf16 v[72:75], v[178:181], v[206:209], v[72:75]
	v_mfma_f32_16x16x32_bf16 v[68:71], v[170:173], v[214:217], v[68:71]
	v_mfma_f32_16x16x32_bf16 v[64:67], v[178:181], v[214:217], v[64:67]
	s_setprio 0
	s_barrier
; #define PG8_STAGE(bufoff, gbase, voff) do { _Pragma("unroll") for (int _i = 0; _i < 2; ++_i) \
;         __builtin_amdgcn_global_load_lds((const unsigned*)((const char*)(gbase) + (voff)[_i]), (PG8_LAS unsigned*)(lds + (bufoff) + ldsw + _i * 8192), 16, 0, 0); } while (0)
; #define PG8_LDA(dst, b, h) do { _Pragma("unroll") for (int m = 0; m < 4; ++m) _Pragma("unroll") for (int k = 0; k < 2; ++k) dst[m][k] = *(const PG8_LAS bf16x8*)(lds + PG8_SA(b, h) + aoff + m * 2048 + k * 1024); } while (0)
; #define PG8_MMA(ai, bj, At, Bt) do { __builtin_amdgcn_s_setprio(1); _Pragma("unroll") for (int m = 0; m < 4; ++m) _Pragma("unroll") for (int n = 0; n < 2; ++n) _Pragma("unroll") for (int k = 0; k < 2; ++k) \
;         acc[ai][bj][m][n] = __builtin_amdgcn_mfma_f32_16x16x32_bf16(Bt[n][k], At[m][k], acc[ai][bj][m][n], 0, 0, 0); __builtin_amdgcn_s_setprio(0); } while (0)
; #define PG8_WAIT_V(n) asm volatile("s_waitcnt vmcnt(" #n ")" ::: "memory")
; #define PG8_WAIT_L(n) asm volatile("s_waitcnt lgkmcnt(" #n ")" ::: "memory")
; #define PG8_BAR __builtin_amdgcn_s_barrier()
; #define PG8_SCHED __builtin_amdgcn_sched_barrier(0)
; template <class Epi, class Sched, bool ALIGN_EPI = false, bool SP2 = false>
; __device__ __forceinline__ void gemm_phase(PG8_LAS unsigned char* lds, const Gemm g, const Sched& S, const Epi& E, const int wv0) {
;     ...
;         for (int t = 0; t < nt; t += 2) {
;             const bool last = (t == nt - 2);
;             const char* a1 = cA + (size_t)(t + 1) * kstep;
;             const char* a2 = last ? nA : cA + (size_t)(t + 2) * kstep; const char* b2 = last ? nB : cB + (size_t)(t + 2) * kstep;
;     ...
;             PG8_LDA(At, 1, 1); PG8_STAGE(PG8_SB(1, 0), b3, voffB); PG8_STAGE(PG8_SB(1, 1), b3 + hstepB, voffB); PG8_STAGE(PG8_SA(1, 0), a3, voffA);
;             PG8_WAIT_V(8); PG8_WAIT_L(0); PG8_BAR; PG8_MMA(1, 0, At, B0); PG8_MMA(1, 1, At, B1); PG8_BAR; PG8_SCHED;
	s_add_i32 s34, s57, s45
	v_lshl_add_u64 v[202:203], v[202:203], 0, s[8:9]
	s_mov_b32 m0, s34
	ds_read_b128 v[182:185], v157 offset:49152
	ds_read_b128 v[186:189], v157 offset:50176
	ds_read_b128 v[190:193], v157 offset:51200
	ds_read_b128 v[194:197], v157 offset:52224
	ds_read_b128 v[198:201], v157 offset:53248
	ds_read_b128 v[206:209], v157 offset:54272
	ds_read_b128 v[210:213], v157 offset:55296
	ds_read_b128 v[214:217], v157 offset:56320
	global_load_lds_dwordx4 v[202:203], off
	s_add_i32 m0, s34, 0x2000
	s_add_u32 s30, s30, 0x80080
	v_lshl_add_u64 v[202:203], v[218:219], 0, s[8:9]
	s_addc_u32 s31, s31, 0
	s_add_i32 s34, s58, s45
	global_load_lds_dwordx4 v[202:203], off
	v_lshl_add_u64 v[202:203], s[30:31], 0, v[130:131]
	s_mov_b32 m0, s34
	s_nop 0
	global_load_lds_dwordx4 v[202:203], off
	v_lshl_add_u64 v[202:203], s[30:31], 0, v[134:135]
	s_add_i32 m0, s34, 0x2000
	s_nop 0
	global_load_lds_dwordx4 v[202:203], off
	v_lshl_add_u64 v[202:203], v[220:221], 0, s[8:9]
	s_mov_b32 m0, s50
	s_nop 0
	global_load_lds_dwordx4 v[202:203], off
	v_lshl_add_u64 v[202:203], v[222:223], 0, s[8:9]
	s_mov_b32 m0, s51
	s_nop 0
	global_load_lds_dwordx4 v[202:203], off
	s_waitcnt vmcnt(8)
	s_waitcnt lgkmcnt(0)
	s_barrier
	s_setprio 1
	v_mfma_f32_16x16x32_bf16 v[60:63], v[144:147], v[182:185], v[60:63]
	v_mfma_f32_16x16x32_bf16 v[56:59], v[158:161], v[182:185], v[56:59]
	v_mfma_f32_16x16x32_bf16 v[52:55], v[144:147], v[190:193], v[52:55]
	v_mfma_f32_16x16x32_bf16 v[48:51], v[158:161], v[190:193], v[48:51]
	v_mfma_f32_16x16x32_bf16 v[28:31], v[144:147], v[198:201], v[28:31]
	v_mfma_f32_16x16x32_bf16 v[24:27], v[158:161], v[198:201], v[24:27]
	v_mfma_f32_16x16x32_bf16 v[20:23], v[144:147], v[210:213], v[20:23]
	v_mfma_f32_16x16x32_bf16 v[16:19], v[158:161], v[210:213], v[16:19]
	v_mfma_f32_16x16x32_bf16 v[60:63], v[148:151], v[186:189], v[60:63]
	v_mfma_f32_16x16x32_bf16 v[56:59], v[162:165], v[186:189], v[56:59]
	v_mfma_f32_16x16x32_bf16 v[52:55], v[148:151], v[194:197], v[52:55]
	v_mfma_f32_16x16x32_bf16 v[48:51], v[162:165], v[194:197], v[48:51]
	v_mfma_f32_16x16x32_bf16 v[28:31], v[148:151], v[206:209], v[28:31]
	v_mfma_f32_16x16x32_bf16 v[24:27], v[162:165], v[206:209], v[24:27]
	v_mfma_f32_16x16x32_bf16 v[20:23], v[148:151], v[214:217], v[20:23]
	v_mfma_f32_16x16x32_bf16 v[16:19], v[162:165], v[214:217], v[16:19]
	v_mfma_f32_16x16x32_bf16 v[44:47], v[166:169], v[182:185], v[44:47]
	v_mfma_f32_16x16x32_bf16 v[40:43], v[174:177], v[182:185], v[40:43]
	v_mfma_f32_16x16x32_bf16 v[36:39], v[166:169], v[190:193], v[36:39]
	v_mfma_f32_16x16x32_bf16 v[32:35], v[174:177], v[190:193], v[32:35]
	v_mfma_f32_16x16x32_bf16 v[12:15], v[166:169], v[198:201], v[12:15]
	v_mfma_f32_16x16x32_bf16 v[8:11], v[174:177], v[198:201], v[8:11]
	v_mfma_f32_16x16x32_bf16 v[4:7], v[166:169], v[210:213], v[4:7]
	v_mfma_f32_16x16x32_bf16 v[0:3], v[174:177], v[210:213], v[0:3]
	v_mfma_f32_16x16x32_bf16 v[44:47], v[170:173], v[186:189], v[44:47]
	v_mfma_f32_16x16x32_bf16 v[40:43], v[178:181], v[186:189], v[40:43]
	v_mfma_f32_16x16x32_bf16 v[36:39], v[170:173], v[194:197], v[36:39]
	v_mfma_f32_16x16x32_bf16 v[32:35], v[178:181], v[194:197], v[32:35]
	v_mfma_f32_16x16x32_bf16 v[12:15], v[170:173], v[206:209], v[12:15]
	v_mfma_f32_16x16x32_bf16 v[8:11], v[178:181], v[206:209], v[8:11]
	v_mfma_f32_16x16x32_bf16 v[4:7], v[170:173], v[214:217], v[4:7]
	v_mfma_f32_16x16x32_bf16 v[0:3], v[178:181], v[214:217], v[0:3]
	s_setprio 0
	s_barrier
	s_add_i32 s56, s56, 2
	s_add_u32 s19, s19, 0x100
	s_addc_u32 s21, s21, 0
	s_add_u32 s28, s28, 0x100
	s_addc_u32 s29, s29, 0
	s_cmp_gt_u32 s56, 29
	s_cbranch_scc0 .LBB0_1608
	s_and_b64 vcc, exec, s[10:11]
	s_cbranch_vccz .LBB0_1611
	s_barrier

; #define PG8_STAGE(bufoff, gbase, voff) do { _Pragma("unroll") for (int _i = 0; _i < 2; ++_i) \
;         __builtin_amdgcn_global_load_lds((const unsigned*)((const char*)(gbase) + (voff)[_i]), (PG8_LAS unsigned*)(lds + (bufoff) + ldsw + _i * 8192), 16, 0, 0); } while (0)
; #define PG8_LDA(dst, b, h) do { _Pragma("unroll") for (int m = 0; m < 4; ++m) _Pragma("unroll") for (int k = 0; k < 2; ++k) dst[m][k] = *(const PG8_LAS bf16x8*)(lds + PG8_SA(b, h) + aoff + m * 2048 + k * 1024); } while (0)
; #define PG8_LDB(dst, b, h) do { _Pragma("unroll") for (int n = 0; n < 2; ++n) _Pragma("unroll") for (int k = 0; k < 2; ++k) dst[n][k] = *(const PG8_LAS bf16x8*)(lds + PG8_SB(b, h) + boff + n * 2048 + k * 1024); } while (0)
; #define PG8_MMA(ai, bj, At, Bt) do { __builtin_amdgcn_s_setprio(1); _Pragma("unroll") for (int m = 0; m < 4; ++m) _Pragma("unroll") for (int n = 0; n < 2; ++n) _Pragma("unroll") for (int k = 0; k < 2; ++k) \
;         acc[ai][bj][m][n] = __builtin_amdgcn_mfma_f32_16x16x32_bf16(Bt[n][k], At[m][k], acc[ai][bj][m][n], 0, 0, 0); __builtin_amdgcn_s_setprio(0); } while (0)
; #define PG8_WAIT_V(n) asm volatile("s_waitcnt vmcnt(" #n ")" ::: "memory")
; #define PG8_WAIT_L(n) asm volatile("s_waitcnt lgkmcnt(" #n ")" ::: "memory")
; #define PG8_BAR __builtin_amdgcn_s_barrier()
; #define PG8_SCHED __builtin_amdgcn_sched_barrier(0)
; template <class Epi, class Sched, bool ALIGN_EPI = false, bool SP2 = false>
; __device__ __forceinline__ void gemm_phase(PG8_LAS unsigned char* lds, const Gemm g, const Sched& S, const Epi& E, const int wv0) {
;     ...
;             PG8_LDB(B0, 0, 0); PG8_LDB(B1, 0, 1); PG8_SCHED; PG8_LDA(At, 0, 0); PG8_STAGE(PG8_SA(1, 1), a1 + hstepA, voffA);
;             PG8_WAIT_V(8); PG8_WAIT_L(0); PG8_BAR; PG8_MMA(0, 0, At, B0); PG8_MMA(0, 1, At, B1); PG8_BAR; PG8_SCHED;
;             PG8_LDA(At, 0, 1); PG8_STAGE(PG8_SB(0, 0), b2, voffB); PG8_STAGE(PG8_SB(0, 1), b2 + hstepB, voffB); PG8_STAGE(PG8_SA(0, 0), a2, voffA);
.LBB0_1808:
	ds_read_b128 v[144:147], v153
	ds_read_b128 v[156:159], v153 offset:1024
	ds_read_b128 v[160:163], v153 offset:2048
	ds_read_b128 v[164:167], v153 offset:3072
	ds_read_b128 v[168:171], v154
	ds_read_b128 v[172:175], v154 offset:1024
	ds_read_b128 v[176:179], v154 offset:2048
	ds_read_b128 v[180:183], v154 offset:3072
	s_add_u32 s18, s16, 0x100
	s_addc_u32 s19, s17, 0
	s_cmpk_eq_i32 s48, 0x54
	s_cselect_b32 s23, s13, s19
	s_cselect_b32 s22, s12, s18
	s_cselect_b32 s21, s15, s47
	s_cselect_b32 s20, s14, s46
	v_lshl_add_u64 v[148:149], s[16:17], 0, v[138:139]
	s_add_i32 m0, s30, 0xc000
	ds_read_b128 v[184:187], v155
	ds_read_b128 v[188:191], v155 offset:1024
	ds_read_b128 v[192:195], v155 offset:2048
	ds_read_b128 v[196:199], v155 offset:3072
	ds_read_b128 v[200:203], v155 offset:4096
	ds_read_b128 v[204:207], v155 offset:5120
	ds_read_b128 v[208:211], v155 offset:6144
	ds_read_b128 v[212:215], v155 offset:7168
	global_load_lds_dwordx4 v[148:149], off
	v_lshl_add_u64 v[148:149], s[16:17], 0, v[136:137]
	s_add_i32 m0, s30, 0xe000
	s_nop 0
	global_load_lds_dwordx4 v[148:149], off
	s_waitcnt vmcnt(8)
	s_waitcnt lgkmcnt(0)
	s_barrier
	s_setprio 1
	v_mfma_f32_16x16x32_bf16 v[124:127], v[144:147], v[184:187], v[124:127]
	v_mfma_f32_16x16x32_bf16 v[120:123], v[160:163], v[184:187], v[120:123]
	v_mfma_f32_16x16x32_bf16 v[116:119], v[144:147], v[192:195], v[116:119]
	v_mfma_f32_16x16x32_bf16 v[112:115], v[160:163], v[192:195], v[112:115]
	v_mfma_f32_16x16x32_bf16 v[92:95], v[144:147], v[200:203], v[92:95]
	v_mfma_f32_16x16x32_bf16 v[88:91], v[160:163], v[200:203], v[88:91]
	v_mfma_f32_16x16x32_bf16 v[84:87], v[144:147], v[208:211], v[84:87]
	v_mfma_f32_16x16x32_bf16 v[80:83], v[160:163], v[208:211], v[80:83]
	v_mfma_f32_16x16x32_bf16 v[124:127], v[156:159], v[188:191], v[124:127]
	v_mfma_f32_16x16x32_bf16 v[120:123], v[164:167], v[188:191], v[120:123]
	v_mfma_f32_16x16x32_bf16 v[116:119], v[156:159], v[196:199], v[116:119]
	v_mfma_f32_16x16x32_bf16 v[112:115], v[164:167], v[196:199], v[112:115]
	v_mfma_f32_16x16x32_bf16 v[92:95], v[156:159], v[204:207], v[92:95]
	v_mfma_f32_16x16x32_bf16 v[88:91], v[164:167], v[204:207], v[88:91]
	v_mfma_f32_16x16x32_bf16 v[84:87], v[156:159], v[212:215], v[84:87]
	v_mfma_f32_16x16x32_bf16 v[80:83], v[164:167], v[212:215], v[80:83]
	v_mfma_f32_16x16x32_bf16 v[108:111], v[168:171], v[184:187], v[108:111]
	v_mfma_f32_16x16x32_bf16 v[104:107], v[176:179], v[184:187], v[104:107]
	v_mfma_f32_16x16x32_bf16 v[100:103], v[168:171], v[192:195], v[100:103]
	v_mfma_f32_16x16x32_bf16 v[96:99], v[176:179], v[192:195], v[96:99]
	v_mfma_f32_16x16x32_bf16 v[76:79], v[168:171], v[200:203], v[76:79]
	v_mfma_f32_16x16x32_bf16 v[72:75], v[176:179], v[200:203], v[72:75]
	v_mfma_f32_16x16x32_bf16 v[68:71], v[168:171], v[208:211], v[68:71]
	v_mfma_f32_16x16x32_bf16 v[64:67], v[176:179], v[208:211], v[64:67]
	v_mfma_f32_16x16x32_bf16 v[108:111], v[172:175], v[188:191], v[108:111]
	v_mfma_f32_16x16x32_bf16 v[104:107], v[180:183], v[188:191], v[104:107]
	v_mfma_f32_16x16x32_bf16 v[100:103], v[172:175], v[196:199], v[100:103]
	v_mfma_f32_16x16x32_bf16 v[96:99], v[180:183], v[196:199], v[96:99]
	v_mfma_f32_16x16x32_bf16 v[76:79], v[172:175], v[204:207], v[76:79]
	v_mfma_f32_16x16x32_bf16 v[72:75], v[180:183], v[204:207], v[72:75]
	v_mfma_f32_16x16x32_bf16 v[68:71], v[172:175], v[212:215], v[68:71]
	v_mfma_f32_16x16x32_bf16 v[64:67], v[180:183], v[212:215], v[64:67]
	s_setprio 0
	s_barrier
	s_add_i32 s16, s40, s29
	v_lshl_add_u64 v[148:149], s[20:21], 0, v[130:131]
	s_mov_b32 m0, s16
	ds_read_b128 v[184:187], v155 offset:16384
	ds_read_b128 v[188:191], v155 offset:17408
	ds_read_b128 v[192:195], v155 offset:18432
	ds_read_b128 v[196:199], v155 offset:19456
	ds_read_b128 v[200:203], v155 offset:20480
	ds_read_b128 v[204:207], v155 offset:21504
	ds_read_b128 v[208:211], v155 offset:22528
	ds_read_b128 v[212:215], v155 offset:23552
	global_load_lds_dwordx4 v[148:149], off
	s_add_i32 m0, s16, 0x2000
	s_add_u32 s16, s20, 0x160000
	v_lshl_add_u64 v[216:217], s[20:21], 0, v[134:135]
	s_addc_u32 s17, s21, 0
	s_add_i32 s49, s41, s29
	global_load_lds_dwordx4 v[216:217], off
	v_lshl_add_u64 v[218:219], s[16:17], 0, v[130:131]
	s_mov_b32 m0, s49
	v_lshl_add_u64 v[220:221], s[22:23], 0, v[132:133]
	global_load_lds_dwordx4 v[218:219], off
	v_lshl_add_u64 v[218:219], s[16:17], 0, v[134:135]
	s_add_i32 m0, s49, 0x2000
	s_nop 0
	global_load_lds_dwordx4 v[218:219], off
	v_lshl_add_u64 v[218:219], s[22:23], 0, v[128:129]
	s_mov_b32 m0, s30
	s_nop 0
	global_load_lds_dwordx4 v[218:219], off
	s_mov_b32 m0, s31
	s_nop 0
	global_load_lds_dwordx4 v[220:221], off
	s_waitcnt vmcnt(8)
	s_waitcnt lgkmcnt(0)
	s_barrier
; #define PG8_STAGE(bufoff, gbase, voff) do { _Pragma("unroll") for (int _i = 0; _i < 2; ++_i) \
;         __builtin_amdgcn_global_load_lds((const unsigned*)((const char*)(gbase) + (voff)[_i]), (PG8_LAS unsigned*)(lds + (bufoff) + ldsw + _i * 8192), 16, 0, 0); } while (0)
; #define PG8_LDA(dst, b, h) do { _Pragma("unroll") for (int m = 0; m < 4; ++m) _Pragma("unroll") for (int k = 0; k < 2; ++k) dst[m][k] = *(const PG8_LAS bf16x8*)(lds + PG8_SA(b, h) + aoff + m * 2048 + k * 1024); } while (0)
; #define PG8_LDB(dst, b, h) do { _Pragma("unroll") for (int n = 0; n < 2; ++n) _Pragma("unroll") for (int k = 0; k < 2; ++k) dst[n][k] = *(const PG8_LAS bf16x8*)(lds + PG8_SB(b, h) + boff + n * 2048 + k * 1024); } while (0)
; #define PG8_MMA(ai, bj, At, Bt) do { __builtin_amdgcn_s_setprio(1); _Pragma("unroll") for (int m = 0; m < 4; ++m) _Pragma("unroll") for (int n = 0; n < 2; ++n) _Pragma("unroll") for (int k = 0; k < 2; ++k) \
;         acc[ai][bj][m][n] = __builtin_amdgcn_mfma_f32_16x16x32_bf16(Bt[n][k], At[m][k], acc[ai][bj][m][n], 0, 0, 0); __builtin_amdgcn_s_setprio(0); } while (0)
; #define PG8_WAIT_V(n) asm volatile("s_waitcnt vmcnt(" #n ")" ::: "memory")
; #define PG8_WAIT_L(n) asm volatile("s_waitcnt lgkmcnt(" #n ")" ::: "memory")
; #define PG8_BAR __builtin_amdgcn_s_barrier()
; #define PG8_SCHED __builtin_amdgcn_sched_barrier(0)
; template <class Epi, class Sched, bool ALIGN_EPI = false, bool SP2 = false>
; __device__ __forceinline__ void gemm_phase(PG8_LAS unsigned char* lds, const Gemm g, const Sched& S, const Epi& E, const int wv0) {
;     ...
;             PG8_WAIT_V(8); PG8_WAIT_L(0); PG8_BAR; PG8_MMA(1, 0, At, B0); PG8_MMA(1, 1, At, B1); PG8_BAR; PG8_SCHED;
;             PG8_LDB(B0, 1, 0); PG8_LDB(B1, 1, 1); PG8_SCHED; PG8_LDA(At, 1, 0); PG8_STAGE(PG8_SA(0, 1), a2 + hstepA, voffA);
;             PG8_WAIT_V(8); PG8_WAIT_L(0); PG8_BAR; PG8_MMA(0, 0, At, B0); PG8_MMA(0, 1, At, B1); PG8_BAR; PG8_SCHED;
	s_setprio 1
	v_mfma_f32_16x16x32_bf16 v[60:63], v[144:147], v[184:187], v[60:63]
	v_mfma_f32_16x16x32_bf16 v[56:59], v[160:163], v[184:187], v[56:59]
	v_mfma_f32_16x16x32_bf16 v[52:55], v[144:147], v[192:195], v[52:55]
	v_mfma_f32_16x16x32_bf16 v[48:51], v[160:163], v[192:195], v[48:51]
	v_mfma_f32_16x16x32_bf16 v[28:31], v[144:147], v[200:203], v[28:31]
	v_mfma_f32_16x16x32_bf16 v[24:27], v[160:163], v[200:203], v[24:27]
	v_mfma_f32_16x16x32_bf16 v[20:23], v[144:147], v[208:211], v[20:23]
	v_mfma_f32_16x16x32_bf16 v[16:19], v[160:163], v[208:211], v[16:19]
	v_mfma_f32_16x16x32_bf16 v[60:63], v[156:159], v[188:191], v[60:63]
	v_mfma_f32_16x16x32_bf16 v[56:59], v[164:167], v[188:191], v[56:59]
	v_mfma_f32_16x16x32_bf16 v[52:55], v[156:159], v[196:199], v[52:55]
	v_mfma_f32_16x16x32_bf16 v[48:51], v[164:167], v[196:199], v[48:51]
	v_mfma_f32_16x16x32_bf16 v[28:31], v[156:159], v[204:207], v[28:31]
	v_mfma_f32_16x16x32_bf16 v[24:27], v[164:167], v[204:207], v[24:27]
	v_mfma_f32_16x16x32_bf16 v[20:23], v[156:159], v[212:215], v[20:23]
	v_mfma_f32_16x16x32_bf16 v[16:19], v[164:167], v[212:215], v[16:19]
	v_mfma_f32_16x16x32_bf16 v[44:47], v[168:171], v[184:187], v[44:47]
	v_mfma_f32_16x16x32_bf16 v[40:43], v[176:179], v[184:187], v[40:43]
	v_mfma_f32_16x16x32_bf16 v[36:39], v[168:171], v[192:195], v[36:39]
	v_mfma_f32_16x16x32_bf16 v[32:35], v[176:179], v[192:195], v[32:35]
	v_mfma_f32_16x16x32_bf16 v[12:15], v[168:171], v[200:203], v[12:15]
	v_mfma_f32_16x16x32_bf16 v[8:11], v[176:179], v[200:203], v[8:11]
	v_mfma_f32_16x16x32_bf16 v[4:7], v[168:171], v[208:211], v[4:7]
	v_mfma_f32_16x16x32_bf16 v[0:3], v[176:179], v[208:211], v[0:3]
	v_mfma_f32_16x16x32_bf16 v[44:47], v[172:175], v[188:191], v[44:47]
	v_mfma_f32_16x16x32_bf16 v[40:43], v[180:183], v[188:191], v[40:43]
	v_mfma_f32_16x16x32_bf16 v[36:39], v[172:175], v[196:199], v[36:39]
	v_mfma_f32_16x16x32_bf16 v[32:35], v[180:183], v[196:199], v[32:35]
	v_mfma_f32_16x16x32_bf16 v[12:15], v[172:175], v[204:207], v[12:15]
	v_mfma_f32_16x16x32_bf16 v[8:11], v[180:183], v[204:207], v[8:11]
	v_mfma_f32_16x16x32_bf16 v[4:7], v[172:175], v[212:215], v[4:7]
	v_mfma_f32_16x16x32_bf16 v[0:3], v[180:183], v[212:215], v[0:3]
	s_setprio 0
	s_barrier
	s_add_i32 s49, 0, 0x18000
	s_add_i32 s50, 0, 0x1c000
	v_add_u32_e32 v164, s49, v151
	v_add_u32_e32 v180, s50, v151
	ds_read_b128 v[144:147], v164
	ds_read_b128 v[156:159], v164 offset:1024
	ds_read_b128 v[160:163], v164 offset:2048
	ds_read_b128 v[164:167], v164 offset:3072
	ds_read_b128 v[168:171], v180
	ds_read_b128 v[172:175], v180 offset:1024
	ds_read_b128 v[176:179], v180 offset:2048
	ds_read_b128 v[180:183], v180 offset:3072
	s_add_u32 s16, s22, 0x160000
	s_addc_u32 s17, s23, 0
	s_mov_b32 m0, s34
	v_lshl_add_u64 v[222:223], s[16:17], 0, v[128:129]
	ds_read_b128 v[184:187], v155 offset:32768
	ds_read_b128 v[188:191], v155 offset:33792
	ds_read_b128 v[192:195], v155 offset:34816
	ds_read_b128 v[196:199], v155 offset:35840
	ds_read_b128 v[200:203], v155 offset:36864
	ds_read_b128 v[204:207], v155 offset:37888
	ds_read_b128 v[208:211], v155 offset:38912
	ds_read_b128 v[212:215], v155 offset:39936
	global_load_lds_dwordx4 v[222:223], off
	v_lshl_add_u64 v[222:223], s[16:17], 0, v[132:133]
	s_mov_b32 m0, s35
	s_nop 0
	global_load_lds_dwordx4 v[222:223], off
	s_waitcnt vmcnt(8)
	s_waitcnt lgkmcnt(0)
	s_barrier
	s_setprio 1
	v_mfma_f32_16x16x32_bf16 v[124:127], v[144:147], v[184:187], v[124:127]
	v_mfma_f32_16x16x32_bf16 v[120:123], v[160:163], v[184:187], v[120:123]
	v_mfma_f32_16x16x32_bf16 v[116:119], v[144:147], v[192:195], v[116:119]
	v_mfma_f32_16x16x32_bf16 v[112:115], v[160:163], v[192:195], v[112:115]
	v_mfma_f32_16x16x32_bf16 v[92:95], v[144:147], v[200:203], v[92:95]
	v_mfma_f32_16x16x32_bf16 v[88:91], v[160:163], v[200:203], v[88:91]
	v_mfma_f32_16x16x32_bf16 v[84:87], v[144:147], v[208:211], v[84:87]
	v_mfma_f32_16x16x32_bf16 v[80:83], v[160:163], v[208:211], v[80:83]
	v_mfma_f32_16x16x32_bf16 v[124:127], v[156:159], v[188:191], v[124:127]
	v_mfma_f32_16x16x32_bf16 v[120:123], v[164:167], v[188:191], v[120:123]
	v_mfma_f32_16x16x32_bf16 v[116:119], v[156:159], v[196:199], v[116:119]
	v_mfma_f32_16x16x32_bf16 v[112:115], v[164:167], v[196:199], v[112:115]
	v_mfma_f32_16x16x32_bf16 v[92:95], v[156:159], v[204:207], v[92:95]
	v_mfma_f32_16x16x32_bf16 v[88:91], v[164:167], v[204:207], v[88:91]
	v_mfma_f32_16x16x32_bf16 v[84:87], v[156:159], v[212:215], v[84:87]
	v_mfma_f32_16x16x32_bf16 v[80:83], v[164:167], v[212:215], v[80:83]
	v_mfma_f32_16x16x32_bf16 v[108:111], v[168:171], v[184:187], v[108:111]
	v_mfma_f32_16x16x32_bf16 v[104:107], v[176:179], v[184:187], v[104:107]
	v_mfma_f32_16x16x32_bf16 v[100:103], v[168:171], v[192:195], v[100:103]
	v_mfma_f32_16x16x32_bf16 v[96:99], v[176:179], v[192:195], v[96:99]
	v_mfma_f32_16x16x32_bf16 v[76:79], v[168:171], v[200:203], v[76:79]
	v_mfma_f32_16x16x32_bf16 v[72:75], v[176:179], v[200:203], v[72:75]
	v_mfma_f32_16x16x32_bf16 v[68:71], v[168:171], v[208:211], v[68:71]
	v_mfma_f32_16x16x32_bf16 v[64:67], v[176:179], v[208:211], v[64:67]
	v_mfma_f32_16x16x32_bf16 v[108:111], v[172:175], v[188:191], v[108:111]
	v_mfma_f32_16x16x32_bf16 v[104:107], v[180:183], v[188:191], v[104:107]
	v_mfma_f32_16x16x32_bf16 v[100:103], v[172:175], v[196:199], v[100:103]
	v_mfma_f32_16x16x32_bf16 v[96:99], v[180:183], v[196:199], v[96:99]
	v_mfma_f32_16x16x32_bf16 v[76:79], v[172:175], v[204:207], v[76:79]
	v_mfma_f32_16x16x32_bf16 v[72:75], v[180:183], v[204:207], v[72:75]
	v_mfma_f32_16x16x32_bf16 v[68:71], v[172:175], v[212:215], v[68:71]
	v_mfma_f32_16x16x32_bf16 v[64:67], v[180:183], v[212:215], v[64:67]
	s_setprio 0
	s_barrier
; #define PG8_STAGE(bufoff, gbase, voff) do { _Pragma("unroll") for (int _i = 0; _i < 2; ++_i) \
;         __builtin_amdgcn_global_load_lds((const unsigned*)((const char*)(gbase) + (voff)[_i]), (PG8_LAS unsigned*)(lds + (bufoff) + ldsw + _i * 8192), 16, 0, 0); } while (0)
; #define PG8_LDA(dst, b, h) do { _Pragma("unroll") for (int m = 0; m < 4; ++m) _Pragma("unroll") for (int k = 0; k < 2; ++k) dst[m][k] = *(const PG8_LAS bf16x8*)(lds + PG8_SA(b, h) + aoff + m * 2048 + k * 1024); } while (0)
; #define PG8_MMA(ai, bj, At, Bt) do { __builtin_amdgcn_s_setprio(1); _Pragma("unroll") for (int m = 0; m < 4; ++m) _Pragma("unroll") for (int n = 0; n < 2; ++n) _Pragma("unroll") for (int k = 0; k < 2; ++k) \
;         acc[ai][bj][m][n] = __builtin_amdgcn_mfma_f32_16x16x32_bf16(Bt[n][k], At[m][k], acc[ai][bj][m][n], 0, 0, 0); __builtin_amdgcn_s_setprio(0); } while (0)
; #define PG8_WAIT_V(n) asm volatile("s_waitcnt vmcnt(" #n ")" ::: "memory")
; #define PG8_WAIT_L(n) asm volatile("s_waitcnt lgkmcnt(" #n ")" ::: "memory")
; #define PG8_BAR __builtin_amdgcn_s_barrier()
; #define PG8_SCHED __builtin_amdgcn_sched_barrier(0)
; template <class Epi, class Sched, bool ALIGN_EPI = false, bool SP2 = false>
; __device__ __forceinline__ void gemm_phase(PG8_LAS unsigned char* lds, const Gemm g, const Sched& S, const Epi& E, const int wv0) {
;     ...
;         for (int t = 0; t < nt; t += 2) {
;             const bool last = (t == nt - 2);
;             const char* a1 = cA + (size_t)(t + 1) * kstep;
;             const char* a2 = last ? nA : cA + (size_t)(t + 2) * kstep; const char* b2 = last ? nB : cB + (size_t)(t + 2) * kstep;
;     ...
;             PG8_LDA(At, 1, 1); PG8_STAGE(PG8_SB(1, 0), b3, voffB); PG8_STAGE(PG8_SB(1, 1), b3 + hstepB, voffB); PG8_STAGE(PG8_SA(1, 0), a3, voffA);
;             PG8_WAIT_V(8); PG8_WAIT_L(0); PG8_BAR; PG8_MMA(1, 0, At, B0); PG8_MMA(1, 1, At, B1); PG8_BAR; PG8_SCHED;
	s_add_i32 s16, s49, s29
	v_lshl_add_u64 v[148:149], v[148:149], 0, s[8:9]
	s_mov_b32 m0, s16
	ds_read_b128 v[184:187], v155 offset:49152
	ds_read_b128 v[188:191], v155 offset:50176
	ds_read_b128 v[192:195], v155 offset:51200
	ds_read_b128 v[196:199], v155 offset:52224
	ds_read_b128 v[200:203], v155 offset:53248
	ds_read_b128 v[204:207], v155 offset:54272
	ds_read_b128 v[208:211], v155 offset:55296
	ds_read_b128 v[212:215], v155 offset:56320
	global_load_lds_dwordx4 v[148:149], off
	s_add_i32 m0, s16, 0x2000
	s_add_u32 s16, s20, 0x160080
	v_lshl_add_u64 v[148:149], v[216:217], 0, s[8:9]
	s_addc_u32 s17, s21, 0
	s_add_i32 s20, s50, s29
	global_load_lds_dwordx4 v[148:149], off
	v_lshl_add_u64 v[148:149], s[16:17], 0, v[130:131]
	s_mov_b32 m0, s20
	s_nop 0
	global_load_lds_dwordx4 v[148:149], off
	v_lshl_add_u64 v[148:149], s[16:17], 0, v[134:135]
	s_add_i32 m0, s20, 0x2000
	s_nop 0
	global_load_lds_dwordx4 v[148:149], off
	v_lshl_add_u64 v[148:149], v[218:219], 0, s[8:9]
	s_mov_b32 m0, s37
	s_nop 0
	global_load_lds_dwordx4 v[148:149], off
	v_lshl_add_u64 v[148:149], v[220:221], 0, s[8:9]
	s_mov_b32 m0, s38
	s_nop 0
	global_load_lds_dwordx4 v[148:149], off
	s_waitcnt vmcnt(8)
	s_waitcnt lgkmcnt(0)
	s_barrier
	s_setprio 1
	v_mfma_f32_16x16x32_bf16 v[60:63], v[144:147], v[184:187], v[60:63]
	v_mfma_f32_16x16x32_bf16 v[56:59], v[160:163], v[184:187], v[56:59]
	v_mfma_f32_16x16x32_bf16 v[52:55], v[144:147], v[192:195], v[52:55]
	v_mfma_f32_16x16x32_bf16 v[48:51], v[160:163], v[192:195], v[48:51]
	v_mfma_f32_16x16x32_bf16 v[28:31], v[144:147], v[200:203], v[28:31]
	v_mfma_f32_16x16x32_bf16 v[24:27], v[160:163], v[200:203], v[24:27]
	v_mfma_f32_16x16x32_bf16 v[20:23], v[144:147], v[208:211], v[20:23]
	v_mfma_f32_16x16x32_bf16 v[16:19], v[160:163], v[208:211], v[16:19]
	v_mfma_f32_16x16x32_bf16 v[60:63], v[156:159], v[188:191], v[60:63]
	v_mfma_f32_16x16x32_bf16 v[56:59], v[164:167], v[188:191], v[56:59]
	v_mfma_f32_16x16x32_bf16 v[52:55], v[156:159], v[196:199], v[52:55]
	v_mfma_f32_16x16x32_bf16 v[48:51], v[164:167], v[196:199], v[48:51]
	v_mfma_f32_16x16x32_bf16 v[28:31], v[156:159], v[204:207], v[28:31]
	v_mfma_f32_16x16x32_bf16 v[24:27], v[164:167], v[204:207], v[24:27]
	v_mfma_f32_16x16x32_bf16 v[20:23], v[156:159], v[212:215], v[20:23]
	v_mfma_f32_16x16x32_bf16 v[16:19], v[164:167], v[212:215], v[16:19]
	v_mfma_f32_16x16x32_bf16 v[44:47], v[168:171], v[184:187], v[44:47]
	v_mfma_f32_16x16x32_bf16 v[40:43], v[176:179], v[184:187], v[40:43]
	v_mfma_f32_16x16x32_bf16 v[36:39], v[168:171], v[192:195], v[36:39]
	v_mfma_f32_16x16x32_bf16 v[32:35], v[176:179], v[192:195], v[32:35]
	v_mfma_f32_16x16x32_bf16 v[12:15], v[168:171], v[200:203], v[12:15]
	v_mfma_f32_16x16x32_bf16 v[8:11], v[176:179], v[200:203], v[8:11]
	v_mfma_f32_16x16x32_bf16 v[4:7], v[168:171], v[208:211], v[4:7]
	v_mfma_f32_16x16x32_bf16 v[0:3], v[176:179], v[208:211], v[0:3]
	v_mfma_f32_16x16x32_bf16 v[44:47], v[172:175], v[188:191], v[44:47]
	v_mfma_f32_16x16x32_bf16 v[40:43], v[180:183], v[188:191], v[40:43]
	v_mfma_f32_16x16x32_bf16 v[36:39], v[172:175], v[196:199], v[36:39]
	v_mfma_f32_16x16x32_bf16 v[32:35], v[180:183], v[196:199], v[32:35]
	v_mfma_f32_16x16x32_bf16 v[12:15], v[172:175], v[204:207], v[12:15]
	v_mfma_f32_16x16x32_bf16 v[8:11], v[180:183], v[204:207], v[8:11]
	v_mfma_f32_16x16x32_bf16 v[4:7], v[172:175], v[212:215], v[4:7]
	v_mfma_f32_16x16x32_bf16 v[0:3], v[180:183], v[212:215], v[0:3]
	s_setprio 0
	s_barrier
	s_add_i32 s48, s48, 2
	s_add_u32 s46, s46, 0x100
	s_addc_u32 s47, s47, 0
	s_cmpk_gt_u32 s48, 0x55
	s_mov_b64 s[16:17], s[18:19]
	s_cbranch_scc0 .LBB0_1808
	s_and_b64 vcc, exec, s[10:11]
	s_cbranch_vccz .LBB0_1811
	s_barrier
